# activations H also in blocked layout for in-proj GEMMs; all flat loads/stores converted to global
# speedup vs baseline: 1.0585x; 1.0249x over previous
.LBB0_23:
	s_or_b64 exec, exec, s[38:39]
	v_lshlrev_b64 v[50:51], 12, v[50:51]
	v_lshl_add_u64 v[52:53], s[24:25], 0, v[56:57]
	v_lshl_add_u64 v[50:51], v[54:55], 0, v[50:51]
	v_lshl_add_u64 v[58:59], v[52:53], 0, s[98:99]
	v_lshl_add_u64 v[50:51], v[50:51], 0, v[100:101]
	v_lshl_add_u64 v[54:55], v[52:53], 0, v[100:101]
	v_lshl_add_u64 v[52:53], v[58:59], 0, v[100:101]
	v_lshl_add_u64 v[56:57], v[58:59], 0, v[102:103]
	global_load_dwordx4 v[86:89], v[50:51], off
	global_load_dwordx4 v[70:73], v[50:51], off offset:1024
	global_load_dwordx4 v[90:93], v[54:55], off
	global_load_dwordx4 v[74:77], v[54:55], off offset:1024
	global_load_dwordx4 v[94:97], v[52:53], off
	global_load_dwordx4 v[82:85], v[56:57], off
	global_load_dwordx4 v[62:65], v[50:51], off offset:2048
	s_nop 0
	global_load_dwordx4 v[50:53], v[50:51], off offset:3072
	s_nop 0
	global_load_dwordx4 v[66:69], v[54:55], off offset:2048
	s_nop 0
	global_load_dwordx4 v[54:57], v[54:55], off offset:3072
	v_lshl_add_u64 v[60:61], v[58:59], 0, v[104:105]
	v_lshl_add_u64 v[58:59], v[58:59], 0, v[106:107]
	global_load_dwordx4 v[78:81], v[60:61], off
	s_nop 0
	global_load_dwordx4 v[58:61], v[58:59], off
	v_add_u32_e32 v110, s4, v108
	v_cmp_gt_i32_e32 vcc, s14, v110
	s_and_saveexec_b64 s[38:39], vcc
	s_cbranch_execz .LBB0_29
	v_mul_hi_i32 v0, v110, s30
	v_lshrrev_b32_e32 v2, 31, v0
	v_ashrrev_i32_e32 v0, 9, v0
	v_add_u32_e32 v4, v0, v2
	v_mul_i32_i24_e32 v0, 0x900, v4
	v_sub_u32_e32 v2, v110, v0
	v_cmp_lt_i32_e32 vcc, s97, v2
	v_ashrrev_i32_e32 v5, 31, v4
	s_and_saveexec_b64 s[6:7], vcc
	s_xor_b64 s[40:41], exec, s[6:7]
	s_cbranch_execz .LBB0_26
	v_readlane_b32 s44, v253, 4
	v_add_u32_e32 v0, 0xffffff00, v2
	v_lshlrev_b64 v[2:3], 23, v[4:5]
	v_readlane_b32 s45, v253, 5
	v_mul_hi_i32_i24_e32 v9, 0x3000, v4
	v_mul_i32_i24_e32 v8, 0x3000, v4
	v_lshl_add_u64 v[6:7], s[44:45], 0, v[2:3]
	v_mov_b64_e32 v[2:3], v[0:1]
	v_readlane_b32 s46, v253, 6
	v_readlane_b32 s47, v253, 7
	v_readlane_b32 s48, v253, 8
	v_readlane_b32 s49, v253, 9
	v_readlane_b32 s50, v253, 10
	v_readlane_b32 s51, v253, 11
	v_readlane_b32 s52, v253, 12
	v_readlane_b32 s53, v253, 13
	v_readlane_b32 s54, v253, 14
	v_readlane_b32 s55, v253, 15
	v_readlane_b32 s56, v253, 16
	v_readlane_b32 s57, v253, 17
	v_readlane_b32 s58, v253, 18
	v_readlane_b32 s59, v253, 19

.LBB0_28:
	s_or_b64 exec, exec, s[40:41]
	v_lshlrev_b64 v[2:3], 12, v[2:3]
	v_lshl_add_u64 v[4:5], s[24:25], 0, v[8:9]
	v_lshl_add_u64 v[2:3], v[6:7], 0, v[2:3]
	v_lshl_add_u64 v[42:43], v[4:5], 0, s[98:99]
	v_lshl_add_u64 v[22:23], v[2:3], 0, v[100:101]
	v_lshl_add_u64 v[38:39], v[4:5], 0, v[100:101]
	v_lshl_add_u64 v[18:19], v[42:43], 0, v[100:101]
	v_lshl_add_u64 v[20:21], v[42:43], 0, v[102:103]
	global_load_dwordx4 v[2:5], v[22:23], off
	global_load_dwordx4 v[6:9], v[22:23], off offset:1024
	global_load_dwordx4 v[10:13], v[38:39], off
	global_load_dwordx4 v[14:17], v[38:39], off offset:1024
	global_load_dwordx4 v[26:29], v[18:19], off
	global_load_dwordx4 v[30:33], v[20:21], off
	s_nop 0
	global_load_dwordx4 v[18:21], v[22:23], off offset:2048
	s_nop 0
	global_load_dwordx4 v[22:25], v[22:23], off offset:3072
	s_nop 0
	global_load_dwordx4 v[34:37], v[38:39], off offset:2048
	s_nop 0
	global_load_dwordx4 v[38:41], v[38:39], off offset:3072
	v_lshl_add_u64 v[44:45], v[42:43], 0, v[104:105]
	v_lshl_add_u64 v[46:47], v[42:43], 0, v[106:107]
	global_load_dwordx4 v[42:45], v[44:45], off
	s_nop 0
	global_load_dwordx4 v[46:49], v[46:47], off
.LBB0_29:
	s_or_b64 exec, exec, s[38:39]
	v_ashrrev_i32_e32 v109, 31, v108
	s_waitcnt vmcnt(0) lgkmcnt(0)
	v_pk_add_f32 v[96:97], v[96:97], 1.0 op_sel_hi:[1,0]
	v_pk_add_f32 v[94:95], v[94:95], 1.0 op_sel_hi:[1,0]
	v_pk_add_f32 v[84:85], v[84:85], 1.0 op_sel_hi:[1,0]
	v_pk_add_f32 v[82:83], v[82:83], 1.0 op_sel_hi:[1,0]
	v_lshlrev_b64 v[108:109], 11, v[108:109]
	v_pk_fma_f32 v[88:89], v[88:89], v[96:97], v[92:93]
	v_pk_fma_f32 v[86:87], v[86:87], v[94:95], v[90:91]
	v_pk_fma_f32 v[72:73], v[72:73], v[84:85], v[76:77]
	v_pk_fma_f32 v[70:71], v[70:71], v[82:83], v[74:75]
	v_cvt_pk_bf16_f32 v86, v86, v87
	v_cvt_pk_bf16_f32 v87, v88, v89
	v_lshl_add_u64 v[88:89], v[98:99], 0, v[108:109]
	v_cvt_pk_bf16_f32 v70, v70, v71
	v_cvt_pk_bf16_f32 v71, v72, v73
	v_subrev_u32_e32 v240, s94, v88
	v_add_u32_e32 v240, 0x200, v240
	v_bfe_u32 v241, v240, 6, 5
	v_and_b32_e32 v242, 63, v240
	v_lshl_or_b32 v242, v241, 10, v242
	v_bfe_u32 v241, v240, 11, 4
	v_lshl_or_b32 v242, v241, 6, v242
	v_and_b32_e32 v241, 0x7fff, v240
	v_sub_u32_e32 v242, v242, v241
	v_add_u32_e32 v242, 0x200, v242
	v_ashrrev_i32_e32 v243, 31, v242
	v_lshl_add_u64 v[240:241], v[88:89], 0, v[242:243]
	global_store_dwordx2 v[240:241], v[70:71], off
	v_pk_add_f32 v[70:71], v[80:81], 1.0 op_sel_hi:[1,0]
	v_pk_add_f32 v[72:73], v[78:79], 1.0 op_sel_hi:[1,0]
	v_pk_add_f32 v[60:61], v[60:61], 1.0 op_sel_hi:[1,0]
	v_pk_add_f32 v[58:59], v[58:59], 1.0 op_sel_hi:[1,0]
	v_pk_fma_f32 v[64:65], v[64:65], v[70:71], v[68:69]
	v_pk_fma_f32 v[62:63], v[62:63], v[72:73], v[66:67]
	v_pk_fma_f32 v[52:53], v[52:53], v[60:61], v[56:57]
	v_pk_fma_f32 v[50:51], v[50:51], v[58:59], v[54:55]
	v_cvt_pk_bf16_f32 v62, v62, v63
	v_cvt_pk_bf16_f32 v63, v64, v65
	v_cvt_pk_bf16_f32 v50, v50, v51
	v_cvt_pk_bf16_f32 v51, v52, v53
	v_cmp_gt_i32_e32 vcc, s14, v110
	v_subrev_u32_e32 v240, s94, v88
	v_bfe_u32 v241, v240, 6, 5
	v_and_b32_e32 v242, 63, v240
	v_lshl_or_b32 v242, v241, 10, v242
	v_bfe_u32 v241, v240, 11, 4
	v_lshl_or_b32 v242, v241, 6, v242
	v_and_b32_e32 v241, 0x7fff, v240
	v_sub_u32_e32 v242, v242, v241
	v_ashrrev_i32_e32 v243, 31, v242
	v_lshl_add_u64 v[240:241], v[88:89], 0, v[242:243]
	global_store_dwordx2 v[240:241], v[86:87], off
	v_subrev_u32_e32 v240, s94, v88
	v_add_u32_e32 v240, 0x400, v240
	v_bfe_u32 v241, v240, 6, 5
	v_and_b32_e32 v242, 63, v240
	v_lshl_or_b32 v242, v241, 10, v242
	v_bfe_u32 v241, v240, 11, 4
	v_lshl_or_b32 v242, v241, 6, v242
	v_and_b32_e32 v241, 0x7fff, v240
	v_sub_u32_e32 v242, v242, v241
	v_add_u32_e32 v242, 0x400, v242
	v_ashrrev_i32_e32 v243, 31, v242
	v_lshl_add_u64 v[240:241], v[88:89], 0, v[242:243]
	global_store_dwordx2 v[240:241], v[62:63], off
	v_subrev_u32_e32 v240, s94, v88
	v_add_u32_e32 v240, 0x600, v240
	v_bfe_u32 v241, v240, 6, 5
	v_and_b32_e32 v242, 63, v240
	v_lshl_or_b32 v242, v241, 10, v242
	v_bfe_u32 v241, v240, 11, 4
	v_lshl_or_b32 v242, v241, 6, v242
	v_and_b32_e32 v241, 0x7fff, v240
	v_sub_u32_e32 v242, v242, v241
	v_add_u32_e32 v242, 0x600, v242
	v_ashrrev_i32_e32 v243, 31, v242
	v_lshl_add_u64 v[240:241], v[88:89], 0, v[242:243]
	global_store_dwordx2 v[240:241], v[50:51], off
	s_and_saveexec_b64 s[38:39], vcc
	s_cbranch_execz .LBB0_18
	v_ashrrev_i32_e32 v111, 31, v110
	v_pk_add_f32 v[52:53], v[28:29], 1.0 op_sel_hi:[1,0]
	v_pk_add_f32 v[54:55], v[26:27], 1.0 op_sel_hi:[1,0]
	v_lshlrev_b64 v[50:51], 11, v[110:111]
	v_pk_fma_f32 v[52:53], v[4:5], v[52:53], v[12:13]
	v_pk_fma_f32 v[54:55], v[2:3], v[54:55], v[10:11]
	v_lshl_add_u64 v[50:51], v[98:99], 0, v[50:51]
	v_cvt_pk_bf16_f32 v54, v54, v55
	v_cvt_pk_bf16_f32 v55, v52, v53
	v_subrev_u32_e32 v240, s94, v50
	v_bfe_u32 v241, v240, 6, 5
	v_and_b32_e32 v242, 63, v240
	v_lshl_or_b32 v242, v241, 10, v242
	v_bfe_u32 v241, v240, 11, 4
	v_lshl_or_b32 v242, v241, 6, v242
	v_and_b32_e32 v241, 0x7fff, v240
	v_sub_u32_e32 v242, v242, v241
	v_ashrrev_i32_e32 v243, 31, v242
	v_lshl_add_u64 v[240:241], v[50:51], 0, v[242:243]
	global_store_dwordx2 v[240:241], v[54:55], off
	v_pk_add_f32 v[52:53], v[32:33], 1.0 op_sel_hi:[1,0]
	v_pk_add_f32 v[54:55], v[30:31], 1.0 op_sel_hi:[1,0]
	v_pk_fma_f32 v[52:53], v[8:9], v[52:53], v[16:17]
	v_pk_fma_f32 v[54:55], v[6:7], v[54:55], v[14:15]
	s_nop 0
	v_cvt_pk_bf16_f32 v54, v54, v55
	v_cvt_pk_bf16_f32 v55, v52, v53
	v_subrev_u32_e32 v240, s94, v50
	v_add_u32_e32 v240, 0x200, v240
	v_bfe_u32 v241, v240, 6, 5
	v_and_b32_e32 v242, 63, v240
	v_lshl_or_b32 v242, v241, 10, v242
	v_bfe_u32 v241, v240, 11, 4
	v_lshl_or_b32 v242, v241, 6, v242
	v_and_b32_e32 v241, 0x7fff, v240
	v_sub_u32_e32 v242, v242, v241
	v_add_u32_e32 v242, 0x200, v242
	v_ashrrev_i32_e32 v243, 31, v242
	v_lshl_add_u64 v[240:241], v[50:51], 0, v[242:243]
	global_store_dwordx2 v[240:241], v[54:55], off
	v_pk_add_f32 v[52:53], v[44:45], 1.0 op_sel_hi:[1,0]
	v_pk_add_f32 v[54:55], v[42:43], 1.0 op_sel_hi:[1,0]
	v_pk_fma_f32 v[52:53], v[20:21], v[52:53], v[36:37]
	v_pk_fma_f32 v[54:55], v[18:19], v[54:55], v[34:35]
	s_nop 0
	v_cvt_pk_bf16_f32 v54, v54, v55
	v_cvt_pk_bf16_f32 v55, v52, v53
	v_subrev_u32_e32 v240, s94, v50
	v_add_u32_e32 v240, 0x400, v240
	v_bfe_u32 v241, v240, 6, 5
	v_and_b32_e32 v242, 63, v240
	v_lshl_or_b32 v242, v241, 10, v242
	v_bfe_u32 v241, v240, 11, 4
	v_lshl_or_b32 v242, v241, 6, v242
	v_and_b32_e32 v241, 0x7fff, v240
	v_sub_u32_e32 v242, v242, v241
	v_add_u32_e32 v242, 0x400, v242
	v_ashrrev_i32_e32 v243, 31, v242
	v_lshl_add_u64 v[240:241], v[50:51], 0, v[242:243]
	global_store_dwordx2 v[240:241], v[54:55], off
	v_pk_add_f32 v[52:53], v[48:49], 1.0 op_sel_hi:[1,0]
	v_pk_add_f32 v[54:55], v[46:47], 1.0 op_sel_hi:[1,0]
	v_pk_fma_f32 v[52:53], v[24:25], v[52:53], v[40:41]
	v_pk_fma_f32 v[54:55], v[22:23], v[54:55], v[38:39]
	s_nop 0
	v_cvt_pk_bf16_f32 v54, v54, v55
	v_cvt_pk_bf16_f32 v55, v52, v53
	v_subrev_u32_e32 v240, s94, v50
	v_add_u32_e32 v240, 0x600, v240
	v_bfe_u32 v241, v240, 6, 5
	v_and_b32_e32 v242, 63, v240
	v_lshl_or_b32 v242, v241, 10, v242
	v_bfe_u32 v241, v240, 11, 4
	v_lshl_or_b32 v242, v241, 6, v242
	v_and_b32_e32 v241, 0x7fff, v240
	v_sub_u32_e32 v242, v242, v241
	v_add_u32_e32 v242, 0x600, v242
	v_ashrrev_i32_e32 v243, 31, v242
	v_lshl_add_u64 v[240:241], v[50:51], 0, v[242:243]
	global_store_dwordx2 v[240:241], v[54:55], off
	s_branch .LBB0_18

.LBB0_62:
	v_mul_hi_i32 v0, v130, s30
	v_lshrrev_b32_e32 v98, 31, v0
	v_ashrrev_i32_e32 v0, 9, v0
	v_add_u32_e32 v182, v0, v98
	v_mul_i32_i24_e32 v0, 0x900, v182
	v_sub_u32_e32 v137, v130, v0
	v_cmp_lt_i32_e32 vcc, s97, v137
	s_or_b64 s[52:53], s[40:41], vcc
	v_mov_b32_e32 v0, 0
	v_ashrrev_i32_e32 v183, 31, v182
	v_add_u32_e32 v139, 0xffffff00, v137
	v_ashrrev_i32_e32 v141, 31, v137
	v_ashrrev_i32_e32 v131, 31, v130
	v_lshlrev_b32_e32 v176, 2, v132
	s_and_saveexec_b64 s[50:51], s[52:53]
	s_cbranch_execz .LBB0_72
	s_movk_i32 s0, 0x100
	v_cmp_gt_i32_e32 vcc, s0, v137
	v_mov_b32_e32 v98, s12
	v_mov_b32_e32 v99, s10
	v_cndmask_b32_e32 v99, v98, v99, vcc
	v_mov_b32_e32 v98, s13
	v_mov_b32_e32 v100, s11
	v_cndmask_b32_e64 v102, 23, 20, vcc
	v_cndmask_b32_e32 v98, v98, v100, vcc
	v_cndmask_b32_e32 v101, 0, v141, vcc
	v_cndmask_b32_e32 v100, v139, v137, vcc
	v_lshlrev_b64 v[102:103], v102, v[182:183]
	v_cndmask_b32_e64 v0, v182, 8, vcc
	v_lshl_add_u64 v[98:99], v[98:99], 0, v[102:103]
	v_lshlrev_b64 v[100:101], 12, v[100:101]
	v_lshl_add_u64 v[98:99], v[98:99], 0, v[100:101]
	v_add_u32_e32 v100, s5, v0
	v_mov_b64_e32 v[106:107], s[18:19]
	v_mad_i64_i32 v[100:101], s[0:1], v100, s33, v[106:107]
	s_mov_b64 s[0:1], 0x2000
	s_nop 0
	v_lshl_add_u64 v[126:127], v[100:101], 0, s[0:1]
	v_mov_b32_e32 v177, v1
	v_lshlrev_b64 v[102:103], 11, v[130:131]
	v_lshl_add_u64 v[118:119], v[98:99], 0, v[176:177]
	v_lshl_add_u64 v[104:105], v[126:127], 0, v[176:177]
	global_load_dwordx4 v[98:101], v[118:119], off
	v_lshl_add_u64 v[164:165], v[142:143], 0, v[102:103]
	global_load_dwordx4 v[102:105], v[104:105], off
	s_nop 0
	global_load_dwordx2 v[152:153], v[164:165], off
	v_add_u32_e32 v0, s6, v0
	v_mad_i64_i32 v[146:147], s[0:1], v0, s33, v[106:107]
	v_cndmask_b32_e64 v0, 0, 1, s[40:41]
	v_cmp_ne_u32_e64 s[0:1], 1, v0
	s_andn2_b64 vcc, exec, s[40:41]
	v_lshl_add_u64 v[154:155], v[146:147], 0, s[98:99]
	s_cbranch_vccnz .LBB0_65
	v_lshl_add_u64 v[58:59], v[146:147], 0, v[176:177]
	v_lshl_add_u64 v[90:91], v[154:155], 0, v[176:177]
	global_load_dwordx4 v[58:61], v[58:59], off
	s_nop 0
	global_load_dwordx4 v[90:93], v[90:91], off
.LBB0_65:
	v_lshlrev_b32_e32 v0, 2, v136
	v_lshl_add_u64 v[110:111], v[126:127], 0, v[0:1]
	global_load_dwordx4 v[106:109], v[118:119], off offset:1024
	global_load_dwordx4 v[114:117], v[110:111], off
	global_load_dwordx2 v[160:161], v[164:165], off offset:512
	s_and_b64 vcc, exec, s[0:1]
	s_cbranch_vccnz .LBB0_67
	v_mov_b32_e32 v177, v1
	v_lshl_add_u64 v[62:63], v[146:147], 0, v[176:177]
	v_lshl_add_u64 v[94:95], v[154:155], 0, v[0:1]
	global_load_dwordx4 v[62:65], v[62:63], off offset:1024
	s_nop 0
	global_load_dwordx4 v[94:97], v[94:95], off
.LBB0_67:
	v_lshlrev_b32_e32 v0, 2, v138
	v_lshl_add_u64 v[120:121], v[126:127], 0, v[0:1]
	global_load_dwordx4 v[110:113], v[118:119], off offset:2048
	global_load_dwordx4 v[122:125], v[120:121], off
	global_load_dwordx2 v[168:169], v[164:165], off offset:1024
	s_and_b64 vcc, exec, s[0:1]
	s_cbranch_vccnz .LBB0_69
	v_mov_b32_e32 v177, v1
	v_lshl_add_u64 v[54:55], v[146:147], 0, v[176:177]
	v_lshl_add_u64 v[86:87], v[154:155], 0, v[0:1]
	global_load_dwordx4 v[54:57], v[54:55], off offset:2048
	s_nop 0
	global_load_dwordx4 v[86:89], v[86:87], off
.LBB0_69:
	v_lshlrev_b32_e32 v0, 2, v140
	v_lshl_add_u64 v[126:127], v[126:127], 0, v[0:1]
	global_load_dwordx4 v[118:121], v[118:119], off offset:3072
	s_nop 0
	global_load_dwordx4 v[126:129], v[126:127], off
	s_nop 0
	global_load_dwordx2 v[174:175], v[164:165], off offset:1536
	s_and_b64 vcc, exec, s[0:1]
	s_cbranch_vccnz .LBB0_71
	v_mov_b32_e32 v177, v1
	v_lshl_add_u64 v[50:51], v[146:147], 0, v[176:177]
	v_lshl_add_u64 v[82:83], v[154:155], 0, v[0:1]
	global_load_dwordx4 v[50:53], v[50:51], off offset:3072
	s_nop 0
	global_load_dwordx4 v[82:85], v[82:83], off

.LBB0_72:
	s_or_b64 exec, exec, s[50:51]
	v_add_u32_e32 v178, s4, v130
	v_cmp_lt_i32_e32 vcc, s15, v178
	s_and_saveexec_b64 s[0:1], vcc
	s_xor_b64 s[0:1], exec, s[0:1]
	s_mov_b64 s[50:51], 0
	s_or_saveexec_b64 s[54:55], s[0:1]
	v_mul_hi_i32 v98, v178, s30
	v_lshrrev_b32_e32 v99, 31, v98
	v_ashrrev_i32_e32 v98, 9, v98
	v_add_u32_e32 v180, v98, v99
	v_mul_i32_i24_e32 v98, 0x900, v180
	v_sub_u32_e32 v135, v178, v98
	v_mov_b64_e32 v[102:103], v[0:1]
	s_xor_b64 exec, exec, s[54:55]
	s_cbranch_execz .LBB0_86
	v_cmp_lt_i32_e32 vcc, s97, v135
	s_or_b64 s[56:57], s[40:41], vcc
	v_mov_b64_e32 v[102:103], v[0:1]
	s_and_saveexec_b64 s[58:59], s[56:57]
	s_cbranch_execz .LBB0_85
	s_movk_i32 s0, 0x100
	v_cmp_gt_i32_e32 vcc, s0, v135
	v_mov_b32_e32 v98, s12
	v_mov_b32_e32 v99, s10
	v_ashrrev_i32_e32 v100, 31, v135
	v_add_u32_e32 v102, 0xffffff00, v135
	v_cndmask_b32_e32 v99, v98, v99, vcc
	v_mov_b32_e32 v98, s13
	v_mov_b32_e32 v101, s11
	v_ashrrev_i32_e32 v181, 31, v180
	v_cndmask_b32_e32 v98, v98, v101, vcc
	v_cndmask_b32_e32 v101, 0, v100, vcc
	v_cndmask_b32_e32 v100, v102, v135, vcc
	v_cndmask_b32_e64 v102, 23, 20, vcc
	v_lshlrev_b64 v[102:103], v102, v[180:181]
	v_cndmask_b32_e64 v108, v180, 8, vcc
	v_lshl_add_u64 v[98:99], v[98:99], 0, v[102:103]
	v_lshlrev_b64 v[100:101], 12, v[100:101]
	v_lshl_add_u64 v[98:99], v[98:99], 0, v[100:101]
	v_add_u32_e32 v100, s5, v108
	v_mov_b64_e32 v[106:107], s[18:19]
	v_mad_i64_i32 v[100:101], s[0:1], v100, s33, v[106:107]
	s_mov_b64 s[0:1], 0x2000
	s_nop 0
	v_lshl_add_u64 v[126:127], v[100:101], 0, s[0:1]
	v_ashrrev_i32_e32 v179, 31, v178
	v_mov_b32_e32 v177, v1
	v_lshlrev_b64 v[102:103], 11, v[178:179]
	v_lshl_add_u64 v[122:123], v[98:99], 0, v[176:177]
	v_lshl_add_u64 v[104:105], v[126:127], 0, v[176:177]
	global_load_dwordx4 v[98:101], v[122:123], off
	v_lshl_add_u64 v[158:159], v[142:143], 0, v[102:103]
	global_load_dwordx4 v[102:105], v[104:105], off
	s_nop 0
	global_load_dwordx2 v[148:149], v[158:159], off
	v_add_u32_e32 v108, s6, v108
	v_mad_i64_i32 v[144:145], s[0:1], v108, s33, v[106:107]
	v_cndmask_b32_e64 v106, 0, 1, s[40:41]
	v_cmp_ne_u32_e64 s[0:1], 1, v106
	s_andn2_b64 vcc, exec, s[40:41]
	v_lshl_add_u64 v[150:151], v[144:145], 0, s[98:99]
	s_cbranch_vccnz .LBB0_78
	v_lshl_add_u64 v[42:43], v[144:145], 0, v[176:177]
	v_lshl_add_u64 v[74:75], v[150:151], 0, v[176:177]
	global_load_dwordx4 v[42:45], v[42:43], off
	s_nop 0
	global_load_dwordx4 v[74:77], v[74:75], off
.LBB0_78:
	v_lshlrev_b32_e32 v114, 2, v136
	v_mov_b32_e32 v115, v1
	v_lshl_add_u64 v[110:111], v[126:127], 0, v[114:115]
	global_load_dwordx4 v[106:109], v[122:123], off offset:1024
	s_nop 0
	global_load_dwordx4 v[110:113], v[110:111], off
	s_nop 0
	global_load_dwordx2 v[156:157], v[158:159], off offset:512
	s_and_b64 vcc, exec, s[0:1]
	s_cbranch_vccnz .LBB0_80
	v_mov_b32_e32 v177, v1
	v_lshl_add_u64 v[46:47], v[144:145], 0, v[176:177]
	v_lshl_add_u64 v[78:79], v[150:151], 0, v[114:115]
	global_load_dwordx4 v[46:49], v[46:47], off offset:1024
	s_nop 0
	global_load_dwordx4 v[78:81], v[78:79], off
.LBB0_80:
	v_lshlrev_b32_e32 v124, 2, v138
	v_mov_b32_e32 v125, v1
	v_lshl_add_u64 v[118:119], v[126:127], 0, v[124:125]
	global_load_dwordx4 v[114:117], v[122:123], off offset:2048
	s_nop 0
	global_load_dwordx4 v[118:121], v[118:119], off
	s_nop 0
	global_load_dwordx2 v[162:163], v[158:159], off offset:1024
	s_and_b64 vcc, exec, s[0:1]
	s_cbranch_vccnz .LBB0_82
	v_mov_b32_e32 v177, v1
	v_lshl_add_u64 v[38:39], v[144:145], 0, v[176:177]
	v_lshl_add_u64 v[70:71], v[150:151], 0, v[124:125]
	global_load_dwordx4 v[38:41], v[38:39], off offset:2048
	s_nop 0
	global_load_dwordx4 v[70:73], v[70:71], off
.LBB0_82:
	v_lshlrev_b32_e32 v166, 2, v140
	v_mov_b32_e32 v167, v1
	v_lshl_add_u64 v[126:127], v[126:127], 0, v[166:167]
	global_load_dwordx4 v[122:125], v[122:123], off offset:3072
	s_nop 0
	global_load_dwordx4 v[126:129], v[126:127], off
	s_nop 0
	global_load_dwordx2 v[170:171], v[158:159], off offset:1536
	s_and_b64 vcc, exec, s[0:1]
	s_cbranch_vccnz .LBB0_84
	v_mov_b32_e32 v177, v1
	v_lshl_add_u64 v[34:35], v[144:145], 0, v[176:177]
	v_lshl_add_u64 v[66:67], v[150:151], 0, v[166:167]
	global_load_dwordx4 v[34:37], v[34:35], off offset:3072
	s_nop 0
	global_load_dwordx4 v[66:69], v[66:67], off

.LBB0_86:
	s_or_b64 exec, exec, s[54:55]
	s_and_saveexec_b64 s[0:1], s[52:53]
	s_cbranch_execz .LBB0_95
	s_movk_i32 s14, 0x100
	v_cmp_gt_i32_e32 vcc, s14, v137
	v_mov_b32_e32 v0, s29
	v_mov_b32_e32 v98, s9
	v_cndmask_b32_e32 v99, v0, v98, vcc
	v_mov_b32_e32 v0, s28
	v_mov_b32_e32 v98, s8
	v_cndmask_b32_e32 v98, v0, v98, vcc
	v_cndmask_b32_e64 v0, 23, 20, vcc
	v_lshlrev_b64 v[104:105], v0, v[182:183]
	ds_bpermute_b32 v0, v188, v102
	v_cndmask_b32_e32 v101, 0, v141, vcc
	v_cndmask_b32_e32 v100, v139, v137, vcc
	v_lshl_add_u64 v[98:99], v[98:99], 0, v[104:105]
	v_lshlrev_b64 v[100:101], 12, v[100:101]
	s_waitcnt lgkmcnt(0)
	v_add_f32_e32 v0, v102, v0
	ds_bpermute_b32 v102, v189, v0
	v_lshl_add_u64 v[128:129], v[98:99], 0, v[100:101]
	v_mov_b32_e32 v177, v1
	s_mov_b64 s[52:53], -1
	s_waitcnt lgkmcnt(0)
	v_add_f32_e32 v0, v0, v102
	ds_bpermute_b32 v102, v190, v0
	s_waitcnt lgkmcnt(0)
	v_add_f32_e32 v0, v0, v102
	ds_bpermute_b32 v102, v185, v0
	s_waitcnt lgkmcnt(0)
	v_add_f32_e32 v0, v0, v102
	ds_bpermute_b32 v102, v186, v0
	s_waitcnt lgkmcnt(0)
	v_add_f32_e32 v0, v0, v102
	ds_bpermute_b32 v102, v187, v0
	s_waitcnt lgkmcnt(0)
	v_add_f32_e32 v0, v0, v102
	v_mul_f32_e32 v0, 0x3a800000, v0
	v_pk_add_f32 v[98:99], v[146:147], v[0:1] op_sel_hi:[1,0] neg_lo:[0,1] neg_hi:[0,1]
	v_pk_add_f32 v[182:183], v[152:153], v[0:1] op_sel_hi:[1,0] neg_lo:[0,1] neg_hi:[0,1]
	v_pk_mul_f32 v[100:101], v[98:99], v[98:99]
	v_pk_add_f32 v[116:117], v[154:155], v[0:1] op_sel_hi:[1,0] neg_lo:[0,1] neg_hi:[0,1]
	v_pk_add_f32 v[112:113], v[160:161], v[0:1] op_sel_hi:[1,0] neg_lo:[0,1] neg_hi:[0,1]
	v_pk_add_f32 v[108:109], v[164:165], v[0:1] op_sel_hi:[1,0] neg_lo:[0,1] neg_hi:[0,1]
	v_pk_add_f32 v[110:111], v[168:169], v[0:1] op_sel_hi:[1,0] neg_lo:[0,1] neg_hi:[0,1]
	v_pk_add_f32 v[106:107], v[172:173], v[0:1] op_sel_hi:[1,0] neg_lo:[0,1] neg_hi:[0,1]
	v_pk_add_f32 v[104:105], v[174:175], v[0:1] op_sel_hi:[1,0] neg_lo:[0,1] neg_hi:[0,1]
	v_pk_mul_f32 v[192:193], v[182:183], v[182:183]
	v_add_f32_e32 v0, v100, v101
	v_add_f32_e32 v0, v192, v0
	v_pk_mul_f32 v[114:115], v[116:117], v[116:117]
	v_add_f32_e32 v0, v193, v0
	v_add_f32_e32 v0, v114, v0
	v_pk_mul_f32 v[118:119], v[112:113], v[112:113]
	v_add_f32_e32 v0, v115, v0
	v_add_f32_e32 v0, v118, v0
	v_pk_mul_f32 v[120:121], v[108:109], v[108:109]
	v_add_f32_e32 v0, v119, v0
	v_add_f32_e32 v0, v120, v0
	v_pk_mul_f32 v[122:123], v[110:111], v[110:111]
	v_add_f32_e32 v0, v121, v0
	v_add_f32_e32 v0, v122, v0
	v_pk_mul_f32 v[124:125], v[106:107], v[106:107]
	v_add_f32_e32 v0, v123, v0
	v_add_f32_e32 v0, v124, v0
	v_pk_mul_f32 v[126:127], v[104:105], v[104:105]
	v_add_f32_e32 v0, v125, v0
	v_add_f32_e32 v0, v126, v0
	v_add_f32_e32 v0, v127, v0
	ds_bpermute_b32 v100, v188, v0
	v_lshl_add_u64 v[120:121], v[128:129], 0, v[176:177]
	s_waitcnt lgkmcnt(0)
	v_add_f32_e32 v0, v0, v100
	ds_bpermute_b32 v100, v189, v0
	s_waitcnt lgkmcnt(0)
	v_add_f32_e32 v0, v0, v100
	ds_bpermute_b32 v100, v190, v0
	s_waitcnt lgkmcnt(0)
	v_add_f32_e32 v0, v0, v100
	ds_bpermute_b32 v100, v185, v0
	s_waitcnt lgkmcnt(0)
	v_add_f32_e32 v0, v0, v100
	ds_bpermute_b32 v100, v186, v0
	s_waitcnt lgkmcnt(0)
	v_add_f32_e32 v0, v0, v100
	ds_bpermute_b32 v100, v187, v0
	s_waitcnt lgkmcnt(0)
	v_add_f32_e32 v0, v0, v100
	v_mov_b32_e32 v100, 0x3727c5ac
	v_fmamk_f32 v0, v0, 0x3a800000, v100
	v_cmp_gt_f32_e32 vcc, s31, v0
	v_mul_f32_e32 v100, 0x4b800000, v0
	s_nop 0
	v_cndmask_b32_e32 v0, v0, v100, vcc
	v_rsq_f32_e32 v0, v0
	s_nop 0
	v_mul_f32_e32 v100, 0x45800000, v0
	v_cndmask_b32_e32 v114, v0, v100, vcc
	v_mov_b32_e32 v118, v114
	v_mov_b32_e32 v119, v114
	v_pk_mul_f32 v[98:99], v[98:99], v[114:115] op_sel_hi:[1,0]
	v_pk_mul_f32 v[100:101], v[182:183], v[114:115] op_sel_hi:[1,0]
	s_waitcnt vmcnt(0)
	v_pk_fma_f32 v[98:99], v[30:31], v[98:99], v[22:23]
	v_pk_fma_f32 v[100:101], v[32:33], v[100:101], v[24:25]
	s_and_b64 vcc, exec, s[42:43]
	v_pk_mul_f32 v[122:123], v[116:117], v[118:119]
	global_store_dwordx4 v[120:121], v[98:101], off
	s_cbranch_vccz .LBB0_89
	v_mov_b32_e32 v115, v114
	v_pk_mul_f32 v[116:117], v[112:113], v[114:115]
	v_pk_fma_f32 v[124:125], v[26:27], v[122:123], v[18:19]
	v_pk_fma_f32 v[126:127], v[28:29], v[116:117], v[20:21]
	global_store_dwordx4 v[120:121], v[124:127], off offset:1024
	s_mov_b64 s[52:53], 0
.LBB0_89:
	v_lshlrev_b64 v[116:117], 11, v[130:131]
	s_andn2_b64 vcc, exec, s[52:53]
	v_lshl_add_u64 v[116:117], s[94:95], 0, v[116:117]
	s_cbranch_vccnz .LBB0_91
	v_pk_add_f32 v[124:125], v[92:93], 1.0 op_sel_hi:[1,0]
	v_pk_add_f32 v[126:127], v[90:91], 1.0 op_sel_hi:[1,0]
	v_pk_fma_f32 v[100:101], v[124:125], v[100:101], v[60:61]
	v_pk_fma_f32 v[98:99], v[126:127], v[98:99], v[58:59]
	v_lshlrev_b32_e32 v0, 1, v132
	v_cvt_pk_bf16_f32 v98, v98, v99
	v_cvt_pk_bf16_f32 v99, v100, v101
	v_lshl_add_u64 v[124:125], v[116:117], 0, v[0:1]
	v_mov_b32_e32 v115, v114
	v_subrev_u32_e32 v240, s94, v124
	v_bfe_u32 v241, v240, 6, 5
	v_and_b32_e32 v242, 63, v240
	v_lshl_or_b32 v242, v241, 10, v242
	v_bfe_u32 v241, v240, 11, 4
	v_lshl_or_b32 v242, v241, 6, v242
	v_and_b32_e32 v241, 0x7fff, v240
	v_sub_u32_e32 v242, v242, v241
	v_ashrrev_i32_e32 v243, 31, v242
	v_lshl_add_u64 v[240:241], v[124:125], 0, v[242:243]
	global_store_dwordx2 v[240:241], v[98:99], off
	v_pk_mul_f32 v[98:99], v[112:113], v[114:115]
	v_pk_add_f32 v[112:113], v[96:97], 1.0 op_sel_hi:[1,0]
	v_pk_fma_f32 v[100:101], v[28:29], v[98:99], v[20:21]
	v_pk_fma_f32 v[98:99], v[26:27], v[122:123], v[18:19]
	v_pk_add_f32 v[122:123], v[94:95], 1.0 op_sel_hi:[1,0]
	global_store_dwordx4 v[120:121], v[98:101], off offset:1024
	s_nop 1
	v_pk_fma_f32 v[100:101], v[112:113], v[100:101], v[64:65]
	v_pk_fma_f32 v[98:99], v[122:123], v[98:99], v[62:63]
	s_nop 0
	v_cvt_pk_bf16_f32 v98, v98, v99
	v_cvt_pk_bf16_f32 v99, v100, v101
	v_subrev_u32_e32 v240, s94, v124
	v_add_u32_e32 v240, 0x200, v240
	v_bfe_u32 v241, v240, 6, 5
	v_and_b32_e32 v242, 63, v240
	v_lshl_or_b32 v242, v241, 10, v242
	v_bfe_u32 v241, v240, 11, 4
	v_lshl_or_b32 v242, v241, 6, v242
	v_and_b32_e32 v241, 0x7fff, v240
	v_sub_u32_e32 v242, v242, v241
	v_add_u32_e32 v242, 0x200, v242
	v_ashrrev_i32_e32 v243, 31, v242
	v_lshl_add_u64 v[240:241], v[124:125], 0, v[242:243]
	global_store_dwordx2 v[240:241], v[98:99], off
.LBB0_91:
	v_mov_b32_e32 v115, v114
	v_pk_mul_f32 v[98:99], v[108:109], v[118:119]
	v_pk_mul_f32 v[100:101], v[110:111], v[114:115]
	v_pk_fma_f32 v[98:99], v[14:15], v[98:99], v[6:7]
	v_pk_fma_f32 v[100:101], v[16:17], v[100:101], v[8:9]
	s_mov_b64 s[52:53], -1
	s_and_b64 vcc, exec, s[42:43]
	v_pk_mul_f32 v[106:107], v[106:107], v[118:119]
	global_store_dwordx4 v[120:121], v[98:101], off offset:2048
	s_cbranch_vccz .LBB0_93
	v_pk_mul_f32 v[108:109], v[104:105], v[114:115]
	s_mov_b64 s[52:53], 0
	v_pk_fma_f32 v[110:111], v[12:13], v[108:109], v[4:5]
	v_pk_fma_f32 v[108:109], v[10:11], v[106:107], v[2:3]
	global_store_dwordx4 v[120:121], v[108:111], off offset:3072
.LBB0_93:
	s_andn2_b64 vcc, exec, s[52:53]
	s_cbranch_vccnz .LBB0_95
	v_pk_add_f32 v[108:109], v[88:89], 1.0 op_sel_hi:[1,0]
	v_pk_add_f32 v[110:111], v[86:87], 1.0 op_sel_hi:[1,0]
	v_pk_fma_f32 v[100:101], v[108:109], v[100:101], v[56:57]
	v_pk_fma_f32 v[98:99], v[110:111], v[98:99], v[54:55]
	v_lshlrev_b32_e32 v0, 1, v132
	v_cvt_pk_bf16_f32 v98, v98, v99
	v_cvt_pk_bf16_f32 v99, v100, v101
	v_lshl_add_u64 v[108:109], v[116:117], 0, v[0:1]
	v_mov_b32_e32 v115, v114
	v_subrev_u32_e32 v240, s94, v108
	v_add_u32_e32 v240, 0x400, v240
	v_bfe_u32 v241, v240, 6, 5
	v_and_b32_e32 v242, 63, v240
	v_lshl_or_b32 v242, v241, 10, v242
	v_bfe_u32 v241, v240, 11, 4
	v_lshl_or_b32 v242, v241, 6, v242
	v_and_b32_e32 v241, 0x7fff, v240
	v_sub_u32_e32 v242, v242, v241
	v_add_u32_e32 v242, 0x400, v242
	v_ashrrev_i32_e32 v243, 31, v242
	v_lshl_add_u64 v[240:241], v[108:109], 0, v[242:243]
	global_store_dwordx2 v[240:241], v[98:99], off
	v_pk_mul_f32 v[98:99], v[104:105], v[114:115]
	v_pk_add_f32 v[104:105], v[84:85], 1.0 op_sel_hi:[1,0]
	v_pk_fma_f32 v[100:101], v[12:13], v[98:99], v[4:5]
	v_pk_fma_f32 v[98:99], v[10:11], v[106:107], v[2:3]
	v_pk_add_f32 v[106:107], v[82:83], 1.0 op_sel_hi:[1,0]
	global_store_dwordx4 v[120:121], v[98:101], off offset:3072
	s_nop 1
	v_pk_fma_f32 v[100:101], v[104:105], v[100:101], v[52:53]
	v_pk_fma_f32 v[98:99], v[106:107], v[98:99], v[50:51]
	s_nop 0
	v_cvt_pk_bf16_f32 v98, v98, v99
	v_cvt_pk_bf16_f32 v99, v100, v101
	v_subrev_u32_e32 v240, s94, v108
	v_add_u32_e32 v240, 0x600, v240
	v_bfe_u32 v241, v240, 6, 5
	v_and_b32_e32 v242, 63, v240
	v_lshl_or_b32 v242, v241, 10, v242
	v_bfe_u32 v241, v240, 11, 4
	v_lshl_or_b32 v242, v241, 6, v242
	v_and_b32_e32 v241, 0x7fff, v240
	v_sub_u32_e32 v242, v242, v241
	v_add_u32_e32 v242, 0x600, v242
	v_ashrrev_i32_e32 v243, 31, v242
	v_lshl_add_u64 v[240:241], v[108:109], 0, v[242:243]
	global_store_dwordx2 v[240:241], v[98:99], off
.LBB0_95:
	s_or_b64 exec, exec, s[0:1]
	s_and_saveexec_b64 s[0:1], s[50:51]
	s_cbranch_execz .LBB0_61
	s_movk_i32 s14, 0x100
	v_cmp_gt_i32_e32 vcc, s14, v135
	v_mov_b32_e32 v98, s29
	v_mov_b32_e32 v99, s9
	v_ashrrev_i32_e32 v0, 31, v135
	v_cndmask_b32_e32 v99, v98, v99, vcc
	v_mov_b32_e32 v98, s28
	v_mov_b32_e32 v101, s8
	v_ashrrev_i32_e32 v181, 31, v180
	v_cndmask_b32_e32 v98, v98, v101, vcc
	v_cndmask_b32_e32 v101, 0, v0, vcc
	v_cndmask_b32_e64 v0, 23, 20, vcc
	v_lshlrev_b64 v[104:105], v0, v[180:181]
	ds_bpermute_b32 v0, v188, v103
	v_add_u32_e32 v100, 0xffffff00, v135
	v_cndmask_b32_e32 v100, v100, v135, vcc
	v_lshl_add_u64 v[98:99], v[98:99], 0, v[104:105]
	v_lshlrev_b64 v[100:101], 12, v[100:101]
	s_waitcnt lgkmcnt(0)
	v_add_f32_e32 v0, v103, v0
	ds_bpermute_b32 v102, v189, v0
	v_lshl_add_u64 v[126:127], v[98:99], 0, v[100:101]
	v_mov_b32_e32 v177, v1
	s_mov_b64 s[50:51], -1
	s_waitcnt lgkmcnt(0)
	v_add_f32_e32 v0, v0, v102
	ds_bpermute_b32 v102, v190, v0
	s_waitcnt lgkmcnt(0)
	v_add_f32_e32 v0, v0, v102
	ds_bpermute_b32 v102, v185, v0
	s_waitcnt lgkmcnt(0)
	v_add_f32_e32 v0, v0, v102
	ds_bpermute_b32 v102, v186, v0
	s_waitcnt lgkmcnt(0)
	v_add_f32_e32 v0, v0, v102
	ds_bpermute_b32 v102, v187, v0
	s_waitcnt lgkmcnt(0)
	v_add_f32_e32 v0, v0, v102
	v_mul_f32_e32 v0, 0x3a800000, v0
	v_pk_add_f32 v[98:99], v[144:145], v[0:1] op_sel_hi:[1,0] neg_lo:[0,1] neg_hi:[0,1]
	v_pk_add_f32 v[128:129], v[148:149], v[0:1] op_sel_hi:[1,0] neg_lo:[0,1] neg_hi:[0,1]
	v_pk_mul_f32 v[100:101], v[98:99], v[98:99]
	v_pk_add_f32 v[114:115], v[150:151], v[0:1] op_sel_hi:[1,0] neg_lo:[0,1] neg_hi:[0,1]
	v_pk_add_f32 v[110:111], v[156:157], v[0:1] op_sel_hi:[1,0] neg_lo:[0,1] neg_hi:[0,1]
	v_pk_add_f32 v[106:107], v[158:159], v[0:1] op_sel_hi:[1,0] neg_lo:[0,1] neg_hi:[0,1]
	v_pk_add_f32 v[108:109], v[162:163], v[0:1] op_sel_hi:[1,0] neg_lo:[0,1] neg_hi:[0,1]
	v_pk_add_f32 v[104:105], v[166:167], v[0:1] op_sel_hi:[1,0] neg_lo:[0,1] neg_hi:[0,1]
	v_pk_add_f32 v[102:103], v[170:171], v[0:1] op_sel_hi:[1,0] neg_lo:[0,1] neg_hi:[0,1]
	v_pk_mul_f32 v[180:181], v[128:129], v[128:129]
	v_add_f32_e32 v0, v100, v101
	v_add_f32_e32 v0, v180, v0
	v_pk_mul_f32 v[112:113], v[114:115], v[114:115]
	v_add_f32_e32 v0, v181, v0
	v_add_f32_e32 v0, v112, v0
	v_pk_mul_f32 v[116:117], v[110:111], v[110:111]
	v_add_f32_e32 v0, v113, v0
	v_add_f32_e32 v0, v116, v0
	v_pk_mul_f32 v[118:119], v[106:107], v[106:107]
	v_add_f32_e32 v0, v117, v0
	v_add_f32_e32 v0, v118, v0
	v_pk_mul_f32 v[120:121], v[108:109], v[108:109]
	v_add_f32_e32 v0, v119, v0
	v_add_f32_e32 v0, v120, v0
	v_pk_mul_f32 v[122:123], v[104:105], v[104:105]
	v_add_f32_e32 v0, v121, v0
	v_add_f32_e32 v0, v122, v0
	v_pk_mul_f32 v[124:125], v[102:103], v[102:103]
	v_add_f32_e32 v0, v123, v0
	v_add_f32_e32 v0, v124, v0
	v_add_f32_e32 v0, v125, v0
	ds_bpermute_b32 v100, v188, v0
	v_lshl_add_u64 v[118:119], v[126:127], 0, v[176:177]
	s_waitcnt lgkmcnt(0)
	v_add_f32_e32 v0, v0, v100
	ds_bpermute_b32 v100, v189, v0
	s_waitcnt lgkmcnt(0)
	v_add_f32_e32 v0, v0, v100
	ds_bpermute_b32 v100, v190, v0
	s_waitcnt lgkmcnt(0)
	v_add_f32_e32 v0, v0, v100
	ds_bpermute_b32 v100, v185, v0
	s_waitcnt lgkmcnt(0)
	v_add_f32_e32 v0, v0, v100
	ds_bpermute_b32 v100, v186, v0
	s_waitcnt lgkmcnt(0)
	v_add_f32_e32 v0, v0, v100
	ds_bpermute_b32 v100, v187, v0
	s_waitcnt lgkmcnt(0)
	v_add_f32_e32 v0, v0, v100
	v_mov_b32_e32 v100, 0x3727c5ac
	v_fmamk_f32 v0, v0, 0x3a800000, v100
	v_cmp_gt_f32_e32 vcc, s31, v0
	v_mul_f32_e32 v100, 0x4b800000, v0
	s_nop 0
	v_cndmask_b32_e32 v0, v0, v100, vcc
	v_rsq_f32_e32 v0, v0
	s_nop 0
	v_mul_f32_e32 v100, 0x45800000, v0
	v_cndmask_b32_e32 v112, v0, v100, vcc
	v_mov_b32_e32 v116, v112
	v_mov_b32_e32 v117, v112
	v_pk_mul_f32 v[98:99], v[98:99], v[112:113] op_sel_hi:[1,0]
	v_pk_mul_f32 v[100:101], v[128:129], v[112:113] op_sel_hi:[1,0]
	s_waitcnt vmcnt(0)
	v_pk_fma_f32 v[98:99], v[30:31], v[98:99], v[22:23]
	v_pk_fma_f32 v[100:101], v[32:33], v[100:101], v[24:25]
	s_and_b64 vcc, exec, s[42:43]
	v_pk_mul_f32 v[120:121], v[114:115], v[116:117]
	global_store_dwordx4 v[118:119], v[98:101], off
	s_cbranch_vccz .LBB0_98
	v_mov_b32_e32 v113, v112
	v_pk_mul_f32 v[114:115], v[110:111], v[112:113]
	v_pk_fma_f32 v[122:123], v[26:27], v[120:121], v[18:19]
	v_pk_fma_f32 v[124:125], v[28:29], v[114:115], v[20:21]
	global_store_dwordx4 v[118:119], v[122:125], off offset:1024
	s_mov_b64 s[50:51], 0
.LBB0_98:
	v_ashrrev_i32_e32 v179, 31, v178
	v_lshlrev_b64 v[114:115], 11, v[178:179]
	v_lshl_add_u64 v[114:115], s[94:95], 0, v[114:115]
	s_andn2_b64 vcc, exec, s[50:51]
	v_lshlrev_b32_e32 v0, 1, v132
	s_cbranch_vccnz .LBB0_100
	v_pk_add_f32 v[122:123], v[76:77], 1.0 op_sel_hi:[1,0]
	v_pk_add_f32 v[124:125], v[74:75], 1.0 op_sel_hi:[1,0]
	v_pk_fma_f32 v[100:101], v[122:123], v[100:101], v[44:45]
	v_pk_fma_f32 v[98:99], v[124:125], v[98:99], v[42:43]
	v_lshl_add_u64 v[122:123], v[114:115], 0, v[0:1]
	v_cvt_pk_bf16_f32 v98, v98, v99
	v_cvt_pk_bf16_f32 v99, v100, v101
	v_mov_b32_e32 v113, v112
	v_subrev_u32_e32 v240, s94, v122
	v_bfe_u32 v241, v240, 6, 5
	v_and_b32_e32 v242, 63, v240
	v_lshl_or_b32 v242, v241, 10, v242
	v_bfe_u32 v241, v240, 11, 4
	v_lshl_or_b32 v242, v241, 6, v242
	v_and_b32_e32 v241, 0x7fff, v240
	v_sub_u32_e32 v242, v242, v241
	v_ashrrev_i32_e32 v243, 31, v242
	v_lshl_add_u64 v[240:241], v[122:123], 0, v[242:243]
	global_store_dwordx2 v[240:241], v[98:99], off
	v_pk_mul_f32 v[98:99], v[110:111], v[112:113]
	v_pk_add_f32 v[110:111], v[80:81], 1.0 op_sel_hi:[1,0]
	v_pk_fma_f32 v[100:101], v[28:29], v[98:99], v[20:21]
	v_pk_fma_f32 v[98:99], v[26:27], v[120:121], v[18:19]
	v_pk_add_f32 v[120:121], v[78:79], 1.0 op_sel_hi:[1,0]
	global_store_dwordx4 v[118:119], v[98:101], off offset:1024
	s_nop 1
	v_pk_fma_f32 v[100:101], v[110:111], v[100:101], v[48:49]
	v_pk_fma_f32 v[98:99], v[120:121], v[98:99], v[46:47]
	s_nop 0
	v_cvt_pk_bf16_f32 v98, v98, v99
	v_cvt_pk_bf16_f32 v99, v100, v101
	v_subrev_u32_e32 v240, s94, v122
	v_add_u32_e32 v240, 0x200, v240
	v_bfe_u32 v241, v240, 6, 5
	v_and_b32_e32 v242, 63, v240
	v_lshl_or_b32 v242, v241, 10, v242
	v_bfe_u32 v241, v240, 11, 4
	v_lshl_or_b32 v242, v241, 6, v242
	v_and_b32_e32 v241, 0x7fff, v240
	v_sub_u32_e32 v242, v242, v241
	v_add_u32_e32 v242, 0x200, v242
	v_ashrrev_i32_e32 v243, 31, v242
	v_lshl_add_u64 v[240:241], v[122:123], 0, v[242:243]
	global_store_dwordx2 v[240:241], v[98:99], off
.LBB0_100:
	v_mov_b32_e32 v113, v112
	v_pk_mul_f32 v[98:99], v[106:107], v[116:117]
	v_pk_mul_f32 v[100:101], v[108:109], v[112:113]
	v_pk_fma_f32 v[98:99], v[14:15], v[98:99], v[6:7]
	v_pk_fma_f32 v[100:101], v[16:17], v[100:101], v[8:9]
	s_mov_b64 s[50:51], -1
	s_and_b64 vcc, exec, s[42:43]
	v_pk_mul_f32 v[104:105], v[104:105], v[116:117]
	global_store_dwordx4 v[118:119], v[98:101], off offset:2048
	s_cbranch_vccz .LBB0_102
	v_pk_mul_f32 v[106:107], v[102:103], v[112:113]
	s_mov_b64 s[50:51], 0
	v_pk_fma_f32 v[108:109], v[12:13], v[106:107], v[4:5]
	v_pk_fma_f32 v[106:107], v[10:11], v[104:105], v[2:3]
	global_store_dwordx4 v[118:119], v[106:109], off offset:3072
.LBB0_102:
	s_andn2_b64 vcc, exec, s[50:51]
	s_cbranch_vccnz .LBB0_61
	v_pk_add_f32 v[106:107], v[72:73], 1.0 op_sel_hi:[1,0]
	v_pk_add_f32 v[108:109], v[70:71], 1.0 op_sel_hi:[1,0]
	v_pk_fma_f32 v[100:101], v[106:107], v[100:101], v[40:41]
	v_pk_fma_f32 v[98:99], v[108:109], v[98:99], v[38:39]
	v_lshl_add_u64 v[106:107], v[114:115], 0, v[0:1]
	v_cvt_pk_bf16_f32 v98, v98, v99
	v_cvt_pk_bf16_f32 v99, v100, v101
	v_mov_b32_e32 v113, v112
	v_subrev_u32_e32 v240, s94, v106
	v_add_u32_e32 v240, 0x400, v240
	v_bfe_u32 v241, v240, 6, 5
	v_and_b32_e32 v242, 63, v240
	v_lshl_or_b32 v242, v241, 10, v242
	v_bfe_u32 v241, v240, 11, 4
	v_lshl_or_b32 v242, v241, 6, v242
	v_and_b32_e32 v241, 0x7fff, v240
	v_sub_u32_e32 v242, v242, v241
	v_add_u32_e32 v242, 0x400, v242
	v_ashrrev_i32_e32 v243, 31, v242
	v_lshl_add_u64 v[240:241], v[106:107], 0, v[242:243]
	global_store_dwordx2 v[240:241], v[98:99], off
	v_pk_mul_f32 v[98:99], v[102:103], v[112:113]
	v_pk_add_f32 v[102:103], v[68:69], 1.0 op_sel_hi:[1,0]
	v_pk_fma_f32 v[100:101], v[12:13], v[98:99], v[4:5]
	v_pk_fma_f32 v[98:99], v[10:11], v[104:105], v[2:3]
	v_pk_add_f32 v[104:105], v[66:67], 1.0 op_sel_hi:[1,0]
	global_store_dwordx4 v[118:119], v[98:101], off offset:3072
	s_nop 1
	v_pk_fma_f32 v[100:101], v[102:103], v[100:101], v[36:37]
	v_pk_fma_f32 v[98:99], v[104:105], v[98:99], v[34:35]
	s_nop 0
	v_cvt_pk_bf16_f32 v98, v98, v99
	v_cvt_pk_bf16_f32 v99, v100, v101
	v_subrev_u32_e32 v240, s94, v106
	v_add_u32_e32 v240, 0x600, v240
	v_bfe_u32 v241, v240, 6, 5
	v_and_b32_e32 v242, 63, v240
	v_lshl_or_b32 v242, v241, 10, v242
	v_bfe_u32 v241, v240, 11, 4
	v_lshl_or_b32 v242, v241, 6, v242
	v_and_b32_e32 v241, 0x7fff, v240
	v_sub_u32_e32 v242, v242, v241
	v_add_u32_e32 v242, 0x600, v242
	v_ashrrev_i32_e32 v243, 31, v242
	v_lshl_add_u64 v[240:241], v[106:107], 0, v[242:243]
	global_store_dwordx2 v[240:241], v[98:99], off
	s_branch .LBB0_61

.LBB0_123:
	s_or_b64 exec, exec, s[58:59]
	v_ashrrev_i32_e32 v13, 31, v12
	v_lshlrev_b64 v[12:13], 11, v[12:13]
	v_lshl_add_u64 v[12:13], s[0:1], 0, v[12:13]
	v_lshlrev_b32_e32 v0, 1, v15
	v_lshl_add_u64 v[12:13], v[12:13], 0, v[0:1]
	v_add_co_u32_e32 v12, vcc, 0x600000, v12
	v_add_u32_e32 v45, 0x100, v45
	s_nop 0
	v_addc_co_u32_e32 v13, vcc, 0, v13, vcc
	v_add_co_u32_e32 v14, vcc, 1, v14
	s_or_b64 s[56:57], vcc, s[56:57]
	v_subrev_u32_e32 v240, s94, v12
	v_bfe_u32 v241, v240, 6, 5
	v_and_b32_e32 v242, 63, v240
	v_lshl_or_b32 v242, v241, 10, v242
	v_bfe_u32 v241, v240, 11, 4
	v_lshl_or_b32 v242, v241, 6, v242
	v_and_b32_e32 v241, 0x7fff, v240
	v_sub_u32_e32 v242, v242, v241
	v_ashrrev_i32_e32 v243, 31, v242
	v_lshl_add_u64 v[240:241], v[12:13], 0, v[242:243]
	global_store_short v[240:241], v16, off
	s_andn2_b64 exec, exec, s[56:57]
	s_cbranch_execz .LBB0_126

.LBB0_129:
	s_or_b64 exec, exec, s[56:57]
	v_ashrrev_i32_e32 v29, 31, v28
	v_lshlrev_b64 v[28:29], 11, v[28:29]
	v_lshl_add_u64 v[28:29], v[26:27], 0, v[28:29]
	v_add_co_u32_e32 v28, vcc, 0x600000, v28
	s_nop 1
	v_addc_co_u32_e32 v29, vcc, 0, v29, vcc
	v_cmp_lt_i32_e32 vcc, s82, v45
	s_or_b64 s[54:55], vcc, s[54:55]
	v_add_u32_e32 v45, 0x400, v45
	v_subrev_u32_e32 v240, s94, v28
	v_bfe_u32 v241, v240, 6, 5
	v_and_b32_e32 v242, 63, v240
	v_lshl_or_b32 v242, v241, 10, v242
	v_bfe_u32 v241, v240, 11, 4
	v_lshl_or_b32 v242, v241, 6, v242
	v_and_b32_e32 v241, 0x7fff, v240
	v_sub_u32_e32 v242, v242, v241
	v_ashrrev_i32_e32 v243, 31, v242
	v_lshl_add_u64 v[240:241], v[28:29], 0, v[242:243]
	global_store_short v[240:241], v46, off
	s_andn2_b64 exec, exec, s[54:55]
	s_cbranch_execz .LBB0_138

.LBB0_132:
	s_or_b64 exec, exec, s[56:57]
	v_ashrrev_i32_e32 v29, 31, v28
	v_lshlrev_b64 v[28:29], 11, v[28:29]
	v_lshl_add_u64 v[28:29], v[14:15], 0, v[28:29]
	v_add_co_u32_e32 v28, vcc, 0x600000, v28
	v_add_u32_e32 v47, 0x100, v45
	s_nop 0
	v_addc_co_u32_e32 v29, vcc, 0, v29, vcc
	v_subrev_u32_e32 v240, s94, v28
	v_bfe_u32 v241, v240, 6, 5
	v_and_b32_e32 v242, 63, v240
	v_lshl_or_b32 v242, v241, 10, v242
	v_bfe_u32 v241, v240, 11, 4
	v_lshl_or_b32 v242, v241, 6, v242
	v_and_b32_e32 v241, 0x7fff, v240
	v_sub_u32_e32 v242, v242, v241
	v_ashrrev_i32_e32 v243, 31, v242
	v_lshl_add_u64 v[240:241], v[28:29], 0, v[242:243]
	global_store_short v[240:241], v0, off
	v_ashrrev_i32_e32 v0, 10, v47
	v_add_u32_e32 v28, s8, v0
	v_cmp_gt_i32_e32 vcc, 32, v28
	s_and_saveexec_b64 s[56:57], vcc
	s_cbranch_execz .LBB0_134
	v_ashrrev_i32_e32 v48, 4, v28
	v_ashrrev_i32_e32 v49, 31, v48
	v_and_b32_e32 v0, 15, v28
	v_lshlrev_b64 v[48:49], 16, v[48:49]
	v_lshl_add_u64 v[48:49], v[16:17], 0, v[48:49]
	v_lshlrev_b32_e32 v0, 2, v0
	v_lshl_add_u64 v[48:49], v[48:49], 0, v[0:1]
	global_load_dword v0, v[48:49], off
	s_waitcnt vmcnt(0)
	v_cvt_pk_bf16_f32 v46, v0, s0
.LBB0_134:
	s_or_b64 exec, exec, s[56:57]
	v_ashrrev_i32_e32 v29, 31, v28
	v_lshlrev_b64 v[28:29], 11, v[28:29]
	v_lshl_add_u64 v[28:29], v[18:19], 0, v[28:29]
	v_add_co_u32_e32 v28, vcc, 0x600000, v28
	v_add_u32_e32 v47, 0x100, v47
	s_nop 0
	v_addc_co_u32_e32 v29, vcc, 0, v29, vcc
	v_ashrrev_i32_e32 v0, 10, v47
	v_subrev_u32_e32 v240, s94, v28
	v_bfe_u32 v241, v240, 6, 5
	v_and_b32_e32 v242, 63, v240
	v_lshl_or_b32 v242, v241, 10, v242
	v_bfe_u32 v241, v240, 11, 4
	v_lshl_or_b32 v242, v241, 6, v242
	v_and_b32_e32 v241, 0x7fff, v240
	v_sub_u32_e32 v242, v242, v241
	v_ashrrev_i32_e32 v243, 31, v242
	v_lshl_add_u64 v[240:241], v[28:29], 0, v[242:243]
	global_store_short v[240:241], v46, off
	v_add_u32_e32 v28, s8, v0
	v_cmp_gt_i32_e32 vcc, 32, v28
	v_mov_b32_e32 v46, 0
	v_mov_b32_e32 v0, 0
	s_and_saveexec_b64 s[56:57], vcc
	s_cbranch_execz .LBB0_136
	v_ashrrev_i32_e32 v48, 4, v28
	v_ashrrev_i32_e32 v49, 31, v48
	v_and_b32_e32 v0, 15, v28
	v_lshlrev_b64 v[48:49], 16, v[48:49]
	v_lshl_add_u64 v[48:49], v[20:21], 0, v[48:49]
	v_lshlrev_b32_e32 v0, 2, v0
	v_lshl_add_u64 v[48:49], v[48:49], 0, v[0:1]
	global_load_dword v0, v[48:49], off
	s_waitcnt vmcnt(0)
	v_cvt_pk_bf16_f32 v0, v0, s0
.LBB0_136:
	s_or_b64 exec, exec, s[56:57]
	v_ashrrev_i32_e32 v29, 31, v28
	v_lshlrev_b64 v[28:29], 11, v[28:29]
	v_lshl_add_u64 v[28:29], v[22:23], 0, v[28:29]
	v_add_co_u32_e32 v28, vcc, 0x600000, v28
	s_nop 1
	v_addc_co_u32_e32 v29, vcc, 0, v29, vcc
	v_subrev_u32_e32 v240, s94, v28
	v_bfe_u32 v241, v240, 6, 5
	v_and_b32_e32 v242, 63, v240
	v_lshl_or_b32 v242, v241, 10, v242
	v_bfe_u32 v241, v240, 11, 4
	v_lshl_or_b32 v242, v241, 6, v242
	v_and_b32_e32 v241, 0x7fff, v240
	v_sub_u32_e32 v242, v242, v241
	v_ashrrev_i32_e32 v243, 31, v242
	v_lshl_add_u64 v[240:241], v[28:29], 0, v[242:243]
	global_store_short v[240:241], v0, off
	v_add_u32_e32 v0, 0x100, v47
	v_ashrrev_i32_e32 v0, 10, v0
	v_add_u32_e32 v28, s8, v0
	v_cmp_gt_i32_e32 vcc, 32, v28
	s_and_saveexec_b64 s[56:57], vcc
	s_cbranch_execz .LBB0_129
	v_ashrrev_i32_e32 v46, 4, v28
	v_ashrrev_i32_e32 v47, 31, v46
	v_and_b32_e32 v0, 15, v28
	v_lshlrev_b64 v[46:47], 16, v[46:47]
	v_lshl_add_u64 v[46:47], v[24:25], 0, v[46:47]
	v_lshlrev_b32_e32 v0, 2, v0
	v_lshl_add_u64 v[46:47], v[46:47], 0, v[0:1]
	global_load_dword v0, v[46:47], off
	s_waitcnt vmcnt(0)
	v_cvt_pk_bf16_f32 v46, v0, s0
	s_branch .LBB0_129

.LBB0_142:
	ds_read2_b32 v[12:13], v36 offset1:65
	ds_read2_b32 v[14:15], v36 offset0:130 offset1:195
	v_add_u32_e32 v0, 0x400, v36
	ds_read2_b32 v[18:19], v0 offset0:134 offset1:199
	v_mov_b32_e32 v11, v1
	s_waitcnt lgkmcnt(0)
	v_cvt_pk_bf16_f32 v12, v12, v13
	v_cvt_pk_bf16_f32 v13, v14, v15
	ds_read2_b32 v[14:15], v0 offset0:4 offset1:69
	v_lshl_add_u64 v[16:17], s[48:49], 0, v[10:11]
	v_add_u32_e32 v0, 0x400, v37
	s_waitcnt lgkmcnt(0)
	v_cvt_pk_bf16_f32 v14, v14, v15
	v_cvt_pk_bf16_f32 v15, v18, v19
	v_add_u32_e32 v18, s44, v3
	v_ashrrev_i32_e32 v19, 31, v18
	v_lshlrev_b64 v[18:19], 11, v[18:19]
	v_lshl_add_u64 v[18:19], v[16:17], 0, v[18:19]
	v_subrev_u32_e32 v240, s94, v18
	v_bfe_u32 v241, v240, 6, 5
	v_and_b32_e32 v242, 63, v240
	v_lshl_or_b32 v242, v241, 10, v242
	v_bfe_u32 v241, v240, 11, 4
	v_lshl_or_b32 v242, v241, 6, v242
	v_and_b32_e32 v241, 0x7fff, v240
	v_sub_u32_e32 v242, v242, v241
	v_ashrrev_i32_e32 v243, 31, v242
	v_lshl_add_u64 v[240:241], v[18:19], 0, v[242:243]
	global_store_dwordx4 v[240:241], v[12:15], off
	ds_read2_b32 v[12:13], v37 offset1:65
	ds_read2_b32 v[14:15], v37 offset0:130 offset1:195
	ds_read2_b32 v[18:19], v0 offset0:134 offset1:199
	s_waitcnt lgkmcnt(0)
	v_cvt_pk_bf16_f32 v12, v12, v13
	v_cvt_pk_bf16_f32 v13, v14, v15
	ds_read2_b32 v[14:15], v0 offset0:4 offset1:69
	s_waitcnt lgkmcnt(0)
	v_cvt_pk_bf16_f32 v14, v14, v15
	v_cvt_pk_bf16_f32 v15, v18, v19
	v_add_u32_e32 v18, s44, v35
	v_ashrrev_i32_e32 v19, 31, v18
	v_lshlrev_b64 v[18:19], 11, v[18:19]
	v_lshl_add_u64 v[16:17], v[16:17], 0, v[18:19]
	v_subrev_u32_e32 v240, s94, v16
	v_bfe_u32 v241, v240, 6, 5
	v_and_b32_e32 v242, 63, v240
	v_lshl_or_b32 v242, v241, 10, v242
	v_bfe_u32 v241, v240, 11, 4
	v_lshl_or_b32 v242, v241, 6, v242
	v_and_b32_e32 v241, 0x7fff, v240
	v_sub_u32_e32 v242, v242, v241
	v_ashrrev_i32_e32 v243, 31, v242
	v_lshl_add_u64 v[240:241], v[16:17], 0, v[242:243]
	global_store_dwordx4 v[240:241], v[12:15], off
	s_branch .LBB0_107

.LBB0_150:
	v_ashrrev_i32_e32 v63, 31, v62
	v_lshlrev_b64 v[64:65], 11, v[62:63]
	s_waitcnt vmcnt(0)
	v_lshl_or_b32 v18, v42, 1, v64
	v_mov_b32_e32 v19, v65
	v_lshl_add_u64 v[20:21], s[26:27], 0, v[18:19]
	v_lshl_add_u64 v[22:23], s[94:95], 0, v[18:19]
	v_lshl_add_u64 v[18:19], s[28:29], 0, v[18:19]
	global_load_dwordx4 v[34:37], v[20:21], off
	global_load_dwordx4 v[30:33], v[20:21], off offset:16
	global_load_dwordx4 v[38:41], v[22:23], off
	global_load_dwordx4 v[26:29], v[22:23], off offset:16
	s_nop 0
	global_load_dwordx4 v[22:25], v[18:19], off
	s_nop 0
	global_load_dwordx4 v[18:21], v[18:19], off offset:16
	v_add_u32_e32 v62, s4, v62
	v_cmp_gt_i32_e32 vcc, s14, v62
	v_ashrrev_i32_e32 v63, 31, v62
	s_and_saveexec_b64 s[40:41], vcc
	s_cbranch_execz .LBB0_152
	v_lshlrev_b64 v[46:47], 11, v[62:63]
	v_lshl_or_b32 v46, v42, 1, v46
	v_lshl_add_u64 v[74:75], s[26:27], 0, v[46:47]
	v_lshl_add_u64 v[80:81], s[94:95], 0, v[46:47]
	v_lshl_add_u64 v[84:85], s[28:29], 0, v[46:47]
	global_load_dwordx4 v[56:59], v[74:75], off
	global_load_dwordx4 v[66:69], v[80:81], off
	global_load_dwordx4 v[70:73], v[84:85], off
	global_load_dwordx4 v[76:79], v[74:75], off offset:16
	s_nop 0
	global_load_dwordx4 v[80:83], v[80:81], off offset:16
	s_nop 0
	global_load_dwordx4 v[84:87], v[84:85], off offset:16
	s_waitcnt vmcnt(0) lgkmcnt(0)
	v_lshlrev_b32_e32 v46, 16, v56
	v_and_b32_e32 v47, 0xffff0000, v56
	v_lshlrev_b32_e32 v48, 16, v66
	v_and_b32_e32 v49, 0xffff0000, v66
	v_lshlrev_b32_e32 v50, 16, v57
	v_and_b32_e32 v51, 0xffff0000, v57
	v_lshlrev_b32_e32 v52, 16, v67
	v_and_b32_e32 v53, 0xffff0000, v67
	v_lshlrev_b32_e32 v54, 16, v58
	v_and_b32_e32 v55, 0xffff0000, v58
	v_lshlrev_b32_e32 v56, 16, v68
	v_and_b32_e32 v57, 0xffff0000, v68
	v_lshlrev_b32_e32 v58, 16, v59
	v_and_b32_e32 v59, 0xffff0000, v59
	v_lshlrev_b32_e32 v60, 16, v69
	v_and_b32_e32 v61, 0xffff0000, v69
	v_pk_add_f32 v[48:49], v[46:47], v[48:49]
	v_lshlrev_b32_e32 v46, 16, v70
	v_and_b32_e32 v47, 0xffff0000, v70
	v_pk_add_f32 v[52:53], v[50:51], v[52:53]
	v_lshlrev_b32_e32 v50, 16, v71
	v_and_b32_e32 v51, 0xffff0000, v71
	v_pk_add_f32 v[56:57], v[54:55], v[56:57]
	v_lshlrev_b32_e32 v54, 16, v72
	v_and_b32_e32 v55, 0xffff0000, v72
	v_pk_add_f32 v[60:61], v[58:59], v[60:61]
	v_lshlrev_b32_e32 v58, 16, v73
	v_and_b32_e32 v59, 0xffff0000, v73
	v_lshlrev_b32_e32 v66, 16, v76
	v_and_b32_e32 v67, 0xffff0000, v76
	v_lshlrev_b32_e32 v68, 16, v80
	v_and_b32_e32 v69, 0xffff0000, v80
	v_lshlrev_b32_e32 v70, 16, v77
	v_and_b32_e32 v71, 0xffff0000, v77
	v_lshlrev_b32_e32 v72, 16, v81
	v_and_b32_e32 v73, 0xffff0000, v81
	v_lshlrev_b32_e32 v74, 16, v78
	v_and_b32_e32 v75, 0xffff0000, v78
	v_lshlrev_b32_e32 v76, 16, v82
	v_and_b32_e32 v77, 0xffff0000, v82
	v_lshlrev_b32_e32 v78, 16, v79
	v_and_b32_e32 v79, 0xffff0000, v79
	v_lshlrev_b32_e32 v80, 16, v83
	v_and_b32_e32 v81, 0xffff0000, v83
	v_pk_add_f32 v[66:67], v[66:67], v[68:69]
	v_lshlrev_b32_e32 v68, 16, v84
	v_and_b32_e32 v69, 0xffff0000, v84
	v_pk_add_f32 v[70:71], v[70:71], v[72:73]
	v_lshlrev_b32_e32 v72, 16, v85
	v_and_b32_e32 v73, 0xffff0000, v85
	v_pk_add_f32 v[74:75], v[74:75], v[76:77]
	v_lshlrev_b32_e32 v76, 16, v86
	v_and_b32_e32 v77, 0xffff0000, v86
	v_pk_add_f32 v[78:79], v[78:79], v[80:81]
	v_lshlrev_b32_e32 v80, 16, v87
	v_and_b32_e32 v81, 0xffff0000, v87
.LBB0_152:
	s_or_b64 exec, exec, s[40:41]
	s_waitcnt vmcnt(0) lgkmcnt(0)
	v_lshlrev_b32_e32 v82, 16, v34
	v_and_b32_e32 v83, 0xffff0000, v34
	v_lshlrev_b32_e32 v84, 16, v38
	v_and_b32_e32 v85, 0xffff0000, v38
	v_lshlrev_b32_e32 v34, 16, v35
	v_and_b32_e32 v35, 0xffff0000, v35
	v_lshlrev_b32_e32 v38, 16, v39
	v_and_b32_e32 v39, 0xffff0000, v39
	v_pk_add_f32 v[82:83], v[82:83], v[84:85]
	v_pk_add_f32 v[34:35], v[34:35], v[38:39]
	v_lshlrev_b32_e32 v38, 16, v36
	v_and_b32_e32 v39, 0xffff0000, v36
	v_lshlrev_b32_e32 v84, 16, v40
	v_and_b32_e32 v85, 0xffff0000, v40
	v_lshlrev_b32_e32 v36, 16, v37
	v_and_b32_e32 v37, 0xffff0000, v37
	v_lshlrev_b32_e32 v40, 16, v41
	v_and_b32_e32 v41, 0xffff0000, v41
	v_pk_add_f32 v[38:39], v[38:39], v[84:85]
	v_pk_add_f32 v[36:37], v[36:37], v[40:41]
	v_lshlrev_b32_e32 v40, 16, v30
	v_and_b32_e32 v41, 0xffff0000, v30
	v_lshlrev_b32_e32 v84, 16, v26
	v_and_b32_e32 v85, 0xffff0000, v26
	v_lshlrev_b32_e32 v30, 16, v31
	v_and_b32_e32 v31, 0xffff0000, v31
	v_lshlrev_b32_e32 v26, 16, v27
	v_and_b32_e32 v27, 0xffff0000, v27
	v_pk_add_f32 v[40:41], v[40:41], v[84:85]
	v_pk_add_f32 v[26:27], v[30:31], v[26:27]
	v_lshlrev_b32_e32 v30, 16, v32
	v_and_b32_e32 v31, 0xffff0000, v32
	v_lshlrev_b32_e32 v84, 16, v28
	v_and_b32_e32 v85, 0xffff0000, v28
	v_lshlrev_b32_e32 v32, 16, v33
	v_and_b32_e32 v33, 0xffff0000, v33
	v_lshlrev_b32_e32 v28, 16, v29
	v_and_b32_e32 v29, 0xffff0000, v29
	v_pk_add_f32 v[28:29], v[32:33], v[28:29]
	v_pk_mul_f32 v[32:33], v[82:83], v[82:83]
	v_pk_add_f32 v[30:31], v[30:31], v[84:85]
	v_pk_mul_f32 v[84:85], v[34:35], v[34:35]
	v_add_f32_e32 v0, v32, v33
	v_add_f32_e32 v0, v84, v0
	v_pk_mul_f32 v[86:87], v[38:39], v[38:39]
	v_add_f32_e32 v0, v85, v0
	v_add_f32_e32 v0, v86, v0
	v_pk_mul_f32 v[88:89], v[36:37], v[36:37]
	v_add_f32_e32 v0, v87, v0
	v_add_f32_e32 v0, v88, v0
	v_pk_mul_f32 v[90:91], v[40:41], v[40:41]
	v_add_f32_e32 v0, v89, v0
	v_add_f32_e32 v0, v90, v0
	v_pk_mul_f32 v[92:93], v[26:27], v[26:27]
	v_add_f32_e32 v0, v91, v0
	v_add_f32_e32 v0, v92, v0
	v_pk_mul_f32 v[94:95], v[30:31], v[30:31]
	v_add_f32_e32 v0, v93, v0
	v_add_f32_e32 v0, v94, v0
	v_pk_mul_f32 v[96:97], v[28:29], v[28:29]
	v_add_f32_e32 v0, v95, v0
	v_add_f32_e32 v0, v96, v0
	v_add_f32_e32 v0, v97, v0
	ds_bpermute_b32 v43, v188, v0
	v_lshlrev_b32_e32 v86, 16, v18
	v_and_b32_e32 v87, 0xffff0000, v18
	v_lshlrev_b32_e32 v32, 16, v22
	v_and_b32_e32 v33, 0xffff0000, v22
	s_waitcnt lgkmcnt(0)
	v_add_f32_e32 v0, v0, v43
	ds_bpermute_b32 v43, v189, v0
	v_lshlrev_b32_e32 v88, 16, v19
	v_and_b32_e32 v89, 0xffff0000, v19
	v_mul_f32_e32 v19, 0xbfb8aa3b, v33
	v_exp_f32_e32 v19, v19
	s_waitcnt lgkmcnt(0)
	v_add_f32_e32 v0, v0, v43
	ds_bpermute_b32 v43, v190, v0
	v_lshlrev_b32_e32 v22, 16, v23
	v_add_f32_e32 v19, 1.0, v19
	v_rcp_f32_e32 v19, v19
	v_and_b32_e32 v23, 0xffff0000, v23
	s_waitcnt lgkmcnt(0)
	v_add_f32_e32 v0, v0, v43
	ds_bpermute_b32 v18, v185, v0
	v_lshlrev_b32_e32 v90, 16, v20
	v_and_b32_e32 v91, 0xffff0000, v20
	v_lshlrev_b32_e32 v92, 16, v21
	v_and_b32_e32 v93, 0xffff0000, v21
	s_waitcnt lgkmcnt(0)
	v_add_f32_e32 v0, v0, v18
	v_mov_b32_e32 v18, 0x358637bd
	v_fmamk_f32 v0, v0, 0x3b800000, v18
	v_mul_f32_e32 v18, 0x4b800000, v0
	v_cmp_gt_f32_e32 vcc, s31, v0
	v_lshlrev_b32_e32 v84, 16, v24
	v_and_b32_e32 v85, 0xffff0000, v24
	v_cndmask_b32_e32 v0, v0, v18, vcc
	v_mul_f32_e32 v18, 0xbfb8aa3b, v32
	v_exp_f32_e32 v18, v18
	v_rsq_f32_e32 v0, v0
	v_lshlrev_b32_e32 v24, 16, v25
	v_and_b32_e32 v25, 0xffff0000, v25
	v_add_f32_e32 v18, 1.0, v18
	v_rcp_f32_e32 v18, v18
	v_mul_f32_e32 v20, 0x45800000, v0
	v_cndmask_b32_e32 v0, v0, v20, vcc
	v_pk_mul_f32 v[20:21], v[82:83], v[0:1] op_sel_hi:[1,0]
	v_pk_mul_f32 v[18:19], v[18:19], v[32:33]
	v_mul_f32_e32 v32, 0xbfb8aa3b, v22
	v_mul_f32_e32 v33, 0xbfb8aa3b, v23
	v_exp_f32_e32 v32, v32
	v_exp_f32_e32 v33, v33
	v_pk_mul_f32 v[20:21], v[14:15], v[20:21]
	v_pk_mul_f32 v[26:27], v[26:27], v[0:1] op_sel_hi:[1,0]
	v_pk_mul_f32 v[18:19], v[18:19], v[20:21]
	v_add_f32_e32 v20, 1.0, v32
	v_add_f32_e32 v21, 1.0, v33
	v_rcp_f32_e32 v20, v20
	v_rcp_f32_e32 v21, v21
	v_cvt_pk_bf16_f32 v18, v18, v19
	v_mul_f32_e32 v19, 0xbfb8aa3b, v84
	v_exp_f32_e32 v19, v19
	v_pk_mul_f32 v[20:21], v[20:21], v[22:23]
	v_mul_f32_e32 v22, 0xbfb8aa3b, v85
	v_exp_f32_e32 v23, v22
	v_pk_mul_f32 v[32:33], v[34:35], v[0:1] op_sel_hi:[1,0]
	v_add_f32_e32 v19, 1.0, v19
	v_pk_mul_f32 v[32:33], v[16:17], v[32:33]
	v_rcp_f32_e32 v22, v19
	v_add_f32_e32 v19, 1.0, v23
	v_pk_mul_f32 v[20:21], v[20:21], v[32:33]
	v_rcp_f32_e32 v23, v19
	v_mul_f32_e32 v32, 0xbfb8aa3b, v24
	v_mul_f32_e32 v33, 0xbfb8aa3b, v25
	v_exp_f32_e32 v32, v32
	v_exp_f32_e32 v33, v33
	v_cvt_pk_bf16_f32 v19, v20, v21
	v_pk_mul_f32 v[20:21], v[38:39], v[0:1] op_sel_hi:[1,0]
	v_pk_mul_f32 v[22:23], v[22:23], v[84:85]
	v_pk_mul_f32 v[20:21], v[10:11], v[20:21]
	v_pk_mul_f32 v[26:27], v[8:9], v[26:27]
	v_pk_mul_f32 v[20:21], v[22:23], v[20:21]
	v_add_f32_e32 v22, 1.0, v32
	v_add_f32_e32 v23, 1.0, v33
	v_rcp_f32_e32 v22, v22
	v_rcp_f32_e32 v23, v23
	v_cvt_pk_bf16_f32 v20, v20, v21
	v_mul_f32_e32 v21, 0xbfb8aa3b, v86
	v_exp_f32_e32 v21, v21
	v_pk_mul_f32 v[22:23], v[22:23], v[24:25]
	v_mul_f32_e32 v24, 0xbfb8aa3b, v87
	v_exp_f32_e32 v25, v24
	v_add_f32_e32 v21, 1.0, v21
	v_pk_mul_f32 v[32:33], v[36:37], v[0:1] op_sel_hi:[1,0]
	v_rcp_f32_e32 v24, v21
	v_add_f32_e32 v21, 1.0, v25
	v_pk_mul_f32 v[32:33], v[12:13], v[32:33]
	v_rcp_f32_e32 v25, v21
	v_pk_mul_f32 v[22:23], v[22:23], v[32:33]
	v_mul_f32_e32 v32, 0xbfb8aa3b, v88
	v_mul_f32_e32 v33, 0xbfb8aa3b, v89
	v_exp_f32_e32 v32, v32
	v_exp_f32_e32 v33, v33
	v_cvt_pk_bf16_f32 v21, v22, v23
	v_pk_mul_f32 v[22:23], v[40:41], v[0:1] op_sel_hi:[1,0]
	v_pk_mul_f32 v[24:25], v[24:25], v[86:87]
	v_pk_mul_f32 v[22:23], v[6:7], v[22:23]
	v_pk_mul_f32 v[28:29], v[28:29], v[0:1] op_sel_hi:[1,0]
	v_pk_mul_f32 v[22:23], v[24:25], v[22:23]
	v_add_f32_e32 v24, 1.0, v32
	v_add_f32_e32 v25, 1.0, v33
	v_cvt_pk_bf16_f32 v22, v22, v23
	v_mul_f32_e32 v23, 0xbfb8aa3b, v90
	v_rcp_f32_e32 v24, v24
	v_rcp_f32_e32 v25, v25
	v_exp_f32_e32 v23, v23
	v_mul_f32_e32 v32, 0xbfb8aa3b, v91
	v_exp_f32_e32 v32, v32
	v_pk_mul_f32 v[24:25], v[24:25], v[88:89]
	v_add_f32_e32 v23, 1.0, v23
	v_pk_mul_f32 v[24:25], v[24:25], v[26:27]
	v_rcp_f32_e32 v26, v23
	v_add_f32_e32 v23, 1.0, v32
	v_rcp_f32_e32 v27, v23
	v_cvt_pk_bf16_f32 v23, v24, v25
	v_pk_mul_f32 v[24:25], v[30:31], v[0:1] op_sel_hi:[1,0]
	v_mul_f32_e32 v30, 0xbfb8aa3b, v92
	v_mul_f32_e32 v31, 0xbfb8aa3b, v93
	v_exp_f32_e32 v30, v30
	v_exp_f32_e32 v31, v31
	v_pk_mul_f32 v[24:25], v[2:3], v[24:25]
	v_pk_mul_f32 v[26:27], v[26:27], v[90:91]
	v_pk_mul_f32 v[28:29], v[4:5], v[28:29]
	v_pk_mul_f32 v[24:25], v[26:27], v[24:25]
	v_add_f32_e32 v26, 1.0, v30
	v_add_f32_e32 v27, 1.0, v31
	v_rcp_f32_e32 v26, v26
	v_rcp_f32_e32 v27, v27
	v_cvt_pk_bf16_f32 v24, v24, v25
	v_cmp_gt_i32_e32 vcc, s14, v62
	v_pk_mul_f32 v[26:27], v[26:27], v[92:93]
	s_nop 0
	v_pk_mul_f32 v[26:27], v[26:27], v[28:29]
	s_nop 0
	v_cvt_pk_bf16_f32 v25, v26, v27
	v_lshl_add_u64 v[26:27], v[44:45], 0, v[64:65]
	global_store_dwordx4 v[26:27], v[18:21], off
	global_store_dwordx4 v[26:27], v[22:25], off offset:16
	s_and_saveexec_b64 s[40:41], vcc
	s_cbranch_execz .LBB0_149
	v_pk_mul_f32 v[18:19], v[48:49], v[48:49]
	v_pk_mul_f32 v[20:21], v[52:53], v[52:53]
	v_add_f32_e32 v0, v19, v18
	v_add_f32_e32 v0, v20, v0
	v_pk_mul_f32 v[22:23], v[56:57], v[56:57]
	v_add_f32_e32 v0, v21, v0
	v_add_f32_e32 v0, v22, v0
	v_pk_mul_f32 v[24:25], v[60:61], v[60:61]
	v_add_f32_e32 v0, v23, v0
	v_add_f32_e32 v0, v24, v0
	v_pk_mul_f32 v[26:27], v[66:67], v[66:67]
	v_add_f32_e32 v0, v25, v0
	v_add_f32_e32 v0, v26, v0
	v_pk_mul_f32 v[28:29], v[70:71], v[70:71]
	v_add_f32_e32 v0, v27, v0
	v_add_f32_e32 v0, v28, v0
	v_pk_mul_f32 v[30:31], v[74:75], v[74:75]
	v_add_f32_e32 v0, v29, v0
	v_add_f32_e32 v0, v30, v0
	v_pk_mul_f32 v[32:33], v[78:79], v[78:79]
	v_add_f32_e32 v0, v31, v0
	v_add_f32_e32 v0, v32, v0
	v_add_f32_e32 v0, v33, v0
	ds_bpermute_b32 v18, v188, v0
	v_mul_f32_e32 v19, 0xbfb8aa3b, v46
	v_mul_f32_e32 v20, 0xbfb8aa3b, v47
	v_exp_f32_e32 v19, v19
	v_exp_f32_e32 v20, v20
	s_waitcnt lgkmcnt(0)
	v_add_f32_e32 v0, v0, v18
	ds_bpermute_b32 v18, v189, v0
	v_mul_f32_e32 v23, 0xbfb8aa3b, v51
	v_exp_f32_e32 v23, v23
	v_mul_f32_e32 v24, 0xbfb8aa3b, v55
	v_exp_f32_e32 v24, v24
	s_waitcnt lgkmcnt(0)
	v_add_f32_e32 v0, v0, v18
	ds_bpermute_b32 v18, v190, v0
	v_mul_f32_e32 v25, 0xbfb8aa3b, v59
	v_exp_f32_e32 v25, v25
	v_mul_f32_e32 v26, 0xbfb8aa3b, v69
	v_exp_f32_e32 v26, v26
	s_waitcnt lgkmcnt(0)
	v_add_f32_e32 v0, v0, v18
	ds_bpermute_b32 v21, v185, v0
	v_add_f32_e32 v18, 1.0, v19
	v_add_f32_e32 v19, 1.0, v20
	v_mov_b32_e32 v20, 0x358637bd
	v_rcp_f32_e32 v18, v18
	s_waitcnt lgkmcnt(0)
	v_add_f32_e32 v0, v0, v21
	v_fmamk_f32 v0, v0, 0x3b800000, v20
	v_mul_f32_e32 v20, 0x4b800000, v0
	v_cmp_gt_f32_e32 vcc, s31, v0
	v_rcp_f32_e32 v19, v19
	v_mul_f32_e32 v27, 0xbfb8aa3b, v73
	v_cndmask_b32_e32 v0, v0, v20, vcc
	v_rsq_f32_e32 v0, v0
	v_mul_f32_e32 v20, 0xbfb8aa3b, v50
	v_exp_f32_e32 v22, v20
	v_pk_mul_f32 v[18:19], v[46:47], v[18:19]
	v_mul_f32_e32 v20, 0x45800000, v0
	v_cndmask_b32_e32 v0, v0, v20, vcc
	v_pk_mul_f32 v[20:21], v[48:49], v[0:1] op_sel_hi:[1,0]
	v_exp_f32_e32 v27, v27
	v_pk_mul_f32 v[20:21], v[14:15], v[20:21]
	v_mul_f32_e32 v28, 0xbfb8aa3b, v77
	v_pk_mul_f32 v[18:19], v[18:19], v[20:21]
	v_add_f32_e32 v20, 1.0, v22
	v_add_f32_e32 v21, 1.0, v23
	v_cvt_pk_bf16_f32 v18, v18, v19
	v_mul_f32_e32 v19, 0xbfb8aa3b, v54
	v_rcp_f32_e32 v20, v20
	v_rcp_f32_e32 v21, v21
	v_exp_f32_e32 v19, v19
	v_pk_mul_f32 v[22:23], v[52:53], v[0:1] op_sel_hi:[1,0]
	v_exp_f32_e32 v28, v28
	v_pk_mul_f32 v[22:23], v[16:17], v[22:23]
	v_pk_mul_f32 v[20:21], v[50:51], v[20:21]
	v_add_f32_e32 v19, 1.0, v19
	v_pk_mul_f32 v[20:21], v[20:21], v[22:23]
	v_rcp_f32_e32 v22, v19
	v_add_f32_e32 v19, 1.0, v24
	v_rcp_f32_e32 v23, v19
	v_mul_f32_e32 v24, 0xbfb8aa3b, v58
	v_exp_f32_e32 v24, v24
	v_cvt_pk_bf16_f32 v19, v20, v21
	v_pk_mul_f32 v[20:21], v[56:57], v[0:1] op_sel_hi:[1,0]
	v_pk_mul_f32 v[22:23], v[54:55], v[22:23]
	v_pk_mul_f32 v[20:21], v[10:11], v[20:21]
	v_mul_f32_e32 v29, 0xbfb8aa3b, v81
	v_pk_mul_f32 v[20:21], v[22:23], v[20:21]
	v_add_f32_e32 v22, 1.0, v24
	v_add_f32_e32 v23, 1.0, v25
	v_cvt_pk_bf16_f32 v20, v20, v21
	v_mul_f32_e32 v21, 0xbfb8aa3b, v68
	v_rcp_f32_e32 v22, v22
	v_rcp_f32_e32 v23, v23
	v_exp_f32_e32 v21, v21
	v_pk_mul_f32 v[24:25], v[60:61], v[0:1] op_sel_hi:[1,0]
	v_exp_f32_e32 v29, v29
	v_pk_mul_f32 v[24:25], v[12:13], v[24:25]
	v_pk_mul_f32 v[22:23], v[58:59], v[22:23]
	v_add_f32_e32 v21, 1.0, v21
	v_pk_mul_f32 v[22:23], v[22:23], v[24:25]
	v_rcp_f32_e32 v24, v21
	v_add_f32_e32 v21, 1.0, v26
	v_rcp_f32_e32 v25, v21
	v_mul_f32_e32 v26, 0xbfb8aa3b, v72
	v_exp_f32_e32 v26, v26
	v_cvt_pk_bf16_f32 v21, v22, v23
	v_pk_mul_f32 v[22:23], v[66:67], v[0:1] op_sel_hi:[1,0]
	v_pk_mul_f32 v[24:25], v[68:69], v[24:25]
	v_pk_mul_f32 v[22:23], v[6:7], v[22:23]
	s_nop 0
	v_pk_mul_f32 v[22:23], v[24:25], v[22:23]
	v_add_f32_e32 v24, 1.0, v26
	v_add_f32_e32 v25, 1.0, v27
	v_cvt_pk_bf16_f32 v22, v22, v23
	v_mul_f32_e32 v23, 0xbfb8aa3b, v76
	v_rcp_f32_e32 v24, v24
	v_rcp_f32_e32 v25, v25
	v_exp_f32_e32 v23, v23
	v_pk_mul_f32 v[26:27], v[70:71], v[0:1] op_sel_hi:[1,0]
	v_pk_mul_f32 v[24:25], v[72:73], v[24:25]
	v_pk_mul_f32 v[26:27], v[8:9], v[26:27]
	v_add_f32_e32 v23, 1.0, v23
	v_pk_mul_f32 v[24:25], v[24:25], v[26:27]
	v_rcp_f32_e32 v26, v23
	v_add_f32_e32 v23, 1.0, v28
	v_rcp_f32_e32 v27, v23
	v_mul_f32_e32 v28, 0xbfb8aa3b, v80
	v_exp_f32_e32 v28, v28
	v_cvt_pk_bf16_f32 v23, v24, v25
	v_pk_mul_f32 v[24:25], v[74:75], v[0:1] op_sel_hi:[1,0]
	v_pk_mul_f32 v[26:27], v[76:77], v[26:27]
	v_pk_mul_f32 v[24:25], v[2:3], v[24:25]
	s_nop 0
	v_pk_mul_f32 v[24:25], v[26:27], v[24:25]
	v_add_f32_e32 v26, 1.0, v28
	v_add_f32_e32 v27, 1.0, v29
	v_rcp_f32_e32 v26, v26
	v_rcp_f32_e32 v27, v27
	v_pk_mul_f32 v[28:29], v[78:79], v[0:1] op_sel_hi:[1,0]
	v_cvt_pk_bf16_f32 v24, v24, v25
	v_pk_mul_f32 v[28:29], v[4:5], v[28:29]
	v_pk_mul_f32 v[26:27], v[80:81], v[26:27]
	s_nop 0
	v_pk_mul_f32 v[26:27], v[26:27], v[28:29]
	s_nop 0
	v_cvt_pk_bf16_f32 v25, v26, v27
	v_lshlrev_b64 v[26:27], 11, v[62:63]
	v_lshl_add_u64 v[26:27], v[44:45], 0, v[26:27]
	global_store_dwordx4 v[26:27], v[18:21], off
	global_store_dwordx4 v[26:27], v[22:25], off offset:16
	s_branch .LBB0_149

.LBB0_159:
	ds_read_b128 v[2:5], v151 offset:40960
	ds_read_b128 v[6:9], v152 offset:40960
	ds_read_b128 v[10:13], v129 offset:32768
	ds_read_b128 v[14:17], v129 offset:34816
	ds_read_b128 v[26:29], v0 offset:32768
	ds_read_b128 v[30:33], v0 offset:34816
	ds_read2st64_b64 v[34:37], v143 offset1:8
	ds_read_b128 v[46:49], v129 offset:36864
	ds_read_b128 v[50:53], v129 offset:38912
	ds_read2st64_b64 v[54:57], v144 offset1:8
	ds_read_b128 v[58:61], v0 offset:36864
	ds_read_b128 v[62:65], v0 offset:38912
	ds_read2st64_b64 v[70:73], v143 offset0:16 offset1:24
	ds_read2st64_b64 v[74:77], v144 offset0:16 offset1:24
	ds_read2st64_b64 v[78:81], v145 offset1:8
	ds_read2st64_b64 v[82:85], v146 offset1:8
	ds_read2st64_b64 v[86:89], v145 offset0:16 offset1:24
	ds_read2st64_b64 v[90:93], v146 offset0:16 offset1:24
	s_and_b64 s[8:9], s[22:23], exec
	s_movk_i32 s7, 0x8c0
	s_cselect_b32 s92, s7, 0x100
	s_waitcnt lgkmcnt(11)
	v_mov_b32_e32 v66, v34
	v_mov_b32_e32 v67, v35
	s_waitcnt lgkmcnt(8)
	v_mov_b32_e32 v68, v54
	v_mov_b32_e32 v69, v55
	v_mov_b32_e32 v54, v36
	v_mov_b32_e32 v55, v37
	s_waitcnt lgkmcnt(5)
	v_mov_b32_e32 v34, v70
	v_mov_b32_e32 v35, v71
	s_waitcnt lgkmcnt(4)
	v_mov_b32_e32 v36, v74
	v_mov_b32_e32 v37, v75
	v_mov_b32_e32 v74, v72
	v_mov_b32_e32 v75, v73
	s_waitcnt lgkmcnt(3)
	v_mov_b32_e32 v70, v78
	v_mov_b32_e32 v71, v79
	s_waitcnt lgkmcnt(2)
	v_mov_b32_e32 v72, v82
	v_mov_b32_e32 v73, v83
	v_mov_b32_e32 v82, v80
	v_mov_b32_e32 v83, v81
	s_waitcnt lgkmcnt(1)
	v_mov_b32_e32 v78, v86
	v_mov_b32_e32 v79, v87
	s_waitcnt lgkmcnt(0)
	v_mov_b32_e32 v80, v90
	v_mov_b32_e32 v81, v91
	v_mov_b32_e32 v90, v88
	v_mov_b32_e32 v91, v89
	v_mfma_f32_16x16x32_bf16 v[10:13], v[2:5], v[10:13], 0
	v_mfma_f32_16x16x32_bf16 v[10:13], v[6:9], v[26:29], v[10:13]
	v_mfma_f32_16x16x32_bf16 v[14:17], v[2:5], v[14:17], 0
	v_mfma_f32_16x16x32_bf16 v[26:29], v[2:5], v[46:49], 0
	v_mfma_f32_16x16x32_bf16 v[2:5], v[2:5], v[50:53], 0
	v_mfma_f32_16x16x32_bf16 v[14:17], v[6:9], v[30:33], v[14:17]
	v_mfma_f32_16x16x32_bf16 v[26:29], v[6:9], v[58:61], v[26:29]
	v_mfma_f32_16x16x32_bf16 v[2:5], v[6:9], v[62:65], v[2:5]
	ds_read2st64_b64 v[6:9], v147 offset1:8
	ds_read2st64_b64 v[30:33], v148 offset1:8
	ds_read2st64_b64 v[46:49], v147 offset0:16 offset1:24
	ds_read2st64_b64 v[58:61], v148 offset0:16 offset1:24
	ds_read2st64_b64 v[62:65], v149 offset1:8
	ds_read2st64_b64 v[86:89], v150 offset1:8
	ds_read2st64_b64 v[94:97], v149 offset0:16 offset1:24
	ds_read2st64_b64 v[98:101], v150 offset0:16 offset1:24
	s_waitcnt lgkmcnt(7)
	v_mov_b32_e32 v50, v6
	v_mov_b32_e32 v51, v7
	s_waitcnt lgkmcnt(6)
	v_mov_b32_e32 v52, v30
	v_mov_b32_e32 v53, v31
	v_mov_b32_e32 v30, v8
	v_mov_b32_e32 v31, v9
	s_waitcnt lgkmcnt(5)
	v_mov_b32_e32 v6, v46
	v_mov_b32_e32 v7, v47
	s_waitcnt lgkmcnt(4)
	v_mov_b32_e32 v8, v58
	v_mov_b32_e32 v9, v59
	v_mov_b32_e32 v58, v48
	v_mov_b32_e32 v59, v49
	s_waitcnt lgkmcnt(3)
	v_mov_b32_e32 v46, v62
	v_mov_b32_e32 v47, v63
	s_waitcnt lgkmcnt(2)
	v_mov_b32_e32 v48, v86
	v_mov_b32_e32 v49, v87
	v_mov_b32_e32 v86, v64
	v_mov_b32_e32 v87, v65
	s_waitcnt lgkmcnt(1)
	v_mov_b32_e32 v62, v94
	v_mov_b32_e32 v63, v95
	s_waitcnt lgkmcnt(0)
	v_mov_b32_e32 v64, v98
	v_mov_b32_e32 v65, v99
	v_mov_b32_e32 v98, v96
	v_mov_b32_e32 v99, v97
	v_mfma_f32_16x16x32_bf16 v[10:13], v[42:45], v[66:69], v[10:13]
	v_mfma_f32_16x16x32_bf16 v[14:17], v[42:45], v[54:57], v[14:17]
	v_mfma_f32_16x16x32_bf16 v[26:29], v[42:45], v[34:37], v[26:29]
	v_mfma_f32_16x16x32_bf16 v[2:5], v[42:45], v[74:77], v[2:5]
	v_mfma_f32_16x16x32_bf16 v[10:13], v[38:41], v[70:73], v[10:13]
	v_mfma_f32_16x16x32_bf16 v[14:17], v[38:41], v[82:85], v[14:17]
	v_mfma_f32_16x16x32_bf16 v[26:29], v[38:41], v[78:81], v[26:29]
	v_mfma_f32_16x16x32_bf16 v[2:5], v[38:41], v[90:93], v[2:5]
	v_mfma_f32_16x16x32_bf16 v[10:13], v[22:25], v[50:53], v[10:13]
	v_mfma_f32_16x16x32_bf16 v[14:17], v[22:25], v[30:33], v[14:17]
	v_mfma_f32_16x16x32_bf16 v[6:9], v[22:25], v[6:9], v[26:29]
	v_mfma_f32_16x16x32_bf16 v[2:5], v[22:25], v[58:61], v[2:5]
	v_mfma_f32_16x16x32_bf16 v[10:13], v[18:21], v[46:49], v[10:13]
	v_mfma_f32_16x16x32_bf16 v[14:17], v[18:21], v[86:89], v[14:17]
	v_mfma_f32_16x16x32_bf16 v[6:9], v[18:21], v[62:65], v[6:9]
	v_mfma_f32_16x16x32_bf16 v[2:5], v[18:21], v[98:101], v[2:5]
	v_lshl_add_u64 v[18:19], v[130:131], 0, s[92:93]
	s_nop 3
	v_cvt_pk_bf16_f32 v10, v10, v11
	v_cvt_pk_bf16_f32 v11, v12, v13
	v_lshlrev_b64 v[12:13], 11, v[18:19]
	v_lshl_add_u64 v[12:13], v[132:133], 0, v[12:13]
	global_store_dwordx2 v[12:13], v[10:11], off
	v_cvt_pk_bf16_f32 v10, v14, v15
	v_add_co_u32_e32 v14, vcc, s3, v12
	v_cvt_pk_bf16_f32 v6, v6, v7
	s_nop 0
	v_addc_co_u32_e32 v15, vcc, 0, v13, vcc
	v_cvt_pk_bf16_f32 v7, v8, v9
	v_add_co_u32_e32 v8, vcc, s36, v12
	v_cvt_pk_bf16_f32 v2, v2, v3
	s_nop 0
	v_addc_co_u32_e32 v9, vcc, 0, v13, vcc
	v_cvt_pk_bf16_f32 v3, v4, v5
	v_add_co_u32_e32 v4, vcc, 0x18000, v12
	v_cvt_pk_bf16_f32 v11, v16, v17
	s_nop 0
	v_addc_co_u32_e32 v5, vcc, 0, v13, vcc
	global_store_dwordx2 v[14:15], v[10:11], off
	global_store_dwordx2 v[8:9], v[6:7], off
	global_store_dwordx2 v[4:5], v[2:3], off
	s_add_i32 s6, s6, s34
	s_cmpk_gt_i32 s6, 0xff
	s_waitcnt lgkmcnt(0)
	s_barrier
	s_cbranch_scc1 .LBB0_171
.LBB0_160:
	s_bfe_i32 s7, s6, 0x10002
	s_bfe_u32 s26, s6, 0x10002
	s_bfe_u32 s10, s6, 0x20003
	s_cmp_eq_u32 s26, 0
	s_cselect_b64 s[22:23], -1, 0
	s_ashr_i32 s28, s6, 5
	s_and_b32 s16, s7, 3
	s_mul_i32 s7, s28, 36
	s_or_b32 s8, s16, s7
	s_ashr_i32 s9, s8, 31
	s_lshl_b64 s[40:41], s[8:9], 3
	s_lshl_b32 s92, s10, 1
	s_or_b32 s8, s40, s92
	s_ashr_i32 s29, s28, 31
	s_or_b32 s40, s8, s26
	s_lshl_b64 s[8:9], s[28:29], 10
	s_lshl_b32 s10, s10, 8
	s_lshl_b32 s11, s6, 6
	s_or_b32 s8, s8, s10
	s_and_b32 s11, s11, 0xc0
	s_or_b32 s8, s8, s11
	s_mulk_i32 s9, 0x1200
	s_mul_hi_u32 s14, s8, 0x1200
	s_add_i32 s9, s14, s9
	s_lshl_b64 s[14:15], s[40:41], 14
	v_lshl_add_u64 v[2:3], v[114:115], 0, s[14:15]
	v_add_co_u32_e32 v4, vcc, s85, v2
	s_waitcnt lgkmcnt(0)
	s_nop 0
	v_addc_co_u32_e32 v5, vcc, 0, v3, vcc
	s_barrier
	global_load_dwordx4 v[6:9], v[2:3], off
	global_load_dwordx4 v[10:13], v[4:5], off
	v_add_co_u32_e32 v4, vcc, s37, v2
	s_lshl_b64 s[12:13], s[40:41], 13
	s_nop 0
	v_addc_co_u32_e32 v5, vcc, 0, v3, vcc
	v_add_co_u32_e32 v2, vcc, s33, v2
	s_mulk_i32 s8, 0x1200
	s_nop 0
	v_addc_co_u32_e32 v3, vcc, 0, v3, vcc
	global_load_dwordx4 v[14:17], v[4:5], off
	global_load_dwordx4 v[18:21], v[2:3], off
	v_lshl_add_u64 v[2:3], v[116:117], 0, s[14:15]
	v_add_co_u32_e32 v4, vcc, s85, v2
	s_add_u32 s8, s4, s8
	s_nop 0
	v_addc_co_u32_e32 v5, vcc, 0, v3, vcc
	global_load_dwordx4 v[22:25], v[2:3], off
	global_load_dwordx4 v[26:29], v[4:5], off
	v_add_co_u32_e32 v4, vcc, s37, v2
	s_addc_u32 s9, s5, s9
	s_nop 0
	v_addc_co_u32_e32 v5, vcc, 0, v3, vcc
	v_add_co_u32_e32 v2, vcc, s33, v2
	v_mov_b32_e32 v0, v1
	s_nop 0
	v_addc_co_u32_e32 v3, vcc, 0, v3, vcc
	global_load_dwordx4 v[30:33], v[4:5], off
	global_load_dwordx4 v[34:37], v[2:3], off
	v_lshl_add_u64 v[2:3], v[118:119], 0, s[12:13]
	s_lshl_b32 s12, s16, 7
	s_add_u32 s12, s8, s12
	v_add_co_u32_e32 v4, vcc, s85, v2
	s_addc_u32 s13, s9, 0
	s_nop 0
	v_addc_co_u32_e32 v5, vcc, 0, v3, vcc
	global_load_dwordx4 v[38:41], v[2:3], off
	global_load_dwordx4 v[42:45], v[4:5], off
	v_lshl_add_u64 v[2:3], s[12:13], 0, v[120:121]
	v_lshl_add_u64 v[4:5], s[12:13], 0, v[122:123]
	global_load_dwordx4 v[46:49], v[2:3], off
	global_load_dwordx4 v[50:53], v[4:5], off
	v_mov_b32_e32 v2, v1
	v_mov_b32_e32 v3, v1
	v_mov_b64_e32 v[4:5], v[2:3]
	v_mov_b64_e32 v[2:3], v[0:1]
	s_and_saveexec_b64 s[42:43], s[38:39]
	s_cbranch_execz .LBB0_162
	s_lshl_b64 s[12:13], s[40:41], 9
	v_lshl_add_u64 v[2:3], v[124:125], 0, s[12:13]
	global_load_dwordx4 v[2:5], v[2:3], off

.LBB0_165:
	s_add_i32 s11, s12, 1
	s_cmp_lt_u32 s12, 3
	s_cselect_b32 s13, 3, 39
	s_add_i32 s13, s13, s10
	s_and_b64 s[14:15], s[22:23], exec
	s_cselect_b32 s13, s11, s13
	s_add_i32 s14, s13, s7
	s_ashr_i32 s15, s14, 31
	s_lshl_b64 s[14:15], s[14:15], 3
	s_or_b64 s[28:29], s[14:15], s[26:27]
	s_lshl_b64 s[18:19], s[28:29], 14
	v_lshl_add_u64 v[62:63], v[114:115], 0, s[18:19]
	v_add_co_u32_e32 v58, vcc, s85, v62
	v_lshl_add_u64 v[78:79], v[116:117], 0, s[18:19]
	s_nop 0
	v_addc_co_u32_e32 v59, vcc, 0, v63, vcc
	v_add_co_u32_e32 v64, vcc, s37, v62
	s_lshl_b32 s16, s13, 6
	s_nop 0
	v_addc_co_u32_e32 v65, vcc, 0, v63, vcc
	v_add_co_u32_e32 v66, vcc, s33, v62
	s_lshl_b64 s[14:15], s[28:29], 13
	s_nop 0
	v_addc_co_u32_e32 v67, vcc, 0, v63, vcc
	v_add_co_u32_e32 v74, vcc, s85, v78
	s_ashr_i32 s17, s16, 31
	s_nop 0
	v_addc_co_u32_e32 v75, vcc, 0, v79, vcc
	v_add_co_u32_e32 v80, vcc, s37, v78
	v_lshl_add_u64 v[86:87], v[118:119], 0, s[14:15]
	s_nop 0
	v_addc_co_u32_e32 v81, vcc, 0, v79, vcc
	v_add_co_u32_e32 v82, vcc, s33, v78
	s_lshl_b64 s[14:15], s[16:17], 1
	s_nop 0
	v_addc_co_u32_e32 v83, vcc, 0, v79, vcc
	s_add_u32 s14, s8, s14
	v_add_co_u32_e32 v90, vcc, s85, v86
	s_addc_u32 s15, s9, s15
	s_nop 0
	v_addc_co_u32_e32 v91, vcc, 0, v87, vcc
	v_lshl_add_u64 v[94:95], s[14:15], 0, v[120:121]
	v_lshl_add_u64 v[98:99], s[14:15], 0, v[122:123]
	global_load_dwordx4 v[54:57], v[62:63], off
	s_nop 0
	global_load_dwordx4 v[58:61], v[58:59], off
	s_nop 0
	global_load_dwordx4 v[62:65], v[64:65], off
	s_nop 0
	global_load_dwordx4 v[66:69], v[66:67], off
	s_nop 0
	global_load_dwordx4 v[70:73], v[78:79], off
	s_nop 0
	global_load_dwordx4 v[74:77], v[74:75], off
	s_nop 0
	global_load_dwordx4 v[78:81], v[80:81], off
	s_nop 0
	global_load_dwordx4 v[82:85], v[82:83], off
	s_nop 0
	global_load_dwordx4 v[86:89], v[86:87], off
	s_nop 0
	global_load_dwordx4 v[90:93], v[90:91], off
	s_nop 0
	global_load_dwordx4 v[94:97], v[94:95], off
	s_nop 0
	global_load_dwordx4 v[98:101], v[98:99], off
	s_and_saveexec_b64 s[40:41], s[38:39]
	s_cbranch_execz .LBB0_167
	s_lshl_b64 s[14:15], s[28:29], 9
	v_lshl_add_u64 v[2:3], v[124:125], 0, s[14:15]
	global_load_dwordx4 v[2:5], v[2:3], off
.LBB0_167:
	s_or_b64 exec, exec, s[40:41]
	v_add_u32_e32 v151, v113, v136
	v_add_u32_e32 v129, v111, v136
	s_cmp_gt_u32 s12, 3
	v_add_u32_e32 v152, v113, v137
	ds_read_b128 v[106:109], v151 offset:40960
	ds_read_b128 v[102:105], v152 offset:40960
	v_add_u32_e32 v0, v111, v137
	ds_read_b128 v[154:157], v129 offset:32768
	ds_read_b128 v[158:161], v129 offset:34816
	ds_read_b128 v[162:165], v0 offset:32768
	ds_read_b128 v[166:169], v0 offset:34816
	ds_read2st64_b64 v[170:173], v143 offset1:8
	ds_read_b128 v[174:177], v129 offset:36864
	ds_read_b128 v[178:181], v129 offset:38912
	ds_read2st64_b64 v[200:203], v144 offset1:8
	ds_read_b128 v[204:207], v0 offset:36864
	ds_read_b128 v[208:211], v0 offset:38912
	ds_read2st64_b64 v[216:219], v143 offset0:16 offset1:24
	ds_read2st64_b64 v[220:223], v144 offset0:16 offset1:24
	ds_read2st64_b64 v[224:227], v145 offset1:8
	ds_read2st64_b64 v[228:231], v146 offset1:8
	ds_read2st64_b64 v[232:235], v145 offset0:16 offset1:24
	ds_read2st64_b64 v[236:239], v146 offset0:16 offset1:24
	s_cselect_b32 s13, 39, 3
	s_add_i32 s13, s13, s10
	s_add_i32 s13, s13, 1
	s_and_b64 s[14:15], s[22:23], exec
	s_cselect_b32 s12, s12, s13
	s_waitcnt lgkmcnt(0)
	v_mov_b32_e32 v212, v170
	v_mov_b32_e32 v213, v171
	v_mov_b32_e32 v214, v200
	v_mov_b32_e32 v215, v201
	v_mov_b32_e32 v200, v172
	v_mov_b32_e32 v201, v173
	v_mov_b32_e32 v170, v216
	v_mov_b32_e32 v171, v217
	v_mov_b32_e32 v172, v220
	v_mov_b32_e32 v173, v221
	v_mov_b32_e32 v220, v218
	v_mov_b32_e32 v221, v219
	v_mov_b32_e32 v216, v224
	v_mov_b32_e32 v217, v225
	v_mov_b32_e32 v218, v228
	v_mov_b32_e32 v219, v229
	v_mov_b32_e32 v228, v226
	v_mov_b32_e32 v229, v227
	v_mov_b32_e32 v224, v232
	v_mov_b32_e32 v225, v233
	v_mov_b32_e32 v226, v236
	v_mov_b32_e32 v227, v237
	v_mov_b32_e32 v236, v234
	v_mov_b32_e32 v237, v235
	v_mfma_f32_16x16x32_bf16 v[154:157], v[106:109], v[154:157], 0
	v_mfma_f32_16x16x32_bf16 v[158:161], v[106:109], v[158:161], 0
	v_mfma_f32_16x16x32_bf16 v[154:157], v[102:105], v[162:165], v[154:157]
	v_mfma_f32_16x16x32_bf16 v[158:161], v[102:105], v[166:169], v[158:161]
	v_mfma_f32_16x16x32_bf16 v[162:165], v[106:109], v[174:177], 0
	v_mfma_f32_16x16x32_bf16 v[166:169], v[106:109], v[178:181], 0
	v_mfma_f32_16x16x32_bf16 v[162:165], v[102:105], v[204:207], v[162:165]
	v_mfma_f32_16x16x32_bf16 v[166:169], v[102:105], v[208:211], v[166:169]
	ds_read2st64_b64 v[174:177], v147 offset1:8
	ds_read2st64_b64 v[178:181], v148 offset1:8
	ds_read2st64_b64 v[204:207], v147 offset0:16 offset1:24
	ds_read2st64_b64 v[232:235], v148 offset0:16 offset1:24
	ds_read2st64_b64 v[240:243], v149 offset1:8
	ds_read2st64_b64 v[244:247], v150 offset1:8
	ds_read2st64_b64 v[248:251], v149 offset0:16 offset1:24
	ds_read2st64_b64 v[192:195], v150 offset0:16 offset1:24
	s_waitcnt lgkmcnt(0)
	v_mov_b32_e32 v208, v174
	v_mov_b32_e32 v209, v175
	v_mov_b32_e32 v210, v178
	v_mov_b32_e32 v211, v179
	v_mov_b32_e32 v178, v176
	v_mov_b32_e32 v179, v177
	v_mov_b32_e32 v174, v204
	v_mov_b32_e32 v175, v205
	v_mov_b32_e32 v176, v232
	v_mov_b32_e32 v177, v233
	v_mov_b32_e32 v232, v206
	v_mov_b32_e32 v233, v207
	v_mov_b32_e32 v204, v240
	v_mov_b32_e32 v205, v241
	v_mov_b32_e32 v206, v244
	v_mov_b32_e32 v207, v245
	v_mov_b32_e32 v244, v242
	v_mov_b32_e32 v245, v243
	v_mov_b32_e32 v240, v248
	v_mov_b32_e32 v241, v249
	v_mov_b32_e32 v242, v192
	v_mov_b32_e32 v243, v193
	v_mov_b32_e32 v192, v250
	v_mov_b32_e32 v193, v251
	v_mfma_f32_16x16x32_bf16 v[154:157], v[42:45], v[212:215], v[154:157]
	v_mfma_f32_16x16x32_bf16 v[158:161], v[42:45], v[200:203], v[158:161]
	v_mfma_f32_16x16x32_bf16 v[162:165], v[42:45], v[170:173], v[162:165]
	v_mfma_f32_16x16x32_bf16 v[42:45], v[42:45], v[220:223], v[166:169]
	v_mfma_f32_16x16x32_bf16 v[154:157], v[38:41], v[216:219], v[154:157]
	v_mfma_f32_16x16x32_bf16 v[158:161], v[38:41], v[228:231], v[158:161]
	v_mfma_f32_16x16x32_bf16 v[162:165], v[38:41], v[224:227], v[162:165]
	v_mfma_f32_16x16x32_bf16 v[38:41], v[38:41], v[236:239], v[42:45]
	s_nop 3
	ds_read_b128 v[42:45], v135 offset:49152
	ds_read_b128 v[166:169], v135 offset:49216
	ds_read_b128 v[170:173], v129 offset:16384
	ds_read_b128 v[200:203], v129 offset:18432
	ds_read_b128 v[212:215], v0 offset:16384
	ds_read_b128 v[216:219], v0 offset:18432
	v_mfma_f32_16x16x32_bf16 v[154:157], v[22:25], v[208:211], v[154:157]
	v_mfma_f32_16x16x32_bf16 v[158:161], v[22:25], v[178:181], v[158:161]
	v_mfma_f32_16x16x32_bf16 v[162:165], v[22:25], v[174:177], v[162:165]
	v_mfma_f32_16x16x32_bf16 v[22:25], v[22:25], v[232:235], v[38:41]
	v_mfma_f32_16x16x32_bf16 v[38:41], v[18:21], v[204:207], v[154:157]
	v_mfma_f32_16x16x32_bf16 v[154:157], v[18:21], v[244:247], v[158:161]
	v_mfma_f32_16x16x32_bf16 v[158:161], v[18:21], v[240:243], v[162:165]
	v_mfma_f32_16x16x32_bf16 v[18:21], v[18:21], v[192:195], v[22:25]
	s_nop 3
	ds_read_b128 v[22:25], v135 offset:49280
	ds_read_b128 v[162:165], v135 offset:49344
	ds_read_b128 v[174:177], v129 offset:20480
	ds_read_b128 v[178:181], v129 offset:22528
	ds_read_b128 v[192:195], v0 offset:20480
	ds_read_b128 v[204:207], v0 offset:22528
	s_waitcnt lgkmcnt(0)
	v_pk_mul_f32 v[8:9], v[8:9], v[44:45]
	v_pk_mul_f32 v[6:7], v[6:7], v[42:43]
	v_pk_mul_f32 v[12:13], v[12:13], v[168:169]
	v_pk_mul_f32 v[10:11], v[10:11], v[166:167]
	v_mfma_f32_16x16x32_bf16 v[6:9], v[170:173], v[106:109], v[6:9]
	s_nop 0
	v_mfma_f32_16x16x32_bf16 v[10:13], v[200:203], v[106:109], v[10:13]
	v_mfma_f32_16x16x32_bf16 v[6:9], v[212:215], v[102:105], v[6:9]
	v_mfma_f32_16x16x32_bf16 v[10:13], v[216:219], v[102:105], v[10:13]
	s_lshl_b32 s12, s12, 6
	s_ashr_i32 s13, s12, 31
	v_lshl_add_u64 v[42:43], v[130:131], 0, s[12:13]
	v_cvt_pk_bf16_f32 v38, v38, v39
	v_cvt_pk_bf16_f32 v39, v40, v41
	v_lshlrev_b64 v[40:41], 11, v[42:43]
	v_lshl_add_u64 v[40:41], v[132:133], 0, v[40:41]
	v_add_co_u32_e32 v42, vcc, s3, v40
	global_store_dwordx2 v[40:41], v[38:39], off
	v_cvt_pk_bf16_f32 v38, v154, v155
	v_cvt_pk_bf16_f32 v39, v156, v157
	v_addc_co_u32_e32 v43, vcc, 0, v41, vcc
	global_store_dwordx2 v[42:43], v[38:39], off
	v_add_co_u32_e32 v42, vcc, s36, v40
	s_mov_b32 s12, 0x18000
	s_nop 0
	v_addc_co_u32_e32 v43, vcc, 0, v41, vcc
	v_cvt_pk_bf16_f32 v18, v18, v19
	v_cvt_pk_bf16_f32 v19, v20, v21
	v_add_co_u32_e32 v20, vcc, s12, v40
	v_cvt_pk_bf16_f32 v38, v158, v159
	v_cvt_pk_bf16_f32 v39, v160, v161
	v_addc_co_u32_e32 v21, vcc, 0, v41, vcc
	global_store_dwordx2 v[42:43], v[38:39], off
	global_store_dwordx2 v[20:21], v[18:19], off
	ds_read_b128 v[18:21], v135 offset:49408
	ds_read_b128 v[38:41], v135 offset:49472
	ds_read_b128 v[42:45], v129 offset:24576
	ds_read_b128 v[154:157], v129 offset:26624
	ds_read_b128 v[158:161], v0 offset:24576
	ds_read_b128 v[166:169], v0 offset:26624
	v_pk_mul_f32 v[16:17], v[16:17], v[24:25]
	v_pk_mul_f32 v[14:15], v[14:15], v[22:23]
	v_pk_mul_f32 v[24:25], v[28:29], v[164:165]
	v_pk_mul_f32 v[22:23], v[26:27], v[162:163]
	v_mfma_f32_16x16x32_bf16 v[14:17], v[174:177], v[106:109], v[14:17]
	s_nop 0
	v_mfma_f32_16x16x32_bf16 v[22:25], v[178:181], v[106:109], v[22:25]
	v_mfma_f32_16x16x32_bf16 v[14:17], v[192:195], v[102:105], v[14:17]
	v_mfma_f32_16x16x32_bf16 v[26:29], v[204:207], v[102:105], v[22:25]
	s_nop 5
	ds_read_b128 v[22:25], v135 offset:49536
	ds_read_b128 v[162:165], v135 offset:49600
	ds_read_b128 v[170:173], v129 offset:28672
	ds_read_b128 v[174:177], v129 offset:30720
	ds_read_b128 v[178:181], v0 offset:28672
	ds_read_b128 v[192:195], v0 offset:30720
	s_waitcnt lgkmcnt(0)
	v_pk_mul_f32 v[20:21], v[32:33], v[20:21]
	v_pk_mul_f32 v[18:19], v[30:31], v[18:19]
	s_nop 1
	v_mfma_f32_16x16x32_bf16 v[18:21], v[42:45], v[106:109], v[18:21]
	v_mfma_f32_16x16x32_bf16 v[30:33], v[158:161], v[102:105], v[18:21]
	s_nop 6
	v_mul_f32_e64 v20, v36, v40
	v_mul_f32_e64 v21, v37, v41
	v_pk_mul_f32 v[18:19], v[34:35], v[38:39]
	s_nop 1
	v_mfma_f32_16x16x32_bf16 v[18:21], v[154:157], v[106:109], v[18:21]
	v_mfma_f32_16x16x32_bf16 v[34:37], v[166:169], v[102:105], v[18:21]
	s_nop 6
	v_mul_f32_e64 v20, v52, v24
	v_mul_f32_e64 v21, v53, v25
	v_pk_mul_f32 v[18:19], v[50:51], v[22:23]
	v_pk_mul_f32 v[24:25], v[48:49], v[164:165]
	v_pk_mul_f32 v[22:23], v[46:47], v[162:163]
	v_mfma_f32_16x16x32_bf16 v[18:21], v[170:173], v[106:109], v[18:21]
	s_barrier
	v_mfma_f32_16x16x32_bf16 v[50:53], v[178:181], v[102:105], v[18:21]
	s_waitcnt vmcnt(0)
	ds_write_b128 v138, v[54:57]
	ds_write_b128 v139, v[58:61]
	ds_write_b128 v140, v[62:65]
	ds_write_b128 v141, v[66:69]
	ds_write_b128 v142, v[70:73] offset:16384
	ds_write_b128 v142, v[74:77] offset:20480
	ds_write_b128 v142, v[78:81] offset:24576
	ds_write_b128 v142, v[82:85] offset:28672
	ds_write_b128 v142, v[86:89] offset:32768
	ds_write_b128 v142, v[90:93] offset:36864
	ds_write_b128 v142, v[94:97] offset:40960
	ds_write_b128 v142, v[98:101] offset:45056
	v_mfma_f32_16x16x32_bf16 v[18:21], v[174:177], v[106:109], v[22:25]
	v_mfma_f32_16x16x32_bf16 v[46:49], v[192:195], v[102:105], v[18:21]
	s_and_saveexec_b64 s[28:29], s[38:39]
	ds_write_b128 v112, v[2:5] offset:49152
	s_or_b64 exec, exec, s[28:29]
	s_add_i32 s10, s10, -1
	v_cvt_pk_bf16_f32 v42, v6, v7
	v_cvt_pk_bf16_f32 v43, v8, v9
	v_cvt_pk_bf16_f32 v44, v10, v11
	v_cvt_pk_bf16_f32 v45, v12, v13
	v_cvt_pk_bf16_f32 v38, v14, v15
	v_cvt_pk_bf16_f32 v39, v16, v17
	v_cvt_pk_bf16_f32 v40, v26, v27
	v_cvt_pk_bf16_f32 v41, v28, v29
	v_cvt_pk_bf16_f32 v22, v30, v31
	v_cvt_pk_bf16_f32 v23, v32, v33
	v_cvt_pk_bf16_f32 v24, v34, v35
	v_cvt_pk_bf16_f32 v25, v36, v37
	v_cvt_pk_bf16_f32 v18, v50, v51
	v_cvt_pk_bf16_f32 v19, v52, v53
	v_cvt_pk_bf16_f32 v20, v46, v47
	v_cvt_pk_bf16_f32 v21, v48, v49
	s_cmp_eq_u32 s11, 35
	s_waitcnt lgkmcnt(0)
	s_barrier
	s_cbranch_scc1 .LBB0_159
	s_mov_b32 s12, s11
	s_branch .LBB0_165

.LBB0_182:
	ds_bpermute_b32 v0, v186, v10
	v_add_lshl_u32 v22, s25, v89, 10
	s_add_i32 s23, s23, s34
	s_cmp_ge_i32 s23, s35
	s_waitcnt lgkmcnt(0)
	v_add_f32_e32 v0, v10, v0
	ds_bpermute_b32 v10, v187, v0
	s_waitcnt lgkmcnt(0)
	v_add_f32_e32 v0, v0, v10
	v_rcp_f32_e32 v18, v0
	v_or3_b32 v0, s24, v80, v22
	v_lshlrev_b64 v[14:15], 1, v[0:1]
	v_lshl_add_u64 v[10:11], s[76:77], 0, v[14:15]
	global_load_dwordx4 v[10:13], v[10:11], off
	v_pk_mul_f32 v[20:21], v[58:59], v[18:19] op_sel_hi:[1,0]
	v_pk_mul_f32 v[16:17], v[60:61], v[18:19] op_sel_hi:[1,0]
	v_pk_mul_f32 v[26:27], v[66:67], v[18:19] op_sel_hi:[1,0]
	v_pk_mul_f32 v[24:25], v[68:69], v[18:19] op_sel_hi:[1,0]
	v_lshl_add_u64 v[14:15], s[94:95], 0, v[14:15]
	v_or_b32_e32 v0, 32, v0
	s_waitcnt vmcnt(0) lgkmcnt(0)
	v_lshlrev_b32_e32 v28, 16, v10
	v_and_b32_e32 v29, 0xffff0000, v10
	v_mul_f32_e32 v10, 0xbfb8aa3b, v28
	v_exp_f32_e32 v10, v10
	s_nop 0
	v_add_f32_e32 v10, 1.0, v10
	v_rcp_f32_e32 v30, v10
	v_mul_f32_e32 v10, 0xbfb8aa3b, v29
	v_exp_f32_e32 v10, v10
	s_nop 0
	v_add_f32_e32 v10, 1.0, v10
	v_rcp_f32_e32 v31, v10
	s_nop 0
	v_pk_mul_f32 v[28:29], v[30:31], v[28:29]
	s_nop 0
	v_pk_mul_f32 v[20:21], v[20:21], v[28:29]
	s_nop 0
	v_cvt_pk_bf16_f32 v10, v20, v21
	v_lshlrev_b32_e32 v20, 16, v11
	v_and_b32_e32 v21, 0xffff0000, v11
	v_mul_f32_e32 v11, 0xbfb8aa3b, v20
	v_exp_f32_e32 v11, v11
	s_nop 0
	v_add_f32_e32 v11, 1.0, v11
	v_rcp_f32_e32 v28, v11
	v_mul_f32_e32 v11, 0xbfb8aa3b, v21
	v_exp_f32_e32 v11, v11
	s_nop 0
	v_add_f32_e32 v11, 1.0, v11
	v_rcp_f32_e32 v29, v11
	s_nop 0
	v_pk_mul_f32 v[20:21], v[28:29], v[20:21]
	s_nop 0
	v_pk_mul_f32 v[16:17], v[16:17], v[20:21]
	s_nop 0
	v_cvt_pk_bf16_f32 v11, v16, v17
	v_lshlrev_b32_e32 v16, 16, v12
	v_and_b32_e32 v17, 0xffff0000, v12
	v_mul_f32_e32 v12, 0xbfb8aa3b, v16
	v_exp_f32_e32 v12, v12
	s_nop 0
	v_add_f32_e32 v12, 1.0, v12
	v_rcp_f32_e32 v20, v12
	v_mul_f32_e32 v12, 0xbfb8aa3b, v17
	v_exp_f32_e32 v12, v12
	s_nop 0
	v_add_f32_e32 v12, 1.0, v12
	v_rcp_f32_e32 v21, v12
	s_nop 0
	v_pk_mul_f32 v[16:17], v[20:21], v[16:17]
	s_nop 0
	v_pk_mul_f32 v[16:17], v[26:27], v[16:17]
	s_nop 0
	v_cvt_pk_bf16_f32 v12, v16, v17
	v_lshlrev_b32_e32 v16, 16, v13
	v_and_b32_e32 v17, 0xffff0000, v13
	v_mul_f32_e32 v13, 0xbfb8aa3b, v16
	v_exp_f32_e32 v13, v13
	s_nop 0
	v_add_f32_e32 v13, 1.0, v13
	v_rcp_f32_e32 v20, v13
	v_mul_f32_e32 v13, 0xbfb8aa3b, v17
	v_exp_f32_e32 v13, v13
	s_nop 0
	v_add_f32_e32 v13, 1.0, v13
	v_rcp_f32_e32 v21, v13
	s_nop 0
	v_pk_mul_f32 v[16:17], v[20:21], v[16:17]
	s_nop 0
	v_pk_mul_f32 v[16:17], v[24:25], v[16:17]
	v_pk_mul_f32 v[24:25], v[50:51], v[18:19] op_sel_hi:[1,0]
	v_cvt_pk_bf16_f32 v13, v16, v17
	global_store_dwordx4 v[14:15], v[10:13], off
	v_pk_mul_f32 v[20:21], v[52:53], v[18:19] op_sel_hi:[1,0]
	v_pk_mul_f32 v[16:17], v[56:57], v[18:19] op_sel_hi:[1,0]
	v_lshl_add_u64 v[10:11], v[0:1], 1, s[76:77]
	global_load_dwordx4 v[10:13], v[10:11], off
	v_pk_mul_f32 v[18:19], v[54:55], v[18:19] op_sel_hi:[1,0]
	s_waitcnt vmcnt(0) lgkmcnt(0)
	v_lshlrev_b32_e32 v26, 16, v10
	v_mul_f32_e32 v0, 0xbfb8aa3b, v26
	v_exp_f32_e32 v0, v0
	v_and_b32_e32 v27, 0xffff0000, v10
	v_add_f32_e32 v0, 1.0, v0
	v_rcp_f32_e32 v28, v0
	v_mul_f32_e32 v0, 0xbfb8aa3b, v27
	v_exp_f32_e32 v0, v0
	s_nop 0
	v_add_f32_e32 v0, 1.0, v0
	v_rcp_f32_e32 v29, v0
	s_nop 0
	v_pk_mul_f32 v[26:27], v[28:29], v[26:27]
	s_nop 0
	v_pk_mul_f32 v[24:25], v[24:25], v[26:27]
	s_nop 0
	v_cvt_pk_bf16_f32 v10, v24, v25
	v_lshlrev_b32_e32 v24, 16, v11
	v_mul_f32_e32 v0, 0xbfb8aa3b, v24
	v_exp_f32_e32 v0, v0
	v_and_b32_e32 v25, 0xffff0000, v11
	v_add_f32_e32 v0, 1.0, v0
	v_rcp_f32_e32 v26, v0
	v_mul_f32_e32 v0, 0xbfb8aa3b, v25
	v_exp_f32_e32 v0, v0
	s_nop 0
	v_add_f32_e32 v0, 1.0, v0
	v_rcp_f32_e32 v27, v0
	s_nop 0
	v_pk_mul_f32 v[24:25], v[26:27], v[24:25]
	s_nop 0
	v_pk_mul_f32 v[20:21], v[20:21], v[24:25]
	s_nop 0
	v_cvt_pk_bf16_f32 v11, v20, v21
	v_lshlrev_b32_e32 v20, 16, v12
	v_mul_f32_e32 v0, 0xbfb8aa3b, v20
	v_exp_f32_e32 v0, v0
	v_and_b32_e32 v21, 0xffff0000, v12
	v_add_f32_e32 v0, 1.0, v0
	v_rcp_f32_e32 v24, v0
	v_mul_f32_e32 v0, 0xbfb8aa3b, v21
	v_exp_f32_e32 v0, v0
	s_nop 0
	v_add_f32_e32 v0, 1.0, v0
	v_rcp_f32_e32 v25, v0
	s_nop 0
	v_pk_mul_f32 v[20:21], v[24:25], v[20:21]
	s_nop 0
	v_pk_mul_f32 v[18:19], v[18:19], v[20:21]
	s_nop 0
	v_cvt_pk_bf16_f32 v12, v18, v19
	v_lshlrev_b32_e32 v18, 16, v13
	v_mul_f32_e32 v0, 0xbfb8aa3b, v18
	v_exp_f32_e32 v0, v0
	v_and_b32_e32 v19, 0xffff0000, v13
	v_add_f32_e32 v0, 1.0, v0
	v_rcp_f32_e32 v20, v0
	v_mul_f32_e32 v0, 0xbfb8aa3b, v19
	v_exp_f32_e32 v0, v0
	s_nop 0
	v_add_f32_e32 v0, 1.0, v0
	v_rcp_f32_e32 v21, v0
	ds_bpermute_b32 v0, v186, v76
	v_pk_mul_f32 v[18:19], v[20:21], v[18:19]
	s_nop 0
	v_pk_mul_f32 v[16:17], v[16:17], v[18:19]
	s_waitcnt lgkmcnt(0)
	v_add_f32_e32 v0, v76, v0
	v_cvt_pk_bf16_f32 v13, v16, v17
	global_store_dwordx4 v[14:15], v[10:13], off offset:64
	ds_bpermute_b32 v10, v187, v0
	s_waitcnt lgkmcnt(0)
	v_add_f32_e32 v0, v0, v10
	v_rcp_f32_e32 v16, v0
	v_add_u32_e32 v0, v22, v105
	v_or_b32_e32 v0, s24, v0
	v_lshlrev_b64 v[14:15], 1, v[0:1]
	v_lshl_add_u64 v[10:11], s[76:77], 0, v[14:15]
	global_load_dwordx4 v[10:13], v[10:11], off
	v_pk_mul_f32 v[20:21], v[42:43], v[16:17] op_sel_hi:[1,0]
	v_pk_mul_f32 v[18:19], v[44:45], v[16:17] op_sel_hi:[1,0]
	v_pk_mul_f32 v[24:25], v[46:47], v[16:17] op_sel_hi:[1,0]
	v_pk_mul_f32 v[22:23], v[48:49], v[16:17] op_sel_hi:[1,0]
	v_lshl_add_u64 v[14:15], s[94:95], 0, v[14:15]
	v_or_b32_e32 v0, 32, v0
	v_pk_mul_f32 v[4:5], v[4:5], v[16:17] op_sel_hi:[1,0]
	v_pk_mul_f32 v[2:3], v[2:3], v[16:17] op_sel_hi:[1,0]
	v_pk_mul_f32 v[8:9], v[8:9], v[16:17] op_sel_hi:[1,0]
	v_pk_mul_f32 v[6:7], v[6:7], v[16:17] op_sel_hi:[1,0]
	s_waitcnt vmcnt(0) lgkmcnt(0)
	v_lshlrev_b32_e32 v26, 16, v10
	v_and_b32_e32 v27, 0xffff0000, v10
	v_mul_f32_e32 v10, 0xbfb8aa3b, v26
	v_exp_f32_e32 v10, v10
	s_nop 0
	v_add_f32_e32 v10, 1.0, v10
	v_rcp_f32_e32 v28, v10
	v_mul_f32_e32 v10, 0xbfb8aa3b, v27
	v_exp_f32_e32 v10, v10
	s_nop 0
	v_add_f32_e32 v10, 1.0, v10
	v_rcp_f32_e32 v29, v10
	s_nop 0
	v_pk_mul_f32 v[26:27], v[28:29], v[26:27]
	s_nop 0
	v_pk_mul_f32 v[20:21], v[20:21], v[26:27]
	s_nop 0
	v_cvt_pk_bf16_f32 v10, v20, v21
	v_lshlrev_b32_e32 v20, 16, v11
	v_and_b32_e32 v21, 0xffff0000, v11
	v_mul_f32_e32 v11, 0xbfb8aa3b, v20
	v_exp_f32_e32 v11, v11
	s_nop 0
	v_add_f32_e32 v11, 1.0, v11
	v_rcp_f32_e32 v26, v11
	v_mul_f32_e32 v11, 0xbfb8aa3b, v21
	v_exp_f32_e32 v11, v11
	s_nop 0
	v_add_f32_e32 v11, 1.0, v11
	v_rcp_f32_e32 v27, v11
	s_nop 0
	v_pk_mul_f32 v[20:21], v[26:27], v[20:21]
	s_nop 0
	v_pk_mul_f32 v[18:19], v[18:19], v[20:21]
	s_nop 0
	v_cvt_pk_bf16_f32 v11, v18, v19
	v_lshlrev_b32_e32 v18, 16, v12
	v_and_b32_e32 v19, 0xffff0000, v12
	v_mul_f32_e32 v12, 0xbfb8aa3b, v18
	v_exp_f32_e32 v12, v12
	s_nop 0
	v_add_f32_e32 v12, 1.0, v12
	v_rcp_f32_e32 v20, v12
	v_mul_f32_e32 v12, 0xbfb8aa3b, v19
	v_exp_f32_e32 v12, v12
	s_nop 0
	v_add_f32_e32 v12, 1.0, v12
	v_rcp_f32_e32 v21, v12
	s_nop 0
	v_pk_mul_f32 v[18:19], v[20:21], v[18:19]
	s_nop 0
	v_pk_mul_f32 v[18:19], v[24:25], v[18:19]
	s_nop 0
	v_cvt_pk_bf16_f32 v12, v18, v19
	v_lshlrev_b32_e32 v18, 16, v13
	v_and_b32_e32 v19, 0xffff0000, v13
	v_mul_f32_e32 v13, 0xbfb8aa3b, v18
	v_exp_f32_e32 v13, v13
	s_nop 0
	v_add_f32_e32 v13, 1.0, v13
	v_rcp_f32_e32 v20, v13
	v_mul_f32_e32 v13, 0xbfb8aa3b, v19
	v_exp_f32_e32 v13, v13
	s_nop 0
	v_add_f32_e32 v13, 1.0, v13
	v_rcp_f32_e32 v21, v13
	s_nop 0
	v_pk_mul_f32 v[18:19], v[20:21], v[18:19]
	s_nop 0
	v_pk_mul_f32 v[18:19], v[22:23], v[18:19]
	s_nop 0
	v_cvt_pk_bf16_f32 v13, v18, v19
	global_store_dwordx4 v[14:15], v[10:13], off
	s_nop 1
	v_lshl_add_u64 v[10:11], v[0:1], 1, s[76:77]
	global_load_dwordx4 v[10:13], v[10:11], off
	s_waitcnt vmcnt(0) lgkmcnt(0)
	v_lshlrev_b32_e32 v16, 16, v10
	v_mul_f32_e32 v0, 0xbfb8aa3b, v16
	v_exp_f32_e32 v0, v0
	v_and_b32_e32 v17, 0xffff0000, v10
	v_lshlrev_b32_e32 v10, 16, v11
	v_and_b32_e32 v11, 0xffff0000, v11
	v_add_f32_e32 v0, 1.0, v0
	v_rcp_f32_e32 v18, v0
	v_mul_f32_e32 v0, 0xbfb8aa3b, v17
	v_exp_f32_e32 v0, v0
	s_nop 0
	v_add_f32_e32 v0, 1.0, v0
	v_rcp_f32_e32 v19, v0
	v_mul_f32_e32 v0, 0xbfb8aa3b, v10
	v_exp_f32_e32 v0, v0
	v_pk_mul_f32 v[16:17], v[18:19], v[16:17]
	s_nop 0
	v_pk_mul_f32 v[2:3], v[2:3], v[16:17]
	v_add_f32_e32 v0, 1.0, v0
	v_rcp_f32_e32 v16, v0
	v_mul_f32_e32 v0, 0xbfb8aa3b, v11
	v_exp_f32_e32 v0, v0
	v_cvt_pk_bf16_f32 v2, v2, v3
	v_add_f32_e32 v0, 1.0, v0
	v_rcp_f32_e32 v17, v0
	s_nop 0
	v_pk_mul_f32 v[10:11], v[16:17], v[10:11]
	s_nop 0
	v_pk_mul_f32 v[4:5], v[4:5], v[10:11]
	s_nop 0
	v_cvt_pk_bf16_f32 v3, v4, v5
	v_lshlrev_b32_e32 v4, 16, v12
	v_mul_f32_e32 v0, 0xbfb8aa3b, v4
	v_exp_f32_e32 v0, v0
	v_and_b32_e32 v5, 0xffff0000, v12
	v_add_f32_e32 v0, 1.0, v0
	v_rcp_f32_e32 v10, v0
	v_mul_f32_e32 v0, 0xbfb8aa3b, v5
	v_exp_f32_e32 v0, v0
	s_nop 0
	v_add_f32_e32 v0, 1.0, v0
	v_rcp_f32_e32 v11, v0
	s_nop 0
	v_pk_mul_f32 v[4:5], v[10:11], v[4:5]
	s_nop 0
	v_pk_mul_f32 v[4:5], v[6:7], v[4:5]
	v_lshlrev_b32_e32 v6, 16, v13
	v_mul_f32_e32 v0, 0xbfb8aa3b, v6
	v_exp_f32_e32 v0, v0
	v_and_b32_e32 v7, 0xffff0000, v13
	v_cvt_pk_bf16_f32 v4, v4, v5
	v_add_f32_e32 v0, 1.0, v0
	v_rcp_f32_e32 v10, v0
	v_mul_f32_e32 v0, 0xbfb8aa3b, v7
	v_exp_f32_e32 v0, v0
	s_nop 0
	v_add_f32_e32 v0, 1.0, v0
	v_rcp_f32_e32 v11, v0
	s_nop 0
	v_pk_mul_f32 v[6:7], v[10:11], v[6:7]
	s_nop 0
	v_pk_mul_f32 v[6:7], v[8:9], v[6:7]
	s_nop 0
	v_cvt_pk_bf16_f32 v5, v6, v7
	global_store_dwordx4 v[14:15], v[2:5], off offset:64
	s_cbranch_scc1 .LBB0_220

.LBB0_193:
	s_or_b64 exec, exec, s[0:1]
	s_mul_i32 s0, s4, s21
	s_sub_i32 s1, s23, s0
	s_lshl_b32 s0, s1, 1
	s_max_i32 s6, s0, 4
	s_add_i32 s6, s6, -4
	s_min_u32 s80, s6, 24
	s_max_i32 s6, s0, 3
	s_add_i32 s6, s6, -3
	s_min_u32 s6, s6, 24
	s_ashr_i32 s7, s4, 4
	s_add_i32 s6, s6, 7
	s_cmp_lt_i32 s1, 16
	s_movk_i32 s8, 0xf800
	s_cselect_b32 s81, s80, 0
	s_cselect_b32 s6, s6, -1
	s_cselect_b32 s8, 0x100, s8
	s_lshl_b32 s1, s1, 7
	s_sub_i32 s82, s6, s81
	s_mul_i32 s6, s7, 0x900
	s_add_i32 s25, s8, s1
	s_add_i32 s25, s25, s6
	s_lshl_b32 s24, s5, 6
	v_or_b32_e32 v6, s24, v90
	v_add_u32_e32 v0, s25, v101
	v_lshl_or_b32 v0, v0, 10, v6
	v_lshl_add_u64 v[2:3], v[0:1], 1, s[26:27]
	global_load_dwordx4 v[2:5], v[2:3], off
	v_add_u32_e32 v0, s25, v102
	v_lshl_or_b32 v0, v0, 10, v6
	s_lshl_b32 s1, s81, 6
	s_not_b32 s5, s82
	s_addk_i32 s1, 0x100
	s_lshl_b32 s5, s5, 6
	s_cmp_lt_i32 s82, 0
	s_cselect_b32 s5, s5, s1
	v_add_u32_e32 v122, s6, v91
	v_readfirstlane_b32 s1, v94
	s_mov_b32 m0, s1
	s_lshl_b32 s1, s7, 10
	s_or_b32 s7, s24, s1
	v_add_u32_e32 v123, s6, v98
	s_mov_b32 s83, 0
	s_cmp_gt_i32 s82, -5
	s_waitcnt vmcnt(0) lgkmcnt(0)
	ds_write_b128 v118, v[2:5] offset:32768
	v_lshl_add_u64 v[2:3], v[0:1], 1, s[26:27]
	global_load_dwordx4 v[2:5], v[2:3], off
	v_add_u32_e32 v0, s25, v103
	v_lshl_or_b32 v0, v0, 10, v6
	s_waitcnt vmcnt(0) lgkmcnt(0)
	ds_write_b128 v119, v[2:5] offset:32768
	v_lshl_add_u64 v[2:3], v[0:1], 1, s[26:27]
	global_load_dwordx4 v[2:5], v[2:3], off
	v_add_u32_e32 v0, s25, v104
	v_lshl_or_b32 v0, v0, 10, v6
	s_waitcnt vmcnt(0) lgkmcnt(0)
	ds_write_b128 v120, v[2:5] offset:32768
	v_lshl_add_u64 v[2:3], v[0:1], 1, s[26:27]
	global_load_dwordx4 v[2:5], v[2:3], off
	v_add_lshl_u32 v0, s5, v122, 10
	v_or3_b32 v0, v0, s24, v92
	s_waitcnt vmcnt(0) lgkmcnt(0)
	ds_write_b128 v121, v[2:5] offset:32768
	v_lshl_add_u64 v[2:3], v[0:1], 1, s[28:29]
	v_add_u32_e32 v0, s7, v97
	v_mul_lo_u32 v0, v0, s96
	v_or_b32_e32 v0, v0, v92
	v_add_u32_e32 v0, s5, v0
	global_load_lds_dwordx4 v[2:3], off
	v_lshl_add_u64 v[2:3], v[0:1], 1, s[58:59]
	v_add_u32_e32 v0, 0x2000, v94
	s_nop 0
	v_readfirstlane_b32 s8, v0
	v_add_lshl_u32 v0, s5, v123, 10
	s_mov_b32 m0, s8
	v_or3_b32 v0, v0, s24, v99
	global_load_lds_dwordx4 v[2:3], off
	v_lshl_add_u64 v[2:3], v[0:1], 1, s[28:29]
	v_add_u32_e32 v0, 0x400, v94
	s_nop 0
	v_readfirstlane_b32 s6, v0
	v_add_u32_e32 v0, s7, v100
	v_mul_lo_u32 v0, v0, s96
	v_or_b32_e32 v124, v0, v99
	s_mov_b32 m0, s6
	v_add_u32_e32 v0, s5, v124
	global_load_lds_dwordx4 v[2:3], off
	v_lshl_add_u64 v[2:3], v[0:1], 1, s[58:59]
	v_add_u32_e32 v0, 0x2400, v94
	s_nop 0
	v_readfirstlane_b32 s5, v0
	s_mov_b32 m0, s5
	s_nop 0
	global_load_lds_dwordx4 v[2:3], off
	s_waitcnt vmcnt(0) lgkmcnt(0)
	s_barrier
	s_cbranch_scc0 .LBB0_181
	s_or_b32 s0, s0, 1
	s_max_i32 s0, s0, 4
	s_add_i32 s0, s0, -4
	s_min_u32 s56, s0, 24
	s_mul_i32 s0, s62, s4
	v_or_b32_e32 v0, s1, v95
	s_add_i32 s0, s81, s0
	s_lshl_b32 s1, s23, 1
	s_sub_i32 s0, s0, s1
	s_mul_i32 s1, s21, 0xf8
	v_add3_u32 v0, v96, s24, v0
	s_mul_i32 s1, s1, s4
	s_mul_i32 s4, s81, 0x7c
	v_mul_lo_u32 v0, v0, s96
	s_add_i32 s1, s1, s4
	s_mul_i32 s4, s23, 0xf8
	v_mov_b32_e32 v12, v1
	v_mov_b32_e32 v13, v1
	v_or_b32_e32 v125, v0, v92
	s_mulk_i32 s0, 0x7c
	s_sub_i32 s1, s1, s4
	v_mov_b32_e32 v0, v1
	v_mov_b32_e32 v10, v1
	v_mov_b32_e32 v11, v1
	v_mov_b32_e32 v74, 0xe0ad78ec
	v_mov_b64_e32 v[20:21], v[12:13]
	v_mov_b64_e32 v[28:29], v[12:13]
	v_mov_b64_e32 v[32:33], v[12:13]
	v_mov_b64_e32 v[16:17], v[12:13]
	v_mov_b64_e32 v[24:25], v[12:13]
	v_mov_b64_e32 v[36:37], v[12:13]
	v_mov_b64_e32 v[40:41], v[12:13]
	s_add_i32 s88, s82, 1
	s_add_i32 s89, s80, 8
	s_add_i32 s57, s56, 8
	s_add_i32 s22, s82, 4
	s_add_i32 s96, s82, 5
	v_or_b32_e32 v126, s24, v92
	v_or_b32_e32 v127, s24, v99
	s_add_i32 s97, s0, 0x103e0
	v_add_u32_e32 v128, s1, v115
	s_add_i32 s98, s0, 0x103e4
	s_add_i32 s99, s0, 0x103e8
	s_add_i32 s30, s0, 0x103ec
	s_add_i32 s4, s0, 0x10420
	v_mov_b64_e32 v[18:19], v[10:11]
	v_mov_b64_e32 v[26:27], v[10:11]
	v_mov_b64_e32 v[30:31], v[10:11]
	v_mov_b64_e32 v[14:15], v[10:11]
	v_mov_b64_e32 v[22:23], v[10:11]
	v_mov_b64_e32 v[34:35], v[10:11]
	v_mov_b64_e32 v[38:39], v[10:11]
	s_mov_b32 s8, 0
	v_mov_b64_e32 v[78:79], v[0:1]
	v_mov_b32_e32 v75, v74

.LBB0_221:
	s_and_b64 vcc, exec, s[22:23]
	s_cbranch_vccz .LBB0_232
	s_waitcnt vmcnt(0)
	v_lshlrev_b32_e32 v18, 2, v134
	s_add_u32 s0, s94, 0xfeac000
	v_add_u32_e32 v4, 0x400, v18
	s_addc_u32 s1, s95, 0
	v_ashrrev_i32_e32 v5, 31, v4
	v_lshl_add_u64 v[6:7], v[4:5], 2, s[0:1]
	v_add_u32_e32 v4, 0x800, v18
	v_ashrrev_i32_e32 v5, 31, v4
	v_lshl_add_u64 v[10:11], v[4:5], 2, s[0:1]
	v_add_u32_e32 v4, 0xc00, v18
	v_ashrrev_i32_e32 v19, 31, v18
	v_ashrrev_i32_e32 v5, 31, v4
	v_lshl_add_u64 v[2:3], v[18:19], 2, s[0:1]
	v_lshl_add_u64 v[14:15], v[4:5], 2, s[0:1]
	global_load_dwordx4 v[2:5], v[2:3], off
	s_nop 0
	global_load_dwordx4 v[6:9], v[6:7], off
	s_nop 0
	global_load_dwordx4 v[10:13], v[10:11], off
	s_nop 0
	global_load_dwordx4 v[14:17], v[14:15], off
	v_lshlrev_b32_e32 v0, 4, v134
	s_cmpk_gt_i32 s20, 0x8ff
	s_waitcnt vmcnt(0) lgkmcnt(0)
	ds_write_b128 v0, v[2:5] offset:40960
	ds_write_b128 v0, v[6:9] offset:45056
	ds_write_b128 v0, v[10:13] offset:49152
	ds_write_b128 v0, v[14:17] offset:53248
	s_cbranch_scc1 .LBB0_232
	v_and_b32_e32 v12, 15, v134
	v_ashrrev_i32_e32 v3, 6, v134
	v_lshlrev_b32_e32 v0, 1, v12
	v_lshl_add_u64 v[6:7], s[94:95], 0, v[0:1]
	s_mov_b64 s[0:1], 0xfc00000
	v_lshlrev_b32_e32 v21, 4, v3
	v_and_b32_e32 v0, 31, v134
	v_lshl_add_u64 v[24:25], v[6:7], 0, s[0:1]
	v_lshlrev_b32_e32 v72, 2, v0
	v_lshlrev_b32_e32 v0, 1, v3
	v_and_b32_e32 v6, 7, v134
	v_or_b32_e32 v13, v21, v12
	v_bitop3_b32 v7, v0, v134, 7 bitop3:0x78
	v_bitop3_b32 v0, v0, v6, 1 bitop3:0x36
	v_lshlrev_b32_e32 v6, 6, v13
	v_and_b32_e32 v20, 63, v134
	v_bfe_u32 v5, v134, 4, 2
	v_lshlrev_b32_e32 v76, 4, v7
	v_ashrrev_i32_e32 v7, 31, v6
	v_lshlrev_b32_e32 v22, 2, v20
	s_movk_i32 s0, 0x7c
	v_lshlrev_b32_e32 v77, 4, v0
	v_lshl_add_u64 v[6:7], v[6:7], 1, s[94:95]
	v_lshlrev_b32_e32 v0, 3, v5
	v_mad_u32_u24 v74, v20, s0, v22
	v_lshl_add_u64 v[6:7], v[6:7], 0, v[0:1]
	s_mov_b64 s[0:1], 0xd800000
	v_lshl_add_u64 v[26:27], v[6:7], 0, s[0:1]
	v_cmp_lt_i32_e64 s[0:1], 1, v3
	v_ashrrev_i32_e32 v28, 4, v134
	v_xor_b32_e32 v0, v28, v134
	v_writelane_b32 v254, s0, 60
	v_lshlrev_b32_e32 v0, 4, v0
	v_and_b32_e32 v81, 0xf0, v0
	v_writelane_b32 v254, s1, 61
	v_cmp_gt_i32_e64 s[0:1], 1, v3
	v_add_u32_e32 v0, 0x100, v134
	v_ashrrev_i32_e32 v30, 4, v0
	v_writelane_b32 v254, s0, 62
	v_xor_b32_e32 v6, v30, v134
	v_add_u32_e32 v9, 0x200, v134
	v_writelane_b32 v254, s1, 63
	v_cmp_lt_i32_e64 s[0:1], 2, v3
	v_lshlrev_b32_e32 v6, 4, v6
	v_ashrrev_i32_e32 v32, 4, v9
	v_writelane_b32 v255, s0, 0
	v_and_b32_e32 v84, 0xf0, v6
	v_xor_b32_e32 v6, v32, v134
	v_writelane_b32 v255, s1, 1
	v_cmp_gt_i32_e64 s[0:1], 2, v3
	v_add_u32_e32 v10, 0x300, v134
	v_lshlrev_b32_e32 v6, 4, v6
	v_writelane_b32 v255, s0, 2
	v_ashrrev_i32_e32 v34, 4, v10
	v_and_b32_e32 v87, 0xf0, v6
	v_writelane_b32 v255, s1, 3
	v_cmp_lt_i32_e64 s[0:1], 3, v3
	v_xor_b32_e32 v6, v34, v134
	v_lshlrev_b32_e32 v8, 1, v134
	v_writelane_b32 v255, s0, 4
	v_lshlrev_b32_e32 v6, 4, v6
	v_lshlrev_b32_e32 v73, 12, v3
	v_writelane_b32 v255, s1, 5
	v_cmp_gt_i32_e64 s[0:1], 3, v3
	v_and_b32_e32 v90, 0xf0, v6
	v_and_b32_e32 v92, 0x7e, v8
	v_writelane_b32 v255, s0, 6
	v_mov_b32_e32 v6, 0x7e
	s_movk_i32 s4, 0x60
	v_writelane_b32 v255, s1, 7
	s_movk_i32 s1, 0x50
	s_movk_i32 s0, 0x70
	v_bitop3_b32 v16, v8, 16, v6 bitop3:0x6c
	v_bitop3_b32 v17, v8, 32, v6 bitop3:0x6c
	v_bitop3_b32 v38, v8, 48, v6 bitop3:0x6c
	v_bitop3_b32 v39, v8, 64, v6 bitop3:0x6c
	v_bitop3_b32 v40, v8, s1, v6 bitop3:0x6c
	v_bitop3_b32 v41, v8, s4, v6 bitop3:0x6c
	v_bitop3_b32 v42, v8, s0, v6 bitop3:0x6c
	v_bitop3_b32 v6, v92, v73, 32 bitop3:0xde
	v_or_b32_e32 v109, 0x200, v6
	v_or_b32_e32 v133, 0xa00, v6
	v_ashrrev_i32_e32 v6, 3, v0
	v_lshlrev_b32_e32 v45, 7, v6
	v_xor_b32_e32 v6, v6, v134
	v_or_b32_e32 v94, 1, v21
	v_or_b32_e32 v117, 9, v21
	v_lshlrev_b32_e32 v6, 4, v6
	v_lshlrev_b32_e32 v19, 10, v3
	v_lshlrev_b32_e32 v14, 9, v3
	v_cmp_lt_i32_e64 s[8:9], 0, v3
	v_cmp_gt_i32_e64 s[18:19], 0, v3
	v_lshlrev_b32_e32 v3, 8, v94
	v_or_b32_e32 v96, 2, v21
	v_lshlrev_b32_e32 v37, 8, v117
	v_or_b32_e32 v119, 10, v21
	v_and_b32_e32 v46, 0x70, v6
	v_lshlrev_b32_e32 v6, 3, v0
	v_ashrrev_i32_e32 v0, 3, v9
	v_bitop3_b32 v95, v92, v3, 16 bitop3:0xde
	v_lshlrev_b32_e32 v3, 8, v96
	v_or_b32_e32 v98, 3, v21
	v_bitop3_b32 v118, v92, v37, 16 bitop3:0xde
	v_lshlrev_b32_e32 v37, 8, v119
	v_or_b32_e32 v121, 11, v21
	v_lshlrev_b32_e32 v47, 7, v0
	v_xor_b32_e32 v0, v0, v134
	v_bitop3_b32 v97, v92, v3, 32 bitop3:0xde
	v_lshlrev_b32_e32 v3, 8, v98
	v_or_b32_e32 v100, 4, v21
	v_bitop3_b32 v120, v92, v37, 32 bitop3:0xde
	v_lshlrev_b32_e32 v37, 8, v121
	v_or_b32_e32 v123, 12, v21
	v_lshlrev_b32_e32 v0, 4, v0
	v_bitop3_b32 v99, v92, v3, 48 bitop3:0xde
	v_lshlrev_b32_e32 v3, 8, v100
	v_or_b32_e32 v102, 5, v21
	v_bitop3_b32 v122, v92, v37, 48 bitop3:0xde
	v_lshlrev_b32_e32 v37, 8, v123
	v_or_b32_e32 v125, 13, v21
	v_and_b32_e32 v48, 0x70, v0
	v_ashrrev_i32_e32 v0, 3, v10
	v_bitop3_b32 v101, v92, v3, 64 bitop3:0xde
	v_lshlrev_b32_e32 v3, 8, v102
	v_or_b32_e32 v104, 6, v21
	v_bitop3_b32 v124, v92, v37, 64 bitop3:0xde
	v_lshlrev_b32_e32 v37, 8, v125
	v_or_b32_e32 v127, 14, v21
	v_lshlrev_b32_e32 v49, 7, v0
	v_xor_b32_e32 v0, v0, v134
	v_bitop3_b32 v103, v92, v3, s1 bitop3:0xde
	v_lshlrev_b32_e32 v3, 8, v104
	v_or_b32_e32 v106, 7, v21
	v_bitop3_b32 v126, v92, v37, s1 bitop3:0xde
	v_lshlrev_b32_e32 v37, 8, v127
	v_or_b32_e32 v129, 15, v21
	v_lshlrev_b32_e32 v0, 4, v0
	v_lshlrev_b32_e32 v15, 2, v5
	v_bitop3_b32 v105, v92, v3, s4 bitop3:0xde
	v_lshlrev_b32_e32 v3, 8, v106
	v_bitop3_b32 v128, v92, v37, s4 bitop3:0xde
	v_lshlrev_b32_e32 v37, 8, v129
	v_and_b32_e32 v50, 0x70, v0
	v_bitop3_b32 v0, v5, v134, 15 bitop3:0x78
	v_bitop3_b32 v107, v92, v3, s0 bitop3:0xde
	v_bitop3_b32 v11, v92, v73, s1 bitop3:0xde
	v_bitop3_b32 v36, v92, v73, s0 bitop3:0xde
	v_bitop3_b32 v130, v92, v37, s0 bitop3:0xde
	v_lshlrev_b32_e32 v140, 4, v0
	v_bitop3_b32 v0, v5, v12, 4 bitop3:0x36
	v_cmp_gt_i32_e64 s[0:1], v15, v13
	v_lshlrev_b32_e32 v141, 4, v0
	v_bitop3_b32 v0, v5, v12, 8 bitop3:0x36
	v_writelane_b32 v255, s0, 8
	v_lshlrev_b32_e32 v142, 4, v0
	v_bitop3_b32 v0, v5, v12, 12 bitop3:0x36
	v_writelane_b32 v255, s1, 9
	v_cmp_ge_i32_e64 s[0:1], v15, v13
	v_lshlrev_b32_e32 v143, 4, v0
	v_or_b32_e32 v0, 2, v15
	v_writelane_b32 v255, s0, 10
	s_add_u32 s46, s94, 0x2400000
	s_addc_u32 s47, s95, 0
	v_writelane_b32 v255, s1, 11
	v_cmp_gt_i32_e64 s[0:1], v0, v13
	v_or_b32_e32 v0, 3, v15
	s_add_u32 s48, s94, 0x4800000
	v_writelane_b32 v255, s0, 12
	s_addc_u32 s49, s95, 0
	s_add_u32 s50, s94, 0xb400000
	v_writelane_b32 v255, s1, 13
	v_cmp_gt_i32_e64 s[0:1], v0, v13
	v_or_b32_e32 v0, 16, v15
	v_cmp_gt_i32_e64 s[54:55], v0, v13
	v_or_b32_e32 v0, 17, v15
	v_cmp_gt_i32_e64 s[56:57], v0, v13
	v_or_b32_e32 v0, 18, v15
	v_cmp_gt_i32_e64 s[22:23], v0, v13
	v_or_b32_e32 v0, 19, v15
	v_cmp_gt_i32_e64 s[24:25], v0, v13
	v_or_b32_e32 v0, 32, v15
	v_cmp_gt_i32_e64 s[26:27], v0, v13
	v_or_b32_e32 v0, 33, v15
	v_cmp_gt_i32_e64 s[28:29], v0, v13
	v_or_b32_e32 v0, 34, v15
	v_cmp_gt_i32_e64 s[76:77], v0, v13
	v_or_b32_e32 v0, 35, v15
	s_addc_u32 s51, s95, 0
	v_bitop3_b32 v3, v92, v73, 16 bitop3:0xde
	v_writelane_b32 v255, s0, 14
	v_cmp_gt_i32_e64 s[42:43], v0, v13
	v_or_b32_e32 v0, 48, v15
	s_ashr_i32 s21, s20, 31
	v_or_b32_e32 v108, 0x100, v3
	v_or_b32_e32 v132, 0x900, v3
	v_ashrrev_i32_e32 v3, 3, v134
	v_writelane_b32 v255, s1, 15
	v_cmp_gt_i32_e64 s[80:81], v0, v13
	v_or_b32_e32 v0, 49, v15
	s_ashr_i32 s35, s34, 31
	s_lshl_b64 s[0:1], s[20:21], 9
	v_bitop3_b32 v8, v92, v73, 64 bitop3:0xde
	v_bitop3_b32 v23, v92, v73, s4 bitop3:0xde
	v_lshlrev_b32_e32 v43, 7, v3
	v_xor_b32_e32 v3, v3, v134
	v_cmp_gt_i32_e64 s[82:83], v0, v13
	v_or_b32_e32 v0, 50, v15
	s_add_u32 s0, s94, s0
	v_lshlrev_b32_e32 v2, 3, v134
	v_bitop3_b32 v7, v92, v73, 48 bitop3:0xde
	v_or_b32_e32 v111, 0x400, v8
	v_or_b32_e32 v113, 0x600, v23
	v_or_b32_e32 v136, 0xc00, v8
	v_or_b32_e32 v138, 0xe00, v23
	v_lshlrev_b32_e32 v3, 4, v3
	v_lshlrev_b32_e32 v8, 3, v9
	v_lshlrev_b32_e32 v10, 3, v10
	v_cmp_gt_i32_e64 s[40:41], v0, v13
	v_or_b32_e32 v0, 51, v15
	v_mov_b32_e32 v23, v1
	s_addc_u32 s1, s95, s1
	v_and_b32_e32 v4, 0x78, v2
	v_lshlrev_b32_e32 v78, 8, v12
	v_lshlrev_b32_e32 v80, 8, v28
	v_lshlrev_b32_e32 v83, 8, v30
	v_lshlrev_b32_e32 v86, 8, v32
	v_lshlrev_b32_e32 v89, 8, v34
	v_or_b32_e32 v93, v92, v73
	v_or_b32_e32 v110, 0x300, v7
	v_or_b32_e32 v112, 0x500, v11
	v_or_b32_e32 v115, 8, v21
	v_or_b32_e32 v135, 0xb00, v7
	v_or_b32_e32 v137, 0xd00, v11
	v_and_b32_e32 v44, 0x70, v3
	v_ashrrev_i32_e32 v3, 31, v2
	v_ashrrev_i32_e32 v7, 31, v6
	v_ashrrev_i32_e32 v9, 31, v8
	v_ashrrev_i32_e32 v11, 31, v10
	v_cmp_gt_i32_e32 vcc, v0, v13
	v_lshl_add_u64 v[12:13], s[0:1], 0, v[22:23]
	s_mov_b64 s[0:1], 0xfd20000
	v_cmp_gt_u32_e64 s[6:7], 64, v134
	v_cmp_gt_u32_e64 s[38:39], 32, v20
	v_add_u32_e32 v75, 0xe000, v74
	v_or_b32_e32 v79, v73, v78
	v_ashrrev_i32_e32 v29, 31, v28
	v_or_b32_e32 v82, v81, v80
	v_ashrrev_i32_e32 v31, 31, v30
	v_or_b32_e32 v85, v84, v83
	v_ashrrev_i32_e32 v33, 31, v32
	v_or_b32_e32 v88, v87, v86
	v_ashrrev_i32_e32 v35, 31, v34
	v_or_b32_e32 v91, v90, v89
	v_or_b32_e32 v114, 0x700, v36
	v_lshl_or_b32 v116, v115, 8, v92
	v_or_b32_e32 v131, 0x800, v93
	v_or_b32_e32 v139, 0xf00, v36
	v_lshl_add_u64 v[36:37], v[12:13], 0, s[0:1]
	s_lshl_b64 s[52:53], s[34:35], 9
	s_lshl_b32 s44, s20, 6
	s_lshl_b32 s45, s34, 6
	v_lshlrev_b32_e32 v0, 1, v4
	v_add_u32_e32 v23, v22, v14
	v_add_u32_e32 v144, v73, v16
	v_add_u32_e32 v145, v73, v17
	v_add_u32_e32 v146, v73, v38
	v_add_u32_e32 v147, v73, v39
	v_add_u32_e32 v148, v73, v40
	v_add_u32_e32 v149, v73, v41
	v_add_u32_e32 v150, v73, v42
	v_add_u32_e32 v151, v43, v44
	v_lshlrev_b64 v[38:39], 1, v[2:3]
	v_add_u32_e32 v152, v45, v46
	v_lshlrev_b64 v[40:41], 1, v[6:7]
	v_add_u32_e32 v153, v47, v48
	v_lshlrev_b64 v[42:43], 1, v[8:9]
	v_add_u32_e32 v154, v49, v50
	v_lshlrev_b64 v[44:45], 1, v[10:11]
	s_mov_b64 s[58:59], s[20:21]
	s_branch .LBB0_225
.LBB0_224:
	s_or_b64 exec, exec, s[0:1]
	s_cmp_eq_u32 s90, 0
	v_mul_f32_e32 v192, 0x3d800000, v159
	v_mul_f32_e32 v195, 0x3d800000, v160
	v_mul_f32_e32 v160, 0x3d800000, v9
	v_mul_f32_e32 v159, 0x3d800000, v14
	v_cndmask_b32_e64 v9, 0, 1, s[8:9]
	v_cndmask_b32_e64 v14, 0, 1, s[18:19]
	s_cselect_b64 s[88:89], -1, 0
	v_cndmask_b32_e64 v9, v14, v9, s[88:89]
	v_and_b32_e32 v9, 1, v9
	v_cmp_eq_u32_e64 s[0:1], 1, v9
	v_mul_f32_e32 v12, 0x3d800000, v203
	v_mul_f32_e32 v203, 0x3d800000, v207
	v_cndmask_b32_e64 v9, 0, v13, s[0:1]
	v_cndmask_b32_e64 v10, 0, v10, s[0:1]
	v_readlane_b32 s0, v254, 60
	v_readlane_b32 s1, v254, 61
	v_add_f32_e32 v6, v10, v6
	v_add_f32_e32 v7, v9, v7
	v_cndmask_b32_e64 v13, 0, 1, s[0:1]
	v_readlane_b32 s0, v254, 62
	v_readlane_b32 s1, v254, 63
	v_add_u32_e32 v207, v73, v92
	s_cmp_gt_i32 s21, 3
	v_cndmask_b32_e64 v14, 0, 1, s[0:1]
	v_cndmask_b32_e64 v13, v14, v13, s[88:89]
	v_and_b32_e32 v13, 1, v13
	v_cmp_eq_u32_e64 s[0:1], 1, v13
	v_mul_f32_e32 v56, 0x3d800000, v171
	v_mul_f32_e32 v55, 0x3d800000, v174
	v_cndmask_b32_e64 v7, v9, v7, s[0:1]
	v_cndmask_b32_e64 v6, v10, v6, s[0:1]
	v_readlane_b32 s0, v255, 0
	v_readlane_b32 s1, v255, 1
	v_add_f32_e32 v4, v6, v4
	v_add_f32_e32 v5, v7, v5
	v_cndmask_b32_e64 v9, 0, 1, s[0:1]
	v_readlane_b32 s0, v255, 2
	v_readlane_b32 s1, v255, 3
	s_cselect_b64 s[90:91], -1, 0
	v_mul_f32_e32 v65, 0x3d800000, v202
	v_cndmask_b32_e64 v10, 0, 1, s[0:1]
	v_cndmask_b32_e64 v9, v10, v9, s[88:89]
	v_and_b32_e32 v9, 1, v9
	v_cmp_eq_u32_e64 s[0:1], 1, v9
	v_mul_f32_e32 v202, 0x3d800000, v210
	v_mul_f32_e32 v48, 0x3d800000, v183
	v_cndmask_b32_e64 v5, v7, v5, s[0:1]
	v_cndmask_b32_e64 v4, v6, v4, s[0:1]
	v_readlane_b32 s0, v255, 4
	v_readlane_b32 s1, v255, 5
	v_add_f32_e32 v2, v4, v2
	v_add_f32_e32 v3, v5, v3
	v_cndmask_b32_e64 v6, 0, 1, s[0:1]
	v_readlane_b32 s0, v255, 6
	v_readlane_b32 s1, v255, 7
	v_mul_f32_e32 v17, 0x3d800000, v199
	v_mul_f32_e32 v199, 0x3d800000, v211
	v_cndmask_b32_e64 v7, 0, 1, s[0:1]
	v_cndmask_b32_e64 v6, v7, v6, s[88:89]
	v_and_b32_e32 v6, 1, v6
	v_cmp_eq_u32_e64 s[0:1], 1, v6
	ds_read_u16 v7, v207 offset:128
	v_mul_f32_e32 v183, 0x3d800000, v214
	v_cndmask_b32_e64 v171, v5, v3, s[0:1]
	v_cndmask_b32_e64 v174, v4, v2, s[0:1]
	s_max_i32 s0, s21, 4
	s_add_i32 s0, s0, -4
	v_mov_b32_e32 v210, s0
	v_cndmask_b32_e64 v4, v21, v210, s[38:39]
	v_lshl_or_b32 v4, v4, 7, v72
	ds_read_u16 v3, v207 offset:16512
	ds_read_u16 v5, v107 offset:16512
	s_waitcnt lgkmcnt(0)
	v_lshlrev_b32_e32 v2, 16, v7
	ds_read2st64_b32 v[6:7], v4 offset0:160 offset1:192
	ds_read_u16 v4, v95 offset:16512
	ds_read_u16 v211, v97
	ds_read_u16 v9, v95 offset:128
	ds_read_u16 v10, v97 offset:128
	ds_read_u16 v214, v95 offset:16384
	s_waitcnt lgkmcnt(0)
	v_lshlrev_b32_e32 v193, 16, v4
	v_cndmask_b32_e64 v4, v94, v210, s[38:39]
	v_lshl_or_b32 v4, v4, 7, v72
	v_mul_f32_e32 v68, 0x3d800000, v70
	v_mul_f32_e32 v67, 0x3d800000, v177
	v_mul_f32_e32 v66, 0x3d800000, v180
	v_mul_f32_e32 v180, 0x3d800000, v217
	v_mul_f32_e32 v70, 0x3d800000, v218
	v_mul_f32_e32 v69, 0x3d800000, v223
	v_mul_f32_e32 v177, 0x3d800000, v224
	v_mul_f32_e32 v64, 0x3d800000, v225
	ds_read_u16 v217, v95
	v_lshlrev_b32_e32 v194, 16, v9
	ds_read2st64_b32 v[224:225], v4 offset0:160 offset1:192
	ds_read_u16 v218, v97 offset:16384
	ds_read_u16 v4, v97 offset:16512
	ds_read_u16 v223, v99
	ds_read_u16 v244, v99 offset:16384
	ds_read_u16 v9, v99 offset:16512
	ds_read_u16 v245, v101
	ds_read_u16 v13, v101 offset:128
	ds_read_u16 v14, v99 offset:128
	v_mul_f32_e32 v62, 0x3d800000, v165
	v_mul_f32_e32 v165, 0x3d800000, v227
	s_waitcnt lgkmcnt(0)
	v_lshlrev_b32_e32 v227, 16, v4
	v_cndmask_b32_e64 v4, v96, v210, s[38:39]
	v_lshl_or_b32 v4, v4, 7, v72
	ds_read2st64_b32 v[230:231], v4 offset0:160 offset1:192
	v_cndmask_b32_e64 v4, v98, v210, s[38:39]
	v_lshl_or_b32 v4, v4, 7, v72
	v_mul_f32_e32 v243, 0x3d800000, v164
	v_mul_f32_e32 v164, 0x3d800000, v228
	v_lshlrev_b32_e32 v228, 16, v10
	v_lshlrev_b32_e32 v63, 16, v9
	v_lshlrev_b32_e32 v60, 16, v14
	ds_read2st64_b32 v[232:233], v4 offset0:160 offset1:192
	ds_read_u16 v246, v101 offset:16384
	ds_read_u16 v4, v101 offset:16512
	ds_read_u16 v247, v103
	ds_read_u16 v248, v103 offset:16384
	ds_read_u16 v9, v103 offset:16512
	ds_read_u16 v249, v105
	ds_read_u16 v10, v105 offset:128
	ds_read_u16 v14, v103 offset:128
	s_waitcnt lgkmcnt(0)
	v_lshlrev_b32_e32 v57, 16, v4
	v_lshlrev_b32_e32 v54, 16, v13
	v_cndmask_b32_e64 v4, v100, v210, s[38:39]
	v_cndmask_b32_e64 v13, v102, v210, s[38:39]
	v_lshl_or_b32 v4, v4, 7, v72
	v_lshl_or_b32 v13, v13, 7, v72
	ds_read2st64_b32 v[58:59], v4 offset0:160 offset1:192
	v_lshlrev_b32_e32 v4, 16, v14
	ds_read2st64_b32 v[52:53], v13 offset0:160 offset1:192
	ds_read_u16 v13, v105 offset:16512
	ds_read_u16 v250, v105 offset:16384
	ds_read_u16 v251, v107 offset:16384
	ds_read_u16 v197, v107
	ds_read_u16 v14, v107 offset:128
	s_waitcnt lgkmcnt(0)
	v_lshlrev_b32_e32 v49, 16, v13
	v_lshlrev_b32_e32 v16, 16, v10
	v_cndmask_b32_e64 v10, v104, v210, s[38:39]
	v_lshlrev_b32_e32 v13, 16, v5
	v_cndmask_b32_e64 v5, v106, v210, s[38:39]
	v_lshl_or_b32 v10, v10, 7, v72
	v_lshl_or_b32 v5, v5, 7, v72
	v_mul_f32_e32 v61, 0x3d800000, v166
	v_mul_f32_e32 v166, 0x3d800000, v226
	ds_read2st64_b32 v[50:51], v10 offset0:160 offset1:192
	v_lshlrev_b32_e32 v10, 16, v14
	ds_read2st64_b32 v[14:15], v5 offset0:160 offset1:192
	ds_read_u16 v5, v93 offset:16384
	ds_read_u16 v226, v93
	v_mul_f32_e32 v242, 0x3d800000, v163
	v_mul_f32_e32 v163, 0x3d800000, v229
	v_cndmask_b32_e64 v229, v220, v11, s[88:89]
	v_add_f32_e32 v229, v174, v229
	v_cndmask_b32_e64 v234, v219, v8, s[88:89]
	v_mul_f32_e32 v71, 0x3d800000, v71
	v_add_f32_e32 v191, v171, v234
	v_sub_f32_e32 v68, v229, v68
	v_cndmask_b32_e64 v252, v68, v229, s[88:89]
	v_sub_f32_e32 v68, v191, v71
	v_lshlrev_b32_e32 v235, 16, v3
	s_waitcnt lgkmcnt(0)
	v_lshlrev_b32_e32 v234, 16, v226
	v_lshlrev_b32_e32 v3, 16, v5
	v_cndmask_b32_e64 v71, v68, v191, s[88:89]
	v_mov_b32_e32 v238, v7
	v_mov_b32_e32 v239, v6
	v_mov_b32_e32 v68, v7
	v_pk_mov_b32 v[240:241], v[234:235], v[2:3] op_sel:[1,0]
	v_pk_mov_b32 v[236:237], v[2:3], v[234:235] op_sel:[1,0]
	v_pk_mul_f32 v[238:239], v[238:239], v[234:235]
	v_pk_mul_f32 v[240:241], v[68:69], v[240:241] op_sel_hi:[0,1]
	v_pk_fma_f32 v[238:239], v[6:7], v[2:3], v[238:239]
	v_pk_fma_f32 v[6:7], v[6:7], v[236:237], v[240:241] op_sel_hi:[0,1,1] neg_lo:[0,0,1] neg_hi:[0,0,1]
	v_cndmask_b32_e64 v5, v237, v7, s[90:91]
	v_mul_f32_e32 v7, 0xbfb8aa3b, v229
	v_mul_f32_e32 v68, 0xbfb8aa3b, v191
	v_exp_f32_e32 v7, v7
	v_exp_f32_e32 v68, v68
	v_cndmask_b32_e64 v3, v235, v239, s[90:91]
	v_cndmask_b32_e64 v6, v236, v6, s[90:91]
	v_mul_f32_e32 v6, v7, v6
	v_mul_f32_e32 v7, 0x3fb8aa3b, v252
	v_mul_f32_e32 v3, v68, v3
	v_mul_f32_e32 v68, 0x3fb8aa3b, v71
	v_exp_f32_e32 v7, v7
	v_exp_f32_e32 v68, v68
	v_cndmask_b32_e64 v2, v2, v238, s[90:91]
	v_mul_f32_e32 v5, v7, v5
	v_mul_f32_e32 v2, v68, v2
	v_cvt_pk_bf16_f32 v5, v5, s0
	v_cvt_pk_bf16_f32 v2, v2, s0
	ds_write_b16 v93, v5
	ds_write_b16 v207, v2 offset:128
	v_cvt_pk_bf16_f32 v2, v6, s0
	ds_write_b16 v93, v2 offset:16384
	v_cvt_pk_bf16_f32 v2, v3, s0
	ds_write_b16 v207, v2 offset:16512
	v_sub_f32_e32 v2, v220, v11
	v_cndmask_b32_e64 v2, v2, v156, s[88:89]
	v_add_f32_e32 v11, v174, v2
	v_sub_f32_e32 v2, v219, v8
	v_lshlrev_b32_e32 v9, 16, v9
	v_cndmask_b32_e64 v2, v2, v155, s[88:89]
	v_mov_b32_e32 v8, v225
	v_mov_b32_e32 v234, v193
	v_mov_b32_e32 v235, v194
	v_add_f32_e32 v71, v171, v2
	v_sub_f32_e32 v2, v11, v192
	v_pk_mul_f32 v[234:235], v[8:9], v[234:235] op_sel_hi:[0,1]
	v_mul_f32_e32 v8, 0xbfb8aa3b, v11
	v_cndmask_b32_e64 v191, v2, v11, s[88:89]
	v_sub_f32_e32 v2, v71, v195
	v_lshlrev_b32_e32 v192, 16, v217
	v_lshlrev_b32_e32 v195, 16, v214
	v_exp_f32_e32 v8, v8
	v_mul_f32_e32 v68, v222, v3
	v_cndmask_b32_e64 v226, v2, v71, s[88:89]
	v_pk_mov_b32 v[2:3], v[194:195], v[192:193] op_sel:[1,0]
	v_mul_f32_e32 v11, 0xbfb8aa3b, v71
	v_mul_f32_e32 v5, v221, v6
	v_mov_b32_e32 v6, v225
	v_mov_b32_e32 v7, v224
	v_pk_fma_f32 v[2:3], v[224:225], v[2:3], v[234:235] op_sel_hi:[0,1,1] neg_lo:[0,0,1] neg_hi:[0,0,1]
	v_exp_f32_e32 v11, v11
	v_pk_mul_f32 v[6:7], v[6:7], v[192:193]
	v_cndmask_b32_e64 v2, v195, v2, s[90:91]
	v_pk_fma_f32 v[6:7], v[224:225], v[194:195], v[6:7]
	v_mul_f32_e32 v2, v8, v2
	v_mul_f32_e32 v8, 0x3fb8aa3b, v191
	v_cndmask_b32_e64 v7, v193, v7, s[90:91]
	v_exp_f32_e32 v8, v8
	v_mul_f32_e32 v7, v11, v7
	v_mul_f32_e32 v11, 0x3fb8aa3b, v226
	v_exp_f32_e32 v11, v11
	v_cndmask_b32_e64 v3, v192, v3, s[90:91]
	v_mul_f32_e32 v3, v8, v3
	v_cndmask_b32_e64 v6, v194, v6, s[90:91]
	v_cvt_pk_bf16_f32 v3, v3, s0
	ds_write_b16 v144, v3 offset:256
	v_mul_f32_e32 v3, v11, v6
	v_cvt_pk_bf16_f32 v3, v3, s0
	ds_write_b16 v108, v3 offset:128
	v_cvt_pk_bf16_f32 v3, v2, s0
	ds_write_b16 v144, v3 offset:16640
	v_cvt_pk_bf16_f32 v3, v7, s0
	ds_write_b16 v108, v3 offset:16512
	v_mul_f32_e32 v3, v222, v7
	v_mul_f32_e32 v2, v221, v2
	v_cvt_pk_bf16_f32 v6, v5, v2
	v_cvt_pk_bf16_f32 v2, v68, v3
	v_sub_f32_e32 v3, v220, v156
	v_cndmask_b32_e64 v3, v3, v158, s[88:89]
	v_add_f32_e32 v3, v174, v3
	v_sub_f32_e32 v5, v219, v155
	v_cndmask_b32_e64 v5, v5, v157, s[88:89]
	v_sub_f32_e32 v7, v3, v242
	v_add_f32_e32 v5, v171, v5
	v_cndmask_b32_e64 v7, v7, v3, s[88:89]
	v_sub_f32_e32 v8, v5, v243
	v_mul_f32_e32 v7, 0x3fb8aa3b, v7
	v_cndmask_b32_e64 v11, v8, v5, s[88:89]
	v_lshlrev_b32_e32 v226, 16, v211
	v_lshlrev_b32_e32 v229, 16, v218
	v_mov_b32_e32 v8, v231
	v_mov_b32_e32 v224, v227
	v_mov_b32_e32 v225, v228
	v_exp_f32_e32 v7, v7
	v_pk_mov_b32 v[192:193], v[228:229], v[226:227] op_sel:[1,0]
	v_pk_mul_f32 v[224:225], v[8:9], v[224:225] op_sel_hi:[0,1]
	v_mul_f32_e32 v11, 0x3fb8aa3b, v11
	v_mov_b32_e32 v194, v231
	v_mov_b32_e32 v195, v230
	v_pk_fma_f32 v[192:193], v[230:231], v[192:193], v[224:225] op_sel_hi:[0,1,1] neg_lo:[0,0,1] neg_hi:[0,0,1]
	v_mul_f32_e32 v3, 0xbfb8aa3b, v3
	v_exp_f32_e32 v11, v11
	v_pk_mul_f32 v[194:195], v[194:195], v[226:227]
	v_cndmask_b32_e64 v71, v226, v193, s[90:91]
	v_exp_f32_e32 v3, v3
	v_mul_f32_e32 v5, 0xbfb8aa3b, v5
	v_pk_fma_f32 v[194:195], v[230:231], v[228:229], v[194:195]
	v_exp_f32_e32 v5, v5
	v_mul_f32_e32 v7, v7, v71
	v_cndmask_b32_e64 v8, v228, v194, s[90:91]
	v_cvt_pk_bf16_f32 v7, v7, s0
	v_cndmask_b32_e64 v155, v229, v192, s[90:91]
	ds_write_b16 v145, v7 offset:512
	v_mul_f32_e32 v7, v11, v8
	v_cndmask_b32_e64 v68, v227, v195, s[90:91]
	v_mul_f32_e32 v3, v3, v155
	v_cvt_pk_bf16_f32 v7, v7, s0
	v_mul_f32_e32 v5, v5, v68
	ds_write_b16 v109, v7 offset:128
	v_cvt_pk_bf16_f32 v7, v3, s0
	ds_write_b16 v145, v7 offset:16896
	v_cvt_pk_bf16_f32 v7, v5, s0
	ds_write_b16 v109, v7 offset:16512
	v_sub_f32_e32 v7, v220, v158
	v_cndmask_b32_e64 v7, v7, v162, s[88:89]
	v_sub_f32_e32 v8, v219, v157
	v_add_f32_e32 v7, v174, v7
	v_cndmask_b32_e64 v8, v8, v161, s[88:89]
	v_add_f32_e32 v11, v171, v8
	v_sub_f32_e32 v8, v7, v62
	v_cndmask_b32_e64 v68, v8, v7, s[88:89]
	v_sub_f32_e32 v8, v11, v61
	v_cndmask_b32_e64 v71, v8, v11, s[88:89]
	v_mul_f32_e32 v7, 0xbfb8aa3b, v7
	v_mul_f32_e32 v11, 0xbfb8aa3b, v11
	v_lshlrev_b32_e32 v62, 16, v223
	v_lshlrev_b32_e32 v61, 16, v244
	v_mov_b32_e32 v192, v233
	v_mov_b32_e32 v193, v232
	v_mov_b32_e32 v8, v233
	v_mov_b32_e32 v194, v63
	v_mov_b32_e32 v195, v60
	v_exp_f32_e32 v7, v7
	v_exp_f32_e32 v11, v11
	v_pk_mov_b32 v[156:157], v[60:61], v[62:63] op_sel:[1,0]
	v_pk_mul_f32 v[192:193], v[192:193], v[62:63]
	v_pk_mul_f32 v[194:195], v[8:9], v[194:195] op_sel_hi:[0,1]
	v_pk_fma_f32 v[192:193], v[232:233], v[60:61], v[192:193]
	v_pk_fma_f32 v[156:157], v[232:233], v[156:157], v[194:195] op_sel_hi:[0,1,1] neg_lo:[0,0,1] neg_hi:[0,0,1]
	v_cndmask_b32_e64 v8, v60, v192, s[90:91]
	v_cndmask_b32_e64 v60, v63, v193, s[90:91]
	v_cndmask_b32_e64 v61, v61, v156, s[90:91]
	v_mul_f32_e32 v7, v7, v61
	v_mul_f32_e32 v61, 0x3fb8aa3b, v68
	v_mul_f32_e32 v11, v11, v60
	v_mul_f32_e32 v60, 0x3fb8aa3b, v71
	v_exp_f32_e32 v61, v61
	v_exp_f32_e32 v60, v60
	v_cndmask_b32_e64 v62, v62, v157, s[90:91]
	v_mul_f32_e32 v3, v221, v3
	v_mul_f32_e32 v61, v61, v62
	v_mul_f32_e32 v8, v60, v8
	v_cvt_pk_bf16_f32 v61, v61, s0
	v_cvt_pk_bf16_f32 v8, v8, s0
	ds_write_b16 v146, v61 offset:768
	ds_write_b16 v110, v8 offset:128
	v_cvt_pk_bf16_f32 v8, v7, s0
	ds_write_b16 v146, v8 offset:17152
	v_cvt_pk_bf16_f32 v8, v11, s0
	v_mul_f32_e32 v5, v222, v5
	ds_write_b16 v110, v8 offset:16512
	v_mul_f32_e32 v8, v222, v11
	v_mul_f32_e32 v7, v221, v7
	v_cvt_pk_bf16_f32 v7, v3, v7
	v_cvt_pk_bf16_f32 v3, v5, v8
	v_sub_f32_e32 v5, v220, v162
	v_cndmask_b32_e64 v5, v5, v168, s[88:89]
	v_sub_f32_e32 v8, v219, v161
	v_add_f32_e32 v5, v174, v5
	v_cndmask_b32_e64 v8, v8, v167, s[88:89]
	v_add_f32_e32 v11, v171, v8
	v_sub_f32_e32 v8, v5, v56
	v_cndmask_b32_e64 v68, v8, v5, s[88:89]
	v_sub_f32_e32 v8, v11, v55
	v_cndmask_b32_e64 v71, v8, v11, s[88:89]
	v_mul_f32_e32 v5, 0xbfb8aa3b, v5
	v_mul_f32_e32 v11, 0xbfb8aa3b, v11
	v_lshlrev_b32_e32 v56, 16, v245
	v_lshlrev_b32_e32 v55, 16, v246
	v_mov_b32_e32 v62, v59
	v_mov_b32_e32 v63, v58
	v_mov_b32_e32 v8, v59
	v_mov_b32_e32 v156, v57
	v_mov_b32_e32 v157, v54
	v_exp_f32_e32 v5, v5
	v_exp_f32_e32 v11, v11
	v_pk_mov_b32 v[60:61], v[54:55], v[56:57] op_sel:[1,0]
	v_pk_mul_f32 v[62:63], v[62:63], v[56:57]
	v_pk_mul_f32 v[156:157], v[8:9], v[156:157] op_sel_hi:[0,1]
	v_pk_fma_f32 v[62:63], v[58:59], v[54:55], v[62:63]
	v_pk_fma_f32 v[58:59], v[58:59], v[60:61], v[156:157] op_sel_hi:[0,1,1] neg_lo:[0,0,1] neg_hi:[0,0,1]
	v_cndmask_b32_e64 v8, v54, v62, s[90:91]
	v_cndmask_b32_e64 v54, v57, v63, s[90:91]
	v_cndmask_b32_e64 v55, v55, v58, s[90:91]
	v_mul_f32_e32 v5, v5, v55
	v_mul_f32_e32 v55, 0x3fb8aa3b, v68
	v_mul_f32_e32 v11, v11, v54
	v_mul_f32_e32 v54, 0x3fb8aa3b, v71
	v_exp_f32_e32 v55, v55
	v_exp_f32_e32 v54, v54
	v_cndmask_b32_e64 v56, v56, v59, s[90:91]
	v_mul_f32_e32 v62, v221, v5
	v_mul_f32_e32 v55, v55, v56
	v_mul_f32_e32 v8, v54, v8
	v_cvt_pk_bf16_f32 v55, v55, s0
	v_cvt_pk_bf16_f32 v8, v8, s0
	ds_write_b16 v147, v55 offset:1024
	ds_write_b16 v111, v8 offset:128
	v_cvt_pk_bf16_f32 v8, v5, s0
	v_sub_f32_e32 v5, v220, v168
	v_cndmask_b32_e64 v5, v5, v170, s[88:89]
	v_add_f32_e32 v63, v174, v5
	v_sub_f32_e32 v5, v219, v167
	v_cndmask_b32_e64 v5, v5, v169, s[88:89]
	v_add_f32_e32 v68, v171, v5
	v_sub_f32_e32 v5, v63, v67
	ds_write_b16 v147, v8 offset:17408
	v_cvt_pk_bf16_f32 v8, v11, s0
	v_cndmask_b32_e64 v67, v5, v63, s[88:89]
	v_sub_f32_e32 v5, v68, v66
	ds_write_b16 v111, v8 offset:16512
	v_cndmask_b32_e64 v66, v5, v68, s[88:89]
	v_lshlrev_b32_e32 v8, 16, v247
	v_lshlrev_b32_e32 v5, 16, v248
	v_mov_b32_e32 v56, v53
	v_mov_b32_e32 v57, v52
	v_mov_b32_e32 v58, v53
	v_mov_b32_e32 v60, v9
	v_mov_b32_e32 v61, v4
	v_pk_mov_b32 v[54:55], v[4:5], v[8:9] op_sel:[1,0]
	v_pk_mul_f32 v[56:57], v[56:57], v[8:9]
	v_pk_mul_f32 v[58:59], v[58:59], v[60:61] op_sel_hi:[0,1]
	v_pk_fma_f32 v[56:57], v[52:53], v[4:5], v[56:57]
	v_pk_fma_f32 v[52:53], v[52:53], v[54:55], v[58:59] op_sel_hi:[0,1,1] neg_lo:[0,0,1] neg_hi:[0,0,1]
	v_cndmask_b32_e64 v8, v8, v53, s[90:91]
	v_mul_f32_e32 v53, 0xbfb8aa3b, v63
	v_cndmask_b32_e64 v5, v5, v52, s[90:91]
	v_mul_f32_e32 v52, 0xbfb8aa3b, v68
	v_exp_f32_e32 v53, v53
	v_exp_f32_e32 v52, v52
	v_cndmask_b32_e64 v9, v9, v57, s[90:91]
	v_cndmask_b32_e64 v4, v4, v56, s[90:91]
	v_mul_f32_e32 v5, v53, v5
	v_mul_f32_e32 v53, 0x3fb8aa3b, v67
	v_mul_f32_e32 v9, v52, v9
	v_mul_f32_e32 v52, 0x3fb8aa3b, v66
	v_exp_f32_e32 v53, v53
	v_exp_f32_e32 v52, v52
	v_mul_f32_e32 v11, v222, v11
	v_mov_b32_e32 v54, v51
	v_mul_f32_e32 v8, v53, v8
	v_mul_f32_e32 v4, v52, v4
	v_cvt_pk_bf16_f32 v8, v8, s0
	v_cvt_pk_bf16_f32 v4, v4, s0
	ds_write_b16 v148, v8 offset:1280
	ds_write_b16 v112, v4 offset:128
	v_cvt_pk_bf16_f32 v4, v5, s0
	v_mul_f32_e32 v5, v221, v5
	ds_write_b16 v148, v4 offset:17664
	v_cvt_pk_bf16_f32 v4, v9, s0
	v_cvt_pk_bf16_f32 v8, v62, v5
	v_sub_f32_e32 v5, v220, v170
	ds_write_b16 v112, v4 offset:16512
	v_mul_f32_e32 v4, v222, v9
	v_cndmask_b32_e64 v5, v5, v173, s[88:89]
	v_sub_f32_e32 v9, v219, v169
	v_add_f32_e32 v5, v174, v5
	v_cndmask_b32_e64 v9, v9, v172, s[88:89]
	v_cvt_pk_bf16_f32 v4, v11, v4
	v_add_f32_e32 v9, v171, v9
	v_sub_f32_e32 v11, v5, v48
	v_cndmask_b32_e64 v11, v11, v5, s[88:89]
	v_sub_f32_e32 v17, v9, v17
	v_mul_f32_e32 v5, 0xbfb8aa3b, v5
	v_cndmask_b32_e64 v60, v17, v9, s[88:89]
	v_lshlrev_b32_e32 v48, 16, v249
	v_lshlrev_b32_e32 v17, 16, v250
	v_mov_b32_e32 v55, v50
	v_mov_b32_e32 v56, v51
	v_mov_b32_e32 v58, v49
	v_mov_b32_e32 v59, v16
	v_exp_f32_e32 v5, v5
	v_pk_mov_b32 v[52:53], v[16:17], v[48:49] op_sel:[1,0]
	v_pk_mul_f32 v[54:55], v[54:55], v[48:49]
	v_pk_mul_f32 v[56:57], v[56:57], v[58:59] op_sel_hi:[0,1]
	v_pk_fma_f32 v[54:55], v[50:51], v[16:17], v[54:55]
	v_pk_fma_f32 v[50:51], v[50:51], v[52:53], v[56:57] op_sel_hi:[0,1,1] neg_lo:[0,0,1] neg_hi:[0,0,1]
	v_mul_f32_e32 v11, 0x3fb8aa3b, v11
	v_cndmask_b32_e64 v17, v17, v50, s[90:91]
	v_exp_f32_e32 v11, v11
	v_mul_f32_e32 v5, v5, v17
	v_mul_f32_e32 v17, 0x3fb8aa3b, v60
	v_exp_f32_e32 v17, v17
	v_cndmask_b32_e64 v48, v48, v51, s[90:91]
	v_mul_f32_e32 v9, 0xbfb8aa3b, v9
	v_exp_f32_e32 v9, v9
	v_mul_f32_e32 v11, v11, v48
	v_cndmask_b32_e64 v16, v16, v54, s[90:91]
	v_cvt_pk_bf16_f32 v11, v11, s0
	ds_write_b16 v149, v11 offset:1536
	v_mul_f32_e32 v11, v17, v16
	v_cndmask_b32_e64 v49, v49, v55, s[90:91]
	v_cvt_pk_bf16_f32 v11, v11, s0
	v_mul_f32_e32 v9, v9, v49
	ds_write_b16 v113, v11 offset:128
	v_cvt_pk_bf16_f32 v11, v5, s0
	ds_write_b16 v149, v11 offset:17920
	v_cvt_pk_bf16_f32 v11, v9, s0
	v_mul_f32_e32 v54, v222, v9
	v_sub_f32_e32 v9, v220, v173
	ds_write_b16 v113, v11 offset:16512
	v_cndmask_b32_e64 v9, v9, v176, s[88:89]
	v_sub_f32_e32 v11, v219, v172
	v_add_f32_e32 v9, v174, v9
	v_cndmask_b32_e64 v11, v11, v175, s[88:89]
	v_add_f32_e32 v55, v171, v11
	v_sub_f32_e32 v11, v9, v65
	v_cndmask_b32_e64 v56, v11, v9, s[88:89]
	v_sub_f32_e32 v11, v55, v12
	v_cndmask_b32_e64 v57, v11, v55, s[88:89]
	v_lshlrev_b32_e32 v12, 16, v197
	v_lshlrev_b32_e32 v11, 16, v251
	v_mov_b32_e32 v48, v15
	v_mov_b32_e32 v49, v14
	v_mov_b32_e32 v50, v15
	v_mov_b32_e32 v52, v13
	v_mov_b32_e32 v53, v10
	v_pk_mov_b32 v[16:17], v[10:11], v[12:13] op_sel:[1,0]
	v_pk_mul_f32 v[48:49], v[48:49], v[12:13]
	v_pk_mul_f32 v[50:51], v[50:51], v[52:53] op_sel_hi:[0,1]
	v_pk_fma_f32 v[48:49], v[14:15], v[10:11], v[48:49]
	v_pk_fma_f32 v[14:15], v[14:15], v[16:17], v[50:51] op_sel_hi:[0,1,1] neg_lo:[0,0,1] neg_hi:[0,0,1]
	v_mul_f32_e32 v9, 0xbfb8aa3b, v9
	v_cndmask_b32_e64 v11, v11, v14, s[90:91]
	v_mul_f32_e32 v14, 0xbfb8aa3b, v55
	v_exp_f32_e32 v9, v9
	v_exp_f32_e32 v14, v14
	v_cndmask_b32_e64 v13, v13, v49, s[90:91]
	v_cndmask_b32_e64 v10, v10, v48, s[90:91]
	v_mul_f32_e32 v9, v9, v11
	v_mul_f32_e32 v11, 0x3fb8aa3b, v56
	v_mul_f32_e32 v13, v14, v13
	v_mul_f32_e32 v14, 0x3fb8aa3b, v57
	v_exp_f32_e32 v11, v11
	v_exp_f32_e32 v14, v14
	v_cndmask_b32_e64 v12, v12, v15, s[90:91]
	v_mul_f32_e32 v5, v221, v5
	v_mul_f32_e32 v11, v11, v12
	v_mul_f32_e32 v10, v14, v10
	v_cvt_pk_bf16_f32 v11, v11, s0
	v_cvt_pk_bf16_f32 v10, v10, s0
	ds_write_b16 v150, v11 offset:1792
	ds_write_b16 v114, v10 offset:128
	v_cvt_pk_bf16_f32 v10, v9, s0
	ds_write_b16 v150, v10 offset:18176
	v_cvt_pk_bf16_f32 v10, v13, s0
	ds_write_b16 v114, v10 offset:16512
	v_mul_f32_e32 v10, v222, v13
	v_mul_f32_e32 v9, v221, v9
	v_cvt_pk_bf16_f32 v9, v5, v9
	v_cvt_pk_bf16_f32 v5, v54, v10
	ds_read_u16 v12, v118 offset:16384
	v_cndmask_b32_e64 v10, v115, v210, s[38:39]
	v_lshl_or_b32 v10, v10, 7, v72
	ds_read2st64_b32 v[10:11], v10 offset0:160 offset1:192
	ds_read_u16 v13, v118
	ds_read_u16 v16, v118 offset:16512
	ds_read_u16 v49, v118 offset:128
	ds_read_u16 v14, v116 offset:16512
	s_waitcnt lgkmcnt(0)
	v_lshlrev_b32_e32 v15, 16, v12
	v_lshlrev_b32_e32 v156, 16, v13
	ds_read_u16 v13, v120 offset:128
	ds_read_u16 v50, v120 offset:16512
	ds_read_u16 v55, v122 offset:128
	ds_read_u16 v56, v122 offset:16512
	ds_read_u16 v12, v122 offset:16384
	ds_read_u16 v17, v122
	ds_read_u16 v48, v120 offset:16384
	ds_read_u16 v51, v120
	v_cndmask_b32_e64 v52, v117, v210, s[38:39]
	v_lshl_or_b32 v52, v52, 7, v72
	ds_read2st64_b32 v[168:169], v52 offset0:160 offset1:192
	s_waitcnt lgkmcnt(0)
	v_lshlrev_b32_e32 v173, 16, v48
	v_cndmask_b32_e64 v48, v119, v210, s[38:39]
	v_lshl_or_b32 v48, v48, 7, v72
	v_lshlrev_b32_e32 v192, 16, v51
	ds_read2st64_b32 v[194:195], v48 offset0:160 offset1:192
	v_lshlrev_b32_e32 v71, 16, v12
	v_lshlrev_b32_e32 v68, 16, v17
	ds_read_u16 v63, v124 offset:128
	ds_read_u16 v155, v124 offset:16512
	ds_read_u16 v158, v126 offset:128
	ds_read_u16 v161, v126 offset:16512
	ds_read_u16 v12, v126 offset:16384
	ds_read_u16 v48, v126
	ds_read_u16 v17, v124 offset:16384
	ds_read_u16 v51, v124
	v_cndmask_b32_e64 v52, v121, v210, s[38:39]
	v_lshl_or_b32 v52, v52, 7, v72
	ds_read2st64_b32 v[224:225], v52 offset0:160 offset1:192
	s_waitcnt lgkmcnt(0)
	v_lshlrev_b32_e32 v65, 16, v17
	v_cndmask_b32_e64 v17, v123, v210, s[38:39]
	v_lshl_or_b32 v17, v17, 7, v72
	v_lshlrev_b32_e32 v62, 16, v51
	ds_read2st64_b32 v[66:67], v17 offset0:160 offset1:192
	v_lshlrev_b32_e32 v17, 16, v12
	v_lshlrev_b32_e32 v12, 16, v48
	ds_read_u16 v162, v128 offset:128
	ds_read_u16 v167, v128 offset:16512
	ds_read_u16 v170, v130 offset:128
	ds_read_u16 v191, v130 offset:16512
	ds_read_u16 v48, v130 offset:16384
	ds_read_u16 v52, v130
	ds_read_u16 v51, v128 offset:16384
	ds_read_u16 v53, v128
	v_cndmask_b32_e64 v54, v125, v210, s[38:39]
	v_lshl_or_b32 v54, v54, 7, v72
	ds_read2st64_b32 v[60:61], v54 offset0:160 offset1:192
	s_waitcnt lgkmcnt(0)
	v_lshlrev_b32_e32 v57, 16, v51
	v_cndmask_b32_e64 v51, v127, v210, s[38:39]
	v_lshl_or_b32 v51, v51, 7, v72
	ds_read2st64_b32 v[58:59], v51 offset0:160 offset1:192
	v_lshlrev_b32_e32 v51, 16, v48
	v_lshlrev_b32_e32 v48, 16, v52
	v_cndmask_b32_e64 v52, v129, v210, s[38:39]
	v_lshl_or_b32 v52, v52, 7, v72
	v_lshlrev_b32_e32 v54, 16, v53
	ds_read2st64_b32 v[52:53], v52 offset0:160 offset1:192
	ds_read_u16 v157, v116
	ds_read_u16 v172, v116 offset:128
	ds_read_u16 v193, v116 offset:16384
	v_sub_f32_e32 v176, v220, v176
	v_cndmask_b32_e64 v176, v176, v179, s[88:89]
	v_sub_f32_e32 v175, v219, v175
	v_add_f32_e32 v176, v174, v176
	v_cndmask_b32_e64 v175, v175, v178, s[88:89]
	v_add_f32_e32 v175, v171, v175
	s_waitcnt lgkmcnt(0)
	v_lshlrev_b32_e32 v211, 16, v193
	v_lshlrev_b32_e32 v210, 16, v172
	v_lshlrev_b32_e32 v227, 16, v14
	v_lshlrev_b32_e32 v226, 16, v157
	v_mul_f32_e32 v172, 0xbfb8aa3b, v176
	v_sub_f32_e32 v203, v175, v203
	v_mov_b32_e32 v230, v11
	v_mov_b32_e32 v231, v10
	v_mov_b32_e32 v14, v11
	v_pk_mov_b32 v[232:233], v[210:211], v[226:227] op_sel:[1,0]
	v_exp_f32_e32 v172, v172
	v_mul_f32_e32 v206, 0x3d800000, v206
	v_cndmask_b32_e64 v203, v203, v175, s[88:89]
	v_pk_mov_b32 v[228:229], v[226:227], v[210:211] op_sel:[1,0]
	v_pk_mul_f32 v[230:231], v[230:231], v[210:211]
	v_pk_mul_f32 v[232:233], v[14:15], v[232:233] op_sel_hi:[0,1]
	v_mul_f32_e32 v175, 0xbfb8aa3b, v175
	v_sub_f32_e32 v197, v176, v206
	v_pk_fma_f32 v[230:231], v[10:11], v[226:227], v[230:231]
	v_pk_fma_f32 v[10:11], v[10:11], v[228:229], v[232:233] op_sel_hi:[0,1,1] neg_lo:[0,0,1] neg_hi:[0,0,1]
	v_exp_f32_e32 v175, v175
	v_cndmask_b32_e64 v197, v197, v176, s[88:89]
	v_cndmask_b32_e64 v10, v228, v10, s[90:91]
	v_mul_f32_e32 v10, v172, v10
	v_mul_f32_e32 v172, 0x3fb8aa3b, v197
	v_cndmask_b32_e64 v157, v211, v231, s[90:91]
	v_exp_f32_e32 v172, v172
	v_mul_f32_e32 v157, v175, v157
	v_mul_f32_e32 v175, 0x3fb8aa3b, v203
	v_exp_f32_e32 v175, v175
	v_cndmask_b32_e64 v11, v229, v11, s[90:91]
	v_mul_f32_e32 v11, v172, v11
	v_cndmask_b32_e64 v14, v226, v230, s[90:91]
	v_cvt_pk_bf16_f32 v11, v11, s0
	ds_write_b16 v131, v11 offset:128
	v_mul_f32_e32 v11, v175, v14
	v_cvt_pk_bf16_f32 v11, v11, s0
	ds_write_b16 v207, v11 offset:2048
	v_cvt_pk_bf16_f32 v11, v10, s0
	v_mul_f32_e32 v172, v221, v10
	v_sub_f32_e32 v10, v220, v179
	v_cndmask_b32_e64 v10, v10, v182, s[88:89]
	v_add_f32_e32 v176, v174, v10
	v_sub_f32_e32 v10, v219, v178
	v_cndmask_b32_e64 v10, v10, v181, s[88:89]
	v_add_f32_e32 v193, v171, v10
	v_sub_f32_e32 v10, v176, v202
	ds_write_b16 v131, v11 offset:16512
	v_cvt_pk_bf16_f32 v11, v157, s0
	v_mul_f32_e32 v175, v222, v157
	v_cndmask_b32_e64 v197, v10, v176, s[88:89]
	v_sub_f32_e32 v10, v193, v199
	v_lshlrev_b32_e32 v14, 16, v49
	v_lshlrev_b32_e32 v157, 16, v16
	v_mov_b32_e32 v16, v169
	v_mov_b32_e32 v202, v15
	v_mov_b32_e32 v203, v156
	ds_write_b16 v207, v11 offset:18432
	v_cndmask_b32_e64 v199, v10, v193, s[88:89]
	v_pk_mov_b32 v[10:11], v[156:157], v[14:15] op_sel:[1,0]
	v_pk_mul_f32 v[202:203], v[16:17], v[202:203] op_sel_hi:[0,1]
	v_mov_b32_e32 v178, v169
	v_mov_b32_e32 v179, v168
	v_pk_fma_f32 v[10:11], v[168:169], v[10:11], v[202:203] op_sel_hi:[0,1,1] neg_lo:[0,0,1] neg_hi:[0,0,1]
	v_pk_mul_f32 v[178:179], v[178:179], v[14:15]
	v_cndmask_b32_e64 v11, v14, v11, s[90:91]
	v_mul_f32_e32 v14, 0xbfb8aa3b, v176
	v_exp_f32_e32 v14, v14
	v_mul_f32_e32 v49, 0xbfb8aa3b, v193
	v_exp_f32_e32 v49, v49
	v_cndmask_b32_e64 v10, v157, v10, s[90:91]
	v_pk_fma_f32 v[178:179], v[168:169], v[156:157], v[178:179]
	v_mul_f32_e32 v10, v14, v10
	v_mul_f32_e32 v14, 0x3fb8aa3b, v197
	v_cndmask_b32_e64 v15, v15, v179, s[90:91]
	v_exp_f32_e32 v14, v14
	v_mul_f32_e32 v15, v49, v15
	v_mul_f32_e32 v49, 0x3fb8aa3b, v199
	v_exp_f32_e32 v49, v49
	v_mul_f32_e32 v11, v14, v11
	v_cndmask_b32_e64 v16, v156, v178, s[90:91]
	v_cvt_pk_bf16_f32 v11, v11, s0
	ds_write_b16 v132, v11 offset:128
	v_mul_f32_e32 v11, v49, v16
	v_cvt_pk_bf16_f32 v11, v11, s0
	ds_write_b16 v144, v11 offset:2304
	v_cvt_pk_bf16_f32 v11, v10, s0
	ds_write_b16 v132, v11 offset:16512
	v_cvt_pk_bf16_f32 v11, v15, s0
	ds_write_b16 v144, v11 offset:18688
	v_mul_f32_e32 v11, v222, v15
	v_mul_f32_e32 v10, v221, v10
	v_cvt_pk_bf16_f32 v14, v172, v10
	v_cvt_pk_bf16_f32 v10, v175, v11
	v_sub_f32_e32 v11, v220, v182
	v_cndmask_b32_e64 v11, v11, v201, s[88:89]
	v_sub_f32_e32 v15, v219, v181
	v_add_f32_e32 v11, v174, v11
	v_cndmask_b32_e64 v15, v15, v200, s[88:89]
	v_add_f32_e32 v15, v171, v15
	v_sub_f32_e32 v16, v11, v183
	v_cndmask_b32_e64 v49, v16, v11, s[88:89]
	v_sub_f32_e32 v16, v15, v180
	v_cndmask_b32_e64 v175, v16, v15, s[88:89]
	v_mul_f32_e32 v15, 0xbfb8aa3b, v15
	v_lshlrev_b32_e32 v172, 16, v13
	v_mov_b32_e32 v168, v195
	v_mov_b32_e32 v169, v194
	v_exp_f32_e32 v15, v15
	v_lshlrev_b32_e32 v193, 16, v50
	v_pk_mul_f32 v[168:169], v[168:169], v[172:173]
	v_mov_b32_e32 v16, v195
	v_pk_fma_f32 v[168:169], v[194:195], v[192:193], v[168:169]
	v_mov_b32_e32 v178, v173
	v_mov_b32_e32 v179, v192
	v_pk_mul_f32 v[178:179], v[16:17], v[178:179] op_sel_hi:[0,1]
	v_cndmask_b32_e64 v16, v173, v169, s[90:91]
	v_mul_f32_e32 v49, 0x3fb8aa3b, v49
	v_mul_f32_e32 v15, v15, v16
	v_mul_f32_e32 v16, 0x3fb8aa3b, v175
	v_mul_f32_e32 v11, 0xbfb8aa3b, v11
	v_exp_f32_e32 v49, v49
	v_exp_f32_e32 v16, v16
	v_pk_mov_b32 v[156:157], v[192:193], v[172:173] op_sel:[1,0]
	v_exp_f32_e32 v11, v11
	v_pk_fma_f32 v[156:157], v[194:195], v[156:157], v[178:179] op_sel_hi:[0,1,1] neg_lo:[0,0,1] neg_hi:[0,0,1]
	v_cndmask_b32_e64 v13, v192, v168, s[90:91]
	v_cndmask_b32_e64 v50, v172, v157, s[90:91]
	v_cndmask_b32_e64 v156, v193, v156, s[90:91]
	v_mul_f32_e32 v49, v49, v50
	v_mul_f32_e32 v13, v16, v13
	v_mul_f32_e32 v11, v11, v156
	v_cvt_pk_bf16_f32 v49, v49, s0
	v_cvt_pk_bf16_f32 v13, v13, s0
	ds_write_b16 v133, v49 offset:128
	ds_write_b16 v145, v13 offset:2560
	v_cvt_pk_bf16_f32 v13, v11, s0
	ds_write_b16 v133, v13 offset:16512
	v_cvt_pk_bf16_f32 v13, v15, s0
	ds_write_b16 v145, v13 offset:18944
	v_mul_f32_e32 v13, v222, v15
	v_sub_f32_e32 v15, v220, v201
	v_cndmask_b32_e64 v15, v15, v205, s[88:89]
	v_sub_f32_e32 v16, v219, v200
	v_add_f32_e32 v15, v174, v15
	v_cndmask_b32_e64 v16, v16, v204, s[88:89]
	v_add_f32_e32 v49, v171, v16
	v_sub_f32_e32 v16, v15, v70
	v_cndmask_b32_e64 v50, v16, v15, s[88:89]
	v_sub_f32_e32 v16, v49, v69
	v_cndmask_b32_e64 v175, v16, v49, s[88:89]
	v_mul_f32_e32 v49, 0xbfb8aa3b, v49
	v_lshlrev_b32_e32 v70, 16, v55
	v_mov_b32_e32 v168, v225
	v_mov_b32_e32 v169, v224
	v_exp_f32_e32 v49, v49
	v_lshlrev_b32_e32 v69, 16, v56
	v_pk_mul_f32 v[168:169], v[168:169], v[70:71]
	v_mul_f32_e32 v50, 0x3fb8aa3b, v50
	v_pk_fma_f32 v[168:169], v[224:225], v[68:69], v[168:169]
	v_mov_b32_e32 v16, v225
	v_cndmask_b32_e64 v55, v71, v169, s[90:91]
	v_mul_f32_e32 v49, v49, v55
	v_mul_f32_e32 v55, 0x3fb8aa3b, v175
	v_mov_b32_e32 v172, v71
	v_mov_b32_e32 v173, v68
	v_mul_f32_e32 v15, 0xbfb8aa3b, v15
	v_exp_f32_e32 v50, v50
	v_exp_f32_e32 v55, v55
	v_pk_mov_b32 v[156:157], v[68:69], v[70:71] op_sel:[1,0]
	v_pk_mul_f32 v[172:173], v[16:17], v[172:173] op_sel_hi:[0,1]
	v_exp_f32_e32 v15, v15
	v_pk_fma_f32 v[156:157], v[224:225], v[156:157], v[172:173] op_sel_hi:[0,1,1] neg_lo:[0,0,1] neg_hi:[0,0,1]
	v_cndmask_b32_e64 v16, v68, v168, s[90:91]
	v_cndmask_b32_e64 v56, v70, v157, s[90:91]
	v_cndmask_b32_e64 v68, v69, v156, s[90:91]
	v_mul_f32_e32 v50, v50, v56
	v_mul_f32_e32 v16, v55, v16
	v_mul_f32_e32 v15, v15, v68
	v_cvt_pk_bf16_f32 v50, v50, s0
	v_cvt_pk_bf16_f32 v16, v16, s0
	ds_write_b16 v135, v50 offset:128
	ds_write_b16 v146, v16 offset:2816
	v_cvt_pk_bf16_f32 v16, v15, s0
	ds_write_b16 v135, v16 offset:16512
	v_cvt_pk_bf16_f32 v16, v49, s0
	v_mul_f32_e32 v11, v221, v11
	ds_write_b16 v146, v16 offset:19200
	v_mul_f32_e32 v16, v222, v49
	v_mul_f32_e32 v15, v221, v15
	v_cvt_pk_bf16_f32 v15, v11, v15
	v_cvt_pk_bf16_f32 v11, v13, v16
	v_sub_f32_e32 v13, v220, v205
	v_cndmask_b32_e64 v13, v13, v209, s[88:89]
	v_sub_f32_e32 v16, v219, v204
	v_add_f32_e32 v13, v174, v13
	v_cndmask_b32_e64 v16, v16, v208, s[88:89]
	v_add_f32_e32 v49, v171, v16
	v_sub_f32_e32 v16, v13, v177
	v_cndmask_b32_e64 v50, v16, v13, s[88:89]
	v_sub_f32_e32 v16, v49, v64
	v_cndmask_b32_e64 v55, v16, v49, s[88:89]
	v_mul_f32_e32 v50, 0x3fb8aa3b, v50
	v_mul_f32_e32 v55, 0x3fb8aa3b, v55
	v_lshlrev_b32_e32 v64, 16, v63
	v_lshlrev_b32_e32 v63, 16, v155
	v_mov_b32_e32 v70, v67
	v_mov_b32_e32 v71, v66
	v_mov_b32_e32 v16, v67
	v_mov_b32_e32 v156, v65
	v_mov_b32_e32 v157, v62
	v_mul_f32_e32 v13, 0xbfb8aa3b, v13
	v_exp_f32_e32 v50, v50
	v_exp_f32_e32 v55, v55
	v_pk_mov_b32 v[68:69], v[62:63], v[64:65] op_sel:[1,0]
	v_pk_mul_f32 v[70:71], v[70:71], v[64:65]
	v_pk_mul_f32 v[156:157], v[16:17], v[156:157] op_sel_hi:[0,1]
	v_exp_f32_e32 v13, v13
	v_pk_fma_f32 v[70:71], v[66:67], v[62:63], v[70:71]
	v_pk_fma_f32 v[66:67], v[66:67], v[68:69], v[156:157] op_sel_hi:[0,1,1] neg_lo:[0,0,1] neg_hi:[0,0,1]
	v_cndmask_b32_e64 v16, v62, v70, s[90:91]
	v_cndmask_b32_e64 v62, v64, v67, s[90:91]
	v_mul_f32_e32 v49, 0xbfb8aa3b, v49
	v_cndmask_b32_e64 v63, v63, v66, s[90:91]
	v_exp_f32_e32 v49, v49
	v_mul_f32_e32 v50, v50, v62
	v_mul_f32_e32 v16, v55, v16
	v_mul_f32_e32 v13, v13, v63
	v_cvt_pk_bf16_f32 v50, v50, s0
	v_cvt_pk_bf16_f32 v16, v16, s0
	ds_write_b16 v136, v50 offset:128
	ds_write_b16 v147, v16 offset:3072
	v_cvt_pk_bf16_f32 v16, v13, s0
	v_mul_f32_e32 v55, v221, v13
	v_sub_f32_e32 v13, v220, v209
	v_cndmask_b32_e64 v56, v65, v71, s[90:91]
	v_cndmask_b32_e64 v13, v13, v213, s[88:89]
	v_mul_f32_e32 v49, v49, v56
	v_add_f32_e32 v56, v174, v13
	v_sub_f32_e32 v13, v219, v208
	v_cndmask_b32_e64 v13, v13, v212, s[88:89]
	v_add_f32_e32 v68, v171, v13
	v_sub_f32_e32 v13, v56, v166
	v_mov_b32_e32 v50, v61
	v_mov_b32_e32 v66, v17
	v_mov_b32_e32 v67, v12
	ds_write_b16 v136, v16 offset:16512
	v_cvt_pk_bf16_f32 v16, v49, s0
	v_cndmask_b32_e64 v69, v13, v56, s[88:89]
	v_sub_f32_e32 v13, v68, v165
	v_pk_mul_f32 v[66:67], v[50:51], v[66:67] op_sel_hi:[0,1]
	v_mul_f32_e32 v50, 0xbfb8aa3b, v56
	v_mul_f32_e32 v56, 0xbfb8aa3b, v68
	ds_write_b16 v147, v16 offset:19456
	v_cndmask_b32_e64 v70, v13, v68, s[88:89]
	v_lshlrev_b32_e32 v16, 16, v158
	v_lshlrev_b32_e32 v13, 16, v161
	v_mov_b32_e32 v64, v61
	v_mov_b32_e32 v65, v60
	v_exp_f32_e32 v50, v50
	v_exp_f32_e32 v56, v56
	v_pk_mov_b32 v[62:63], v[12:13], v[16:17] op_sel:[1,0]
	v_pk_mul_f32 v[64:65], v[64:65], v[16:17]
	v_mul_f32_e32 v49, v222, v49
	v_pk_fma_f32 v[64:65], v[60:61], v[12:13], v[64:65]
	v_pk_fma_f32 v[60:61], v[60:61], v[62:63], v[66:67] op_sel_hi:[0,1,1] neg_lo:[0,0,1] neg_hi:[0,0,1]
	v_cndmask_b32_e64 v17, v17, v65, s[90:91]
	v_cndmask_b32_e64 v13, v13, v60, s[90:91]
	v_mul_f32_e32 v13, v50, v13
	v_mul_f32_e32 v50, 0x3fb8aa3b, v69
	v_mul_f32_e32 v17, v56, v17
	v_mul_f32_e32 v56, 0x3fb8aa3b, v70
	v_exp_f32_e32 v50, v50
	v_exp_f32_e32 v56, v56
	v_cndmask_b32_e64 v12, v12, v64, s[90:91]
	v_cndmask_b32_e64 v16, v16, v61, s[90:91]
	v_mul_f32_e32 v16, v50, v16
	v_mul_f32_e32 v12, v56, v12
	v_cvt_pk_bf16_f32 v16, v16, s0
	v_cvt_pk_bf16_f32 v12, v12, s0
	ds_write_b16 v137, v16 offset:128
	ds_write_b16 v148, v12 offset:3328
	v_cvt_pk_bf16_f32 v12, v13, s0
	ds_write_b16 v137, v12 offset:16512
	v_cvt_pk_bf16_f32 v12, v17, s0
	ds_write_b16 v148, v12 offset:19712
	v_mul_f32_e32 v12, v222, v17
	v_sub_f32_e32 v17, v219, v212
	v_mul_f32_e32 v13, v221, v13
	v_cndmask_b32_e64 v17, v17, v215, s[88:89]
	v_cvt_pk_bf16_f32 v16, v55, v13
	v_sub_f32_e32 v13, v220, v213
	v_add_f32_e32 v17, v171, v17
	v_cndmask_b32_e64 v13, v13, v216, s[88:89]
	v_sub_f32_e32 v50, v17, v163
	v_add_f32_e32 v13, v174, v13
	v_cndmask_b32_e64 v66, v50, v17, s[88:89]
	v_mul_f32_e32 v17, 0xbfb8aa3b, v17
	v_cvt_pk_bf16_f32 v12, v49, v12
	v_sub_f32_e32 v49, v13, v164
	v_lshlrev_b32_e32 v56, 16, v162
	v_mov_b32_e32 v62, v59
	v_mov_b32_e32 v63, v58
	v_exp_f32_e32 v17, v17
	v_cndmask_b32_e64 v49, v49, v13, s[88:89]
	v_lshlrev_b32_e32 v55, 16, v167
	v_pk_mul_f32 v[62:63], v[62:63], v[56:57]
	v_mov_b32_e32 v50, v59
	v_pk_fma_f32 v[62:63], v[58:59], v[54:55], v[62:63]
	v_mov_b32_e32 v64, v57
	v_mov_b32_e32 v65, v54
	v_mul_f32_e32 v49, 0x3fb8aa3b, v49
	v_pk_mov_b32 v[60:61], v[54:55], v[56:57] op_sel:[1,0]
	v_pk_mul_f32 v[64:65], v[50:51], v[64:65] op_sel_hi:[0,1]
	v_cndmask_b32_e64 v50, v54, v62, s[90:91]
	v_cndmask_b32_e64 v54, v57, v63, s[90:91]
	v_exp_f32_e32 v49, v49
	v_mul_f32_e32 v17, v17, v54
	v_mul_f32_e32 v54, 0x3fb8aa3b, v66
	v_pk_fma_f32 v[58:59], v[58:59], v[60:61], v[64:65] op_sel_hi:[0,1,1] neg_lo:[0,0,1] neg_hi:[0,0,1]
	v_mul_f32_e32 v13, 0xbfb8aa3b, v13
	v_exp_f32_e32 v54, v54
	v_cndmask_b32_e64 v56, v56, v59, s[90:91]
	v_exp_f32_e32 v13, v13
	v_mul_f32_e32 v49, v49, v56
	v_cvt_pk_bf16_f32 v49, v49, s0
	v_cndmask_b32_e64 v55, v55, v58, s[90:91]
	ds_write_b16 v138, v49 offset:128
	v_mul_f32_e32 v49, v54, v50
	v_mul_f32_e32 v13, v13, v55
	v_cvt_pk_bf16_f32 v49, v49, s0
	ds_write_b16 v149, v49 offset:3584
	v_cvt_pk_bf16_f32 v49, v13, s0
	ds_write_b16 v138, v49 offset:16512
	v_cvt_pk_bf16_f32 v49, v17, s0
	v_mul_f32_e32 v62, v221, v13
	v_mul_f32_e32 v13, v222, v17
	v_sub_f32_e32 v17, v220, v216
	ds_write_b16 v149, v49 offset:19968
	v_cndmask_b32_e64 v17, v17, v220, s[88:89]
	v_sub_f32_e32 v49, v219, v215
	v_add_f32_e32 v17, v174, v17
	v_cndmask_b32_e64 v49, v49, v219, s[88:89]
	v_add_f32_e32 v63, v171, v49
	v_sub_f32_e32 v49, v17, v160
	v_cndmask_b32_e64 v64, v49, v17, s[88:89]
	v_sub_f32_e32 v49, v63, v159
	v_cndmask_b32_e64 v65, v49, v63, s[88:89]
	v_lshlrev_b32_e32 v50, 16, v170
	v_lshlrev_b32_e32 v49, 16, v191
	v_mov_b32_e32 v56, v53
	v_mov_b32_e32 v57, v52
	v_mov_b32_e32 v58, v53
	v_mov_b32_e32 v60, v51
	v_mov_b32_e32 v61, v48
	v_pk_mov_b32 v[54:55], v[48:49], v[50:51] op_sel:[1,0]
	v_pk_mul_f32 v[56:57], v[56:57], v[50:51]
	v_pk_mul_f32 v[58:59], v[58:59], v[60:61] op_sel_hi:[0,1]
	v_pk_fma_f32 v[56:57], v[52:53], v[48:49], v[56:57]
	v_pk_fma_f32 v[52:53], v[52:53], v[54:55], v[58:59] op_sel_hi:[0,1,1] neg_lo:[0,0,1] neg_hi:[0,0,1]
	v_mul_f32_e32 v17, 0xbfb8aa3b, v17
	v_cndmask_b32_e64 v49, v49, v52, s[90:91]
	v_mul_f32_e32 v52, 0xbfb8aa3b, v63
	v_exp_f32_e32 v17, v17
	v_exp_f32_e32 v52, v52
	v_cndmask_b32_e64 v51, v51, v57, s[90:91]
	v_cndmask_b32_e64 v48, v48, v56, s[90:91]
	v_mul_f32_e32 v17, v17, v49
	v_mul_f32_e32 v49, 0x3fb8aa3b, v64
	v_mul_f32_e32 v51, v52, v51
	v_mul_f32_e32 v52, 0x3fb8aa3b, v65
	v_exp_f32_e32 v49, v49
	v_exp_f32_e32 v52, v52
	v_cndmask_b32_e64 v50, v50, v53, s[90:91]
	v_add_u32_e32 v56, v79, v141
	v_mul_f32_e32 v49, v49, v50
	v_mul_f32_e32 v48, v52, v48
	v_cvt_pk_bf16_f32 v49, v49, s0
	v_cvt_pk_bf16_f32 v48, v48, s0
	ds_write_b16 v139, v49 offset:128
	ds_write_b16 v150, v48 offset:3840
	v_cvt_pk_bf16_f32 v48, v17, s0
	ds_write_b16 v139, v48 offset:16512
	v_cvt_pk_bf16_f32 v48, v51, s0
	ds_write_b16 v150, v48 offset:20224
	v_mul_f32_e32 v48, v222, v51
	v_cvt_pk_bf16_f32 v13, v13, v48
	v_mul_f32_e32 v17, v221, v17
	v_add_u32_e32 v48, v74, v76
	v_cvt_pk_bf16_f32 v17, v62, v17
	ds_write_b128 v48, v[6:9] offset:57344
	v_add_u32_e32 v6, v74, v77
	ds_write_b128 v6, v[14:17] offset:57344
	v_add_u32_e32 v6, v75, v76
	ds_write_b128 v6, v[2:5] offset:8192
	v_add_u32_e32 v2, v75, v77
	ds_write_b128 v2, v[10:13] offset:8192
	s_waitcnt lgkmcnt(0)
	s_barrier
	ds_read_b128 v[2:5], v151 offset:57344
	v_lshlrev_b64 v[6:7], 14, v[46:47]
	v_lshl_add_u64 v[8:9], s[50:51], 0, v[6:7]
	v_lshl_add_u64 v[10:11], v[8:9], 0, v[38:39]
	v_lshl_add_u64 v[6:7], s[48:49], 0, v[6:7]
	s_waitcnt lgkmcnt(0)
	global_store_dwordx4 v[10:11], v[2:5], off
	ds_read_b128 v[2:5], v152 offset:57344
	v_lshl_add_u64 v[10:11], v[8:9], 0, v[40:41]
	v_add_u32_e32 v48, v78, v140
	v_add_u32_e32 v60, v78, v141
	v_add_u32_e32 v64, v78, v142
	s_waitcnt lgkmcnt(0)
	global_store_dwordx4 v[10:11], v[2:5], off
	ds_read_b128 v[2:5], v153 offset:57344
	v_lshl_add_u64 v[10:11], v[8:9], 0, v[42:43]
	v_lshl_add_u64 v[8:9], v[8:9], 0, v[44:45]
	v_readlane_b32 s0, v255, 8
	v_readlane_b32 s1, v255, 9
	s_waitcnt lgkmcnt(0)
	global_store_dwordx4 v[10:11], v[2:5], off
	ds_read_b128 v[2:5], v154 offset:57344
	s_xor_b64 s[0:1], s[0:1], s[88:89]
	v_lshlrev_b64 v[46:47], 13, v[46:47]
	v_lshl_add_u64 v[46:47], v[26:27], 0, v[46:47]
	v_lshl_add_u64 v[36:37], v[36:37], 0, s[52:53]
	s_waitcnt lgkmcnt(0)
	global_store_dwordx4 v[8:9], v[2:5], off
	v_lshl_add_u64 v[8:9], v[6:7], 0, v[38:39]
	s_nop 0
	v_add_u32_e32 v2, v80, v81
	ds_read_b128 v[2:5], v2
	s_waitcnt lgkmcnt(0)
	global_store_dwordx4 v[8:9], v[2:5], off
	s_nop 1
	v_add_u32_e32 v2, v83, v84
	ds_read_b128 v[2:5], v2
	v_lshl_add_u64 v[8:9], v[6:7], 0, v[40:41]
	s_waitcnt lgkmcnt(0)
	global_store_dwordx4 v[8:9], v[2:5], off
	s_nop 1
	v_add_u32_e32 v2, v86, v87
	ds_read_b128 v[2:5], v2
	v_lshl_add_u64 v[8:9], v[6:7], 0, v[42:43]
	v_lshl_add_u64 v[6:7], v[6:7], 0, v[44:45]
	s_waitcnt lgkmcnt(0)
	global_store_dwordx4 v[8:9], v[2:5], off
	s_nop 1
	v_add_u32_e32 v2, v89, v90
	ds_read_b128 v[2:5], v2
	s_waitcnt lgkmcnt(0)
	global_store_dwordx4 v[6:7], v[2:5], off
	ds_read_b128 v[2:5], v48 offset:16384
	v_add_u32_e32 v6, v79, v140
	ds_read_b128 v[6:9], v6
	ds_read_b128 v[10:13], v48 offset:20480
	ds_read_b128 v[14:17], v48 offset:24576
	ds_read_b128 v[56:59], v56
	ds_read_b128 v[48:51], v48 offset:28672
	ds_read_b128 v[52:55], v60 offset:16384
	s_waitcnt lgkmcnt(0)
	v_mfma_f32_16x16x32_bf16 v[2:5], v[2:5], v[6:9], 0
	v_mfma_f32_16x16x32_bf16 v[10:13], v[10:13], v[6:9], 0
	v_mfma_f32_16x16x32_bf16 v[14:17], v[14:17], v[6:9], 0
	v_mfma_f32_16x16x32_bf16 v[6:9], v[48:51], v[6:9], 0
	ds_read_b128 v[48:51], v60 offset:20480
	v_mfma_f32_16x16x32_bf16 v[2:5], v[52:55], v[56:59], v[2:5]
	ds_read_b128 v[52:55], v60 offset:24576
	s_waitcnt lgkmcnt(0)
	v_mfma_f32_16x16x32_bf16 v[10:13], v[48:51], v[56:59], v[10:13]
	ds_read_b128 v[48:51], v60 offset:28672
	v_mfma_f32_16x16x32_bf16 v[14:17], v[52:55], v[56:59], v[14:17]
	ds_read_b128 v[52:55], v64 offset:16384
	v_add_u32_e32 v60, v79, v142
	ds_read_b128 v[60:63], v60
	s_waitcnt lgkmcnt(0)
	v_mfma_f32_16x16x32_bf16 v[6:9], v[48:51], v[56:59], v[6:9]
	ds_read_b128 v[48:51], v64 offset:20480
	v_add_u32_e32 v56, v79, v143
	ds_read_b128 v[56:59], v56
	v_mfma_f32_16x16x32_bf16 v[2:5], v[52:55], v[60:63], v[2:5]
	ds_read_b128 v[52:55], v64 offset:24576
	s_waitcnt lgkmcnt(0)
	v_mfma_f32_16x16x32_bf16 v[10:13], v[48:51], v[60:63], v[10:13]
	ds_read_b128 v[48:51], v64 offset:28672
	v_add_u32_e32 v64, v78, v143
	v_mfma_f32_16x16x32_bf16 v[14:17], v[52:55], v[60:63], v[14:17]
	ds_read_b128 v[52:55], v64 offset:16384
	s_waitcnt lgkmcnt(0)
	v_mfma_f32_16x16x32_bf16 v[6:9], v[48:51], v[60:63], v[6:9]
	ds_read_b128 v[48:51], v64 offset:20480
	v_mfma_f32_16x16x32_bf16 v[2:5], v[52:55], v[56:59], v[2:5]
	ds_read_b128 v[52:55], v64 offset:24576
	s_waitcnt lgkmcnt(0)
	v_mfma_f32_16x16x32_bf16 v[10:13], v[48:51], v[56:59], v[10:13]
	ds_read_b128 v[48:51], v64 offset:28672
	s_nop 3
	v_cndmask_b32_e64 v2, 0, v2, s[0:1]
	v_readlane_b32 s0, v255, 10
	v_readlane_b32 s1, v255, 11
	s_xor_b64 s[0:1], s[0:1], s[88:89]
	v_mfma_f32_16x16x32_bf16 v[14:17], v[52:55], v[56:59], v[14:17]
	v_cndmask_b32_e64 v3, 0, v3, s[0:1]
	v_readlane_b32 s0, v255, 12
	v_readlane_b32 s1, v255, 13
	s_xor_b64 s[0:1], s[0:1], s[88:89]
	v_cvt_pk_bf16_f32 v2, v2, v3
	v_cndmask_b32_e64 v4, 0, v4, s[0:1]
	v_readlane_b32 s0, v255, 14
	v_readlane_b32 s1, v255, 15
	s_xor_b64 s[0:1], s[0:1], s[88:89]
	s_waitcnt lgkmcnt(0)
	v_mfma_f32_16x16x32_bf16 v[6:9], v[48:51], v[56:59], v[6:9]
	v_cndmask_b32_e64 v5, 0, v5, s[0:1]
	v_cvt_pk_bf16_f32 v3, v4, v5
	s_xor_b64 s[0:1], s[54:55], s[88:89]
	global_store_dwordx2 v[46:47], v[2:3], off
	v_cndmask_b32_e64 v2, 0, v10, s[0:1]
	s_xor_b64 s[0:1], s[56:57], s[88:89]
	v_cndmask_b32_e64 v3, 0, v11, s[0:1]
	s_xor_b64 s[0:1], s[22:23], s[88:89]
	v_cndmask_b32_e64 v4, 0, v12, s[0:1]
	s_xor_b64 s[0:1], s[24:25], s[88:89]
	v_cndmask_b32_e64 v5, 0, v13, s[0:1]
	v_cvt_pk_bf16_f32 v2, v2, v3
	v_cvt_pk_bf16_f32 v3, v4, v5
	s_xor_b64 s[0:1], s[26:27], s[88:89]
	global_store_dwordx2 v[46:47], v[2:3], off offset:32
	v_cndmask_b32_e64 v2, 0, v14, s[0:1]
	s_xor_b64 s[0:1], s[28:29], s[88:89]
	v_cndmask_b32_e64 v3, 0, v15, s[0:1]
	s_xor_b64 s[0:1], s[76:77], s[88:89]
	v_cndmask_b32_e64 v4, 0, v16, s[0:1]
	s_xor_b64 s[0:1], s[42:43], s[88:89]
	v_cndmask_b32_e64 v5, 0, v17, s[0:1]
	v_cvt_pk_bf16_f32 v2, v2, v3
	v_cvt_pk_bf16_f32 v3, v4, v5
	s_xor_b64 s[0:1], s[80:81], s[88:89]
	global_store_dwordx2 v[46:47], v[2:3], off offset:64
	v_cndmask_b32_e64 v2, 0, v6, s[0:1]
	s_xor_b64 s[0:1], s[82:83], s[88:89]
	v_cndmask_b32_e64 v3, 0, v7, s[0:1]
	s_xor_b64 s[0:1], s[40:41], s[88:89]
	v_cndmask_b32_e64 v4, 0, v8, s[0:1]
	s_xor_b64 s[0:1], vcc, s[88:89]
	s_add_u32 s58, s58, s34
	v_cndmask_b32_e64 v5, 0, v9, s[0:1]
	s_addc_u32 s59, s59, s35
	s_add_i32 s44, s44, s45
	v_cvt_pk_bf16_f32 v2, v2, v3
	v_cvt_pk_bf16_f32 v3, v4, v5
	s_cmpk_gt_i32 s58, 0x8ff
	global_store_dwordx2 v[46:47], v[2:3], off offset:96
	s_cbranch_scc1 .LBB0_231
.LBB0_225:
	s_ashr_i32 s0, s58, 3
	s_mul_hi_i32 s1, s0, 0x38e38e39
	s_lshr_b32 s4, s1, 31
	s_ashr_i32 s1, s1, 3
	s_add_i32 s1, s1, s4
	s_mul_i32 s4, s1, 36
	s_sub_i32 s21, s0, s4
	s_lshl_b32 s0, s21, 6
	s_mul_hi_i32 s4, s1, 0x900
	s_mulk_i32 s1, 0x900
	s_ashr_i32 s5, s0, 31
	s_add_u32 s0, s1, s0
	s_addc_u32 s1, s4, s5
	v_lshl_add_u64 v[10:11], s[0:1], 0, v[28:29]
	s_and_b32 s4, s44, 0x180
	v_lshlrev_b64 v[2:3], 11, v[10:11]
	v_lshl_add_u64 v[2:3], s[46:47], 0, v[2:3]
	s_lshl_b32 s92, s4, 1
	v_lshl_add_u64 v[2:3], v[2:3], 0, s[92:93]
	v_lshl_add_u64 v[6:7], v[2:3], 0, v[0:1]
	s_waitcnt lgkmcnt(0)
	s_barrier
	global_load_dwordx4 v[2:5], v[6:7], off
	s_nop 0
	global_load_dwordx4 v[6:9], v[6:7], off offset:1024
	v_lshl_add_u64 v[12:13], s[0:1], 0, v[30:31]
	v_lshl_add_u64 v[14:15], s[0:1], 0, v[32:33]
	v_lshl_add_u64 v[16:17], s[0:1], 0, v[34:35]
	s_and_b32 s90, s58, 1
	s_or_b32 s88, s90, s2
	s_ashr_i32 s89, s88, 31
	v_readlane_b32 s60, v253, 20
	s_lshl_b64 s[0:1], s[88:89], 15
	v_readlane_b32 s66, v253, 26
	v_readlane_b32 s67, v253, 27
	v_readlane_b32 s68, v253, 28
	v_readlane_b32 s69, v253, 29
	v_readlane_b32 s61, v253, 21
	v_readlane_b32 s62, v253, 22
	v_readlane_b32 s63, v253, 23
	v_readlane_b32 s64, v253, 24
	v_readlane_b32 s65, v253, 25
	v_readlane_b32 s70, v253, 30
	v_readlane_b32 s71, v253, 31
	v_readlane_b32 s72, v253, 32
	v_readlane_b32 s73, v253, 33
	v_readlane_b32 s74, v253, 34
	v_readlane_b32 s75, v253, 35
	s_waitcnt vmcnt(0) lgkmcnt(0)
	ds_write_b128 v82, v[2:5]
	ds_write_b128 v82, v[6:9] offset:16384
	v_lshlrev_b64 v[2:3], 11, v[12:13]
	v_lshl_add_u64 v[2:3], s[46:47], 0, v[2:3]
	v_lshl_add_u64 v[2:3], v[2:3], 0, s[92:93]
	v_lshl_add_u64 v[6:7], v[2:3], 0, v[0:1]
	global_load_dwordx4 v[2:5], v[6:7], off
	s_nop 0
	global_load_dwordx4 v[6:9], v[6:7], off offset:1024
	s_waitcnt vmcnt(0) lgkmcnt(0)
	ds_write_b128 v85, v[2:5]
	ds_write_b128 v85, v[6:9] offset:16384
	v_lshlrev_b64 v[2:3], 11, v[14:15]
	v_lshl_add_u64 v[2:3], s[46:47], 0, v[2:3]
	v_lshl_add_u64 v[2:3], v[2:3], 0, s[92:93]
	v_lshl_add_u64 v[6:7], v[2:3], 0, v[0:1]
	global_load_dwordx4 v[2:5], v[6:7], off
	s_nop 0
	global_load_dwordx4 v[6:9], v[6:7], off offset:1024
	s_waitcnt vmcnt(0) lgkmcnt(0)
	ds_write_b128 v88, v[2:5]
	ds_write_b128 v88, v[6:9] offset:16384
	v_lshlrev_b64 v[2:3], 11, v[16:17]
	v_lshl_add_u64 v[2:3], s[46:47], 0, v[2:3]
	v_lshl_add_u64 v[2:3], v[2:3], 0, s[92:93]
	v_lshl_add_u64 v[6:7], v[2:3], 0, v[0:1]
	global_load_dwordx4 v[2:5], v[6:7], off
	s_nop 0
	global_load_dwordx4 v[6:9], v[6:7], off offset:1024
	s_lshl_b32 s92, s90, 5
	s_add_u32 s0, s66, s0
	s_addc_u32 s1, s67, s1
	s_lshl_b32 s5, s4, 2
	s_add_u32 s0, s0, s5
	s_addc_u32 s1, s1, 0
	s_waitcnt vmcnt(0) lgkmcnt(0)
	ds_write_b128 v91, v[2:5]
	ds_write_b128 v91, v[6:9] offset:16384
	v_lshl_add_u64 v[2:3], v[24:25], 0, s[92:93]
	v_lshlrev_b64 v[4:5], 6, v[10:11]
	v_lshl_add_u64 v[4:5], v[2:3], 0, v[4:5]
	global_load_ushort v4, v[4:5], off
	s_waitcnt vmcnt(0) lgkmcnt(0)
	v_lshlrev_b32_e32 v6, 16, v4
	v_lshlrev_b64 v[4:5], 6, v[12:13]
	v_lshl_add_u64 v[4:5], v[2:3], 0, v[4:5]
	global_load_ushort v4, v[4:5], off
	s_waitcnt vmcnt(0) lgkmcnt(0)
	v_lshlrev_b32_e32 v4, 16, v4
	ds_write2st64_b32 v18, v6, v4 offset0:128 offset1:132
	v_lshlrev_b64 v[4:5], 6, v[14:15]
	v_lshl_add_u64 v[4:5], v[2:3], 0, v[4:5]
	global_load_ushort v4, v[4:5], off
	s_waitcnt vmcnt(0) lgkmcnt(0)
	v_lshlrev_b32_e32 v6, 16, v4
	v_lshlrev_b64 v[4:5], 6, v[16:17]
	v_lshl_add_u64 v[2:3], v[2:3], 0, v[4:5]
	global_load_ushort v2, v[2:3], off
	v_mov_b32_e32 v3, v1
	s_waitcnt vmcnt(0) lgkmcnt(0)
	v_lshlrev_b32_e32 v2, 16, v2
	ds_write2st64_b32 v18, v6, v2 offset0:136 offset1:140
	v_lshlrev_b32_e32 v2, 2, v20
	v_lshl_add_u64 v[4:5], s[0:1], 0, v[2:3]
	global_load_dword v60, v2, s[0:1]
	global_load_dword v61, v2, s[0:1] offset:256
	global_load_dword v62, v2, s[0:1] offset:2048
	global_load_dword v63, v2, s[0:1] offset:2304
	v_add_co_u32_e64 v2, s[0:1], s85, v4
	s_nop 1
	v_addc_co_u32_e64 v3, s[0:1], 0, v5, s[0:1]
	v_add_co_u32_e64 v6, s[0:1], s37, v4
	s_nop 1
	v_addc_co_u32_e64 v7, s[0:1], 0, v5, s[0:1]
	global_load_dword v64, v[6:7], off offset:-4096
	global_load_dword v65, v[2:3], off offset:256
	global_load_dword v66, v[2:3], off offset:2048
	global_load_dword v67, v[2:3], off offset:2304
	global_load_dword v47, v[6:7], off
	global_load_dword v46, v[6:7], off offset:256
	global_load_dword v17, v[6:7], off offset:2048
	global_load_dword v16, v[6:7], off offset:2304
	v_add_co_u32_e64 v2, s[0:1], s33, v4
	s_nop 1
	v_addc_co_u32_e64 v3, s[0:1], 0, v5, s[0:1]
	s_movk_i32 s0, 0x4000
	s_nop 0
	v_add_co_u32_e64 v6, s[0:1], s0, v4
	s_nop 1
	v_addc_co_u32_e64 v7, s[0:1], 0, v5, s[0:1]
	s_movk_i32 s0, 0x5000
	global_load_dword v52, v[6:7], off offset:-4096
	global_load_dword v53, v[2:3], off offset:256
	global_load_dword v54, v[2:3], off offset:2048
	global_load_dword v55, v[2:3], off offset:2304
	global_load_dword v48, v[6:7], off
	global_load_dword v49, v[6:7], off offset:256
	global_load_dword v50, v[6:7], off offset:2048
	global_load_dword v51, v[6:7], off offset:2304
	v_add_co_u32_e64 v2, s[0:1], s0, v4
	s_nop 1
	v_addc_co_u32_e64 v3, s[0:1], 0, v5, s[0:1]
	s_movk_i32 s0, 0x6000
	s_nop 0
	v_add_co_u32_e64 v8, s[0:1], s0, v4
	s_nop 1
	v_addc_co_u32_e64 v9, s[0:1], 0, v5, s[0:1]
	s_movk_i32 s0, 0x7000
	global_load_dword v56, v[8:9], off offset:-4096
	global_load_dword v57, v[2:3], off offset:256
	global_load_dword v58, v[2:3], off offset:2048
	global_load_dword v59, v[2:3], off offset:2304
	global_load_dword v12, v[8:9], off
	global_load_dword v13, v[8:9], off offset:256
	global_load_dword v6, v[8:9], off offset:2048
	global_load_dword v7, v[8:9], off offset:2304
	v_add_co_u32_e64 v2, s[0:1], s0, v4
	s_nop 1
	v_addc_co_u32_e64 v3, s[0:1], 0, v5, s[0:1]
	s_lshl_b32 s0, s88, 9
	s_or_b32 s0, s0, s4
	global_load_dword v14, v[2:3], off
	global_load_dword v15, v[2:3], off offset:256
	global_load_dword v9, v[2:3], off offset:2048
	global_load_dword v10, v[2:3], off offset:2304
	v_or_b32_e32 v2, s0, v20
	v_ashrrev_i32_e32 v3, 31, v2
	v_lshl_add_u64 v[2:3], v[2:3], 2, s[68:69]
	global_load_dword v69, v[2:3], off
	global_load_dword v68, v[2:3], off offset:256
	s_waitcnt lgkmcnt(0)
	s_barrier
	ds_read_b128 v[2:5], v19 offset:32768
	ds_read_b128 v[156:159], v19 offset:32784
	ds_read_b128 v[160:163], v19 offset:32800
	ds_read_b128 v[164:167], v19 offset:32816
	s_waitcnt vmcnt(1) lgkmcnt(3)
	v_fma_f32 v8, v60, v2, v69
	v_fmac_f32_e32 v8, v62, v3
	v_fmac_f32_e32 v8, v64, v4
	v_fmac_f32_e32 v8, v66, v5
	s_waitcnt lgkmcnt(2)
	v_fmac_f32_e32 v8, v47, v156
	v_fmac_f32_e32 v8, v17, v157
	v_fmac_f32_e32 v8, v52, v158
	v_fmac_f32_e32 v8, v54, v159
	s_waitcnt lgkmcnt(1)
	v_fmac_f32_e32 v8, v48, v160
	v_fmac_f32_e32 v8, v50, v161
	v_fmac_f32_e32 v8, v56, v162
	v_fmac_f32_e32 v8, v58, v163
	s_waitcnt lgkmcnt(0)
	v_fmac_f32_e32 v8, v12, v164
	v_fmac_f32_e32 v8, v6, v165
	s_waitcnt vmcnt(0)
	v_fma_f32 v2, v61, v2, v68
	v_fmac_f32_e32 v8, v14, v166
	v_fmac_f32_e32 v2, v63, v3
	v_fmac_f32_e32 v8, v9, v167
	v_fmac_f32_e32 v2, v65, v4
	v_mul_f32_e64 v4, |v8|, s84
	v_exp_f32_e32 v4, v4
	v_fmac_f32_e32 v2, v67, v5
	v_fmac_f32_e32 v2, v46, v156
	v_fmac_f32_e32 v2, v16, v157
	v_add_f32_e32 v4, 1.0, v4
	v_cmp_gt_f32_e64 s[0:1], s31, v4
	v_fmac_f32_e32 v2, v53, v158
	v_fmac_f32_e32 v2, v55, v159
	v_cndmask_b32_e64 v5, 0, 32, s[0:1]
	v_ldexp_f32 v4, v4, v5
	v_log_f32_e32 v4, v4
	v_fmac_f32_e32 v2, v49, v160
	v_fmac_f32_e32 v2, v51, v161
	v_fmac_f32_e32 v2, v57, v162
	v_mul_f32_e32 v5, 0x3f317217, v4
	v_fmac_f32_e32 v2, v59, v163
	v_fma_f32 v5, v4, s78, -v5
	v_fmac_f32_e32 v2, v13, v164
	v_fmac_f32_e32 v5, 0x3377d1cf, v4
	v_fmac_f32_e32 v2, v7, v165
	v_fmac_f32_e32 v5, 0x3f317217, v4
	v_cmp_lt_f32_e64 s[88:89], |v4|, s79
	v_fmac_f32_e32 v2, v15, v166
	v_fmac_f32_e32 v2, v10, v167
	v_cndmask_b32_e64 v4, v4, v5, s[88:89]
	v_cndmask_b32_e64 v5, 0, v198, s[0:1]
	v_min_f32_e32 v3, 0, v8
	v_sub_f32_e32 v4, v4, v5
	v_sub_f32_e32 v70, v3, v4
	v_min_f32_e32 v3, 0, v2
	v_mul_f32_e64 v2, |v2|, s84
	v_exp_f32_e32 v2, v2
	v_fma_f32 v11, v70, s10, 0
	v_add_f32_e32 v2, 1.0, v2
	v_cmp_gt_f32_e64 s[0:1], s31, v2
	s_nop 1
	v_cndmask_b32_e64 v4, 0, 32, s[0:1]
	v_ldexp_f32 v2, v2, v4
	v_log_f32_e32 v2, v2
	s_nop 0
	v_mul_f32_e32 v4, 0x3f317217, v2
	v_fma_f32 v4, v2, s78, -v4
	v_fmac_f32_e32 v4, 0x3377d1cf, v2
	v_fmac_f32_e32 v4, 0x3f317217, v2
	v_cmp_lt_f32_e64 s[88:89], |v2|, s79
	s_nop 1
	v_cndmask_b32_e64 v2, v2, v4, s[88:89]
	v_cndmask_b32_e64 v4, 0, v198, s[0:1]
	v_sub_f32_e32 v2, v2, v4
	v_sub_f32_e32 v71, v3, v2
	ds_read_b128 v[2:5], v19 offset:32832
	v_fma_f32 v8, v71, s10, 0
	s_waitcnt lgkmcnt(0)
	v_fma_f32 v155, v60, v2, v69
	v_fma_f32 v156, v61, v2, v68
	v_fmac_f32_e32 v155, v62, v3
	v_fmac_f32_e32 v156, v63, v3
	v_fmac_f32_e32 v155, v64, v4
	v_fmac_f32_e32 v156, v65, v4
	v_fmac_f32_e32 v155, v66, v5
	v_fmac_f32_e32 v156, v67, v5
	ds_read_b128 v[2:5], v19 offset:32848
	s_waitcnt lgkmcnt(0)
	v_fmac_f32_e32 v155, v47, v2
	v_fmac_f32_e32 v156, v46, v2
	v_fmac_f32_e32 v155, v17, v3
	v_fmac_f32_e32 v156, v16, v3
	v_fmac_f32_e32 v155, v52, v4
	v_fmac_f32_e32 v156, v53, v4
	v_fmac_f32_e32 v155, v54, v5
	v_fmac_f32_e32 v156, v55, v5
	ds_read_b128 v[2:5], v19 offset:32864
	s_waitcnt lgkmcnt(0)
	v_fmac_f32_e32 v155, v48, v2
	v_fmac_f32_e32 v156, v49, v2
	v_fmac_f32_e32 v155, v50, v3
	v_fmac_f32_e32 v156, v51, v3
	v_fmac_f32_e32 v155, v56, v4
	v_fmac_f32_e32 v156, v57, v4
	v_fmac_f32_e32 v155, v58, v5
	v_fmac_f32_e32 v156, v59, v5
	ds_read_b128 v[2:5], v19 offset:32880
	s_waitcnt lgkmcnt(0)
	v_fmac_f32_e32 v155, v12, v2
	v_fmac_f32_e32 v155, v6, v3
	v_fmac_f32_e32 v155, v14, v4
	v_fmac_f32_e32 v156, v13, v2
	v_fmac_f32_e32 v155, v9, v5
	v_fmac_f32_e32 v156, v7, v3
	v_mul_f32_e64 v3, |v155|, s84
	v_exp_f32_e32 v3, v3
	v_fmac_f32_e32 v156, v15, v4
	v_fmac_f32_e32 v156, v10, v5
	v_min_f32_e32 v2, 0, v155
	v_add_f32_e32 v3, 1.0, v3
	v_cmp_gt_f32_e64 s[0:1], s31, v3
	s_nop 1
	v_cndmask_b32_e64 v4, 0, 32, s[0:1]
	v_ldexp_f32 v3, v3, v4
	v_log_f32_e32 v3, v3
	s_nop 0
	v_mul_f32_e32 v4, 0x3f317217, v3
	v_fma_f32 v4, v3, s78, -v4
	v_fmac_f32_e32 v4, 0x3377d1cf, v3
	v_fmac_f32_e32 v4, 0x3f317217, v3
	v_cmp_lt_f32_e64 s[88:89], |v3|, s79
	s_nop 1
	v_cndmask_b32_e64 v3, v3, v4, s[88:89]
	v_cndmask_b32_e64 v4, 0, v198, s[0:1]
	v_sub_f32_e32 v3, v3, v4
	v_sub_f32_e32 v159, v2, v3
	v_mul_f32_e64 v3, |v156|, s84
	v_exp_f32_e32 v3, v3
	v_min_f32_e32 v2, 0, v156
	v_fmamk_f32 v156, v159, 0x3d800000, v11
	v_add_f32_e32 v3, 1.0, v3
	v_cmp_gt_f32_e64 s[0:1], s31, v3
	s_nop 1
	v_cndmask_b32_e64 v4, 0, 32, s[0:1]
	v_ldexp_f32 v3, v3, v4
	v_log_f32_e32 v3, v3
	s_nop 0
	v_mul_f32_e32 v4, 0x3f317217, v3
	v_fma_f32 v4, v3, s78, -v4
	v_fmac_f32_e32 v4, 0x3377d1cf, v3
	v_fmac_f32_e32 v4, 0x3f317217, v3
	v_cmp_lt_f32_e64 s[88:89], |v3|, s79
	s_nop 1
	v_cndmask_b32_e64 v3, v3, v4, s[88:89]
	v_cndmask_b32_e64 v4, 0, v198, s[0:1]
	v_sub_f32_e32 v3, v3, v4
	v_sub_f32_e32 v160, v2, v3
	ds_read_b128 v[2:5], v19 offset:32896
	v_fmamk_f32 v155, v160, 0x3d800000, v8
	s_waitcnt lgkmcnt(0)
	v_fma_f32 v157, v60, v2, v69
	v_fma_f32 v158, v61, v2, v68
	v_fmac_f32_e32 v157, v62, v3
	v_fmac_f32_e32 v158, v63, v3
	v_fmac_f32_e32 v157, v64, v4
	v_fmac_f32_e32 v158, v65, v4
	v_fmac_f32_e32 v157, v66, v5
	v_fmac_f32_e32 v158, v67, v5
	ds_read_b128 v[2:5], v19 offset:32912
	s_waitcnt lgkmcnt(0)
	v_fmac_f32_e32 v157, v47, v2
	v_fmac_f32_e32 v158, v46, v2
	v_fmac_f32_e32 v157, v17, v3
	v_fmac_f32_e32 v158, v16, v3
	v_fmac_f32_e32 v157, v52, v4
	v_fmac_f32_e32 v158, v53, v4
	v_fmac_f32_e32 v157, v54, v5
	v_fmac_f32_e32 v158, v55, v5
	ds_read_b128 v[2:5], v19 offset:32928
	s_waitcnt lgkmcnt(0)
	v_fmac_f32_e32 v157, v48, v2
	v_fmac_f32_e32 v158, v49, v2
	v_fmac_f32_e32 v157, v50, v3
	v_fmac_f32_e32 v158, v51, v3
	v_fmac_f32_e32 v157, v56, v4
	v_fmac_f32_e32 v158, v57, v4
	v_fmac_f32_e32 v157, v58, v5
	v_fmac_f32_e32 v158, v59, v5
	ds_read_b128 v[2:5], v19 offset:32944
	s_waitcnt lgkmcnt(0)
	v_fmac_f32_e32 v157, v12, v2
	v_fmac_f32_e32 v157, v6, v3
	v_fmac_f32_e32 v157, v14, v4
	v_fmac_f32_e32 v158, v13, v2
	v_fmac_f32_e32 v157, v9, v5
	v_fmac_f32_e32 v158, v7, v3
	v_mul_f32_e64 v3, |v157|, s84
	v_exp_f32_e32 v3, v3
	v_fmac_f32_e32 v158, v15, v4
	v_fmac_f32_e32 v158, v10, v5
	v_min_f32_e32 v2, 0, v157
	v_add_f32_e32 v3, 1.0, v3
	v_cmp_gt_f32_e64 s[0:1], s31, v3
	s_nop 1
	v_cndmask_b32_e64 v4, 0, 32, s[0:1]
	v_ldexp_f32 v3, v3, v4
	v_log_f32_e32 v3, v3
	s_nop 0
	v_mul_f32_e32 v4, 0x3f317217, v3
	v_fma_f32 v4, v3, s78, -v4
	v_fmac_f32_e32 v4, 0x3377d1cf, v3
	v_fmac_f32_e32 v4, 0x3f317217, v3
	v_cmp_lt_f32_e64 s[88:89], |v3|, s79
	s_nop 1
	v_cndmask_b32_e64 v3, v3, v4, s[88:89]
	v_cndmask_b32_e64 v4, 0, v198, s[0:1]
	v_sub_f32_e32 v3, v3, v4
	v_sub_f32_e32 v163, v2, v3
	v_mul_f32_e64 v3, |v158|, s84
	v_exp_f32_e32 v3, v3
	v_min_f32_e32 v2, 0, v158
	v_fmamk_f32 v158, v163, 0x3d800000, v156
	v_add_f32_e32 v3, 1.0, v3
	v_cmp_gt_f32_e64 s[0:1], s31, v3
	s_nop 1
	v_cndmask_b32_e64 v4, 0, 32, s[0:1]
	v_ldexp_f32 v3, v3, v4
	v_log_f32_e32 v3, v3
	s_nop 0
	v_mul_f32_e32 v4, 0x3f317217, v3
	v_fma_f32 v4, v3, s78, -v4
	v_fmac_f32_e32 v4, 0x3377d1cf, v3
	v_fmac_f32_e32 v4, 0x3f317217, v3
	v_cmp_lt_f32_e64 s[88:89], |v3|, s79
	s_nop 1
	v_cndmask_b32_e64 v3, v3, v4, s[88:89]
	v_cndmask_b32_e64 v4, 0, v198, s[0:1]
	v_sub_f32_e32 v3, v3, v4
	v_sub_f32_e32 v164, v2, v3
	ds_read_b128 v[2:5], v19 offset:32960
	v_fmamk_f32 v157, v164, 0x3d800000, v155
	s_waitcnt lgkmcnt(0)
	v_fma_f32 v161, v60, v2, v69
	v_fma_f32 v162, v61, v2, v68
	v_fmac_f32_e32 v161, v62, v3
	v_fmac_f32_e32 v162, v63, v3
	v_fmac_f32_e32 v161, v64, v4
	v_fmac_f32_e32 v162, v65, v4
	v_fmac_f32_e32 v161, v66, v5
	v_fmac_f32_e32 v162, v67, v5
	ds_read_b128 v[2:5], v19 offset:32976
	s_waitcnt lgkmcnt(0)
	v_fmac_f32_e32 v161, v47, v2
	v_fmac_f32_e32 v162, v46, v2
	v_fmac_f32_e32 v161, v17, v3
	v_fmac_f32_e32 v162, v16, v3
	v_fmac_f32_e32 v161, v52, v4
	v_fmac_f32_e32 v162, v53, v4
	v_fmac_f32_e32 v161, v54, v5
	v_fmac_f32_e32 v162, v55, v5
	ds_read_b128 v[2:5], v19 offset:32992
	s_waitcnt lgkmcnt(0)
	v_fmac_f32_e32 v161, v48, v2
	v_fmac_f32_e32 v162, v49, v2
	v_fmac_f32_e32 v161, v50, v3
	v_fmac_f32_e32 v162, v51, v3
	v_fmac_f32_e32 v161, v56, v4
	v_fmac_f32_e32 v162, v57, v4
	v_fmac_f32_e32 v161, v58, v5
	v_fmac_f32_e32 v162, v59, v5
	ds_read_b128 v[2:5], v19 offset:33008
	s_waitcnt lgkmcnt(0)
	v_fmac_f32_e32 v161, v12, v2
	v_fmac_f32_e32 v161, v6, v3
	v_fmac_f32_e32 v161, v14, v4
	v_fmac_f32_e32 v162, v13, v2
	v_fmac_f32_e32 v161, v9, v5
	v_fmac_f32_e32 v162, v7, v3
	v_mul_f32_e64 v3, |v161|, s84
	v_exp_f32_e32 v3, v3
	v_fmac_f32_e32 v162, v15, v4
	v_fmac_f32_e32 v162, v10, v5
	v_min_f32_e32 v2, 0, v161
	v_add_f32_e32 v3, 1.0, v3
	v_cmp_gt_f32_e64 s[0:1], s31, v3
	s_nop 1
	v_cndmask_b32_e64 v4, 0, 32, s[0:1]
	v_ldexp_f32 v3, v3, v4
	v_log_f32_e32 v3, v3
	s_nop 0
	v_mul_f32_e32 v4, 0x3f317217, v3
	v_fma_f32 v4, v3, s78, -v4
	v_fmac_f32_e32 v4, 0x3377d1cf, v3
	v_fmac_f32_e32 v4, 0x3f317217, v3
	v_cmp_lt_f32_e64 s[88:89], |v3|, s79
	s_nop 1
	v_cndmask_b32_e64 v3, v3, v4, s[88:89]
	v_cndmask_b32_e64 v4, 0, v198, s[0:1]
	v_sub_f32_e32 v3, v3, v4
	v_sub_f32_e32 v165, v2, v3
	v_mul_f32_e64 v3, |v162|, s84
	v_exp_f32_e32 v3, v3
	v_min_f32_e32 v2, 0, v162
	v_fmamk_f32 v162, v165, 0x3d800000, v158
	v_add_f32_e32 v3, 1.0, v3
	v_cmp_gt_f32_e64 s[0:1], s31, v3
	s_nop 1
	v_cndmask_b32_e64 v4, 0, 32, s[0:1]
	v_ldexp_f32 v3, v3, v4
	v_log_f32_e32 v3, v3
	s_nop 0
	v_mul_f32_e32 v4, 0x3f317217, v3
	v_fma_f32 v4, v3, s78, -v4
	v_fmac_f32_e32 v4, 0x3377d1cf, v3
	v_fmac_f32_e32 v4, 0x3f317217, v3
	v_cmp_lt_f32_e64 s[88:89], |v3|, s79
	s_nop 1
	v_cndmask_b32_e64 v3, v3, v4, s[88:89]
	v_cndmask_b32_e64 v4, 0, v198, s[0:1]
	v_sub_f32_e32 v3, v3, v4
	v_sub_f32_e32 v166, v2, v3
	ds_read_b128 v[2:5], v19 offset:33024
	v_fmamk_f32 v161, v166, 0x3d800000, v157
	s_waitcnt lgkmcnt(0)
	v_fma_f32 v168, v60, v2, v69
	v_fma_f32 v167, v61, v2, v68
	v_fmac_f32_e32 v168, v62, v3
	v_fmac_f32_e32 v167, v63, v3
	v_fmac_f32_e32 v168, v64, v4
	v_fmac_f32_e32 v167, v65, v4
	v_fmac_f32_e32 v168, v66, v5
	v_fmac_f32_e32 v167, v67, v5
	ds_read_b128 v[2:5], v19 offset:33040
	s_waitcnt lgkmcnt(0)
	v_fmac_f32_e32 v168, v47, v2
	v_fmac_f32_e32 v167, v46, v2
	v_fmac_f32_e32 v168, v17, v3
	v_fmac_f32_e32 v167, v16, v3
	v_fmac_f32_e32 v168, v52, v4
	v_fmac_f32_e32 v167, v53, v4
	v_fmac_f32_e32 v168, v54, v5
	v_fmac_f32_e32 v167, v55, v5
	ds_read_b128 v[2:5], v19 offset:33056
	s_waitcnt lgkmcnt(0)
	v_fmac_f32_e32 v168, v48, v2
	v_fmac_f32_e32 v167, v49, v2
	v_fmac_f32_e32 v168, v50, v3
	v_fmac_f32_e32 v167, v51, v3
	v_fmac_f32_e32 v168, v56, v4
	v_fmac_f32_e32 v167, v57, v4
	v_fmac_f32_e32 v168, v58, v5
	v_fmac_f32_e32 v167, v59, v5
	ds_read_b128 v[2:5], v19 offset:33072
	s_waitcnt lgkmcnt(0)
	v_fmac_f32_e32 v168, v12, v2
	v_fmac_f32_e32 v168, v6, v3
	v_fmac_f32_e32 v168, v14, v4
	v_fmac_f32_e32 v167, v13, v2
	v_fmac_f32_e32 v168, v9, v5
	v_fmac_f32_e32 v167, v7, v3
	v_mul_f32_e64 v3, |v168|, s84
	v_exp_f32_e32 v3, v3
	v_fmac_f32_e32 v167, v15, v4
	v_fmac_f32_e32 v167, v10, v5
	v_min_f32_e32 v2, 0, v168
	v_add_f32_e32 v3, 1.0, v3
	v_cmp_gt_f32_e64 s[0:1], s31, v3
	s_nop 1
	v_cndmask_b32_e64 v4, 0, 32, s[0:1]
	v_ldexp_f32 v3, v3, v4
	v_log_f32_e32 v3, v3
	s_nop 0
	v_mul_f32_e32 v4, 0x3f317217, v3
	v_fma_f32 v4, v3, s78, -v4
	v_fmac_f32_e32 v4, 0x3377d1cf, v3
	v_fmac_f32_e32 v4, 0x3f317217, v3
	v_cmp_lt_f32_e64 s[88:89], |v3|, s79
	s_nop 1
	v_cndmask_b32_e64 v3, v3, v4, s[88:89]
	v_cndmask_b32_e64 v4, 0, v198, s[0:1]
	v_sub_f32_e32 v3, v3, v4
	v_sub_f32_e32 v171, v2, v3
	v_mul_f32_e64 v3, |v167|, s84
	v_exp_f32_e32 v3, v3
	v_min_f32_e32 v2, 0, v167
	v_fmamk_f32 v168, v171, 0x3d800000, v162
	v_add_f32_e32 v3, 1.0, v3
	v_cmp_gt_f32_e64 s[0:1], s31, v3
	s_nop 1
	v_cndmask_b32_e64 v4, 0, 32, s[0:1]
	v_ldexp_f32 v3, v3, v4
	v_log_f32_e32 v3, v3
	s_nop 0
	v_mul_f32_e32 v4, 0x3f317217, v3
	v_fma_f32 v4, v3, s78, -v4
	v_fmac_f32_e32 v4, 0x3377d1cf, v3
	v_fmac_f32_e32 v4, 0x3f317217, v3
	v_cmp_lt_f32_e64 s[88:89], |v3|, s79
	s_nop 1
	v_cndmask_b32_e64 v3, v3, v4, s[88:89]
	v_cndmask_b32_e64 v4, 0, v198, s[0:1]
	v_sub_f32_e32 v3, v3, v4
	v_sub_f32_e32 v174, v2, v3
	ds_read_b128 v[2:5], v19 offset:33088
	v_fmamk_f32 v167, v174, 0x3d800000, v161
	s_waitcnt lgkmcnt(0)
	v_fma_f32 v169, v60, v2, v69
	v_fma_f32 v170, v61, v2, v68
	v_fmac_f32_e32 v169, v62, v3
	v_fmac_f32_e32 v170, v63, v3
	v_fmac_f32_e32 v169, v64, v4
	v_fmac_f32_e32 v170, v65, v4
	v_fmac_f32_e32 v169, v66, v5
	v_fmac_f32_e32 v170, v67, v5
	ds_read_b128 v[2:5], v19 offset:33104
	s_waitcnt lgkmcnt(0)
	v_fmac_f32_e32 v169, v47, v2
	v_fmac_f32_e32 v170, v46, v2
	v_fmac_f32_e32 v169, v17, v3
	v_fmac_f32_e32 v170, v16, v3
	v_fmac_f32_e32 v169, v52, v4
	v_fmac_f32_e32 v170, v53, v4
	v_fmac_f32_e32 v169, v54, v5
	v_fmac_f32_e32 v170, v55, v5
	ds_read_b128 v[2:5], v19 offset:33120
	s_waitcnt lgkmcnt(0)
	v_fmac_f32_e32 v169, v48, v2
	v_fmac_f32_e32 v170, v49, v2
	v_fmac_f32_e32 v169, v50, v3
	v_fmac_f32_e32 v170, v51, v3
	v_fmac_f32_e32 v169, v56, v4
	v_fmac_f32_e32 v170, v57, v4
	v_fmac_f32_e32 v169, v58, v5
	v_fmac_f32_e32 v170, v59, v5
	ds_read_b128 v[2:5], v19 offset:33136
	s_waitcnt lgkmcnt(0)
	v_fmac_f32_e32 v169, v12, v2
	v_fmac_f32_e32 v169, v6, v3
	v_fmac_f32_e32 v169, v14, v4
	v_fmac_f32_e32 v170, v13, v2
	v_fmac_f32_e32 v169, v9, v5
	v_fmac_f32_e32 v170, v7, v3
	v_mul_f32_e64 v3, |v169|, s84
	v_exp_f32_e32 v3, v3
	v_fmac_f32_e32 v170, v15, v4
	v_fmac_f32_e32 v170, v10, v5
	v_min_f32_e32 v2, 0, v169
	v_add_f32_e32 v3, 1.0, v3
	v_cmp_gt_f32_e64 s[0:1], s31, v3
	s_nop 1
	v_cndmask_b32_e64 v4, 0, 32, s[0:1]
	v_ldexp_f32 v3, v3, v4
	v_log_f32_e32 v3, v3
	s_nop 0
	v_mul_f32_e32 v4, 0x3f317217, v3
	v_fma_f32 v4, v3, s78, -v4
	v_fmac_f32_e32 v4, 0x3377d1cf, v3
	v_fmac_f32_e32 v4, 0x3f317217, v3
	v_cmp_lt_f32_e64 s[88:89], |v3|, s79
	s_nop 1
	v_cndmask_b32_e64 v3, v3, v4, s[88:89]
	v_cndmask_b32_e64 v4, 0, v198, s[0:1]
	v_sub_f32_e32 v3, v3, v4
	v_sub_f32_e32 v177, v2, v3
	v_mul_f32_e64 v3, |v170|, s84
	v_exp_f32_e32 v3, v3
	v_min_f32_e32 v2, 0, v170
	v_fmamk_f32 v170, v177, 0x3d800000, v168
	v_add_f32_e32 v3, 1.0, v3
	v_cmp_gt_f32_e64 s[0:1], s31, v3
	s_nop 1
	v_cndmask_b32_e64 v4, 0, 32, s[0:1]
	v_ldexp_f32 v3, v3, v4
	v_log_f32_e32 v3, v3
	s_nop 0
	v_mul_f32_e32 v4, 0x3f317217, v3
	v_fma_f32 v4, v3, s78, -v4
	v_fmac_f32_e32 v4, 0x3377d1cf, v3
	v_fmac_f32_e32 v4, 0x3f317217, v3
	v_cmp_lt_f32_e64 s[88:89], |v3|, s79
	s_nop 1
	v_cndmask_b32_e64 v3, v3, v4, s[88:89]
	v_cndmask_b32_e64 v4, 0, v198, s[0:1]
	v_sub_f32_e32 v3, v3, v4
	v_sub_f32_e32 v180, v2, v3
	ds_read_b128 v[2:5], v19 offset:33152
	v_fmamk_f32 v169, v180, 0x3d800000, v167
	s_waitcnt lgkmcnt(0)
	v_fma_f32 v172, v60, v2, v69
	v_fma_f32 v173, v61, v2, v68
	v_fmac_f32_e32 v172, v62, v3
	v_fmac_f32_e32 v173, v63, v3
	v_fmac_f32_e32 v172, v64, v4
	v_fmac_f32_e32 v173, v65, v4
	v_fmac_f32_e32 v172, v66, v5
	v_fmac_f32_e32 v173, v67, v5
	ds_read_b128 v[2:5], v19 offset:33168
	s_waitcnt lgkmcnt(0)
	v_fmac_f32_e32 v172, v47, v2
	v_fmac_f32_e32 v173, v46, v2
	v_fmac_f32_e32 v172, v17, v3
	v_fmac_f32_e32 v173, v16, v3
	v_fmac_f32_e32 v172, v52, v4
	v_fmac_f32_e32 v173, v53, v4
	v_fmac_f32_e32 v172, v54, v5
	v_fmac_f32_e32 v173, v55, v5
	ds_read_b128 v[2:5], v19 offset:33184
	s_waitcnt lgkmcnt(0)
	v_fmac_f32_e32 v172, v48, v2
	v_fmac_f32_e32 v173, v49, v2
	v_fmac_f32_e32 v172, v50, v3
	v_fmac_f32_e32 v173, v51, v3
	v_fmac_f32_e32 v172, v56, v4
	v_fmac_f32_e32 v173, v57, v4
	v_fmac_f32_e32 v172, v58, v5
	v_fmac_f32_e32 v173, v59, v5
	ds_read_b128 v[2:5], v19 offset:33200
	s_waitcnt lgkmcnt(0)
	v_fmac_f32_e32 v172, v12, v2
	v_fmac_f32_e32 v172, v6, v3
	v_fmac_f32_e32 v172, v14, v4
	v_fmac_f32_e32 v173, v13, v2
	v_fmac_f32_e32 v172, v9, v5
	v_fmac_f32_e32 v173, v7, v3
	v_mul_f32_e64 v3, |v172|, s84
	v_exp_f32_e32 v3, v3
	v_fmac_f32_e32 v173, v15, v4
	v_fmac_f32_e32 v173, v10, v5
	v_min_f32_e32 v2, 0, v172
	v_add_f32_e32 v3, 1.0, v3
	v_cmp_gt_f32_e64 s[0:1], s31, v3
	s_nop 1
	v_cndmask_b32_e64 v4, 0, 32, s[0:1]
	v_ldexp_f32 v3, v3, v4
	v_log_f32_e32 v3, v3
	s_nop 0
	v_mul_f32_e32 v4, 0x3f317217, v3
	v_fma_f32 v4, v3, s78, -v4
	v_fmac_f32_e32 v4, 0x3377d1cf, v3
	v_fmac_f32_e32 v4, 0x3f317217, v3
	v_cmp_lt_f32_e64 s[88:89], |v3|, s79
	s_nop 1
	v_cndmask_b32_e64 v3, v3, v4, s[88:89]
	v_cndmask_b32_e64 v4, 0, v198, s[0:1]
	v_sub_f32_e32 v3, v3, v4
	v_sub_f32_e32 v183, v2, v3
	v_mul_f32_e64 v3, |v173|, s84
	v_exp_f32_e32 v3, v3
	v_min_f32_e32 v2, 0, v173
	v_fmamk_f32 v173, v183, 0x3d800000, v170
	v_add_f32_e32 v3, 1.0, v3
	v_cmp_gt_f32_e64 s[0:1], s31, v3
	s_nop 1
	v_cndmask_b32_e64 v4, 0, 32, s[0:1]
	v_ldexp_f32 v3, v3, v4
	v_log_f32_e32 v3, v3
	s_nop 0
	v_mul_f32_e32 v4, 0x3f317217, v3
	v_fma_f32 v4, v3, s78, -v4
	v_fmac_f32_e32 v4, 0x3377d1cf, v3
	v_fmac_f32_e32 v4, 0x3f317217, v3
	v_cmp_lt_f32_e64 s[88:89], |v3|, s79
	s_nop 1
	v_cndmask_b32_e64 v3, v3, v4, s[88:89]
	v_cndmask_b32_e64 v4, 0, v198, s[0:1]
	v_sub_f32_e32 v3, v3, v4
	v_sub_f32_e32 v199, v2, v3
	ds_read_b128 v[2:5], v19 offset:33216
	v_fmamk_f32 v172, v199, 0x3d800000, v169
	s_waitcnt lgkmcnt(0)
	v_fma_f32 v175, v60, v2, v69
	v_fma_f32 v176, v61, v2, v68
	v_fmac_f32_e32 v175, v62, v3
	v_fmac_f32_e32 v176, v63, v3
	v_fmac_f32_e32 v175, v64, v4
	v_fmac_f32_e32 v176, v65, v4
	v_fmac_f32_e32 v175, v66, v5
	v_fmac_f32_e32 v176, v67, v5
	ds_read_b128 v[2:5], v19 offset:33232
	s_waitcnt lgkmcnt(0)
	v_fmac_f32_e32 v175, v47, v2
	v_fmac_f32_e32 v176, v46, v2
	v_fmac_f32_e32 v175, v17, v3
	v_fmac_f32_e32 v176, v16, v3
	v_fmac_f32_e32 v175, v52, v4
	v_fmac_f32_e32 v176, v53, v4
	v_fmac_f32_e32 v175, v54, v5
	v_fmac_f32_e32 v176, v55, v5
	ds_read_b128 v[2:5], v19 offset:33248
	s_waitcnt lgkmcnt(0)
	v_fmac_f32_e32 v175, v48, v2
	v_fmac_f32_e32 v176, v49, v2
	v_fmac_f32_e32 v175, v50, v3
	v_fmac_f32_e32 v176, v51, v3
	v_fmac_f32_e32 v175, v56, v4
	v_fmac_f32_e32 v176, v57, v4
	v_fmac_f32_e32 v175, v58, v5
	v_fmac_f32_e32 v176, v59, v5
	ds_read_b128 v[2:5], v19 offset:33264
	s_waitcnt lgkmcnt(0)
	v_fmac_f32_e32 v175, v12, v2
	v_fmac_f32_e32 v175, v6, v3
	v_fmac_f32_e32 v175, v14, v4
	v_fmac_f32_e32 v176, v13, v2
	v_fmac_f32_e32 v175, v9, v5
	v_fmac_f32_e32 v176, v7, v3
	v_mul_f32_e64 v3, |v175|, s84
	v_exp_f32_e32 v3, v3
	v_fmac_f32_e32 v176, v15, v4
	v_fmac_f32_e32 v176, v10, v5
	v_min_f32_e32 v2, 0, v175
	v_add_f32_e32 v3, 1.0, v3
	v_cmp_gt_f32_e64 s[0:1], s31, v3
	s_nop 1
	v_cndmask_b32_e64 v4, 0, 32, s[0:1]
	v_ldexp_f32 v3, v3, v4
	v_log_f32_e32 v3, v3
	s_nop 0
	v_mul_f32_e32 v4, 0x3f317217, v3
	v_fma_f32 v4, v3, s78, -v4
	v_fmac_f32_e32 v4, 0x3377d1cf, v3
	v_fmac_f32_e32 v4, 0x3f317217, v3
	v_cmp_lt_f32_e64 s[88:89], |v3|, s79
	s_nop 1
	v_cndmask_b32_e64 v3, v3, v4, s[88:89]
	v_cndmask_b32_e64 v4, 0, v198, s[0:1]
	v_sub_f32_e32 v3, v3, v4
	v_sub_f32_e32 v202, v2, v3
	v_mul_f32_e64 v3, |v176|, s84
	v_exp_f32_e32 v3, v3
	v_min_f32_e32 v2, 0, v176
	v_fmamk_f32 v176, v202, 0x3d800000, v173
	v_add_f32_e32 v3, 1.0, v3
	v_cmp_gt_f32_e64 s[0:1], s31, v3
	s_nop 1
	v_cndmask_b32_e64 v4, 0, 32, s[0:1]
	v_ldexp_f32 v3, v3, v4
	v_log_f32_e32 v3, v3
	s_nop 0
	v_mul_f32_e32 v4, 0x3f317217, v3
	v_fma_f32 v4, v3, s78, -v4
	v_fmac_f32_e32 v4, 0x3377d1cf, v3
	v_fmac_f32_e32 v4, 0x3f317217, v3
	v_cmp_lt_f32_e64 s[88:89], |v3|, s79
	s_nop 1
	v_cndmask_b32_e64 v3, v3, v4, s[88:89]
	v_cndmask_b32_e64 v4, 0, v198, s[0:1]
	v_sub_f32_e32 v3, v3, v4
	v_sub_f32_e32 v203, v2, v3
	ds_read_b128 v[2:5], v19 offset:33280
	v_fmamk_f32 v175, v203, 0x3d800000, v172
	s_waitcnt lgkmcnt(0)
	v_fma_f32 v178, v60, v2, v69
	v_fma_f32 v179, v61, v2, v68
	v_fmac_f32_e32 v178, v62, v3
	v_fmac_f32_e32 v179, v63, v3
	v_fmac_f32_e32 v178, v64, v4
	v_fmac_f32_e32 v179, v65, v4
	v_fmac_f32_e32 v178, v66, v5
	v_fmac_f32_e32 v179, v67, v5
	ds_read_b128 v[2:5], v19 offset:33296
	s_waitcnt lgkmcnt(0)
	v_fmac_f32_e32 v178, v47, v2
	v_fmac_f32_e32 v179, v46, v2
	v_fmac_f32_e32 v178, v17, v3
	v_fmac_f32_e32 v179, v16, v3
	v_fmac_f32_e32 v178, v52, v4
	v_fmac_f32_e32 v179, v53, v4
	v_fmac_f32_e32 v178, v54, v5
	v_fmac_f32_e32 v179, v55, v5
	ds_read_b128 v[2:5], v19 offset:33312
	s_waitcnt lgkmcnt(0)
	v_fmac_f32_e32 v178, v48, v2
	v_fmac_f32_e32 v179, v49, v2
	v_fmac_f32_e32 v178, v50, v3
	v_fmac_f32_e32 v179, v51, v3
	v_fmac_f32_e32 v178, v56, v4
	v_fmac_f32_e32 v179, v57, v4
	v_fmac_f32_e32 v178, v58, v5
	v_fmac_f32_e32 v179, v59, v5
	ds_read_b128 v[2:5], v19 offset:33328
	s_waitcnt lgkmcnt(0)
	v_fmac_f32_e32 v178, v12, v2
	v_fmac_f32_e32 v178, v6, v3
	v_fmac_f32_e32 v178, v14, v4
	v_fmac_f32_e32 v179, v13, v2
	v_fmac_f32_e32 v178, v9, v5
	v_fmac_f32_e32 v179, v7, v3
	v_mul_f32_e64 v3, |v178|, s84
	v_exp_f32_e32 v3, v3
	v_fmac_f32_e32 v179, v15, v4
	v_fmac_f32_e32 v179, v10, v5
	v_min_f32_e32 v2, 0, v178
	v_add_f32_e32 v3, 1.0, v3
	v_cmp_gt_f32_e64 s[0:1], s31, v3
	s_nop 1
	v_cndmask_b32_e64 v4, 0, 32, s[0:1]
	v_ldexp_f32 v3, v3, v4
	v_log_f32_e32 v3, v3
	s_nop 0
	v_mul_f32_e32 v4, 0x3f317217, v3
	v_fma_f32 v4, v3, s78, -v4
	v_fmac_f32_e32 v4, 0x3377d1cf, v3
	v_fmac_f32_e32 v4, 0x3f317217, v3
	v_cmp_lt_f32_e64 s[88:89], |v3|, s79
	s_nop 1
	v_cndmask_b32_e64 v3, v3, v4, s[88:89]
	v_cndmask_b32_e64 v4, 0, v198, s[0:1]
	v_sub_f32_e32 v3, v3, v4
	v_sub_f32_e32 v206, v2, v3
	v_mul_f32_e64 v3, |v179|, s84
	v_exp_f32_e32 v3, v3
	v_min_f32_e32 v2, 0, v179
	v_fmamk_f32 v179, v206, 0x3d800000, v176
	v_add_f32_e32 v3, 1.0, v3
	v_cmp_gt_f32_e64 s[0:1], s31, v3
	s_nop 1
	v_cndmask_b32_e64 v4, 0, 32, s[0:1]
	v_ldexp_f32 v3, v3, v4
	v_log_f32_e32 v3, v3
	s_nop 0
	v_mul_f32_e32 v4, 0x3f317217, v3
	v_fma_f32 v4, v3, s78, -v4
	v_fmac_f32_e32 v4, 0x3377d1cf, v3
	v_fmac_f32_e32 v4, 0x3f317217, v3
	v_cmp_lt_f32_e64 s[88:89], |v3|, s79
	s_nop 1
	v_cndmask_b32_e64 v3, v3, v4, s[88:89]
	v_cndmask_b32_e64 v4, 0, v198, s[0:1]
	v_sub_f32_e32 v3, v3, v4
	v_sub_f32_e32 v207, v2, v3
	ds_read_b128 v[2:5], v19 offset:33344
	v_fmamk_f32 v178, v207, 0x3d800000, v175
	s_waitcnt lgkmcnt(0)
	v_fma_f32 v181, v60, v2, v69
	v_fma_f32 v182, v61, v2, v68
	v_fmac_f32_e32 v181, v62, v3
	v_fmac_f32_e32 v182, v63, v3
	v_fmac_f32_e32 v181, v64, v4
	v_fmac_f32_e32 v182, v65, v4
	v_fmac_f32_e32 v181, v66, v5
	v_fmac_f32_e32 v182, v67, v5
	ds_read_b128 v[2:5], v19 offset:33360
	s_waitcnt lgkmcnt(0)
	v_fmac_f32_e32 v181, v47, v2
	v_fmac_f32_e32 v182, v46, v2
	v_fmac_f32_e32 v181, v17, v3
	v_fmac_f32_e32 v182, v16, v3
	v_fmac_f32_e32 v181, v52, v4
	v_fmac_f32_e32 v182, v53, v4
	v_fmac_f32_e32 v181, v54, v5
	v_fmac_f32_e32 v182, v55, v5
	ds_read_b128 v[2:5], v19 offset:33376
	s_waitcnt lgkmcnt(0)
	v_fmac_f32_e32 v181, v48, v2
	v_fmac_f32_e32 v182, v49, v2
	v_fmac_f32_e32 v181, v50, v3
	v_fmac_f32_e32 v182, v51, v3
	v_fmac_f32_e32 v181, v56, v4
	v_fmac_f32_e32 v182, v57, v4
	v_fmac_f32_e32 v181, v58, v5
	v_fmac_f32_e32 v182, v59, v5
	ds_read_b128 v[2:5], v19 offset:33392
	s_waitcnt lgkmcnt(0)
	v_fmac_f32_e32 v181, v12, v2
	v_fmac_f32_e32 v181, v6, v3
	v_fmac_f32_e32 v181, v14, v4
	v_fmac_f32_e32 v182, v13, v2
	v_fmac_f32_e32 v181, v9, v5
	v_fmac_f32_e32 v182, v7, v3
	v_mul_f32_e64 v3, |v181|, s84
	v_exp_f32_e32 v3, v3
	v_fmac_f32_e32 v182, v15, v4
	v_fmac_f32_e32 v182, v10, v5
	v_min_f32_e32 v2, 0, v181
	v_add_f32_e32 v3, 1.0, v3
	v_cmp_gt_f32_e64 s[0:1], s31, v3
	s_nop 1
	v_cndmask_b32_e64 v4, 0, 32, s[0:1]
	v_ldexp_f32 v3, v3, v4
	v_log_f32_e32 v3, v3
	s_nop 0
	v_mul_f32_e32 v4, 0x3f317217, v3
	v_fma_f32 v4, v3, s78, -v4
	v_fmac_f32_e32 v4, 0x3377d1cf, v3
	v_fmac_f32_e32 v4, 0x3f317217, v3
	v_cmp_lt_f32_e64 s[88:89], |v3|, s79
	s_nop 1
	v_cndmask_b32_e64 v3, v3, v4, s[88:89]
	v_cndmask_b32_e64 v4, 0, v198, s[0:1]
	v_sub_f32_e32 v3, v3, v4
	v_sub_f32_e32 v210, v2, v3
	v_mul_f32_e64 v3, |v182|, s84
	v_exp_f32_e32 v3, v3
	v_min_f32_e32 v2, 0, v182
	v_fmamk_f32 v182, v210, 0x3d800000, v179
	v_add_f32_e32 v3, 1.0, v3
	v_cmp_gt_f32_e64 s[0:1], s31, v3
	s_nop 1
	v_cndmask_b32_e64 v4, 0, 32, s[0:1]
	v_ldexp_f32 v3, v3, v4
	v_log_f32_e32 v3, v3
	s_nop 0
	v_mul_f32_e32 v4, 0x3f317217, v3
	v_fma_f32 v4, v3, s78, -v4
	v_fmac_f32_e32 v4, 0x3377d1cf, v3
	v_fmac_f32_e32 v4, 0x3f317217, v3
	v_cmp_lt_f32_e64 s[88:89], |v3|, s79
	s_nop 1
	v_cndmask_b32_e64 v3, v3, v4, s[88:89]
	v_cndmask_b32_e64 v4, 0, v198, s[0:1]
	v_sub_f32_e32 v3, v3, v4
	v_sub_f32_e32 v211, v2, v3
	ds_read_b128 v[2:5], v19 offset:33408
	v_fmamk_f32 v181, v211, 0x3d800000, v178
	s_waitcnt lgkmcnt(0)
	v_fma_f32 v192, v60, v2, v69
	v_fma_f32 v193, v61, v2, v68
	v_fmac_f32_e32 v192, v62, v3
	v_fmac_f32_e32 v193, v63, v3
	v_fmac_f32_e32 v192, v64, v4
	v_fmac_f32_e32 v193, v65, v4
	v_fmac_f32_e32 v192, v66, v5
	v_fmac_f32_e32 v193, v67, v5
	ds_read_b128 v[2:5], v19 offset:33424
	s_waitcnt lgkmcnt(0)
	v_fmac_f32_e32 v192, v47, v2
	v_fmac_f32_e32 v193, v46, v2
	v_fmac_f32_e32 v192, v17, v3
	v_fmac_f32_e32 v193, v16, v3
	v_fmac_f32_e32 v192, v52, v4
	v_fmac_f32_e32 v193, v53, v4
	v_fmac_f32_e32 v192, v54, v5
	v_fmac_f32_e32 v193, v55, v5
	ds_read_b128 v[2:5], v19 offset:33440
	s_waitcnt lgkmcnt(0)
	v_fmac_f32_e32 v192, v48, v2
	v_fmac_f32_e32 v193, v49, v2
	v_fmac_f32_e32 v192, v50, v3
	v_fmac_f32_e32 v193, v51, v3
	v_fmac_f32_e32 v192, v56, v4
	v_fmac_f32_e32 v193, v57, v4
	v_fmac_f32_e32 v192, v58, v5
	v_fmac_f32_e32 v193, v59, v5
	ds_read_b128 v[2:5], v19 offset:33456
	s_waitcnt lgkmcnt(0)
	v_fmac_f32_e32 v192, v12, v2
	v_fmac_f32_e32 v192, v6, v3
	v_fmac_f32_e32 v192, v14, v4
	v_fmac_f32_e32 v193, v13, v2
	v_fmac_f32_e32 v192, v9, v5
	v_fmac_f32_e32 v193, v7, v3
	v_mul_f32_e64 v3, |v192|, s84
	v_exp_f32_e32 v3, v3
	v_fmac_f32_e32 v193, v15, v4
	v_fmac_f32_e32 v193, v10, v5
	v_min_f32_e32 v2, 0, v192
	v_add_f32_e32 v3, 1.0, v3
	v_cmp_gt_f32_e64 s[0:1], s31, v3
	s_nop 1
	v_cndmask_b32_e64 v4, 0, 32, s[0:1]
	v_ldexp_f32 v3, v3, v4
	v_log_f32_e32 v3, v3
	s_nop 0
	v_mul_f32_e32 v4, 0x3f317217, v3
	v_fma_f32 v4, v3, s78, -v4
	v_fmac_f32_e32 v4, 0x3377d1cf, v3
	v_fmac_f32_e32 v4, 0x3f317217, v3
	v_cmp_lt_f32_e64 s[88:89], |v3|, s79
	s_nop 1
	v_cndmask_b32_e64 v3, v3, v4, s[88:89]
	v_cndmask_b32_e64 v4, 0, v198, s[0:1]
	v_sub_f32_e32 v3, v3, v4
	v_sub_f32_e32 v214, v2, v3
	v_mul_f32_e64 v3, |v193|, s84
	v_exp_f32_e32 v3, v3
	v_min_f32_e32 v2, 0, v193
	v_fmamk_f32 v201, v214, 0x3d800000, v182
	v_add_f32_e32 v3, 1.0, v3
	v_cmp_gt_f32_e64 s[0:1], s31, v3
	s_nop 1
	v_cndmask_b32_e64 v4, 0, 32, s[0:1]
	v_ldexp_f32 v3, v3, v4
	v_log_f32_e32 v3, v3
	s_nop 0
	v_mul_f32_e32 v4, 0x3f317217, v3
	v_fma_f32 v4, v3, s78, -v4
	v_fmac_f32_e32 v4, 0x3377d1cf, v3
	v_fmac_f32_e32 v4, 0x3f317217, v3
	v_cmp_lt_f32_e64 s[88:89], |v3|, s79
	s_nop 1
	v_cndmask_b32_e64 v3, v3, v4, s[88:89]
	v_cndmask_b32_e64 v4, 0, v198, s[0:1]
	v_sub_f32_e32 v3, v3, v4
	v_sub_f32_e32 v217, v2, v3
	ds_read_b128 v[2:5], v19 offset:33472
	v_fmamk_f32 v200, v217, 0x3d800000, v181
	s_waitcnt lgkmcnt(0)
	v_fma_f32 v192, v60, v2, v69
	v_fma_f32 v193, v61, v2, v68
	v_fmac_f32_e32 v192, v62, v3
	v_fmac_f32_e32 v193, v63, v3
	v_fmac_f32_e32 v192, v64, v4
	v_fmac_f32_e32 v193, v65, v4
	v_fmac_f32_e32 v192, v66, v5
	v_fmac_f32_e32 v193, v67, v5
	ds_read_b128 v[2:5], v19 offset:33488
	s_waitcnt lgkmcnt(0)
	v_fmac_f32_e32 v192, v47, v2
	v_fmac_f32_e32 v193, v46, v2
	v_fmac_f32_e32 v192, v17, v3
	v_fmac_f32_e32 v193, v16, v3
	v_fmac_f32_e32 v192, v52, v4
	v_fmac_f32_e32 v193, v53, v4
	v_fmac_f32_e32 v192, v54, v5
	v_fmac_f32_e32 v193, v55, v5
	ds_read_b128 v[2:5], v19 offset:33504
	s_waitcnt lgkmcnt(0)
	v_fmac_f32_e32 v192, v48, v2
	v_fmac_f32_e32 v193, v49, v2
	v_fmac_f32_e32 v192, v50, v3
	v_fmac_f32_e32 v193, v51, v3
	v_fmac_f32_e32 v192, v56, v4
	v_fmac_f32_e32 v193, v57, v4
	v_fmac_f32_e32 v192, v58, v5
	v_fmac_f32_e32 v193, v59, v5
	ds_read_b128 v[2:5], v19 offset:33520
	s_waitcnt lgkmcnt(0)
	v_fmac_f32_e32 v192, v12, v2
	v_fmac_f32_e32 v192, v6, v3
	v_fmac_f32_e32 v192, v14, v4
	v_fmac_f32_e32 v193, v13, v2
	v_fmac_f32_e32 v192, v9, v5
	v_fmac_f32_e32 v193, v7, v3
	v_mul_f32_e64 v3, |v192|, s84
	v_exp_f32_e32 v3, v3
	v_fmac_f32_e32 v193, v15, v4
	v_fmac_f32_e32 v193, v10, v5
	v_min_f32_e32 v2, 0, v192
	v_add_f32_e32 v3, 1.0, v3
	v_cmp_gt_f32_e64 s[0:1], s31, v3
	s_nop 1
	v_cndmask_b32_e64 v4, 0, 32, s[0:1]
	v_ldexp_f32 v3, v3, v4
	v_log_f32_e32 v3, v3
	s_nop 0
	v_mul_f32_e32 v4, 0x3f317217, v3
	v_fma_f32 v4, v3, s78, -v4
	v_fmac_f32_e32 v4, 0x3377d1cf, v3
	v_fmac_f32_e32 v4, 0x3f317217, v3
	v_cmp_lt_f32_e64 s[88:89], |v3|, s79
	s_nop 1
	v_cndmask_b32_e64 v3, v3, v4, s[88:89]
	v_cndmask_b32_e64 v4, 0, v198, s[0:1]
	v_sub_f32_e32 v3, v3, v4
	v_sub_f32_e32 v218, v2, v3
	v_mul_f32_e64 v3, |v193|, s84
	v_exp_f32_e32 v3, v3
	v_min_f32_e32 v2, 0, v193
	v_fmamk_f32 v205, v218, 0x3d800000, v201
	v_add_f32_e32 v3, 1.0, v3
	v_cmp_gt_f32_e64 s[0:1], s31, v3
	s_nop 1
	v_cndmask_b32_e64 v4, 0, 32, s[0:1]
	v_ldexp_f32 v3, v3, v4
	v_log_f32_e32 v3, v3
	s_nop 0
	v_mul_f32_e32 v4, 0x3f317217, v3
	v_fma_f32 v4, v3, s78, -v4
	v_fmac_f32_e32 v4, 0x3377d1cf, v3
	v_fmac_f32_e32 v4, 0x3f317217, v3
	v_cmp_lt_f32_e64 s[88:89], |v3|, s79
	s_nop 1
	v_cndmask_b32_e64 v3, v3, v4, s[88:89]
	v_cndmask_b32_e64 v4, 0, v198, s[0:1]
	v_sub_f32_e32 v3, v3, v4
	v_sub_f32_e32 v223, v2, v3
	ds_read_b128 v[2:5], v19 offset:33536
	v_fmamk_f32 v204, v223, 0x3d800000, v200
	s_waitcnt lgkmcnt(0)
	v_fma_f32 v192, v60, v2, v69
	v_fma_f32 v193, v61, v2, v68
	v_fmac_f32_e32 v192, v62, v3
	v_fmac_f32_e32 v193, v63, v3
	v_fmac_f32_e32 v192, v64, v4
	v_fmac_f32_e32 v193, v65, v4
	v_fmac_f32_e32 v192, v66, v5
	v_fmac_f32_e32 v193, v67, v5
	ds_read_b128 v[2:5], v19 offset:33552
	s_waitcnt lgkmcnt(0)
	v_fmac_f32_e32 v192, v47, v2
	v_fmac_f32_e32 v193, v46, v2
	v_fmac_f32_e32 v192, v17, v3
	v_fmac_f32_e32 v193, v16, v3
	v_fmac_f32_e32 v192, v52, v4
	v_fmac_f32_e32 v193, v53, v4
	v_fmac_f32_e32 v192, v54, v5
	v_fmac_f32_e32 v193, v55, v5
	ds_read_b128 v[2:5], v19 offset:33568
	s_waitcnt lgkmcnt(0)
	v_fmac_f32_e32 v192, v48, v2
	v_fmac_f32_e32 v193, v49, v2
	v_fmac_f32_e32 v192, v50, v3
	v_fmac_f32_e32 v193, v51, v3
	v_fmac_f32_e32 v192, v56, v4
	v_fmac_f32_e32 v193, v57, v4
	v_fmac_f32_e32 v192, v58, v5
	v_fmac_f32_e32 v193, v59, v5
	ds_read_b128 v[2:5], v19 offset:33584
	s_waitcnt lgkmcnt(0)
	v_fmac_f32_e32 v192, v12, v2
	v_fmac_f32_e32 v192, v6, v3
	v_fmac_f32_e32 v192, v14, v4
	v_fmac_f32_e32 v193, v13, v2
	v_fmac_f32_e32 v192, v9, v5
	v_fmac_f32_e32 v193, v7, v3
	v_mul_f32_e64 v3, |v192|, s84
	v_exp_f32_e32 v3, v3
	v_fmac_f32_e32 v193, v15, v4
	v_fmac_f32_e32 v193, v10, v5
	v_min_f32_e32 v2, 0, v192
	v_add_f32_e32 v3, 1.0, v3
	v_cmp_gt_f32_e64 s[0:1], s31, v3
	s_nop 1
	v_cndmask_b32_e64 v4, 0, 32, s[0:1]
	v_ldexp_f32 v3, v3, v4
	v_log_f32_e32 v3, v3
	s_nop 0
	v_mul_f32_e32 v4, 0x3f317217, v3
	v_fma_f32 v4, v3, s78, -v4
	v_fmac_f32_e32 v4, 0x3377d1cf, v3
	v_fmac_f32_e32 v4, 0x3f317217, v3
	v_cmp_lt_f32_e64 s[88:89], |v3|, s79
	s_nop 1
	v_cndmask_b32_e64 v3, v3, v4, s[88:89]
	v_cndmask_b32_e64 v4, 0, v198, s[0:1]
	v_sub_f32_e32 v3, v3, v4
	v_sub_f32_e32 v224, v2, v3
	v_mul_f32_e64 v3, |v193|, s84
	v_exp_f32_e32 v3, v3
	v_min_f32_e32 v2, 0, v193
	v_fmamk_f32 v209, v224, 0x3d800000, v205
	v_add_f32_e32 v3, 1.0, v3
	v_cmp_gt_f32_e64 s[0:1], s31, v3
	s_nop 1
	v_cndmask_b32_e64 v4, 0, 32, s[0:1]
	v_ldexp_f32 v3, v3, v4
	v_log_f32_e32 v3, v3
	s_nop 0
	v_mul_f32_e32 v4, 0x3f317217, v3
	v_fma_f32 v4, v3, s78, -v4
	v_fmac_f32_e32 v4, 0x3377d1cf, v3
	v_fmac_f32_e32 v4, 0x3f317217, v3
	v_cmp_lt_f32_e64 s[88:89], |v3|, s79
	s_nop 1
	v_cndmask_b32_e64 v3, v3, v4, s[88:89]
	v_cndmask_b32_e64 v4, 0, v198, s[0:1]
	v_sub_f32_e32 v3, v3, v4
	v_sub_f32_e32 v225, v2, v3
	ds_read_b128 v[2:5], v19 offset:33600
	v_fmamk_f32 v208, v225, 0x3d800000, v204
	s_waitcnt lgkmcnt(0)
	v_fma_f32 v192, v60, v2, v69
	v_fma_f32 v193, v61, v2, v68
	v_fmac_f32_e32 v192, v62, v3
	v_fmac_f32_e32 v193, v63, v3
	v_fmac_f32_e32 v192, v64, v4
	v_fmac_f32_e32 v193, v65, v4
	v_fmac_f32_e32 v192, v66, v5
	v_fmac_f32_e32 v193, v67, v5
	ds_read_b128 v[2:5], v19 offset:33616
	s_waitcnt lgkmcnt(0)
	v_fmac_f32_e32 v192, v47, v2
	v_fmac_f32_e32 v193, v46, v2
	v_fmac_f32_e32 v192, v17, v3
	v_fmac_f32_e32 v193, v16, v3
	v_fmac_f32_e32 v192, v52, v4
	v_fmac_f32_e32 v193, v53, v4
	v_fmac_f32_e32 v192, v54, v5
	v_fmac_f32_e32 v193, v55, v5
	ds_read_b128 v[2:5], v19 offset:33632
	s_waitcnt lgkmcnt(0)
	v_fmac_f32_e32 v192, v48, v2
	v_fmac_f32_e32 v193, v49, v2
	v_fmac_f32_e32 v192, v50, v3
	v_fmac_f32_e32 v193, v51, v3
	v_fmac_f32_e32 v192, v56, v4
	v_fmac_f32_e32 v193, v57, v4
	v_fmac_f32_e32 v192, v58, v5
	v_fmac_f32_e32 v193, v59, v5
	ds_read_b128 v[2:5], v19 offset:33648
	s_waitcnt lgkmcnt(0)
	v_fmac_f32_e32 v192, v12, v2
	v_fmac_f32_e32 v192, v6, v3
	v_fmac_f32_e32 v192, v14, v4
	v_fmac_f32_e32 v193, v13, v2
	v_fmac_f32_e32 v192, v9, v5
	v_fmac_f32_e32 v193, v7, v3
	v_mul_f32_e64 v3, |v192|, s84
	v_exp_f32_e32 v3, v3
	v_fmac_f32_e32 v193, v15, v4
	v_fmac_f32_e32 v193, v10, v5
	v_min_f32_e32 v2, 0, v192
	v_add_f32_e32 v3, 1.0, v3
	v_cmp_gt_f32_e64 s[0:1], s31, v3
	s_nop 1
	v_cndmask_b32_e64 v4, 0, 32, s[0:1]
	v_ldexp_f32 v3, v3, v4
	v_log_f32_e32 v3, v3
	s_nop 0
	v_mul_f32_e32 v4, 0x3f317217, v3
	v_fma_f32 v4, v3, s78, -v4
	v_fmac_f32_e32 v4, 0x3377d1cf, v3
	v_fmac_f32_e32 v4, 0x3f317217, v3
	v_cmp_lt_f32_e64 s[88:89], |v3|, s79
	s_nop 1
	v_cndmask_b32_e64 v3, v3, v4, s[88:89]
	v_cndmask_b32_e64 v4, 0, v198, s[0:1]
	v_sub_f32_e32 v3, v3, v4
	v_sub_f32_e32 v226, v2, v3
	v_mul_f32_e64 v3, |v193|, s84
	v_exp_f32_e32 v3, v3
	v_min_f32_e32 v2, 0, v193
	v_fmamk_f32 v213, v226, 0x3d800000, v209
	v_add_f32_e32 v3, 1.0, v3
	v_cmp_gt_f32_e64 s[0:1], s31, v3
	s_nop 1
	v_cndmask_b32_e64 v4, 0, 32, s[0:1]
	v_ldexp_f32 v3, v3, v4
	v_log_f32_e32 v3, v3
	s_nop 0
	v_mul_f32_e32 v4, 0x3f317217, v3
	v_fma_f32 v4, v3, s78, -v4
	v_fmac_f32_e32 v4, 0x3377d1cf, v3
	v_fmac_f32_e32 v4, 0x3f317217, v3
	v_cmp_lt_f32_e64 s[88:89], |v3|, s79
	s_nop 1
	v_cndmask_b32_e64 v3, v3, v4, s[88:89]
	v_cndmask_b32_e64 v4, 0, v198, s[0:1]
	v_sub_f32_e32 v3, v3, v4
	v_sub_f32_e32 v227, v2, v3
	ds_read_b128 v[2:5], v19 offset:33664
	v_fmamk_f32 v212, v227, 0x3d800000, v208
	s_waitcnt lgkmcnt(0)
	v_fma_f32 v192, v60, v2, v69
	v_fma_f32 v193, v61, v2, v68
	v_fmac_f32_e32 v192, v62, v3
	v_fmac_f32_e32 v193, v63, v3
	v_fmac_f32_e32 v192, v64, v4
	v_fmac_f32_e32 v193, v65, v4
	v_fmac_f32_e32 v192, v66, v5
	v_fmac_f32_e32 v193, v67, v5
	ds_read_b128 v[2:5], v19 offset:33680
	s_waitcnt lgkmcnt(0)
	v_fmac_f32_e32 v192, v47, v2
	v_fmac_f32_e32 v193, v46, v2
	v_fmac_f32_e32 v192, v17, v3
	v_fmac_f32_e32 v193, v16, v3
	v_fmac_f32_e32 v192, v52, v4
	v_fmac_f32_e32 v193, v53, v4
	v_fmac_f32_e32 v192, v54, v5
	v_fmac_f32_e32 v193, v55, v5
	ds_read_b128 v[2:5], v19 offset:33696
	s_waitcnt lgkmcnt(0)
	v_fmac_f32_e32 v192, v48, v2
	v_fmac_f32_e32 v193, v49, v2
	v_fmac_f32_e32 v192, v50, v3
	v_fmac_f32_e32 v193, v51, v3
	v_fmac_f32_e32 v192, v56, v4
	v_fmac_f32_e32 v193, v57, v4
	v_fmac_f32_e32 v192, v58, v5
	v_fmac_f32_e32 v193, v59, v5
	ds_read_b128 v[2:5], v19 offset:33712
	s_waitcnt lgkmcnt(0)
	v_fmac_f32_e32 v192, v12, v2
	v_fmac_f32_e32 v192, v6, v3
	v_fmac_f32_e32 v192, v14, v4
	v_fmac_f32_e32 v193, v13, v2
	v_fmac_f32_e32 v192, v9, v5
	v_fmac_f32_e32 v193, v7, v3
	v_mul_f32_e64 v3, |v192|, s84
	v_exp_f32_e32 v3, v3
	v_fmac_f32_e32 v193, v15, v4
	v_fmac_f32_e32 v193, v10, v5
	v_min_f32_e32 v2, 0, v192
	v_add_f32_e32 v3, 1.0, v3
	v_cmp_gt_f32_e64 s[0:1], s31, v3
	s_nop 1
	v_cndmask_b32_e64 v4, 0, 32, s[0:1]
	v_ldexp_f32 v3, v3, v4
	v_log_f32_e32 v3, v3
	s_nop 0
	v_mul_f32_e32 v4, 0x3f317217, v3
	v_fma_f32 v4, v3, s78, -v4
	v_fmac_f32_e32 v4, 0x3377d1cf, v3
	v_fmac_f32_e32 v4, 0x3f317217, v3
	v_cmp_lt_f32_e64 s[88:89], |v3|, s79
	s_nop 1
	v_cndmask_b32_e64 v3, v3, v4, s[88:89]
	v_cndmask_b32_e64 v4, 0, v198, s[0:1]
	v_sub_f32_e32 v3, v3, v4
	v_sub_f32_e32 v228, v2, v3
	v_mul_f32_e64 v3, |v193|, s84
	v_exp_f32_e32 v3, v3
	v_min_f32_e32 v2, 0, v193
	v_fmamk_f32 v216, v228, 0x3d800000, v213
	v_add_f32_e32 v3, 1.0, v3
	v_cmp_gt_f32_e64 s[0:1], s31, v3
	s_nop 1
	v_cndmask_b32_e64 v4, 0, 32, s[0:1]
	v_ldexp_f32 v3, v3, v4
	v_log_f32_e32 v3, v3
	s_nop 0
	v_mul_f32_e32 v4, 0x3f317217, v3
	v_fma_f32 v4, v3, s78, -v4
	v_fmac_f32_e32 v4, 0x3377d1cf, v3
	v_fmac_f32_e32 v4, 0x3f317217, v3
	v_cmp_lt_f32_e64 s[88:89], |v3|, s79
	s_nop 1
	v_cndmask_b32_e64 v3, v3, v4, s[88:89]
	v_cndmask_b32_e64 v4, 0, v198, s[0:1]
	v_sub_f32_e32 v3, v3, v4
	v_sub_f32_e32 v229, v2, v3
	ds_read_b128 v[2:5], v19 offset:33728
	v_fmamk_f32 v215, v229, 0x3d800000, v212
	s_waitcnt lgkmcnt(0)
	v_fmac_f32_e32 v69, v60, v2
	v_fmac_f32_e32 v68, v61, v2
	v_fmac_f32_e32 v69, v62, v3
	v_fmac_f32_e32 v68, v63, v3
	v_fmac_f32_e32 v69, v64, v4
	v_fmac_f32_e32 v68, v65, v4
	v_fmac_f32_e32 v69, v66, v5
	v_fmac_f32_e32 v68, v67, v5
	ds_read_b128 v[2:5], v19 offset:33744
	s_waitcnt lgkmcnt(0)
	v_fmac_f32_e32 v69, v47, v2
	v_fmac_f32_e32 v68, v46, v2
	v_fmac_f32_e32 v69, v17, v3
	v_fmac_f32_e32 v68, v16, v3
	v_fmac_f32_e32 v69, v52, v4
	v_fmac_f32_e32 v68, v53, v4
	v_fmac_f32_e32 v69, v54, v5
	v_fmac_f32_e32 v68, v55, v5
	ds_read_b128 v[2:5], v19 offset:33760
	v_mov_b64_e32 v[46:47], s[58:59]
	s_waitcnt lgkmcnt(0)
	v_fmac_f32_e32 v69, v48, v2
	v_fmac_f32_e32 v68, v49, v2
	v_fmac_f32_e32 v69, v50, v3
	v_fmac_f32_e32 v68, v51, v3
	v_fmac_f32_e32 v69, v56, v4
	v_fmac_f32_e32 v68, v57, v4
	v_fmac_f32_e32 v69, v58, v5
	v_fmac_f32_e32 v68, v59, v5
	ds_read_b128 v[2:5], v19 offset:33776
	s_waitcnt lgkmcnt(0)
	v_fmac_f32_e32 v69, v12, v2
	v_fmac_f32_e32 v69, v6, v3
	v_fmac_f32_e32 v69, v14, v4
	v_fmac_f32_e32 v68, v13, v2
	v_fmac_f32_e32 v69, v9, v5
	v_fmac_f32_e32 v68, v7, v3
	v_mul_f32_e64 v3, |v69|, s84
	v_exp_f32_e32 v3, v3
	v_fmac_f32_e32 v68, v15, v4
	v_fmac_f32_e32 v68, v10, v5
	v_min_f32_e32 v2, 0, v69
	v_add_f32_e32 v3, 1.0, v3
	v_cmp_gt_f32_e64 s[0:1], s31, v3
	s_nop 1
	v_cndmask_b32_e64 v4, 0, 32, s[0:1]
	v_ldexp_f32 v3, v3, v4
	v_log_f32_e32 v3, v3
	s_nop 0
	v_mul_f32_e32 v4, 0x3f317217, v3
	v_fma_f32 v4, v3, s78, -v4
	v_fmac_f32_e32 v4, 0x3377d1cf, v3
	v_fmac_f32_e32 v4, 0x3f317217, v3
	v_cmp_lt_f32_e64 s[88:89], |v3|, s79
	s_nop 1
	v_cndmask_b32_e64 v3, v3, v4, s[88:89]
	v_cndmask_b32_e64 v4, 0, v198, s[0:1]
	v_sub_f32_e32 v3, v3, v4
	v_sub_f32_e32 v9, v2, v3
	v_mul_f32_e64 v3, |v68|, s84
	v_exp_f32_e32 v3, v3
	v_min_f32_e32 v2, 0, v68
	v_fmamk_f32 v220, v9, 0x3d800000, v216
	v_add_f32_e32 v3, 1.0, v3
	v_cmp_gt_f32_e64 s[0:1], s31, v3
	s_nop 1
	v_cndmask_b32_e64 v4, 0, 32, s[0:1]
	v_ldexp_f32 v3, v3, v4
	v_log_f32_e32 v3, v3
	s_nop 0
	v_mul_f32_e32 v4, 0x3f317217, v3
	v_fma_f32 v4, v3, s78, -v4
	v_fmac_f32_e32 v4, 0x3377d1cf, v3
	v_fmac_f32_e32 v4, 0x3f317217, v3
	v_cmp_lt_f32_e64 s[88:89], |v3|, s79
	s_nop 1
	v_cndmask_b32_e64 v3, v3, v4, s[88:89]
	v_cndmask_b32_e64 v4, 0, v198, s[0:1]
	v_sub_f32_e32 v3, v3, v4
	v_sub_f32_e32 v14, v2, v3
	v_fmamk_f32 v219, v14, 0x3d800000, v215
	ds_write2st64_b32 v23, v220, v219 offset0:144 offset1:145
	s_waitcnt lgkmcnt(0)
	s_barrier
	ds_read2st64_b32 v[2:3], v22 offset0:144 offset1:145
	ds_read2st64_b32 v[6:7], v22 offset0:146 offset1:147
	ds_read2st64_b32 v[4:5], v22 offset0:148 offset1:149
	s_waitcnt lgkmcnt(2)
	v_add_f32_e32 v10, 0, v2
	v_add_f32_e32 v13, 0, v3
	s_waitcnt lgkmcnt(1)
	v_add_f32_e32 v2, v10, v6
	v_add_f32_e32 v3, v13, v7
	s_waitcnt lgkmcnt(0)
	v_add_f32_e32 v12, v2, v4
	v_add_f32_e32 v15, v3, v5
	ds_read2st64_b32 v[2:3], v22 offset0:150 offset1:151
	s_waitcnt lgkmcnt(0)
	v_add_f32_e32 v12, v12, v2
	v_add_f32_e32 v15, v15, v3
	v_mul_f32_e32 v12, 0x3fb8aa3b, v12
	v_exp_f32_e32 v221, v12
	v_mul_f32_e32 v12, 0x3fb8aa3b, v15
	v_exp_f32_e32 v222, v12
	s_and_saveexec_b64 s[0:1], s[6:7]
	s_cbranch_execz .LBB0_224
	s_ashr_i32 s5, s58, 31
	s_mov_b32 s4, s58
	v_mov_b64_e32 v[46:47], s[4:5]
	global_store_dword v[36:37], v221, off
	global_store_dword v[36:37], v222, off offset:256
	s_branch .LBB0_224

.LBB0_233:
	s_and_b64 vcc, exec, s[0:1]
	s_cbranch_vccz .LBB0_279
	s_cmp_lg_u32 s13, 1
	s_cselect_b64 s[0:1], -1, 0
	s_cmp_eq_u32 s13, 1
	s_cselect_b32 s6, 32, 8
	s_cmp_lg_u32 s13, 0
	s_cselect_b64 s[22:23], -1, 0
	s_and_b64 s[4:5], s[22:23], exec
	s_cselect_b32 s21, s6, 25
	s_mul_i32 s35, s21, 0x48
	s_cmp_ge_i32 s20, s35
	s_cbranch_scc1 .LBB0_279
	s_cmp_eq_u32 s13, 2
	s_cselect_b64 s[4:5], -1, 0
	s_and_b64 s[6:7], s[4:5], exec
	s_mov_b32 s6, 0xfa00000
	s_cselect_b32 s6, s6, 0xf200000
	s_add_u32 s54, s94, s6
	s_addc_u32 s55, s95, 0
	v_readlane_b32 s7, v254, 55
	s_cmp_eq_u32 s7, 3
	s_cselect_b64 s[24:25], -1, 0
	s_waitcnt vmcnt(0)
	v_lshrrev_b32_e32 v3, 4, v134
	s_and_b64 s[26:27], s[24:25], s[4:5]
	v_sub_u32_e32 v3, 0, v3
	v_xor_b32_e32 v3, v134, v3
	s_bitcmp1_b32 s20, 8
	v_bfe_u32 v2, v134, 2, 4
	s_mov_b32 s4, 0x1fffc0
	v_lshlrev_b32_e32 v3, 4, v3
	s_cselect_b64 s[28:29], -1, 0
	s_add_u32 s38, s94, 0x4800000
	v_and_or_b32 v2, v134, s4, v2
	v_and_b32_e32 v3, 48, v3
	s_addc_u32 s39, s95, 0
	v_lshl_or_b32 v135, v2, 11, v3
	v_ashrrev_i32_e32 v2, 6, v134
	v_lshrrev_b32_e32 v5, 1, v134
	s_add_u32 s40, s94, 0x6c00000
	v_lshlrev_b32_e32 v4, 5, v2
	v_and_b32_e32 v5, 24, v5
	v_bfe_u32 v6, v134, 2, 2
	s_addc_u32 s41, s95, 0
	v_or3_b32 v4, v4, v5, v6
	s_add_u32 s42, s94, 0x2400000
	v_lshl_or_b32 v145, v4, 11, v3
	v_lshrrev_b32_e32 v5, 4, v4
	v_and_b32_e32 v6, 15, v4
	v_lshl_or_b32 v145, v5, 15, v3
	v_lshl_or_b32 v145, v6, 6, v145
	v_lshlrev_b32_e32 v4, 2, v134
	s_addc_u32 s43, s95, 0
	v_and_b32_e32 v4, 48, v4
	s_add_u32 s44, s94, 0xfc00000
	v_sub_u32_e32 v4, 0, v4
	s_addc_u32 s45, s95, 0
	v_and_b32_e32 v0, 63, v134
	v_lshlrev_b32_e32 v3, 6, v134
	v_bitop3_b32 v4, v134, 48, v4 bitop3:0x48
	s_movk_i32 s4, 0x3c0
	s_add_u32 s56, s94, 0x80
	v_lshlrev_b32_e32 v0, 4, v0
	v_and_or_b32 v4, v3, s4, v4
	v_lshlrev_b32_e32 v5, 12, v2
	s_movk_i32 s4, 0xe000
	s_addc_u32 s57, s95, 0
	v_or_b32_e32 v147, v5, v0
	v_lshl_or_b32 v148, v2, 11, v0
	v_and_or_b32 v149, v3, s4, v4
	v_and_or_b32 v0, v5, s85, v4
	s_add_u32 s58, s56, s6
	v_or_b32_e32 v142, 0x8000, v135
	v_or_b32_e32 v143, 0x10000, v135
	v_or_b32_e32 v144, 0x18000, v135
	v_or_b32_e32 v146, 0x100, v145
	v_or_b32_e32 v150, 0x4000, v0
	v_or_b32_e32 v151, 0xa000, v0
	v_add_u32_e32 v152, 0x6000, v149
	s_addc_u32 s59, s57, 0
	s_add_u32 s58, s58, 0x780
	s_addc_u32 s59, s59, 0
	s_mov_b64 s[60:61], 64
	s_cmp_eq_u32 s13, 2
	s_cbranch_scc1 .Lgemm_a_rm
	v_and_b32_e32 v3, 48, v135
	v_bfe_u32 v4, v134, 2, 4
	v_and_b32_e32 v2, 0x1fffc0, v134
	v_lshlrev_b32_e32 v2, 11, v2
	v_lshl_or_b32 v2, v4, 6, v2
	v_or_b32_e32 v135, v2, v3
	v_or_b32_e32 v142, 0x8000, v135
	v_or_b32_e32 v143, 0x10000, v135
	v_or_b32_e32 v144, 0x18000, v135
	s_add_u32 s56, s56, 0x780
	s_addc_u32 s57, s57, 0
	s_mov_b64 s[60:61], 0x400
.Lgemm_a_rm:
	s_mov_b32 s76, s20
	s_mov_b32 s77, s20
	s_branch .LBB0_237

.LBB0_242:
	s_andn2_b64 vcc, exec, s[48:49]
	s_cbranch_vccnz .LBB0_236
	s_lshl_b32 s48, s6, 8
	s_lshl_b32 s46, s80, 7
	s_ashr_i32 s49, s48, 31
	s_ashr_i32 s47, s46, 31
	s_lshl_b64 s[10:11], s[48:49], 11
	s_lshl_b64 s[50:51], s[46:47], 11
	s_add_u32 s10, s94, s10
	v_readfirstlane_b32 s5, v147
	v_add_u32_e32 v2, 0x400, v147
	s_addc_u32 s11, s95, s11
	v_mov_b32_e32 v0, v135
	s_mov_b32 m0, s5
	v_readfirstlane_b32 s5, v2
	v_add_u32_e32 v2, 0x800, v147
	v_mov_b32_e32 v130, v142
	global_load_lds_dwordx4 v0, s[10:11]
	s_mov_b32 m0, s5
	v_readfirstlane_b32 s5, v2
	v_add_u32_e32 v2, 0xc00, v147
	v_mov_b32_e32 v132, v143
	global_load_lds_dwordx4 v130, s[10:11]
	s_mov_b32 m0, s5
	v_readfirstlane_b32 s5, v2
	v_add_u32_e32 v2, 0x4000, v148
	s_add_u32 s52, s54, s50
	v_mov_b32_e32 v136, v144
	global_load_lds_dwordx4 v132, s[10:11]
	s_mov_b32 m0, s5
	v_readfirstlane_b32 s5, v2
	v_add_u32_e32 v2, 0x4400, v148
	s_addc_u32 s53, s55, s51
	v_mov_b32_e32 v138, v145
	global_load_lds_dwordx4 v136, s[10:11]
	s_mov_b32 m0, s5
	v_readfirstlane_b32 s5, v2
	v_mov_b32_e32 v140, v146
	global_load_lds_dwordx4 v138, s[52:53]
	s_mov_b32 m0, s5
	v_add_u32_e32 v4, 0x6000, v147
	v_mov_b32_e32 v131, v1
	global_load_lds_dwordx4 v140, s[52:53]
	v_readfirstlane_b32 s5, v4
	v_lshl_add_u64 v[2:3], s[10:11], 0, v[0:1]
	v_lshl_add_u64 v[2:3], v[2:3], 0, s[60:61]
	s_mov_b32 m0, s5
	v_add_u32_e32 v4, 0x6400, v147
	global_load_lds_dwordx4 v[2:3], off
	v_readfirstlane_b32 s5, v4
	v_lshl_add_u64 v[2:3], s[10:11], 0, v[130:131]
	v_lshl_add_u64 v[2:3], v[2:3], 0, s[60:61]
	s_mov_b32 m0, s5
	v_mov_b32_e32 v133, v1
	v_add_u32_e32 v4, 0x6800, v147
	global_load_lds_dwordx4 v[2:3], off
	v_readfirstlane_b32 s5, v4
	v_lshl_add_u64 v[2:3], s[10:11], 0, v[132:133]
	v_lshl_add_u64 v[2:3], v[2:3], 0, s[60:61]
	s_mov_b32 m0, s5
	v_mov_b32_e32 v137, v1
	v_add_u32_e32 v4, 0x6c00, v147
	global_load_lds_dwordx4 v[2:3], off
	v_readfirstlane_b32 s5, v4
	v_lshl_add_u64 v[2:3], s[10:11], 0, v[136:137]
	v_lshl_add_u64 v[2:3], v[2:3], 0, s[60:61]
	s_mov_b32 m0, s5
	v_mov_b32_e32 v139, v1
	v_add_u32_e32 v4, 0xa000, v148
	global_load_lds_dwordx4 v[2:3], off
	v_readfirstlane_b32 s5, v4
	v_lshl_add_u64 v[2:3], s[52:53], 0, v[138:139]
	v_lshl_add_u64 v[2:3], v[2:3], 0, s[86:87]
	s_mov_b32 m0, s5
	v_mov_b32_e32 v141, v1
	v_add_u32_e32 v4, 0xa400, v148
	global_load_lds_dwordx4 v[2:3], off
	v_readfirstlane_b32 s5, v4
	v_lshl_add_u64 v[2:3], s[52:53], 0, v[140:141]
	v_lshl_add_u64 v[2:3], v[2:3], 0, s[86:87]
	s_mov_b32 m0, s5
	s_andn2_b64 vcc, exec, s[28:29]
	global_load_lds_dwordx4 v[2:3], off
	s_cbranch_vccnz .LBB0_245
	s_sleep 10

.LBB0_246:
	s_add_i32 s10, s7, 0xffffa000
	s_cmp_lg_u32 s7, 0
	s_cselect_b32 s12, s10, 0xc000
	v_add_u32_e32 v131, s7, v150
	s_waitcnt vmcnt(6)
	s_barrier
	v_add_u32_e32 v133, s7, v149
	ds_read_b128 v[154:157], v131 offset:0
	ds_read_b128 v[158:161], v131 offset:0x400
	ds_read_b128 v[162:165], v131 offset:0x800
	ds_read_b128 v[166:169], v131 offset:0xc00
	v_add_u32_e32 v131, s12, v147
	ds_read_b128 v[170:173], v133 offset:0
	ds_read_b128 v[174:177], v133 offset:0x400
	ds_read_b128 v[178:181], v133 offset:0x800
	ds_read_b128 v[200:203], v133 offset:0xc00
	ds_read_b128 v[204:207], v133 offset:0x1000
	ds_read_b128 v[208:211], v133 offset:0x1400
	ds_read_b128 v[212:215], v133 offset:0x1800
	ds_read_b128 v[216:219], v133 offset:0x1c00
	s_add_u32 s10, s8, s50
	v_readfirstlane_b32 s13, v131
	v_add_u32_e32 v133, 0x400, v131
	s_addc_u32 s11, s9, s51
	s_mov_b32 m0, s13
	v_readfirstlane_b32 s13, v133
	v_add_u32_e32 v133, 0x800, v131
	v_add_u32_e32 v131, 0xc00, v131
	global_load_lds_dwordx4 v0, s[10:11]
	s_mov_b32 m0, s13
	v_readfirstlane_b32 s13, v133
	s_nop 0
	global_load_lds_dwordx4 v130, s[10:11]
	s_mov_b32 m0, s13
	v_readfirstlane_b32 s13, v131
	s_nop 0
	global_load_lds_dwordx4 v132, s[10:11]
	s_mov_b32 m0, s13
	s_nop 0
	global_load_lds_dwordx4 v136, s[10:11]
	s_waitcnt lgkmcnt(4)
	s_nop 0
	v_mfma_f32_16x16x32_bf16 v[126:129], v[154:157], v[170:173], v[126:129]
	v_mfma_f32_16x16x32_bf16 v[122:125], v[154:157], v[174:177], v[122:125]
	v_mfma_f32_16x16x32_bf16 v[118:121], v[154:157], v[178:181], v[118:121]
	v_mfma_f32_16x16x32_bf16 v[114:117], v[154:157], v[200:203], v[114:117]
	v_mfma_f32_16x16x32_bf16 v[110:113], v[158:161], v[170:173], v[110:113]
	v_mfma_f32_16x16x32_bf16 v[102:105], v[158:161], v[174:177], v[102:105]
	v_mfma_f32_16x16x32_bf16 v[94:97], v[158:161], v[178:181], v[94:97]
	v_mfma_f32_16x16x32_bf16 v[86:89], v[158:161], v[200:203], v[86:89]
	v_mfma_f32_16x16x32_bf16 v[78:81], v[162:165], v[170:173], v[78:81]
	v_mfma_f32_16x16x32_bf16 v[70:73], v[162:165], v[174:177], v[70:73]
	v_mfma_f32_16x16x32_bf16 v[62:65], v[162:165], v[178:181], v[62:65]
	v_mfma_f32_16x16x32_bf16 v[54:57], v[162:165], v[200:203], v[54:57]
	v_mfma_f32_16x16x32_bf16 v[46:49], v[166:169], v[170:173], v[46:49]
	v_mfma_f32_16x16x32_bf16 v[38:41], v[166:169], v[174:177], v[38:41]
	v_mfma_f32_16x16x32_bf16 v[30:33], v[166:169], v[178:181], v[30:33]
	v_mfma_f32_16x16x32_bf16 v[22:25], v[166:169], v[200:203], v[22:25]
	v_add_u32_e32 v131, s12, v148
	v_add_u32_e32 v133, 0x4000, v131
	s_add_u32 s10, s5, s100
	v_readfirstlane_b32 s12, v133
	v_add_u32_e32 v131, 0x4400, v131
	s_addc_u32 s11, s6, 0
	s_mov_b32 m0, s12
	v_readfirstlane_b32 s12, v131
	s_nop 0
	global_load_lds_dwordx4 v138, s[10:11]
	s_mov_b32 m0, s12
	s_nop 0
	global_load_lds_dwordx4 v140, s[10:11]
	s_waitcnt lgkmcnt(0)
	s_nop 0
	v_mfma_f32_16x16x32_bf16 v[106:109], v[154:157], v[204:207], v[106:109]
	v_mfma_f32_16x16x32_bf16 v[98:101], v[154:157], v[208:211], v[98:101]
	v_mfma_f32_16x16x32_bf16 v[90:93], v[154:157], v[212:215], v[90:93]
	v_mfma_f32_16x16x32_bf16 v[82:85], v[154:157], v[216:219], v[82:85]
	v_mfma_f32_16x16x32_bf16 v[74:77], v[158:161], v[204:207], v[74:77]
	v_mfma_f32_16x16x32_bf16 v[66:69], v[158:161], v[208:211], v[66:69]
	v_mfma_f32_16x16x32_bf16 v[58:61], v[158:161], v[212:215], v[58:61]
	v_mfma_f32_16x16x32_bf16 v[50:53], v[158:161], v[216:219], v[50:53]
	v_mfma_f32_16x16x32_bf16 v[42:45], v[162:165], v[204:207], v[42:45]
	v_mfma_f32_16x16x32_bf16 v[34:37], v[162:165], v[208:211], v[34:37]
	v_mfma_f32_16x16x32_bf16 v[26:29], v[162:165], v[212:215], v[26:29]
	v_mfma_f32_16x16x32_bf16 v[18:21], v[162:165], v[216:219], v[18:21]
	v_mfma_f32_16x16x32_bf16 v[14:17], v[166:169], v[204:207], v[14:17]
	v_mfma_f32_16x16x32_bf16 v[10:13], v[166:169], v[208:211], v[10:13]
	v_mfma_f32_16x16x32_bf16 v[6:9], v[166:169], v[212:215], v[6:9]
	v_mfma_f32_16x16x32_bf16 v[2:5], v[166:169], v[216:219], v[2:5]
	s_add_i32 s10, s7, 0x6000
	s_cmpk_lg_u32 s7, 0xc000
	s_cselect_b32 s7, s10, 0
	s_addk_i32 s100, 0x400
	s_add_u32 s50, s50, s60
	s_addc_u32 s51, s51, 0
	s_cmpk_lg_i32 s100, 0x7800
	s_cbranch_scc1 .LBB0_246
	s_waitcnt vmcnt(6)
	s_barrier
	v_add_u32_e32 v0, s7, v150
	v_add_u32_e32 v140, s7, v149
	ds_read_b128 v[130:133], v0 offset:0
	ds_read_b128 v[136:139], v0 offset:0x400
	ds_read_b128 v[154:157], v0 offset:0x800
	ds_read_b128 v[158:161], v0 offset:0xc00
	ds_read_b128 v[162:165], v140 offset:0
	ds_read_b128 v[166:169], v140 offset:0x400
	ds_read_b128 v[170:173], v140 offset:0x800
	ds_read_b128 v[174:177], v140 offset:0xc00
	ds_read_b128 v[178:181], v140 offset:0x1000
	ds_read_b128 v[200:203], v140 offset:0x1400
	ds_read_b128 v[204:207], v140 offset:0x1800
	ds_read_b128 v[208:211], v140 offset:0x1c00
	s_lshl_b32 s49, s4, 8
	s_waitcnt lgkmcnt(4)
	s_nop 0
	v_mfma_f32_16x16x32_bf16 v[126:129], v[130:133], v[162:165], v[126:129]
	v_mfma_f32_16x16x32_bf16 v[118:121], v[130:133], v[170:173], v[118:121]
	v_mfma_f32_16x16x32_bf16 v[114:117], v[130:133], v[174:177], v[114:117]
	v_mfma_f32_16x16x32_bf16 v[110:113], v[136:139], v[162:165], v[110:113]
	v_mfma_f32_16x16x32_bf16 v[102:105], v[136:139], v[166:169], v[102:105]
	v_mfma_f32_16x16x32_bf16 v[94:97], v[136:139], v[170:173], v[94:97]
	v_mfma_f32_16x16x32_bf16 v[86:89], v[136:139], v[174:177], v[86:89]
	v_mfma_f32_16x16x32_bf16 v[70:73], v[154:157], v[166:169], v[70:73]
	v_mfma_f32_16x16x32_bf16 v[62:65], v[154:157], v[170:173], v[62:65]
	v_mfma_f32_16x16x32_bf16 v[54:57], v[154:157], v[174:177], v[54:57]
	v_mfma_f32_16x16x32_bf16 v[46:49], v[158:161], v[162:165], v[46:49]
	v_mfma_f32_16x16x32_bf16 v[38:41], v[158:161], v[166:169], v[38:41]
	v_mfma_f32_16x16x32_bf16 v[30:33], v[158:161], v[170:173], v[30:33]
	v_mfma_f32_16x16x32_bf16 v[22:25], v[158:161], v[174:177], v[22:25]
	v_mfma_f32_16x16x32_bf16 v[212:215], v[130:133], v[166:169], v[122:125]
	v_mfma_f32_16x16x32_bf16 v[216:219], v[154:157], v[162:165], v[78:81]
	s_waitcnt lgkmcnt(0)
	s_nop 0
	v_mfma_f32_16x16x32_bf16 v[174:177], v[136:139], v[178:181], v[74:77]
	v_mfma_f32_16x16x32_bf16 v[220:223], v[136:139], v[200:203], v[66:69]
	v_mfma_f32_16x16x32_bf16 v[224:227], v[136:139], v[204:207], v[58:61]
	v_mfma_f32_16x16x32_bf16 v[50:53], v[136:139], v[208:211], v[50:53]
	v_mfma_f32_16x16x32_bf16 v[136:139], v[154:157], v[178:181], v[42:45]
	v_mfma_f32_16x16x32_bf16 v[34:37], v[154:157], v[200:203], v[34:37]
	v_mfma_f32_16x16x32_bf16 v[6:9], v[158:161], v[204:207], v[6:9]
	v_mfma_f32_16x16x32_bf16 v[162:165], v[130:133], v[178:181], v[106:109]
	v_mfma_f32_16x16x32_bf16 v[166:169], v[130:133], v[200:203], v[98:101]
	v_mfma_f32_16x16x32_bf16 v[170:173], v[130:133], v[204:207], v[90:93]
	v_mfma_f32_16x16x32_bf16 v[130:133], v[130:133], v[208:211], v[82:85]
	v_mfma_f32_16x16x32_bf16 v[228:231], v[154:157], v[204:207], v[26:29]
	v_mfma_f32_16x16x32_bf16 v[154:157], v[154:157], v[208:211], v[18:21]
	v_mfma_f32_16x16x32_bf16 v[178:181], v[158:161], v[178:181], v[14:17]
	v_mfma_f32_16x16x32_bf16 v[200:203], v[158:161], v[200:203], v[10:13]
	v_mfma_f32_16x16x32_bf16 v[158:161], v[158:161], v[208:211], v[2:5]
	s_waitcnt vmcnt(0)
	s_barrier
	ds_read_b128 v[2:5], v151 offset:0
	ds_read_b128 v[14:17], v151 offset:0x400
	ds_read_b128 v[204:207], v151 offset:0x800
	ds_read_b128 v[208:211], v151 offset:0xc00
	ds_read_b128 v[10:13], v152 offset:0
	ds_read_b128 v[18:21], v152 offset:0x400
	ds_read_b128 v[26:29], v152 offset:0x800
	ds_read_b128 v[42:45], v152 offset:0xc00
	ds_read_b128 v[232:235], v152 offset:0x1000
	ds_read_b128 v[236:239], v152 offset:0x1400
	ds_read_b128 v[240:243], v152 offset:0x1800
	ds_read_b128 v[244:247], v152 offset:0x1c00
	s_nop 0
	s_waitcnt lgkmcnt(4)
	s_nop 0
	v_mfma_f32_16x16x32_bf16 v[122:125], v[2:5], v[10:13], v[126:129]
	v_mfma_f32_16x16x32_bf16 v[106:109], v[2:5], v[18:21], v[212:215]
	v_mfma_f32_16x16x32_bf16 v[90:93], v[2:5], v[26:29], v[118:121]
	v_mfma_f32_16x16x32_bf16 v[74:77], v[2:5], v[42:45], v[114:117]
	v_mfma_f32_16x16x32_bf16 v[126:129], v[14:17], v[10:13], v[110:113]
	v_mfma_f32_16x16x32_bf16 v[110:113], v[14:17], v[18:21], v[102:105]
	v_mfma_f32_16x16x32_bf16 v[94:97], v[14:17], v[26:29], v[94:97]
	v_mfma_f32_16x16x32_bf16 v[78:81], v[14:17], v[42:45], v[86:89]
	v_mfma_f32_16x16x32_bf16 v[114:117], v[204:207], v[10:13], v[216:219]
	v_mfma_f32_16x16x32_bf16 v[98:101], v[204:207], v[18:21], v[70:73]
	v_mfma_f32_16x16x32_bf16 v[82:85], v[204:207], v[26:29], v[62:65]
	v_mfma_f32_16x16x32_bf16 v[66:69], v[204:207], v[42:45], v[54:57]
	v_mfma_f32_16x16x32_bf16 v[118:121], v[208:211], v[10:13], v[46:49]
	v_mfma_f32_16x16x32_bf16 v[102:105], v[208:211], v[18:21], v[38:41]
	v_mfma_f32_16x16x32_bf16 v[86:89], v[208:211], v[26:29], v[30:33]
	v_mfma_f32_16x16x32_bf16 v[70:73], v[208:211], v[42:45], v[22:25]
	s_waitcnt lgkmcnt(0)
	s_nop 0
	v_mfma_f32_16x16x32_bf16 v[58:61], v[2:5], v[232:235], v[162:165]
	v_mfma_f32_16x16x32_bf16 v[42:45], v[2:5], v[236:239], v[166:169]
	v_mfma_f32_16x16x32_bf16 v[26:29], v[2:5], v[240:243], v[170:173]
	v_mfma_f32_16x16x32_bf16 v[10:13], v[2:5], v[244:247], v[130:133]
	v_mfma_f32_16x16x32_bf16 v[62:65], v[14:17], v[232:235], v[174:177]
	v_mfma_f32_16x16x32_bf16 v[46:49], v[14:17], v[236:239], v[220:223]
	v_mfma_f32_16x16x32_bf16 v[30:33], v[14:17], v[240:243], v[224:227]
	v_mfma_f32_16x16x32_bf16 v[14:17], v[14:17], v[244:247], v[50:53]
	v_mfma_f32_16x16x32_bf16 v[50:53], v[204:207], v[232:235], v[136:139]
	v_mfma_f32_16x16x32_bf16 v[34:37], v[204:207], v[236:239], v[34:37]
	v_mfma_f32_16x16x32_bf16 v[18:21], v[204:207], v[240:243], v[228:231]
	v_mfma_f32_16x16x32_bf16 v[2:5], v[204:207], v[244:247], v[154:157]
	v_mfma_f32_16x16x32_bf16 v[54:57], v[208:211], v[232:235], v[178:181]
	v_mfma_f32_16x16x32_bf16 v[38:41], v[208:211], v[236:239], v[200:203]
	v_mfma_f32_16x16x32_bf16 v[22:25], v[208:211], v[240:243], v[6:9]
	v_mfma_f32_16x16x32_bf16 v[6:9], v[208:211], v[244:247], v[158:161]
	v_mov_b32_e32 v136, v134
	s_mov_b64 s[50:51], -1
	s_and_b64 vcc, exec, s[22:23]
	s_barrier
	s_cbranch_vccz .LBB0_264
	s_and_b64 vcc, exec, s[0:1]
	s_cbranch_vccz .LBB0_250
	v_lshrrev_b32_e32 v0, 6, v136
	v_mul_lo_u32 v137, v0, s14
	v_and_b32_e32 v130, 15, v136
	v_and_or_b32 v0, v136, 48, v137
	s_movk_i32 s4, 0x90
	v_mad_u32_u24 v0, v130, s4, v0
	v_cvt_pk_bf16_f32 v130, v122, v123
	v_cvt_pk_bf16_f32 v131, v124, v125
	v_cvt_pk_bf16_f32 v132, v126, v127
	v_cvt_pk_bf16_f32 v133, v128, v129
	s_waitcnt vmcnt(0)
	ds_write_b128 v0, v[130:133]
	v_cvt_pk_bf16_f32 v130, v114, v115
	v_cvt_pk_bf16_f32 v131, v116, v117
	v_cvt_pk_bf16_f32 v132, v118, v119
	v_cvt_pk_bf16_f32 v133, v120, v121
	ds_write_b128 v0, v[130:133] offset:64
	v_cvt_pk_bf16_f32 v130, v106, v107
	v_cvt_pk_bf16_f32 v131, v108, v109
	v_cvt_pk_bf16_f32 v132, v110, v111
	v_cvt_pk_bf16_f32 v133, v112, v113
	ds_write_b128 v0, v[130:133] offset:2304
	v_cvt_pk_bf16_f32 v130, v98, v99
	v_cvt_pk_bf16_f32 v131, v100, v101
	v_cvt_pk_bf16_f32 v132, v102, v103
	v_cvt_pk_bf16_f32 v133, v104, v105
	ds_write_b128 v0, v[130:133] offset:2368
	v_cvt_pk_bf16_f32 v130, v90, v91
	v_cvt_pk_bf16_f32 v131, v92, v93
	v_cvt_pk_bf16_f32 v132, v94, v95
	v_cvt_pk_bf16_f32 v133, v96, v97
	ds_write_b128 v0, v[130:133] offset:4608
	v_cvt_pk_bf16_f32 v130, v82, v83
	v_cvt_pk_bf16_f32 v131, v84, v85
	v_cvt_pk_bf16_f32 v132, v86, v87
	v_cvt_pk_bf16_f32 v133, v88, v89
	ds_write_b128 v0, v[130:133] offset:4672
	v_cvt_pk_bf16_f32 v130, v74, v75
	v_cvt_pk_bf16_f32 v131, v76, v77
	v_cvt_pk_bf16_f32 v132, v78, v79
	v_cvt_pk_bf16_f32 v133, v80, v81
	ds_write_b128 v0, v[130:133] offset:6912
	v_cvt_pk_bf16_f32 v130, v66, v67
	v_cvt_pk_bf16_f32 v131, v68, v69
	v_cvt_pk_bf16_f32 v132, v70, v71
	v_cvt_pk_bf16_f32 v133, v72, v73
	ds_write_b128 v0, v[130:133] offset:6976
	v_cvt_pk_bf16_f32 v130, v58, v59
	v_cvt_pk_bf16_f32 v131, v60, v61
	v_cvt_pk_bf16_f32 v132, v62, v63
	v_cvt_pk_bf16_f32 v133, v64, v65
	ds_write_b128 v0, v[130:133] offset:9216
	v_cvt_pk_bf16_f32 v130, v50, v51
	v_cvt_pk_bf16_f32 v131, v52, v53
	v_cvt_pk_bf16_f32 v132, v54, v55
	v_cvt_pk_bf16_f32 v133, v56, v57
	ds_write_b128 v0, v[130:133] offset:9280
	v_cvt_pk_bf16_f32 v130, v42, v43
	v_cvt_pk_bf16_f32 v131, v44, v45
	v_cvt_pk_bf16_f32 v132, v46, v47
	v_cvt_pk_bf16_f32 v133, v48, v49
	ds_write_b128 v0, v[130:133] offset:11520
	v_cvt_pk_bf16_f32 v130, v34, v35
	v_cvt_pk_bf16_f32 v131, v36, v37
	v_cvt_pk_bf16_f32 v132, v38, v39
	v_cvt_pk_bf16_f32 v133, v40, v41
	ds_write_b128 v0, v[130:133] offset:11584
	v_cvt_pk_bf16_f32 v130, v26, v27
	v_cvt_pk_bf16_f32 v131, v28, v29
	v_cvt_pk_bf16_f32 v132, v30, v31
	v_cvt_pk_bf16_f32 v133, v32, v33
	ds_write_b128 v0, v[130:133] offset:13824
	v_cvt_pk_bf16_f32 v130, v18, v19
	v_cvt_pk_bf16_f32 v131, v20, v21
	v_cvt_pk_bf16_f32 v132, v22, v23
	v_cvt_pk_bf16_f32 v133, v24, v25
	ds_write_b128 v0, v[130:133] offset:13888
	v_cvt_pk_bf16_f32 v130, v10, v11
	v_cvt_pk_bf16_f32 v131, v12, v13
	v_cvt_pk_bf16_f32 v132, v14, v15
	v_cvt_pk_bf16_f32 v133, v16, v17
	ds_write_b128 v0, v[130:133] offset:16128
	v_cvt_pk_bf16_f32 v130, v2, v3
	v_cvt_pk_bf16_f32 v131, v4, v5
	v_cvt_pk_bf16_f32 v132, v6, v7
	v_cvt_pk_bf16_f32 v133, v8, v9
	ds_write_b128 v0, v[130:133] offset:16192
	v_and_b32_e32 v0, 0xffffff80, v136
	v_add_u32_e32 v130, s48, v0
	v_ashrrev_i32_e32 v131, 31, v130
	v_lshlrev_b64 v[130:131], 11, v[130:131]
	v_lshl_add_u64 v[130:131], s[38:39], 0, v[130:131]
	v_and_b32_e32 v0, 64, v136
	v_lshl_add_u64 v[130:131], s[46:47], 1, v[130:131]
	v_lshlrev_b32_e32 v0, 1, v0
	v_lshl_add_u64 v[138:139], v[130:131], 0, v[0:1]
	v_lshlrev_b32_e32 v0, 4, v136
	v_and_b32_e32 v0, 0x70, v0
	v_bfe_u32 v140, v136, 3, 3
	v_or_b32_e32 v130, v137, v0
	s_waitcnt lgkmcnt(0)
	v_mad_u32_u24 v137, v140, s4, v130
	ds_read_b128 v[130:133], v137
	v_lshl_add_u64 v[138:139], v[138:139], 0, v[0:1]
	v_lshlrev_b32_e32 v0, 11, v140
	v_lshl_add_u64 v[140:141], v[138:139], 0, v[0:1]
	s_mov_b64 s[50:51], 0
	s_waitcnt lgkmcnt(0)
	global_store_dwordx4 v[140:141], v[130:133], off
	ds_read_b128 v[130:133], v137 offset:1152
	v_or_b32_e32 v140, 0x4000, v0
	v_mov_b32_e32 v141, v1
	v_lshl_add_u64 v[140:141], v[138:139], 0, v[140:141]
	s_waitcnt lgkmcnt(0)
	global_store_dwordx4 v[140:141], v[130:133], off
	ds_read_b128 v[130:133], v137 offset:2304
	v_or_b32_e32 v140, 0x8000, v0
	v_mov_b32_e32 v141, v1
	v_lshl_add_u64 v[140:141], v[138:139], 0, v[140:141]
	s_waitcnt lgkmcnt(0)
	global_store_dwordx4 v[140:141], v[130:133], off
	ds_read_b128 v[130:133], v137 offset:3456
	v_or_b32_e32 v140, 0xc000, v0
	v_mov_b32_e32 v141, v1
	v_lshl_add_u64 v[140:141], v[138:139], 0, v[140:141]
	s_waitcnt lgkmcnt(0)
	global_store_dwordx4 v[140:141], v[130:133], off
	ds_read_b128 v[130:133], v137 offset:4608
	v_or_b32_e32 v140, 0x10000, v0
	v_mov_b32_e32 v141, v1
	v_lshl_add_u64 v[140:141], v[138:139], 0, v[140:141]
	s_waitcnt lgkmcnt(0)
	global_store_dwordx4 v[140:141], v[130:133], off
	ds_read_b128 v[130:133], v137 offset:5760
	v_or_b32_e32 v140, 0x14000, v0
	v_mov_b32_e32 v141, v1
	v_lshl_add_u64 v[140:141], v[138:139], 0, v[140:141]
	s_waitcnt lgkmcnt(0)
	global_store_dwordx4 v[140:141], v[130:133], off
	ds_read_b128 v[130:133], v137 offset:6912
	v_or_b32_e32 v140, 0x18000, v0
	v_mov_b32_e32 v141, v1
	v_lshl_add_u64 v[140:141], v[138:139], 0, v[140:141]
	s_waitcnt lgkmcnt(0)
	global_store_dwordx4 v[140:141], v[130:133], off
	ds_read_b128 v[130:133], v137 offset:8064
	v_or_b32_e32 v140, 0x1c000, v0
	v_mov_b32_e32 v141, v1
	v_lshl_add_u64 v[140:141], v[138:139], 0, v[140:141]
	s_waitcnt lgkmcnt(0)
	global_store_dwordx4 v[140:141], v[130:133], off
	ds_read_b128 v[130:133], v137 offset:9216
	v_or_b32_e32 v140, 0x20000, v0
	v_mov_b32_e32 v141, v1
	v_lshl_add_u64 v[140:141], v[138:139], 0, v[140:141]
	s_waitcnt lgkmcnt(0)
	global_store_dwordx4 v[140:141], v[130:133], off
	ds_read_b128 v[130:133], v137 offset:10368
	v_or_b32_e32 v140, 0x24000, v0
	v_mov_b32_e32 v141, v1
	v_lshl_add_u64 v[140:141], v[138:139], 0, v[140:141]
	s_waitcnt lgkmcnt(0)
	global_store_dwordx4 v[140:141], v[130:133], off
	ds_read_b128 v[130:133], v137 offset:11520
	v_or_b32_e32 v140, 0x28000, v0
	v_mov_b32_e32 v141, v1
	v_lshl_add_u64 v[140:141], v[138:139], 0, v[140:141]
	s_waitcnt lgkmcnt(0)
	global_store_dwordx4 v[140:141], v[130:133], off
	ds_read_b128 v[130:133], v137 offset:12672
	v_or_b32_e32 v140, 0x2c000, v0
	v_mov_b32_e32 v141, v1
	v_lshl_add_u64 v[140:141], v[138:139], 0, v[140:141]
	s_waitcnt lgkmcnt(0)
	global_store_dwordx4 v[140:141], v[130:133], off
	ds_read_b128 v[130:133], v137 offset:13824
	v_or_b32_e32 v140, 0x30000, v0
	v_mov_b32_e32 v141, v1
	v_lshl_add_u64 v[140:141], v[138:139], 0, v[140:141]
	s_waitcnt lgkmcnt(0)
	global_store_dwordx4 v[140:141], v[130:133], off
	ds_read_b128 v[130:133], v137 offset:14976
	v_or_b32_e32 v140, 0x34000, v0
	v_mov_b32_e32 v141, v1
	v_lshl_add_u64 v[140:141], v[138:139], 0, v[140:141]
	s_waitcnt lgkmcnt(0)
	global_store_dwordx4 v[140:141], v[130:133], off
	ds_read_b128 v[130:133], v137 offset:16128
	v_or_b32_e32 v140, 0x38000, v0
	v_mov_b32_e32 v141, v1
	v_lshl_add_u64 v[140:141], v[138:139], 0, v[140:141]
	v_or_b32_e32 v0, 0x3c000, v0
	s_waitcnt lgkmcnt(0)
	global_store_dwordx4 v[140:141], v[130:133], off
	ds_read_b128 v[130:133], v137 offset:17280
	v_lshl_add_u64 v[138:139], v[138:139], 0, v[0:1]
	s_waitcnt lgkmcnt(0)
	global_store_dwordx4 v[138:139], v[130:133], off
	s_waitcnt lgkmcnt(0)
	s_barrier
.LBB0_250:
	s_andn2_b64 vcc, exec, s[50:51]
	s_cbranch_vccnz .LBB0_263
	s_cmp_gt_i32 s80, 7
	s_mov_b64 s[50:51], -1
	s_cbranch_scc0 .LBB0_261
	s_cmp_gt_u32 s80, 15
	s_cbranch_scc0 .LBB0_258
	s_cmp_gt_u32 s80, 23
	v_cvt_pk_bf16_f32 v131, v124, v125
	s_cbranch_scc0 .LBB0_255
	v_lshrrev_b32_e32 v0, 6, v136
	v_mul_lo_u32 v137, v0, s14
	v_and_b32_e32 v130, 15, v136
	v_and_or_b32 v0, v136, 48, v137
	s_movk_i32 s4, 0x90
	v_mad_u32_u24 v0, v130, s4, v0
	v_cvt_pk_bf16_f32 v138, v114, v115
	v_cvt_pk_bf16_f32 v139, v116, v117
	v_cvt_pk_bf16_f32 v140, v118, v119
	v_cvt_pk_bf16_f32 v141, v120, v121
	s_waitcnt vmcnt(0)
	ds_write_b128 v0, v[138:141] offset:64
	v_cvt_pk_bf16_f32 v138, v106, v107
	v_cvt_pk_bf16_f32 v139, v108, v109
	v_cvt_pk_bf16_f32 v140, v110, v111
	v_cvt_pk_bf16_f32 v141, v112, v113
	ds_write_b128 v0, v[138:141] offset:2304
	v_cvt_pk_bf16_f32 v138, v98, v99
	v_cvt_pk_bf16_f32 v139, v100, v101
	v_cvt_pk_bf16_f32 v140, v102, v103
	v_cvt_pk_bf16_f32 v141, v104, v105
	ds_write_b128 v0, v[138:141] offset:2368
	v_cvt_pk_bf16_f32 v138, v90, v91
	v_cvt_pk_bf16_f32 v139, v92, v93
	v_cvt_pk_bf16_f32 v140, v94, v95
	v_cvt_pk_bf16_f32 v141, v96, v97
	ds_write_b128 v0, v[138:141] offset:4608
	v_cvt_pk_bf16_f32 v138, v82, v83
	v_cvt_pk_bf16_f32 v139, v84, v85
	v_cvt_pk_bf16_f32 v140, v86, v87
	v_cvt_pk_bf16_f32 v141, v88, v89
	ds_write_b128 v0, v[138:141] offset:4672
	v_cvt_pk_bf16_f32 v138, v74, v75
	v_cvt_pk_bf16_f32 v139, v76, v77
	v_cvt_pk_bf16_f32 v140, v78, v79
	v_cvt_pk_bf16_f32 v141, v80, v81
	ds_write_b128 v0, v[138:141] offset:6912
	v_cvt_pk_bf16_f32 v138, v66, v67
	v_cvt_pk_bf16_f32 v139, v68, v69
	v_cvt_pk_bf16_f32 v140, v70, v71
	v_cvt_pk_bf16_f32 v141, v72, v73
	ds_write_b128 v0, v[138:141] offset:6976
	v_cvt_pk_bf16_f32 v138, v58, v59
	v_cvt_pk_bf16_f32 v139, v60, v61
	v_cvt_pk_bf16_f32 v140, v62, v63
	v_cvt_pk_bf16_f32 v141, v64, v65
	ds_write_b128 v0, v[138:141] offset:9216
	v_cvt_pk_bf16_f32 v138, v50, v51
	v_cvt_pk_bf16_f32 v139, v52, v53
	v_cvt_pk_bf16_f32 v140, v54, v55
	v_cvt_pk_bf16_f32 v141, v56, v57
	ds_write_b128 v0, v[138:141] offset:9280
	v_cvt_pk_bf16_f32 v138, v42, v43
	v_cvt_pk_bf16_f32 v139, v44, v45
	v_cvt_pk_bf16_f32 v140, v46, v47
	v_cvt_pk_bf16_f32 v141, v48, v49
	ds_write_b128 v0, v[138:141] offset:11520
	v_cvt_pk_bf16_f32 v138, v34, v35
	v_cvt_pk_bf16_f32 v139, v36, v37
	v_cvt_pk_bf16_f32 v140, v38, v39
	v_cvt_pk_bf16_f32 v141, v40, v41
	ds_write_b128 v0, v[138:141] offset:11584
	v_cvt_pk_bf16_f32 v138, v26, v27
	v_cvt_pk_bf16_f32 v139, v28, v29
	v_cvt_pk_bf16_f32 v140, v30, v31
	v_cvt_pk_bf16_f32 v141, v32, v33
	ds_write_b128 v0, v[138:141] offset:13824
	v_cvt_pk_bf16_f32 v138, v18, v19
	v_cvt_pk_bf16_f32 v139, v20, v21
	v_cvt_pk_bf16_f32 v140, v22, v23
	v_cvt_pk_bf16_f32 v141, v24, v25
	ds_write_b128 v0, v[138:141] offset:13888
	v_cvt_pk_bf16_f32 v138, v10, v11
	v_cvt_pk_bf16_f32 v139, v12, v13
	v_cvt_pk_bf16_f32 v140, v14, v15
	v_cvt_pk_bf16_f32 v141, v16, v17
	v_cvt_pk_bf16_f32 v130, v122, v123
	v_cvt_pk_bf16_f32 v132, v126, v127
	v_cvt_pk_bf16_f32 v133, v128, v129
	ds_write_b128 v0, v[138:141] offset:16128
	v_cvt_pk_bf16_f32 v138, v2, v3
	v_cvt_pk_bf16_f32 v139, v4, v5
	v_cvt_pk_bf16_f32 v140, v6, v7
	v_cvt_pk_bf16_f32 v141, v8, v9
	ds_write_b128 v0, v[130:133]
	ds_write_b128 v0, v[138:141] offset:16192
	v_and_b32_e32 v0, 0xffffff80, v136
	v_add_u32_e32 v132, s48, v0
	v_ashrrev_i32_e32 v133, 31, v132
	v_lshlrev_b64 v[132:133], 11, v[132:133]
	v_lshl_add_u64 v[132:133], s[94:95], 0, v[132:133]
	s_mov_b32 s92, s46
	v_and_b32_e32 v0, 64, v136
	v_lshl_add_u64 v[132:133], s[92:93], 1, v[132:133]
	v_lshlrev_b32_e32 v0, 1, v0
	v_lshl_add_u64 v[132:133], v[132:133], 0, v[0:1]
	v_lshlrev_b32_e32 v0, 4, v136
	v_and_b32_e32 v0, 0x70, v0
	v_bfe_u32 v130, v136, 3, 3
	v_or_b32_e32 v137, v137, v0
	s_waitcnt lgkmcnt(0)
	v_mad_u32_u24 v137, v130, s4, v137
	ds_read_b128 v[138:141], v137
	v_lshl_add_u64 v[132:133], v[132:133], 0, v[0:1]
	s_mov_b64 s[4:5], 0x8ffe800
	v_lshl_add_u64 v[132:133], v[132:133], 0, s[4:5]
	v_lshlrev_b32_e32 v0, 11, v130
	v_lshl_add_u64 v[154:155], v[132:133], 0, v[0:1]
	s_waitcnt lgkmcnt(0)
	global_store_dwordx4 v[154:155], v[138:141], off
	ds_read_b128 v[138:141], v137 offset:1152
	v_or_b32_e32 v154, 0x4000, v0
	v_mov_b32_e32 v155, v1
	v_lshl_add_u64 v[154:155], v[132:133], 0, v[154:155]
	s_movk_i32 s82, 0x1bff
	s_waitcnt lgkmcnt(0)
	global_store_dwordx4 v[154:155], v[138:141], off
	ds_read_b128 v[138:141], v137 offset:2304
	v_or_b32_e32 v154, 0x8000, v0
	v_mov_b32_e32 v155, v1
	v_lshl_add_u64 v[154:155], v[132:133], 0, v[154:155]
	s_mov_b64 s[50:51], 0
	s_waitcnt lgkmcnt(0)
	global_store_dwordx4 v[154:155], v[138:141], off
	ds_read_b128 v[138:141], v137 offset:3456
	v_or_b32_e32 v154, 0xc000, v0
	v_mov_b32_e32 v155, v1
	v_lshl_add_u64 v[154:155], v[132:133], 0, v[154:155]
	s_waitcnt lgkmcnt(0)
	global_store_dwordx4 v[154:155], v[138:141], off
	ds_read_b128 v[138:141], v137 offset:4608
	v_or_b32_e32 v154, 0x10000, v0
	v_mov_b32_e32 v155, v1
	v_lshl_add_u64 v[154:155], v[132:133], 0, v[154:155]
	s_waitcnt lgkmcnt(0)
	global_store_dwordx4 v[154:155], v[138:141], off
	ds_read_b128 v[138:141], v137 offset:5760
	v_or_b32_e32 v154, 0x14000, v0
	v_mov_b32_e32 v155, v1
	v_lshl_add_u64 v[154:155], v[132:133], 0, v[154:155]
	s_waitcnt lgkmcnt(0)
	global_store_dwordx4 v[154:155], v[138:141], off
	ds_read_b128 v[138:141], v137 offset:6912
	v_or_b32_e32 v154, 0x18000, v0
	v_mov_b32_e32 v155, v1
	v_lshl_add_u64 v[154:155], v[132:133], 0, v[154:155]
	s_waitcnt lgkmcnt(0)
	global_store_dwordx4 v[154:155], v[138:141], off
	ds_read_b128 v[138:141], v137 offset:8064
	v_or_b32_e32 v154, 0x1c000, v0
	v_mov_b32_e32 v155, v1
	v_lshl_add_u64 v[154:155], v[132:133], 0, v[154:155]
	s_waitcnt lgkmcnt(0)
	global_store_dwordx4 v[154:155], v[138:141], off
	ds_read_b128 v[138:141], v137 offset:9216
	v_or_b32_e32 v154, 0x20000, v0
	v_mov_b32_e32 v155, v1
	v_lshl_add_u64 v[154:155], v[132:133], 0, v[154:155]
	s_waitcnt lgkmcnt(0)
	global_store_dwordx4 v[154:155], v[138:141], off
	ds_read_b128 v[138:141], v137 offset:10368
	v_or_b32_e32 v154, 0x24000, v0
	v_mov_b32_e32 v155, v1
	v_lshl_add_u64 v[154:155], v[132:133], 0, v[154:155]
	s_waitcnt lgkmcnt(0)
	global_store_dwordx4 v[154:155], v[138:141], off
	ds_read_b128 v[138:141], v137 offset:11520
	v_or_b32_e32 v154, 0x28000, v0
	v_mov_b32_e32 v155, v1
	v_lshl_add_u64 v[154:155], v[132:133], 0, v[154:155]
	s_waitcnt lgkmcnt(0)
	global_store_dwordx4 v[154:155], v[138:141], off
	ds_read_b128 v[138:141], v137 offset:12672
	v_or_b32_e32 v154, 0x2c000, v0
	v_mov_b32_e32 v155, v1
	v_lshl_add_u64 v[154:155], v[132:133], 0, v[154:155]
	s_waitcnt lgkmcnt(0)
	global_store_dwordx4 v[154:155], v[138:141], off
	ds_read_b128 v[138:141], v137 offset:13824
	v_or_b32_e32 v154, 0x30000, v0
	v_mov_b32_e32 v155, v1
	v_lshl_add_u64 v[154:155], v[132:133], 0, v[154:155]
	s_waitcnt lgkmcnt(0)
	global_store_dwordx4 v[154:155], v[138:141], off
	ds_read_b128 v[138:141], v137 offset:14976
	v_or_b32_e32 v154, 0x34000, v0
	v_mov_b32_e32 v155, v1
	v_lshl_add_u64 v[154:155], v[132:133], 0, v[154:155]
	s_waitcnt lgkmcnt(0)
	global_store_dwordx4 v[154:155], v[138:141], off
	ds_read_b128 v[138:141], v137 offset:16128
	v_or_b32_e32 v154, 0x38000, v0
	v_mov_b32_e32 v155, v1
	v_lshl_add_u64 v[154:155], v[132:133], 0, v[154:155]
	v_or_b32_e32 v0, 0x3c000, v0
	s_waitcnt lgkmcnt(0)
	global_store_dwordx4 v[154:155], v[138:141], off
	ds_read_b128 v[138:141], v137 offset:17280
	v_lshl_add_u64 v[132:133], v[132:133], 0, v[0:1]
	s_waitcnt lgkmcnt(0)
	global_store_dwordx4 v[132:133], v[138:141], off
	s_waitcnt lgkmcnt(0)
	s_barrier
.LBB0_255:
	s_andn2_b64 vcc, exec, s[50:51]
	s_cbranch_vccnz .LBB0_257
	v_and_b32_e32 v0, 64, v136
	v_lshrrev_b32_e32 v130, 1, v136
	v_and_or_b32 v0, v130, 24, v0
	v_lshlrev_b32_e32 v130, 1, v136
	v_and_b32_e32 v130, 0xffffff1e, v130
	s_movk_i32 s7, 0x210
	v_mad_u32_u24 v0, v0, s7, v130
	v_cvt_pk_bf16_f32 v130, v122, v123
	s_waitcnt vmcnt(0)
	ds_write_b16 v0, v130
	ds_write_b16_d16_hi v0, v130 offset:528
	ds_write_b16 v0, v131 offset:1056
	ds_write_b16_d16_hi v0, v131 offset:1584
	v_cvt_pk_bf16_f32 v130, v106, v107
	v_cvt_pk_bf16_f32 v131, v108, v109
	ds_write_b16 v0, v130 offset:32
	ds_write_b16_d16_hi v0, v130 offset:560
	ds_write_b16 v0, v131 offset:1088
	ds_write_b16_d16_hi v0, v131 offset:1616
	v_cvt_pk_bf16_f32 v130, v90, v91
	v_cvt_pk_bf16_f32 v131, v92, v93
	ds_write_b16 v0, v130 offset:64
	ds_write_b16_d16_hi v0, v130 offset:592
	ds_write_b16 v0, v131 offset:1120
	ds_write_b16_d16_hi v0, v131 offset:1648
	v_cvt_pk_bf16_f32 v130, v74, v75
	v_cvt_pk_bf16_f32 v131, v76, v77
	ds_write_b16 v0, v130 offset:96
	ds_write_b16_d16_hi v0, v130 offset:624
	ds_write_b16 v0, v131 offset:1152
	ds_write_b16_d16_hi v0, v131 offset:1680
	v_cvt_pk_bf16_f32 v130, v58, v59
	v_cvt_pk_bf16_f32 v131, v60, v61
	ds_write_b16 v0, v130 offset:128
	ds_write_b16_d16_hi v0, v130 offset:656
	ds_write_b16 v0, v131 offset:1184
	ds_write_b16_d16_hi v0, v131 offset:1712
	v_cvt_pk_bf16_f32 v130, v42, v43
	v_cvt_pk_bf16_f32 v131, v44, v45
	ds_write_b16 v0, v130 offset:160
	ds_write_b16_d16_hi v0, v130 offset:688
	ds_write_b16 v0, v131 offset:1216
	ds_write_b16_d16_hi v0, v131 offset:1744
	v_cvt_pk_bf16_f32 v130, v26, v27
	v_cvt_pk_bf16_f32 v131, v28, v29
	ds_write_b16 v0, v130 offset:192
	ds_write_b16_d16_hi v0, v130 offset:720
	ds_write_b16 v0, v131 offset:1248
	ds_write_b16_d16_hi v0, v131 offset:1776
	v_cvt_pk_bf16_f32 v130, v10, v11
	v_cvt_pk_bf16_f32 v131, v12, v13
	ds_write_b16 v0, v130 offset:224
	ds_write_b16_d16_hi v0, v130 offset:752
	ds_write_b16 v0, v131 offset:1280
	ds_write_b16_d16_hi v0, v131 offset:1808
	v_cvt_pk_bf16_f32 v130, v126, v127
	v_cvt_pk_bf16_f32 v131, v128, v129
	ds_write_b16 v0, v130 offset:2112
	ds_write_b16_d16_hi v0, v130 offset:2640
	ds_write_b16 v0, v131 offset:3168
	ds_write_b16_d16_hi v0, v131 offset:3696
	v_cvt_pk_bf16_f32 v130, v110, v111
	v_cvt_pk_bf16_f32 v131, v112, v113
	ds_write_b16 v0, v130 offset:2144
	ds_write_b16_d16_hi v0, v130 offset:2672
	ds_write_b16 v0, v131 offset:3200
	ds_write_b16_d16_hi v0, v131 offset:3728
	v_cvt_pk_bf16_f32 v130, v94, v95
	v_cvt_pk_bf16_f32 v131, v96, v97
	ds_write_b16 v0, v130 offset:2176
	ds_write_b16_d16_hi v0, v130 offset:2704
	ds_write_b16 v0, v131 offset:3232
	ds_write_b16_d16_hi v0, v131 offset:3760
	v_cvt_pk_bf16_f32 v130, v78, v79
	v_cvt_pk_bf16_f32 v131, v80, v81
	ds_write_b16 v0, v130 offset:2208
	ds_write_b16_d16_hi v0, v130 offset:2736
	ds_write_b16 v0, v131 offset:3264
	ds_write_b16_d16_hi v0, v131 offset:3792
	v_cvt_pk_bf16_f32 v130, v62, v63
	v_cvt_pk_bf16_f32 v131, v64, v65
	ds_write_b16 v0, v130 offset:2240
	ds_write_b16_d16_hi v0, v130 offset:2768
	ds_write_b16 v0, v131 offset:3296
	ds_write_b16_d16_hi v0, v131 offset:3824
	v_cvt_pk_bf16_f32 v130, v46, v47
	v_cvt_pk_bf16_f32 v131, v48, v49
	ds_write_b16 v0, v130 offset:2272
	ds_write_b16_d16_hi v0, v130 offset:2800
	ds_write_b16 v0, v131 offset:3328
	ds_write_b16_d16_hi v0, v131 offset:3856
	v_cvt_pk_bf16_f32 v130, v30, v31
	v_cvt_pk_bf16_f32 v131, v32, v33
	ds_write_b16 v0, v130 offset:2304
	ds_write_b16_d16_hi v0, v130 offset:2832
	ds_write_b16 v0, v131 offset:3360
	ds_write_b16_d16_hi v0, v131 offset:3888
	v_cvt_pk_bf16_f32 v130, v14, v15
	v_cvt_pk_bf16_f32 v131, v16, v17
	ds_write_b16 v0, v130 offset:2336
	ds_write_b16_d16_hi v0, v130 offset:2864
	ds_write_b16 v0, v131 offset:3392
	ds_write_b16_d16_hi v0, v131 offset:3920
	v_cvt_pk_bf16_f32 v130, v114, v115
	v_cvt_pk_bf16_f32 v131, v116, v117
	ds_write_b16 v0, v130 offset:16896
	ds_write_b16_d16_hi v0, v130 offset:17424
	ds_write_b16 v0, v131 offset:17952
	ds_write_b16_d16_hi v0, v131 offset:18480
	v_cvt_pk_bf16_f32 v130, v98, v99
	v_cvt_pk_bf16_f32 v131, v100, v101
	ds_write_b16 v0, v130 offset:16928
	ds_write_b16_d16_hi v0, v130 offset:17456
	ds_write_b16 v0, v131 offset:17984
	ds_write_b16_d16_hi v0, v131 offset:18512
	v_cvt_pk_bf16_f32 v130, v82, v83
	v_cvt_pk_bf16_f32 v131, v84, v85
	ds_write_b16 v0, v130 offset:16960
	ds_write_b16_d16_hi v0, v130 offset:17488
	ds_write_b16 v0, v131 offset:18016
	ds_write_b16_d16_hi v0, v131 offset:18544
	v_cvt_pk_bf16_f32 v130, v66, v67
	v_cvt_pk_bf16_f32 v131, v68, v69
	ds_write_b16 v0, v130 offset:16992
	ds_write_b16_d16_hi v0, v130 offset:17520
	ds_write_b16 v0, v131 offset:18048
	ds_write_b16_d16_hi v0, v131 offset:18576
	v_cvt_pk_bf16_f32 v130, v50, v51
	v_cvt_pk_bf16_f32 v131, v52, v53
	ds_write_b16 v0, v130 offset:17024
	ds_write_b16_d16_hi v0, v130 offset:17552
	ds_write_b16 v0, v131 offset:18080
	ds_write_b16_d16_hi v0, v131 offset:18608
	v_cvt_pk_bf16_f32 v130, v34, v35
	v_cvt_pk_bf16_f32 v131, v36, v37
	ds_write_b16 v0, v130 offset:17056
	ds_write_b16_d16_hi v0, v130 offset:17584
	ds_write_b16 v0, v131 offset:18112
	ds_write_b16_d16_hi v0, v131 offset:18640
	v_cvt_pk_bf16_f32 v130, v18, v19
	v_cvt_pk_bf16_f32 v131, v20, v21
	ds_write_b16 v0, v130 offset:17088
	ds_write_b16_d16_hi v0, v130 offset:17616
	ds_write_b16 v0, v131 offset:18144
	ds_write_b16_d16_hi v0, v131 offset:18672
	v_cvt_pk_bf16_f32 v130, v2, v3
	v_cvt_pk_bf16_f32 v131, v4, v5
	ds_write_b16 v0, v130 offset:17120
	ds_write_b16_d16_hi v0, v130 offset:17648
	ds_write_b16 v0, v131 offset:18176
	ds_write_b16_d16_hi v0, v131 offset:18704
	v_cvt_pk_bf16_f32 v130, v118, v119
	v_cvt_pk_bf16_f32 v131, v120, v121
	ds_write_b16 v0, v130 offset:19008
	ds_write_b16_d16_hi v0, v130 offset:19536
	ds_write_b16 v0, v131 offset:20064
	ds_write_b16_d16_hi v0, v131 offset:20592
	v_cvt_pk_bf16_f32 v130, v102, v103
	v_cvt_pk_bf16_f32 v131, v104, v105
	ds_write_b16 v0, v130 offset:19040
	ds_write_b16_d16_hi v0, v130 offset:19568
	ds_write_b16 v0, v131 offset:20096
	ds_write_b16_d16_hi v0, v131 offset:20624
	v_cvt_pk_bf16_f32 v130, v86, v87
	v_cvt_pk_bf16_f32 v131, v88, v89
	ds_write_b16 v0, v130 offset:19072
	ds_write_b16_d16_hi v0, v130 offset:19600
	ds_write_b16 v0, v131 offset:20128
	ds_write_b16_d16_hi v0, v131 offset:20656
	v_cvt_pk_bf16_f32 v130, v70, v71
	v_cvt_pk_bf16_f32 v131, v72, v73
	ds_write_b16 v0, v130 offset:19104
	ds_write_b16_d16_hi v0, v130 offset:19632
	ds_write_b16 v0, v131 offset:20160
	ds_write_b16_d16_hi v0, v131 offset:20688
	v_cvt_pk_bf16_f32 v130, v54, v55
	v_cvt_pk_bf16_f32 v131, v56, v57
	ds_write_b16 v0, v130 offset:19136
	ds_write_b16_d16_hi v0, v130 offset:19664
	ds_write_b16 v0, v131 offset:20192
	ds_write_b16_d16_hi v0, v131 offset:20720
	v_cvt_pk_bf16_f32 v130, v38, v39
	v_cvt_pk_bf16_f32 v131, v40, v41
	ds_write_b16 v0, v130 offset:19168
	ds_write_b16_d16_hi v0, v130 offset:19696
	ds_write_b16 v0, v131 offset:20224
	ds_write_b16_d16_hi v0, v131 offset:20752
	v_cvt_pk_bf16_f32 v130, v22, v23
	v_cvt_pk_bf16_f32 v131, v24, v25
	ds_write_b16 v0, v130 offset:19200
	ds_write_b16_d16_hi v0, v130 offset:19728
	ds_write_b16 v0, v131 offset:20256
	ds_write_b16_d16_hi v0, v131 offset:20784
	v_cvt_pk_bf16_f32 v130, v6, v7
	s_lshl_b32 s4, s81, 10
	v_cvt_pk_bf16_f32 v131, v8, v9
	ds_write_b16 v0, v130 offset:19232
	ds_write_b16_d16_hi v0, v130 offset:19760
	ds_write_b16 v0, v131 offset:20288
	ds_write_b16_d16_hi v0, v131 offset:20816
	v_and_b32_e32 v130, 31, v136
	s_add_i32 s4, s46, s4
	v_lshlrev_b32_e32 v0, 4, v130
	v_ashrrev_i32_e32 v137, 5, v136
	s_add_i32 s6, s4, 0xfffff800
	v_lshl_or_b32 v138, v130, 3, s49
	v_mad_u64_u32 v[130:131], s[4:5], v137, s7, v[0:1]
	s_waitcnt lgkmcnt(0)
	s_barrier
	ds_read_b128 v[130:133], v130
	v_add_u32_e32 v137, s6, v137
	v_mad_u64_u32 v[140:141], s[4:5], v137, s96, v[138:139]
	v_mov_b32_e32 v141, v1
	v_lshl_add_u64 v[140:141], v[140:141], 1, s[40:41]
	s_waitcnt lgkmcnt(0)
	global_store_dwordx4 v[140:141], v[130:133], off
	s_nop 1
	v_add_u32_e32 v130, 0x100, v136
	v_ashrrev_i32_e32 v137, 5, v130
	v_mad_u64_u32 v[130:131], s[4:5], v137, s7, v[0:1]
	ds_read_b128 v[130:133], v130
	v_add_u32_e32 v137, s6, v137
	v_mad_u64_u32 v[140:141], s[4:5], v137, s96, v[138:139]
	v_mov_b32_e32 v141, v1
	v_lshl_add_u64 v[140:141], v[140:141], 1, s[40:41]
	s_waitcnt lgkmcnt(0)
	global_store_dwordx4 v[140:141], v[130:133], off
	s_nop 1
	v_add_u32_e32 v130, 0x200, v136
	v_ashrrev_i32_e32 v137, 5, v130
	v_mad_u64_u32 v[130:131], s[4:5], v137, s7, v[0:1]
	ds_read_b128 v[130:133], v130
	v_add_u32_e32 v137, s6, v137
	v_mad_u64_u32 v[140:141], s[4:5], v137, s96, v[138:139]
	v_mov_b32_e32 v141, v1
	v_lshl_add_u64 v[140:141], v[140:141], 1, s[40:41]
	s_waitcnt lgkmcnt(0)
	global_store_dwordx4 v[140:141], v[130:133], off
	s_nop 1
	v_add_u32_e32 v130, 0x300, v136
	v_ashrrev_i32_e32 v137, 5, v130
	v_mad_u64_u32 v[130:131], s[4:5], v137, s7, v[0:1]
	ds_read_b128 v[130:133], v130
	v_add_u32_e32 v137, s6, v137
	v_mad_u64_u32 v[140:141], s[4:5], v137, s96, v[138:139]
	v_mov_b32_e32 v141, v1
	v_lshl_add_u64 v[140:141], v[140:141], 1, s[40:41]
	s_waitcnt lgkmcnt(0)
	global_store_dwordx4 v[140:141], v[130:133], off
	s_nop 1
	v_add_u32_e32 v130, 0x400, v136
	v_ashrrev_i32_e32 v137, 5, v130
	v_mad_u64_u32 v[130:131], s[4:5], v137, s7, v[0:1]
	ds_read_b128 v[130:133], v130
	v_add_u32_e32 v137, s6, v137
	v_mad_u64_u32 v[140:141], s[4:5], v137, s96, v[138:139]
	v_mov_b32_e32 v141, v1
	v_lshl_add_u64 v[140:141], v[140:141], 1, s[40:41]
	s_waitcnt lgkmcnt(0)
	global_store_dwordx4 v[140:141], v[130:133], off
	s_nop 1
	v_add_u32_e32 v130, 0x500, v136
	v_ashrrev_i32_e32 v137, 5, v130
	v_mad_u64_u32 v[130:131], s[4:5], v137, s7, v[0:1]
	ds_read_b128 v[130:133], v130
	v_add_u32_e32 v137, s6, v137
	v_mad_u64_u32 v[140:141], s[4:5], v137, s96, v[138:139]
	v_mov_b32_e32 v141, v1
	v_lshl_add_u64 v[140:141], v[140:141], 1, s[40:41]
	s_waitcnt lgkmcnt(0)
	global_store_dwordx4 v[140:141], v[130:133], off
	s_nop 1
	v_add_u32_e32 v130, 0x600, v136
	v_ashrrev_i32_e32 v137, 5, v130
	v_mad_u64_u32 v[130:131], s[4:5], v137, s7, v[0:1]
	ds_read_b128 v[130:133], v130
	v_add_u32_e32 v137, s6, v137
	v_mad_u64_u32 v[140:141], s[4:5], v137, s96, v[138:139]
	v_mov_b32_e32 v141, v1
	v_lshl_add_u64 v[140:141], v[140:141], 1, s[40:41]
	s_waitcnt lgkmcnt(0)
	global_store_dwordx4 v[140:141], v[130:133], off
	s_nop 1
	v_add_u32_e32 v130, 0x700, v136
	v_ashrrev_i32_e32 v137, 5, v130
	v_mad_u64_u32 v[130:131], s[4:5], v137, s7, v[0:1]
	ds_read_b128 v[130:133], v130
	v_add_u32_e32 v137, s6, v137
	v_mad_u64_u32 v[140:141], s[4:5], v137, s96, v[138:139]
	v_mov_b32_e32 v141, v1
	v_lshl_add_u64 v[140:141], v[140:141], 1, s[40:41]
	s_waitcnt lgkmcnt(0)
	global_store_dwordx4 v[140:141], v[130:133], off
	s_nop 1
	v_add_u32_e32 v130, 0x800, v136
	v_ashrrev_i32_e32 v137, 5, v130
	v_mad_u64_u32 v[130:131], s[4:5], v137, s7, v[0:1]
	ds_read_b128 v[130:133], v130
	v_add_u32_e32 v137, s6, v137
	v_mad_u64_u32 v[140:141], s[4:5], v137, s96, v[138:139]
	v_mov_b32_e32 v141, v1
	v_lshl_add_u64 v[140:141], v[140:141], 1, s[40:41]
	s_waitcnt lgkmcnt(0)
	global_store_dwordx4 v[140:141], v[130:133], off
	s_nop 1
	v_add_u32_e32 v130, 0x900, v136
	v_ashrrev_i32_e32 v137, 5, v130
	v_mad_u64_u32 v[130:131], s[4:5], v137, s7, v[0:1]
	ds_read_b128 v[130:133], v130
	v_add_u32_e32 v137, s6, v137
	v_mad_u64_u32 v[140:141], s[4:5], v137, s96, v[138:139]
	v_mov_b32_e32 v141, v1
	v_lshl_add_u64 v[140:141], v[140:141], 1, s[40:41]
	s_waitcnt lgkmcnt(0)
	global_store_dwordx4 v[140:141], v[130:133], off
	s_nop 1
	v_add_u32_e32 v130, 0xa00, v136
	v_ashrrev_i32_e32 v137, 5, v130
	v_mad_u64_u32 v[130:131], s[4:5], v137, s7, v[0:1]
	ds_read_b128 v[130:133], v130
	v_add_u32_e32 v137, s6, v137
	v_mad_u64_u32 v[140:141], s[4:5], v137, s96, v[138:139]
	v_mov_b32_e32 v141, v1
	v_lshl_add_u64 v[140:141], v[140:141], 1, s[40:41]
	s_waitcnt lgkmcnt(0)
	global_store_dwordx4 v[140:141], v[130:133], off
	s_nop 1
	v_add_u32_e32 v130, 0xb00, v136
	v_ashrrev_i32_e32 v137, 5, v130
	v_mad_u64_u32 v[130:131], s[4:5], v137, s7, v[0:1]
	ds_read_b128 v[130:133], v130
	v_add_u32_e32 v137, s6, v137
	v_mad_u64_u32 v[140:141], s[4:5], v137, s96, v[138:139]
	v_mov_b32_e32 v141, v1
	v_lshl_add_u64 v[140:141], v[140:141], 1, s[40:41]
	s_waitcnt lgkmcnt(0)
	global_store_dwordx4 v[140:141], v[130:133], off
	s_nop 1
	v_add_u32_e32 v130, 0xc00, v136
	v_ashrrev_i32_e32 v137, 5, v130
	v_mad_u64_u32 v[130:131], s[4:5], v137, s7, v[0:1]
	ds_read_b128 v[130:133], v130
	v_add_u32_e32 v137, s6, v137
	v_mad_u64_u32 v[140:141], s[4:5], v137, s96, v[138:139]
	v_mov_b32_e32 v141, v1
	v_lshl_add_u64 v[140:141], v[140:141], 1, s[40:41]
	s_waitcnt lgkmcnt(0)
	global_store_dwordx4 v[140:141], v[130:133], off
	s_nop 1
	v_add_u32_e32 v130, 0xd00, v136
	v_ashrrev_i32_e32 v137, 5, v130
	v_mad_u64_u32 v[130:131], s[4:5], v137, s7, v[0:1]
	ds_read_b128 v[130:133], v130
	v_add_u32_e32 v137, s6, v137
	v_mad_u64_u32 v[140:141], s[4:5], v137, s96, v[138:139]
	v_mov_b32_e32 v141, v1
	v_lshl_add_u64 v[140:141], v[140:141], 1, s[40:41]
	s_waitcnt lgkmcnt(0)
	global_store_dwordx4 v[140:141], v[130:133], off
	s_nop 1
	v_add_u32_e32 v130, 0xe00, v136
	v_ashrrev_i32_e32 v137, 5, v130
	v_mad_u64_u32 v[130:131], s[4:5], v137, s7, v[0:1]
	ds_read_b128 v[130:133], v130
	v_add_u32_e32 v137, s6, v137
	v_mad_u64_u32 v[140:141], s[4:5], v137, s96, v[138:139]
	v_mov_b32_e32 v141, v1
	v_lshl_add_u64 v[140:141], v[140:141], 1, s[40:41]
	s_waitcnt lgkmcnt(0)
	global_store_dwordx4 v[140:141], v[130:133], off
	s_nop 1
	v_add_u32_e32 v130, 0xf00, v136
	v_ashrrev_i32_e32 v137, 5, v130
	v_mad_u64_u32 v[130:131], s[4:5], v137, s7, v[0:1]
	ds_read_b128 v[130:133], v130
	v_add_u32_e32 v0, s6, v137
	v_mad_u64_u32 v[138:139], s[4:5], v0, s96, v[138:139]
	v_mov_b32_e32 v139, v1
	v_lshl_add_u64 v[138:139], v[138:139], 1, s[40:41]
	s_waitcnt lgkmcnt(0)
	global_store_dwordx4 v[138:139], v[130:133], off
	s_waitcnt lgkmcnt(0)
	s_barrier

.LBB0_258:
	s_andn2_b64 vcc, exec, s[50:51]
	s_cbranch_vccnz .LBB0_260
	v_lshrrev_b32_e32 v0, 6, v136
	v_mul_lo_u32 v137, v0, s14
	v_and_b32_e32 v130, 15, v136
	v_and_or_b32 v0, v136, 48, v137
	s_movk_i32 s4, 0x90
	v_mad_u32_u24 v0, v130, s4, v0
	v_cvt_pk_bf16_f32 v130, v122, v123
	v_cvt_pk_bf16_f32 v131, v124, v125
	v_cvt_pk_bf16_f32 v132, v126, v127
	v_cvt_pk_bf16_f32 v133, v128, v129
	s_waitcnt vmcnt(0)
	ds_write_b128 v0, v[130:133]
	v_cvt_pk_bf16_f32 v130, v114, v115
	v_cvt_pk_bf16_f32 v131, v116, v117
	v_cvt_pk_bf16_f32 v132, v118, v119
	v_cvt_pk_bf16_f32 v133, v120, v121
	ds_write_b128 v0, v[130:133] offset:64
	v_cvt_pk_bf16_f32 v130, v106, v107
	v_cvt_pk_bf16_f32 v131, v108, v109
	v_cvt_pk_bf16_f32 v132, v110, v111
	v_cvt_pk_bf16_f32 v133, v112, v113
	ds_write_b128 v0, v[130:133] offset:2304
	v_cvt_pk_bf16_f32 v130, v98, v99
	v_cvt_pk_bf16_f32 v131, v100, v101
	v_cvt_pk_bf16_f32 v132, v102, v103
	v_cvt_pk_bf16_f32 v133, v104, v105
	ds_write_b128 v0, v[130:133] offset:2368
	v_cvt_pk_bf16_f32 v130, v90, v91
	v_cvt_pk_bf16_f32 v131, v92, v93
	v_cvt_pk_bf16_f32 v132, v94, v95
	v_cvt_pk_bf16_f32 v133, v96, v97
	ds_write_b128 v0, v[130:133] offset:4608
	v_cvt_pk_bf16_f32 v130, v82, v83
	v_cvt_pk_bf16_f32 v131, v84, v85
	v_cvt_pk_bf16_f32 v132, v86, v87
	v_cvt_pk_bf16_f32 v133, v88, v89
	ds_write_b128 v0, v[130:133] offset:4672
	v_cvt_pk_bf16_f32 v130, v74, v75
	v_cvt_pk_bf16_f32 v131, v76, v77
	v_cvt_pk_bf16_f32 v132, v78, v79
	v_cvt_pk_bf16_f32 v133, v80, v81
	ds_write_b128 v0, v[130:133] offset:6912
	v_cvt_pk_bf16_f32 v130, v66, v67
	v_cvt_pk_bf16_f32 v131, v68, v69
	v_cvt_pk_bf16_f32 v132, v70, v71
	v_cvt_pk_bf16_f32 v133, v72, v73
	ds_write_b128 v0, v[130:133] offset:6976
	v_cvt_pk_bf16_f32 v130, v58, v59
	v_cvt_pk_bf16_f32 v131, v60, v61
	v_cvt_pk_bf16_f32 v132, v62, v63
	v_cvt_pk_bf16_f32 v133, v64, v65
	ds_write_b128 v0, v[130:133] offset:9216
	v_cvt_pk_bf16_f32 v130, v50, v51
	v_cvt_pk_bf16_f32 v131, v52, v53
	v_cvt_pk_bf16_f32 v132, v54, v55
	v_cvt_pk_bf16_f32 v133, v56, v57
	ds_write_b128 v0, v[130:133] offset:9280
	v_cvt_pk_bf16_f32 v130, v42, v43
	v_cvt_pk_bf16_f32 v131, v44, v45
	v_cvt_pk_bf16_f32 v132, v46, v47
	v_cvt_pk_bf16_f32 v133, v48, v49
	ds_write_b128 v0, v[130:133] offset:11520
	v_cvt_pk_bf16_f32 v130, v34, v35
	v_cvt_pk_bf16_f32 v131, v36, v37
	v_cvt_pk_bf16_f32 v132, v38, v39
	v_cvt_pk_bf16_f32 v133, v40, v41
	ds_write_b128 v0, v[130:133] offset:11584
	v_cvt_pk_bf16_f32 v130, v26, v27
	v_cvt_pk_bf16_f32 v131, v28, v29
	v_cvt_pk_bf16_f32 v132, v30, v31
	v_cvt_pk_bf16_f32 v133, v32, v33
	ds_write_b128 v0, v[130:133] offset:13824
	v_cvt_pk_bf16_f32 v130, v18, v19
	v_cvt_pk_bf16_f32 v131, v20, v21
	v_cvt_pk_bf16_f32 v132, v22, v23
	v_cvt_pk_bf16_f32 v133, v24, v25
	ds_write_b128 v0, v[130:133] offset:13888
	v_cvt_pk_bf16_f32 v130, v10, v11
	v_cvt_pk_bf16_f32 v131, v12, v13
	v_cvt_pk_bf16_f32 v132, v14, v15
	v_cvt_pk_bf16_f32 v133, v16, v17
	ds_write_b128 v0, v[130:133] offset:16128
	v_cvt_pk_bf16_f32 v130, v2, v3
	v_cvt_pk_bf16_f32 v131, v4, v5
	v_cvt_pk_bf16_f32 v132, v6, v7
	v_cvt_pk_bf16_f32 v133, v8, v9
	ds_write_b128 v0, v[130:133] offset:16192
	v_and_b32_e32 v0, 0xffffff80, v136
	v_add_u32_e32 v130, s48, v0
	v_ashrrev_i32_e32 v131, 31, v130
	v_lshlrev_b64 v[130:131], 11, v[130:131]
	v_lshl_add_u64 v[130:131], s[94:95], 0, v[130:131]
	s_mov_b32 s92, s46
	v_and_b32_e32 v0, 64, v136
	v_lshl_add_u64 v[130:131], s[92:93], 1, v[130:131]
	v_lshlrev_b32_e32 v0, 1, v0
	v_lshl_add_u64 v[138:139], v[130:131], 0, v[0:1]
	v_lshlrev_b32_e32 v0, 4, v136
	v_and_b32_e32 v0, 0x70, v0
	v_bfe_u32 v140, v136, 3, 3
	v_or_b32_e32 v130, v137, v0
	s_waitcnt lgkmcnt(0)
	v_mad_u32_u24 v137, v140, s4, v130
	ds_read_b128 v[130:133], v137
	v_lshl_add_u64 v[138:139], v[138:139], 0, v[0:1]
	s_mov_b64 s[4:5], 0x47ff800
	v_lshl_add_u64 v[138:139], v[138:139], 0, s[4:5]
	v_lshlrev_b32_e32 v0, 11, v140
	v_lshl_add_u64 v[140:141], v[138:139], 0, v[0:1]
	s_waitcnt lgkmcnt(0)
	global_store_dwordx4 v[140:141], v[130:133], off
	ds_read_b128 v[130:133], v137 offset:1152
	v_or_b32_e32 v140, 0x4000, v0
	v_mov_b32_e32 v141, v1
	v_lshl_add_u64 v[140:141], v[138:139], 0, v[140:141]
	s_movk_i32 s82, 0x1bff
	s_waitcnt lgkmcnt(0)
	global_store_dwordx4 v[140:141], v[130:133], off
	ds_read_b128 v[130:133], v137 offset:2304
	v_or_b32_e32 v140, 0x8000, v0
	v_mov_b32_e32 v141, v1
	v_lshl_add_u64 v[140:141], v[138:139], 0, v[140:141]
	s_waitcnt lgkmcnt(0)
	global_store_dwordx4 v[140:141], v[130:133], off
	ds_read_b128 v[130:133], v137 offset:3456
	v_or_b32_e32 v140, 0xc000, v0
	v_mov_b32_e32 v141, v1
	v_lshl_add_u64 v[140:141], v[138:139], 0, v[140:141]
	s_waitcnt lgkmcnt(0)
	global_store_dwordx4 v[140:141], v[130:133], off
	ds_read_b128 v[130:133], v137 offset:4608
	v_or_b32_e32 v140, 0x10000, v0
	v_mov_b32_e32 v141, v1
	v_lshl_add_u64 v[140:141], v[138:139], 0, v[140:141]
	s_waitcnt lgkmcnt(0)
	global_store_dwordx4 v[140:141], v[130:133], off
	ds_read_b128 v[130:133], v137 offset:5760
	v_or_b32_e32 v140, 0x14000, v0
	v_mov_b32_e32 v141, v1
	v_lshl_add_u64 v[140:141], v[138:139], 0, v[140:141]
	s_waitcnt lgkmcnt(0)
	global_store_dwordx4 v[140:141], v[130:133], off
	ds_read_b128 v[130:133], v137 offset:6912
	v_or_b32_e32 v140, 0x18000, v0
	v_mov_b32_e32 v141, v1
	v_lshl_add_u64 v[140:141], v[138:139], 0, v[140:141]
	s_waitcnt lgkmcnt(0)
	global_store_dwordx4 v[140:141], v[130:133], off
	ds_read_b128 v[130:133], v137 offset:8064
	v_or_b32_e32 v140, 0x1c000, v0
	v_mov_b32_e32 v141, v1
	v_lshl_add_u64 v[140:141], v[138:139], 0, v[140:141]
	s_waitcnt lgkmcnt(0)
	global_store_dwordx4 v[140:141], v[130:133], off
	ds_read_b128 v[130:133], v137 offset:9216
	v_or_b32_e32 v140, 0x20000, v0
	v_mov_b32_e32 v141, v1
	v_lshl_add_u64 v[140:141], v[138:139], 0, v[140:141]
	s_waitcnt lgkmcnt(0)
	global_store_dwordx4 v[140:141], v[130:133], off
	ds_read_b128 v[130:133], v137 offset:10368
	v_or_b32_e32 v140, 0x24000, v0
	v_mov_b32_e32 v141, v1
	v_lshl_add_u64 v[140:141], v[138:139], 0, v[140:141]
	s_waitcnt lgkmcnt(0)
	global_store_dwordx4 v[140:141], v[130:133], off
	ds_read_b128 v[130:133], v137 offset:11520
	v_or_b32_e32 v140, 0x28000, v0
	v_mov_b32_e32 v141, v1
	v_lshl_add_u64 v[140:141], v[138:139], 0, v[140:141]
	s_waitcnt lgkmcnt(0)
	global_store_dwordx4 v[140:141], v[130:133], off
	ds_read_b128 v[130:133], v137 offset:12672
	v_or_b32_e32 v140, 0x2c000, v0
	v_mov_b32_e32 v141, v1
	v_lshl_add_u64 v[140:141], v[138:139], 0, v[140:141]
	s_waitcnt lgkmcnt(0)
	global_store_dwordx4 v[140:141], v[130:133], off
	ds_read_b128 v[130:133], v137 offset:13824
	v_or_b32_e32 v140, 0x30000, v0
	v_mov_b32_e32 v141, v1
	v_lshl_add_u64 v[140:141], v[138:139], 0, v[140:141]
	s_waitcnt lgkmcnt(0)
	global_store_dwordx4 v[140:141], v[130:133], off
	ds_read_b128 v[130:133], v137 offset:14976
	v_or_b32_e32 v140, 0x34000, v0
	v_mov_b32_e32 v141, v1
	v_lshl_add_u64 v[140:141], v[138:139], 0, v[140:141]
	s_waitcnt lgkmcnt(0)
	global_store_dwordx4 v[140:141], v[130:133], off
	ds_read_b128 v[130:133], v137 offset:16128
	v_or_b32_e32 v140, 0x38000, v0
	v_mov_b32_e32 v141, v1
	v_lshl_add_u64 v[140:141], v[138:139], 0, v[140:141]
	v_or_b32_e32 v0, 0x3c000, v0
	s_waitcnt lgkmcnt(0)
	global_store_dwordx4 v[140:141], v[130:133], off
	ds_read_b128 v[130:133], v137 offset:17280
	v_lshl_add_u64 v[138:139], v[138:139], 0, v[0:1]
	s_waitcnt lgkmcnt(0)
	global_store_dwordx4 v[138:139], v[130:133], off
	s_waitcnt lgkmcnt(0)
	s_barrier

.LBB0_261:
	s_andn2_b64 vcc, exec, s[50:51]
	s_cbranch_vccnz .LBB0_263
	v_lshrrev_b32_e32 v0, 6, v136
	v_mul_lo_u32 v137, v0, s14
	v_and_b32_e32 v130, 15, v136
	v_and_or_b32 v0, v136, 48, v137
	s_movk_i32 s4, 0x90
	s_mov_b32 s6, 0x3e38aa3b
	v_mad_u32_u24 v0, v130, s4, v0
	v_pk_mul_f32 v[132:133], v[124:125], s[6:7] op_sel_hi:[1,0]
	v_pk_mul_f32 v[130:131], v[122:123], s[6:7] op_sel_hi:[1,0]
	v_pk_mul_f32 v[138:139], v[128:129], s[6:7] op_sel_hi:[1,0]
	v_pk_mul_f32 v[140:141], v[126:127], s[6:7] op_sel_hi:[1,0]
	v_cvt_pk_bf16_f32 v130, v130, v131
	v_cvt_pk_bf16_f32 v131, v132, v133
	v_cvt_pk_bf16_f32 v132, v140, v141
	v_cvt_pk_bf16_f32 v133, v138, v139
	s_waitcnt vmcnt(0)
	ds_write_b128 v0, v[130:133]
	v_pk_mul_f32 v[132:133], v[116:117], s[6:7] op_sel_hi:[1,0]
	v_pk_mul_f32 v[130:131], v[114:115], s[6:7] op_sel_hi:[1,0]
	v_pk_mul_f32 v[138:139], v[120:121], s[6:7] op_sel_hi:[1,0]
	v_pk_mul_f32 v[140:141], v[118:119], s[6:7] op_sel_hi:[1,0]
	v_cvt_pk_bf16_f32 v130, v130, v131
	v_cvt_pk_bf16_f32 v131, v132, v133
	v_cvt_pk_bf16_f32 v132, v140, v141
	v_cvt_pk_bf16_f32 v133, v138, v139
	ds_write_b128 v0, v[130:133] offset:64
	v_pk_mul_f32 v[132:133], v[108:109], s[6:7] op_sel_hi:[1,0]
	v_pk_mul_f32 v[130:131], v[106:107], s[6:7] op_sel_hi:[1,0]
	v_pk_mul_f32 v[138:139], v[112:113], s[6:7] op_sel_hi:[1,0]
	v_pk_mul_f32 v[140:141], v[110:111], s[6:7] op_sel_hi:[1,0]
	v_cvt_pk_bf16_f32 v130, v130, v131
	v_cvt_pk_bf16_f32 v131, v132, v133
	v_cvt_pk_bf16_f32 v132, v140, v141
	v_cvt_pk_bf16_f32 v133, v138, v139
	ds_write_b128 v0, v[130:133] offset:2304
	v_pk_mul_f32 v[132:133], v[100:101], s[6:7] op_sel_hi:[1,0]
	v_pk_mul_f32 v[130:131], v[98:99], s[6:7] op_sel_hi:[1,0]
	v_pk_mul_f32 v[138:139], v[104:105], s[6:7] op_sel_hi:[1,0]
	v_pk_mul_f32 v[140:141], v[102:103], s[6:7] op_sel_hi:[1,0]
	v_cvt_pk_bf16_f32 v130, v130, v131
	v_cvt_pk_bf16_f32 v131, v132, v133
	v_cvt_pk_bf16_f32 v132, v140, v141
	v_cvt_pk_bf16_f32 v133, v138, v139
	ds_write_b128 v0, v[130:133] offset:2368
	v_pk_mul_f32 v[132:133], v[92:93], s[6:7] op_sel_hi:[1,0]
	v_pk_mul_f32 v[130:131], v[90:91], s[6:7] op_sel_hi:[1,0]
	v_pk_mul_f32 v[138:139], v[96:97], s[6:7] op_sel_hi:[1,0]
	v_pk_mul_f32 v[140:141], v[94:95], s[6:7] op_sel_hi:[1,0]
	v_cvt_pk_bf16_f32 v130, v130, v131
	v_cvt_pk_bf16_f32 v131, v132, v133
	v_cvt_pk_bf16_f32 v132, v140, v141
	v_cvt_pk_bf16_f32 v133, v138, v139
	ds_write_b128 v0, v[130:133] offset:4608
	v_pk_mul_f32 v[132:133], v[84:85], s[6:7] op_sel_hi:[1,0]
	v_pk_mul_f32 v[130:131], v[82:83], s[6:7] op_sel_hi:[1,0]
	v_pk_mul_f32 v[138:139], v[88:89], s[6:7] op_sel_hi:[1,0]
	v_pk_mul_f32 v[140:141], v[86:87], s[6:7] op_sel_hi:[1,0]
	v_cvt_pk_bf16_f32 v130, v130, v131
	v_cvt_pk_bf16_f32 v131, v132, v133
	v_cvt_pk_bf16_f32 v132, v140, v141
	v_cvt_pk_bf16_f32 v133, v138, v139
	ds_write_b128 v0, v[130:133] offset:4672
	v_pk_mul_f32 v[132:133], v[76:77], s[6:7] op_sel_hi:[1,0]
	v_pk_mul_f32 v[130:131], v[74:75], s[6:7] op_sel_hi:[1,0]
	v_pk_mul_f32 v[138:139], v[80:81], s[6:7] op_sel_hi:[1,0]
	v_pk_mul_f32 v[140:141], v[78:79], s[6:7] op_sel_hi:[1,0]
	v_cvt_pk_bf16_f32 v130, v130, v131
	v_cvt_pk_bf16_f32 v131, v132, v133
	v_cvt_pk_bf16_f32 v132, v140, v141
	v_cvt_pk_bf16_f32 v133, v138, v139
	ds_write_b128 v0, v[130:133] offset:6912
	v_pk_mul_f32 v[132:133], v[68:69], s[6:7] op_sel_hi:[1,0]
	v_pk_mul_f32 v[130:131], v[66:67], s[6:7] op_sel_hi:[1,0]
	v_pk_mul_f32 v[138:139], v[72:73], s[6:7] op_sel_hi:[1,0]
	v_pk_mul_f32 v[140:141], v[70:71], s[6:7] op_sel_hi:[1,0]
	v_cvt_pk_bf16_f32 v130, v130, v131
	v_cvt_pk_bf16_f32 v131, v132, v133
	v_cvt_pk_bf16_f32 v132, v140, v141
	v_cvt_pk_bf16_f32 v133, v138, v139
	ds_write_b128 v0, v[130:133] offset:6976
	v_pk_mul_f32 v[132:133], v[60:61], s[6:7] op_sel_hi:[1,0]
	v_pk_mul_f32 v[130:131], v[58:59], s[6:7] op_sel_hi:[1,0]
	v_pk_mul_f32 v[138:139], v[64:65], s[6:7] op_sel_hi:[1,0]
	v_pk_mul_f32 v[140:141], v[62:63], s[6:7] op_sel_hi:[1,0]
	v_cvt_pk_bf16_f32 v130, v130, v131
	v_cvt_pk_bf16_f32 v131, v132, v133
	v_cvt_pk_bf16_f32 v132, v140, v141
	v_cvt_pk_bf16_f32 v133, v138, v139
	ds_write_b128 v0, v[130:133] offset:9216
	v_pk_mul_f32 v[132:133], v[52:53], s[6:7] op_sel_hi:[1,0]
	v_pk_mul_f32 v[130:131], v[50:51], s[6:7] op_sel_hi:[1,0]
	v_pk_mul_f32 v[138:139], v[56:57], s[6:7] op_sel_hi:[1,0]
	v_pk_mul_f32 v[140:141], v[54:55], s[6:7] op_sel_hi:[1,0]
	v_cvt_pk_bf16_f32 v130, v130, v131
	v_cvt_pk_bf16_f32 v131, v132, v133
	v_cvt_pk_bf16_f32 v132, v140, v141
	v_cvt_pk_bf16_f32 v133, v138, v139
	ds_write_b128 v0, v[130:133] offset:9280
	v_pk_mul_f32 v[132:133], v[44:45], s[6:7] op_sel_hi:[1,0]
	v_pk_mul_f32 v[130:131], v[42:43], s[6:7] op_sel_hi:[1,0]
	v_pk_mul_f32 v[138:139], v[48:49], s[6:7] op_sel_hi:[1,0]
	v_pk_mul_f32 v[140:141], v[46:47], s[6:7] op_sel_hi:[1,0]
	v_cvt_pk_bf16_f32 v130, v130, v131
	v_cvt_pk_bf16_f32 v131, v132, v133
	v_cvt_pk_bf16_f32 v132, v140, v141
	v_cvt_pk_bf16_f32 v133, v138, v139
	ds_write_b128 v0, v[130:133] offset:11520
	v_pk_mul_f32 v[132:133], v[36:37], s[6:7] op_sel_hi:[1,0]
	v_pk_mul_f32 v[130:131], v[34:35], s[6:7] op_sel_hi:[1,0]
	v_pk_mul_f32 v[138:139], v[40:41], s[6:7] op_sel_hi:[1,0]
	v_pk_mul_f32 v[140:141], v[38:39], s[6:7] op_sel_hi:[1,0]
	v_cvt_pk_bf16_f32 v130, v130, v131
	v_cvt_pk_bf16_f32 v131, v132, v133
	v_cvt_pk_bf16_f32 v132, v140, v141
	v_cvt_pk_bf16_f32 v133, v138, v139
	ds_write_b128 v0, v[130:133] offset:11584
	v_pk_mul_f32 v[132:133], v[28:29], s[6:7] op_sel_hi:[1,0]
	v_pk_mul_f32 v[130:131], v[26:27], s[6:7] op_sel_hi:[1,0]
	v_pk_mul_f32 v[138:139], v[32:33], s[6:7] op_sel_hi:[1,0]
	v_pk_mul_f32 v[140:141], v[30:31], s[6:7] op_sel_hi:[1,0]
	v_cvt_pk_bf16_f32 v130, v130, v131
	v_cvt_pk_bf16_f32 v131, v132, v133
	v_cvt_pk_bf16_f32 v132, v140, v141
	v_cvt_pk_bf16_f32 v133, v138, v139
	ds_write_b128 v0, v[130:133] offset:13824
	v_pk_mul_f32 v[132:133], v[20:21], s[6:7] op_sel_hi:[1,0]
	v_pk_mul_f32 v[130:131], v[18:19], s[6:7] op_sel_hi:[1,0]
	v_pk_mul_f32 v[138:139], v[24:25], s[6:7] op_sel_hi:[1,0]
	v_pk_mul_f32 v[140:141], v[22:23], s[6:7] op_sel_hi:[1,0]
	v_cvt_pk_bf16_f32 v130, v130, v131
	v_cvt_pk_bf16_f32 v131, v132, v133
	v_cvt_pk_bf16_f32 v132, v140, v141
	v_cvt_pk_bf16_f32 v133, v138, v139
	ds_write_b128 v0, v[130:133] offset:13888
	v_pk_mul_f32 v[132:133], v[12:13], s[6:7] op_sel_hi:[1,0]
	v_pk_mul_f32 v[130:131], v[10:11], s[6:7] op_sel_hi:[1,0]
	v_pk_mul_f32 v[138:139], v[16:17], s[6:7] op_sel_hi:[1,0]
	v_pk_mul_f32 v[140:141], v[14:15], s[6:7] op_sel_hi:[1,0]
	v_cvt_pk_bf16_f32 v130, v130, v131
	v_cvt_pk_bf16_f32 v131, v132, v133
	v_cvt_pk_bf16_f32 v132, v140, v141
	v_cvt_pk_bf16_f32 v133, v138, v139
	ds_write_b128 v0, v[130:133] offset:16128
	v_pk_mul_f32 v[132:133], v[4:5], s[6:7] op_sel_hi:[1,0]
	v_pk_mul_f32 v[130:131], v[2:3], s[6:7] op_sel_hi:[1,0]
	v_pk_mul_f32 v[138:139], v[8:9], s[6:7] op_sel_hi:[1,0]
	v_pk_mul_f32 v[140:141], v[6:7], s[6:7] op_sel_hi:[1,0]
	v_cvt_pk_bf16_f32 v130, v130, v131
	v_cvt_pk_bf16_f32 v131, v132, v133
	v_cvt_pk_bf16_f32 v132, v140, v141
	v_cvt_pk_bf16_f32 v133, v138, v139
	ds_write_b128 v0, v[130:133] offset:16192
	v_and_b32_e32 v0, 0xffffff80, v136
	v_add_u32_e32 v130, s48, v0
	v_ashrrev_i32_e32 v131, 31, v130
	v_lshlrev_b64 v[130:131], 11, v[130:131]
	v_lshl_add_u64 v[130:131], s[42:43], 0, v[130:131]
	v_and_b32_e32 v0, 64, v136
	v_lshl_add_u64 v[130:131], s[46:47], 1, v[130:131]
	v_lshlrev_b32_e32 v0, 1, v0
	v_lshl_add_u64 v[138:139], v[130:131], 0, v[0:1]
	v_lshlrev_b32_e32 v0, 4, v136
	v_and_b32_e32 v0, 0x70, v0
	v_bfe_u32 v140, v136, 3, 3
	v_or_b32_e32 v130, v137, v0
	s_waitcnt lgkmcnt(0)
	v_mad_u32_u24 v137, v140, s4, v130
	ds_read_b128 v[130:133], v137
	v_lshl_add_u64 v[138:139], v[138:139], 0, v[0:1]
	v_lshlrev_b32_e32 v0, 11, v140
	v_lshl_add_u64 v[140:141], v[138:139], 0, v[0:1]
	s_waitcnt lgkmcnt(0)
	global_store_dwordx4 v[140:141], v[130:133], off
	ds_read_b128 v[130:133], v137 offset:1152
	v_or_b32_e32 v140, 0x4000, v0
	v_mov_b32_e32 v141, v1
	v_lshl_add_u64 v[140:141], v[138:139], 0, v[140:141]
	s_waitcnt lgkmcnt(0)
	global_store_dwordx4 v[140:141], v[130:133], off
	ds_read_b128 v[130:133], v137 offset:2304
	v_or_b32_e32 v140, 0x8000, v0
	v_mov_b32_e32 v141, v1
	v_lshl_add_u64 v[140:141], v[138:139], 0, v[140:141]
	s_waitcnt lgkmcnt(0)
	global_store_dwordx4 v[140:141], v[130:133], off
	ds_read_b128 v[130:133], v137 offset:3456
	v_or_b32_e32 v140, 0xc000, v0
	v_mov_b32_e32 v141, v1
	v_lshl_add_u64 v[140:141], v[138:139], 0, v[140:141]
	s_waitcnt lgkmcnt(0)
	global_store_dwordx4 v[140:141], v[130:133], off
	ds_read_b128 v[130:133], v137 offset:4608
	v_or_b32_e32 v140, 0x10000, v0
	v_mov_b32_e32 v141, v1
	v_lshl_add_u64 v[140:141], v[138:139], 0, v[140:141]
	s_waitcnt lgkmcnt(0)
	global_store_dwordx4 v[140:141], v[130:133], off
	ds_read_b128 v[130:133], v137 offset:5760
	v_or_b32_e32 v140, 0x14000, v0
	v_mov_b32_e32 v141, v1
	v_lshl_add_u64 v[140:141], v[138:139], 0, v[140:141]
	s_waitcnt lgkmcnt(0)
	global_store_dwordx4 v[140:141], v[130:133], off
	ds_read_b128 v[130:133], v137 offset:6912
	v_or_b32_e32 v140, 0x18000, v0
	v_mov_b32_e32 v141, v1
	v_lshl_add_u64 v[140:141], v[138:139], 0, v[140:141]
	s_waitcnt lgkmcnt(0)
	global_store_dwordx4 v[140:141], v[130:133], off
	ds_read_b128 v[130:133], v137 offset:8064
	v_or_b32_e32 v140, 0x1c000, v0
	v_mov_b32_e32 v141, v1
	v_lshl_add_u64 v[140:141], v[138:139], 0, v[140:141]
	s_waitcnt lgkmcnt(0)
	global_store_dwordx4 v[140:141], v[130:133], off
	ds_read_b128 v[130:133], v137 offset:9216
	v_or_b32_e32 v140, 0x20000, v0
	v_mov_b32_e32 v141, v1
	v_lshl_add_u64 v[140:141], v[138:139], 0, v[140:141]
	s_waitcnt lgkmcnt(0)
	global_store_dwordx4 v[140:141], v[130:133], off
	ds_read_b128 v[130:133], v137 offset:10368
	v_or_b32_e32 v140, 0x24000, v0
	v_mov_b32_e32 v141, v1
	v_lshl_add_u64 v[140:141], v[138:139], 0, v[140:141]
	s_waitcnt lgkmcnt(0)
	global_store_dwordx4 v[140:141], v[130:133], off
	ds_read_b128 v[130:133], v137 offset:11520
	v_or_b32_e32 v140, 0x28000, v0
	v_mov_b32_e32 v141, v1
	v_lshl_add_u64 v[140:141], v[138:139], 0, v[140:141]
	s_waitcnt lgkmcnt(0)
	global_store_dwordx4 v[140:141], v[130:133], off
	ds_read_b128 v[130:133], v137 offset:12672
	v_or_b32_e32 v140, 0x2c000, v0
	v_mov_b32_e32 v141, v1
	v_lshl_add_u64 v[140:141], v[138:139], 0, v[140:141]
	s_waitcnt lgkmcnt(0)
	global_store_dwordx4 v[140:141], v[130:133], off
	ds_read_b128 v[130:133], v137 offset:13824
	v_or_b32_e32 v140, 0x30000, v0
	v_mov_b32_e32 v141, v1
	v_lshl_add_u64 v[140:141], v[138:139], 0, v[140:141]
	s_waitcnt lgkmcnt(0)
	global_store_dwordx4 v[140:141], v[130:133], off
	ds_read_b128 v[130:133], v137 offset:14976
	v_or_b32_e32 v140, 0x34000, v0
	v_mov_b32_e32 v141, v1
	v_lshl_add_u64 v[140:141], v[138:139], 0, v[140:141]
	s_waitcnt lgkmcnt(0)
	global_store_dwordx4 v[140:141], v[130:133], off
	ds_read_b128 v[130:133], v137 offset:16128
	v_or_b32_e32 v140, 0x38000, v0
	v_mov_b32_e32 v141, v1
	v_lshl_add_u64 v[140:141], v[138:139], 0, v[140:141]
	v_or_b32_e32 v0, 0x3c000, v0
	s_waitcnt lgkmcnt(0)
	global_store_dwordx4 v[140:141], v[130:133], off
	ds_read_b128 v[130:133], v137 offset:17280
	v_lshl_add_u64 v[138:139], v[138:139], 0, v[0:1]
	s_waitcnt lgkmcnt(0)
	global_store_dwordx4 v[138:139], v[130:133], off
	s_waitcnt lgkmcnt(0)
	s_barrier

.LBB0_264:
	s_andn2_b64 vcc, exec, s[50:51]
	s_cbranch_vccnz .LBB0_236
	s_cmp_gt_i32 s80, 7
	s_mov_b64 s[50:51], -1
	s_cbranch_scc0 .LBB0_277
	s_cmp_gt_u32 s80, 15
	s_cbranch_scc0 .LBB0_274
	s_cmp_gt_u32 s80, 23
	s_cbranch_scc0 .LBB0_271
	v_and_b32_e32 v0, 64, v136
	v_cmp_eq_u32_e32 vcc, 0, v0
	s_and_saveexec_b64 s[50:51], vcc
	s_cbranch_execz .LBB0_270
	v_and_b32_e32 v0, 0x7ffff80, v136
	v_add_u32_e32 v0, s48, v0
	v_lshrrev_b32_e32 v130, 1, v136
	v_and_or_b32 v0, v136, 15, v0
	v_and_b32_e32 v137, 24, v130
	v_lshl_or_b32 v0, v0, 5, v137
	v_cvt_pk_bf16_f32 v130, v122, v123
	v_cvt_pk_bf16_f32 v131, v124, v125
	v_cvt_pk_bf16_f32 v132, v126, v127
	v_cvt_pk_bf16_f32 v133, v128, v129
	v_lshl_add_u64 v[138:139], v[0:1], 1, s[44:45]
	s_waitcnt vmcnt(0)
	global_store_dwordx4 v[138:139], v[130:133], off
	v_or_b32_e32 v138, 0x200, v0
	v_mov_b32_e32 v139, v1
	v_cvt_pk_bf16_f32 v130, v106, v107
	v_cvt_pk_bf16_f32 v131, v108, v109
	v_cvt_pk_bf16_f32 v132, v110, v111
	v_cvt_pk_bf16_f32 v133, v112, v113
	v_lshl_add_u64 v[138:139], v[138:139], 1, s[44:45]
	global_store_dwordx4 v[138:139], v[130:133], off
	v_or_b32_e32 v138, 0x400, v0
	v_mov_b32_e32 v139, v1
	v_cvt_pk_bf16_f32 v130, v90, v91
	v_cvt_pk_bf16_f32 v131, v92, v93
	v_cvt_pk_bf16_f32 v132, v94, v95
	v_cvt_pk_bf16_f32 v133, v96, v97
	v_lshl_add_u64 v[138:139], v[138:139], 1, s[44:45]
	global_store_dwordx4 v[138:139], v[130:133], off
	v_or_b32_e32 v138, 0x600, v0
	v_mov_b32_e32 v139, v1
	v_cvt_pk_bf16_f32 v130, v74, v75
	v_cvt_pk_bf16_f32 v131, v76, v77
	v_cvt_pk_bf16_f32 v132, v78, v79
	v_cvt_pk_bf16_f32 v133, v80, v81
	v_lshl_add_u64 v[138:139], v[138:139], 1, s[44:45]
	global_store_dwordx4 v[138:139], v[130:133], off
	v_or_b32_e32 v138, 0x800, v0
	v_mov_b32_e32 v139, v1
	v_cvt_pk_bf16_f32 v130, v58, v59
	v_cvt_pk_bf16_f32 v131, v60, v61
	v_cvt_pk_bf16_f32 v132, v62, v63
	v_cvt_pk_bf16_f32 v133, v64, v65
	v_lshl_add_u64 v[138:139], v[138:139], 1, s[44:45]
	global_store_dwordx4 v[138:139], v[130:133], off
	v_or_b32_e32 v138, 0xa00, v0
	v_mov_b32_e32 v139, v1
	v_cvt_pk_bf16_f32 v130, v42, v43
	v_cvt_pk_bf16_f32 v131, v44, v45
	v_cvt_pk_bf16_f32 v132, v46, v47
	v_cvt_pk_bf16_f32 v133, v48, v49
	v_lshl_add_u64 v[138:139], v[138:139], 1, s[44:45]
	global_store_dwordx4 v[138:139], v[130:133], off
	v_or_b32_e32 v138, 0xc00, v0
	v_mov_b32_e32 v139, v1
	v_cvt_pk_bf16_f32 v130, v26, v27
	v_cvt_pk_bf16_f32 v131, v28, v29
	v_cvt_pk_bf16_f32 v132, v30, v31
	v_cvt_pk_bf16_f32 v133, v32, v33
	v_lshl_add_u64 v[138:139], v[138:139], 1, s[44:45]
	v_or_b32_e32 v0, 0xe00, v0
	global_store_dwordx4 v[138:139], v[130:133], off
	v_lshl_add_u64 v[138:139], v[0:1], 1, s[44:45]
	s_nop 0
	v_cvt_pk_bf16_f32 v130, v10, v11
	v_cvt_pk_bf16_f32 v131, v12, v13
	v_cvt_pk_bf16_f32 v132, v14, v15
	v_cvt_pk_bf16_f32 v133, v16, v17
	global_store_dwordx4 v[138:139], v[130:133], off

.LBB0_271:
	s_andn2_b64 vcc, exec, s[50:51]
	s_cbranch_vccnz .LBB0_273
	v_lshrrev_b32_e32 v0, 6, v136
	v_mul_lo_u32 v137, v0, s14
	v_and_b32_e32 v130, 15, v136
	v_and_or_b32 v0, v136, 48, v137
	s_movk_i32 s4, 0x90
	v_mad_u32_u24 v0, v130, s4, v0
	v_cvt_pk_bf16_f32 v130, v122, v123
	v_cvt_pk_bf16_f32 v131, v124, v125
	v_cvt_pk_bf16_f32 v132, v126, v127
	v_cvt_pk_bf16_f32 v133, v128, v129
	s_waitcnt vmcnt(0)
	ds_write_b128 v0, v[130:133]
	v_cvt_pk_bf16_f32 v130, v114, v115
	v_cvt_pk_bf16_f32 v131, v116, v117
	v_cvt_pk_bf16_f32 v132, v118, v119
	v_cvt_pk_bf16_f32 v133, v120, v121
	ds_write_b128 v0, v[130:133] offset:64
	v_cvt_pk_bf16_f32 v130, v106, v107
	v_cvt_pk_bf16_f32 v131, v108, v109
	v_cvt_pk_bf16_f32 v132, v110, v111
	v_cvt_pk_bf16_f32 v133, v112, v113
	ds_write_b128 v0, v[130:133] offset:2304
	v_cvt_pk_bf16_f32 v130, v98, v99
	v_cvt_pk_bf16_f32 v131, v100, v101
	v_cvt_pk_bf16_f32 v132, v102, v103
	v_cvt_pk_bf16_f32 v133, v104, v105
	ds_write_b128 v0, v[130:133] offset:2368
	v_cvt_pk_bf16_f32 v130, v90, v91
	v_cvt_pk_bf16_f32 v131, v92, v93
	v_cvt_pk_bf16_f32 v132, v94, v95
	v_cvt_pk_bf16_f32 v133, v96, v97
	ds_write_b128 v0, v[130:133] offset:4608
	v_cvt_pk_bf16_f32 v130, v82, v83
	v_cvt_pk_bf16_f32 v131, v84, v85
	v_cvt_pk_bf16_f32 v132, v86, v87
	v_cvt_pk_bf16_f32 v133, v88, v89
	ds_write_b128 v0, v[130:133] offset:4672
	v_cvt_pk_bf16_f32 v130, v74, v75
	v_cvt_pk_bf16_f32 v131, v76, v77
	v_cvt_pk_bf16_f32 v132, v78, v79
	v_cvt_pk_bf16_f32 v133, v80, v81
	ds_write_b128 v0, v[130:133] offset:6912
	v_cvt_pk_bf16_f32 v130, v66, v67
	v_cvt_pk_bf16_f32 v131, v68, v69
	v_cvt_pk_bf16_f32 v132, v70, v71
	v_cvt_pk_bf16_f32 v133, v72, v73
	ds_write_b128 v0, v[130:133] offset:6976
	v_cvt_pk_bf16_f32 v130, v58, v59
	v_cvt_pk_bf16_f32 v131, v60, v61
	v_cvt_pk_bf16_f32 v132, v62, v63
	v_cvt_pk_bf16_f32 v133, v64, v65
	ds_write_b128 v0, v[130:133] offset:9216
	v_cvt_pk_bf16_f32 v130, v50, v51
	v_cvt_pk_bf16_f32 v131, v52, v53
	v_cvt_pk_bf16_f32 v132, v54, v55
	v_cvt_pk_bf16_f32 v133, v56, v57
	ds_write_b128 v0, v[130:133] offset:9280
	v_cvt_pk_bf16_f32 v130, v42, v43
	v_cvt_pk_bf16_f32 v131, v44, v45
	v_cvt_pk_bf16_f32 v132, v46, v47
	v_cvt_pk_bf16_f32 v133, v48, v49
	ds_write_b128 v0, v[130:133] offset:11520
	v_cvt_pk_bf16_f32 v130, v34, v35
	v_cvt_pk_bf16_f32 v131, v36, v37
	v_cvt_pk_bf16_f32 v132, v38, v39
	v_cvt_pk_bf16_f32 v133, v40, v41
	ds_write_b128 v0, v[130:133] offset:11584
	v_cvt_pk_bf16_f32 v130, v26, v27
	v_cvt_pk_bf16_f32 v131, v28, v29
	v_cvt_pk_bf16_f32 v132, v30, v31
	v_cvt_pk_bf16_f32 v133, v32, v33
	ds_write_b128 v0, v[130:133] offset:13824
	v_cvt_pk_bf16_f32 v130, v18, v19
	v_cvt_pk_bf16_f32 v131, v20, v21
	v_cvt_pk_bf16_f32 v132, v22, v23
	v_cvt_pk_bf16_f32 v133, v24, v25
	ds_write_b128 v0, v[130:133] offset:13888
	v_cvt_pk_bf16_f32 v130, v10, v11
	v_cvt_pk_bf16_f32 v131, v12, v13
	v_cvt_pk_bf16_f32 v132, v14, v15
	v_cvt_pk_bf16_f32 v133, v16, v17
	ds_write_b128 v0, v[130:133] offset:16128
	v_cvt_pk_bf16_f32 v130, v2, v3
	v_cvt_pk_bf16_f32 v131, v4, v5
	v_cvt_pk_bf16_f32 v132, v6, v7
	v_cvt_pk_bf16_f32 v133, v8, v9
	ds_write_b128 v0, v[130:133] offset:16192
	v_and_b32_e32 v0, 0xffffff80, v136
	v_add_u32_e32 v130, s48, v0
	v_ashrrev_i32_e32 v131, 31, v130
	v_lshlrev_b64 v[130:131], 11, v[130:131]
	v_lshl_add_u64 v[130:131], s[94:95], 0, v[130:131]
	s_mov_b32 s92, s46
	v_and_b32_e32 v0, 64, v136
	v_lshl_add_u64 v[130:131], s[92:93], 1, v[130:131]
	v_lshlrev_b32_e32 v0, 1, v0
	v_lshl_add_u64 v[138:139], v[130:131], 0, v[0:1]
	v_lshlrev_b32_e32 v0, 4, v136
	v_and_b32_e32 v0, 0x70, v0
	v_bfe_u32 v140, v136, 3, 3
	v_or_b32_e32 v130, v137, v0
	s_waitcnt lgkmcnt(0)
	v_mad_u32_u24 v137, v140, s4, v130
	ds_read_b128 v[130:133], v137
	v_lshl_add_u64 v[138:139], v[138:139], 0, v[0:1]
	s_mov_b64 s[4:5], 0x8fff000
	v_lshl_add_u64 v[138:139], v[138:139], 0, s[4:5]
	v_lshlrev_b32_e32 v0, 11, v140
	v_lshl_add_u64 v[140:141], v[138:139], 0, v[0:1]
	s_waitcnt lgkmcnt(0)
	global_store_dwordx4 v[140:141], v[130:133], off
	ds_read_b128 v[130:133], v137 offset:1152
	v_or_b32_e32 v140, 0x4000, v0
	v_mov_b32_e32 v141, v1
	v_lshl_add_u64 v[140:141], v[138:139], 0, v[140:141]
	s_movk_i32 s82, 0x1bff
	s_waitcnt lgkmcnt(0)
	global_store_dwordx4 v[140:141], v[130:133], off
	ds_read_b128 v[130:133], v137 offset:2304
	v_or_b32_e32 v140, 0x8000, v0
	v_mov_b32_e32 v141, v1
	v_lshl_add_u64 v[140:141], v[138:139], 0, v[140:141]
	s_waitcnt lgkmcnt(0)
	global_store_dwordx4 v[140:141], v[130:133], off
	ds_read_b128 v[130:133], v137 offset:3456
	v_or_b32_e32 v140, 0xc000, v0
	v_mov_b32_e32 v141, v1
	v_lshl_add_u64 v[140:141], v[138:139], 0, v[140:141]
	s_waitcnt lgkmcnt(0)
	global_store_dwordx4 v[140:141], v[130:133], off
	ds_read_b128 v[130:133], v137 offset:4608
	v_or_b32_e32 v140, 0x10000, v0
	v_mov_b32_e32 v141, v1
	v_lshl_add_u64 v[140:141], v[138:139], 0, v[140:141]
	s_waitcnt lgkmcnt(0)
	global_store_dwordx4 v[140:141], v[130:133], off
	ds_read_b128 v[130:133], v137 offset:5760
	v_or_b32_e32 v140, 0x14000, v0
	v_mov_b32_e32 v141, v1
	v_lshl_add_u64 v[140:141], v[138:139], 0, v[140:141]
	s_waitcnt lgkmcnt(0)
	global_store_dwordx4 v[140:141], v[130:133], off
	ds_read_b128 v[130:133], v137 offset:6912
	v_or_b32_e32 v140, 0x18000, v0
	v_mov_b32_e32 v141, v1
	v_lshl_add_u64 v[140:141], v[138:139], 0, v[140:141]
	s_waitcnt lgkmcnt(0)
	global_store_dwordx4 v[140:141], v[130:133], off
	ds_read_b128 v[130:133], v137 offset:8064
	v_or_b32_e32 v140, 0x1c000, v0
	v_mov_b32_e32 v141, v1
	v_lshl_add_u64 v[140:141], v[138:139], 0, v[140:141]
	s_waitcnt lgkmcnt(0)
	global_store_dwordx4 v[140:141], v[130:133], off
	ds_read_b128 v[130:133], v137 offset:9216
	v_or_b32_e32 v140, 0x20000, v0
	v_mov_b32_e32 v141, v1
	v_lshl_add_u64 v[140:141], v[138:139], 0, v[140:141]
	s_waitcnt lgkmcnt(0)
	global_store_dwordx4 v[140:141], v[130:133], off
	ds_read_b128 v[130:133], v137 offset:10368
	v_or_b32_e32 v140, 0x24000, v0
	v_mov_b32_e32 v141, v1
	v_lshl_add_u64 v[140:141], v[138:139], 0, v[140:141]
	s_waitcnt lgkmcnt(0)
	global_store_dwordx4 v[140:141], v[130:133], off
	ds_read_b128 v[130:133], v137 offset:11520
	v_or_b32_e32 v140, 0x28000, v0
	v_mov_b32_e32 v141, v1
	v_lshl_add_u64 v[140:141], v[138:139], 0, v[140:141]
	s_waitcnt lgkmcnt(0)
	global_store_dwordx4 v[140:141], v[130:133], off
	ds_read_b128 v[130:133], v137 offset:12672
	v_or_b32_e32 v140, 0x2c000, v0
	v_mov_b32_e32 v141, v1
	v_lshl_add_u64 v[140:141], v[138:139], 0, v[140:141]
	s_waitcnt lgkmcnt(0)
	global_store_dwordx4 v[140:141], v[130:133], off
	ds_read_b128 v[130:133], v137 offset:13824
	v_or_b32_e32 v140, 0x30000, v0
	v_mov_b32_e32 v141, v1
	v_lshl_add_u64 v[140:141], v[138:139], 0, v[140:141]
	s_waitcnt lgkmcnt(0)
	global_store_dwordx4 v[140:141], v[130:133], off
	ds_read_b128 v[130:133], v137 offset:14976
	v_or_b32_e32 v140, 0x34000, v0
	v_mov_b32_e32 v141, v1
	v_lshl_add_u64 v[140:141], v[138:139], 0, v[140:141]
	s_waitcnt lgkmcnt(0)
	global_store_dwordx4 v[140:141], v[130:133], off
	ds_read_b128 v[130:133], v137 offset:16128
	v_or_b32_e32 v140, 0x38000, v0
	v_mov_b32_e32 v141, v1
	v_lshl_add_u64 v[140:141], v[138:139], 0, v[140:141]
	v_or_b32_e32 v0, 0x3c000, v0
	s_waitcnt lgkmcnt(0)
	global_store_dwordx4 v[140:141], v[130:133], off
	ds_read_b128 v[130:133], v137 offset:17280
	v_lshl_add_u64 v[138:139], v[138:139], 0, v[0:1]
	s_waitcnt lgkmcnt(0)
	global_store_dwordx4 v[138:139], v[130:133], off
	s_waitcnt lgkmcnt(0)
	s_barrier

.LBB0_274:
	s_andn2_b64 vcc, exec, s[50:51]
	s_cbranch_vccnz .LBB0_276
	v_and_b32_e32 v0, 64, v136
	v_lshrrev_b32_e32 v130, 1, v136
	v_and_or_b32 v0, v130, 24, v0
	v_lshlrev_b32_e32 v130, 1, v136
	v_and_b32_e32 v130, 0xffffff1e, v130
	s_movk_i32 s7, 0x210
	v_mad_u32_u24 v0, v0, s7, v130
	v_cvt_pk_bf16_f32 v130, v122, v123
	v_cvt_pk_bf16_f32 v131, v124, v125
	s_waitcnt vmcnt(0)
	ds_write_b16 v0, v130
	ds_write_b16_d16_hi v0, v130 offset:528
	ds_write_b16 v0, v131 offset:1056
	ds_write_b16_d16_hi v0, v131 offset:1584
	v_cvt_pk_bf16_f32 v130, v106, v107
	v_cvt_pk_bf16_f32 v131, v108, v109
	ds_write_b16 v0, v130 offset:32
	ds_write_b16_d16_hi v0, v130 offset:560
	ds_write_b16 v0, v131 offset:1088
	ds_write_b16_d16_hi v0, v131 offset:1616
	v_cvt_pk_bf16_f32 v130, v90, v91
	v_cvt_pk_bf16_f32 v131, v92, v93
	ds_write_b16 v0, v130 offset:64
	ds_write_b16_d16_hi v0, v130 offset:592
	ds_write_b16 v0, v131 offset:1120
	ds_write_b16_d16_hi v0, v131 offset:1648
	v_cvt_pk_bf16_f32 v130, v74, v75
	v_cvt_pk_bf16_f32 v131, v76, v77
	ds_write_b16 v0, v130 offset:96
	ds_write_b16_d16_hi v0, v130 offset:624
	ds_write_b16 v0, v131 offset:1152
	ds_write_b16_d16_hi v0, v131 offset:1680
	v_cvt_pk_bf16_f32 v130, v58, v59
	v_cvt_pk_bf16_f32 v131, v60, v61
	ds_write_b16 v0, v130 offset:128
	ds_write_b16_d16_hi v0, v130 offset:656
	ds_write_b16 v0, v131 offset:1184
	ds_write_b16_d16_hi v0, v131 offset:1712
	v_cvt_pk_bf16_f32 v130, v42, v43
	v_cvt_pk_bf16_f32 v131, v44, v45
	ds_write_b16 v0, v130 offset:160
	ds_write_b16_d16_hi v0, v130 offset:688
	ds_write_b16 v0, v131 offset:1216
	ds_write_b16_d16_hi v0, v131 offset:1744
	v_cvt_pk_bf16_f32 v130, v26, v27
	v_cvt_pk_bf16_f32 v131, v28, v29
	ds_write_b16 v0, v130 offset:192
	ds_write_b16_d16_hi v0, v130 offset:720
	ds_write_b16 v0, v131 offset:1248
	ds_write_b16_d16_hi v0, v131 offset:1776
	v_cvt_pk_bf16_f32 v130, v10, v11
	v_cvt_pk_bf16_f32 v131, v12, v13
	ds_write_b16 v0, v130 offset:224
	ds_write_b16_d16_hi v0, v130 offset:752
	ds_write_b16 v0, v131 offset:1280
	ds_write_b16_d16_hi v0, v131 offset:1808
	v_cvt_pk_bf16_f32 v130, v126, v127
	v_cvt_pk_bf16_f32 v131, v128, v129
	ds_write_b16 v0, v130 offset:2112
	ds_write_b16_d16_hi v0, v130 offset:2640
	ds_write_b16 v0, v131 offset:3168
	ds_write_b16_d16_hi v0, v131 offset:3696
	v_cvt_pk_bf16_f32 v130, v110, v111
	v_cvt_pk_bf16_f32 v131, v112, v113
	ds_write_b16 v0, v130 offset:2144
	ds_write_b16_d16_hi v0, v130 offset:2672
	ds_write_b16 v0, v131 offset:3200
	ds_write_b16_d16_hi v0, v131 offset:3728
	v_cvt_pk_bf16_f32 v130, v94, v95
	v_cvt_pk_bf16_f32 v131, v96, v97
	ds_write_b16 v0, v130 offset:2176
	ds_write_b16_d16_hi v0, v130 offset:2704
	ds_write_b16 v0, v131 offset:3232
	ds_write_b16_d16_hi v0, v131 offset:3760
	v_cvt_pk_bf16_f32 v130, v78, v79
	v_cvt_pk_bf16_f32 v131, v80, v81
	ds_write_b16 v0, v130 offset:2208
	ds_write_b16_d16_hi v0, v130 offset:2736
	ds_write_b16 v0, v131 offset:3264
	ds_write_b16_d16_hi v0, v131 offset:3792
	v_cvt_pk_bf16_f32 v130, v62, v63
	v_cvt_pk_bf16_f32 v131, v64, v65
	ds_write_b16 v0, v130 offset:2240
	ds_write_b16_d16_hi v0, v130 offset:2768
	ds_write_b16 v0, v131 offset:3296
	ds_write_b16_d16_hi v0, v131 offset:3824
	v_cvt_pk_bf16_f32 v130, v46, v47
	v_cvt_pk_bf16_f32 v131, v48, v49
	ds_write_b16 v0, v130 offset:2272
	ds_write_b16_d16_hi v0, v130 offset:2800
	ds_write_b16 v0, v131 offset:3328
	ds_write_b16_d16_hi v0, v131 offset:3856
	v_cvt_pk_bf16_f32 v130, v30, v31
	v_cvt_pk_bf16_f32 v131, v32, v33
	ds_write_b16 v0, v130 offset:2304
	ds_write_b16_d16_hi v0, v130 offset:2832
	ds_write_b16 v0, v131 offset:3360
	ds_write_b16_d16_hi v0, v131 offset:3888
	v_cvt_pk_bf16_f32 v130, v14, v15
	v_cvt_pk_bf16_f32 v131, v16, v17
	ds_write_b16 v0, v130 offset:2336
	ds_write_b16_d16_hi v0, v130 offset:2864
	ds_write_b16 v0, v131 offset:3392
	ds_write_b16_d16_hi v0, v131 offset:3920
	v_cvt_pk_bf16_f32 v130, v114, v115
	v_cvt_pk_bf16_f32 v131, v116, v117
	ds_write_b16 v0, v130 offset:16896
	ds_write_b16_d16_hi v0, v130 offset:17424
	ds_write_b16 v0, v131 offset:17952
	ds_write_b16_d16_hi v0, v131 offset:18480
	v_cvt_pk_bf16_f32 v130, v98, v99
	v_cvt_pk_bf16_f32 v131, v100, v101
	ds_write_b16 v0, v130 offset:16928
	ds_write_b16_d16_hi v0, v130 offset:17456
	ds_write_b16 v0, v131 offset:17984
	ds_write_b16_d16_hi v0, v131 offset:18512
	v_cvt_pk_bf16_f32 v130, v82, v83
	v_cvt_pk_bf16_f32 v131, v84, v85
	ds_write_b16 v0, v130 offset:16960
	ds_write_b16_d16_hi v0, v130 offset:17488
	ds_write_b16 v0, v131 offset:18016
	ds_write_b16_d16_hi v0, v131 offset:18544
	v_cvt_pk_bf16_f32 v130, v66, v67
	v_cvt_pk_bf16_f32 v131, v68, v69
	ds_write_b16 v0, v130 offset:16992
	ds_write_b16_d16_hi v0, v130 offset:17520
	ds_write_b16 v0, v131 offset:18048
	ds_write_b16_d16_hi v0, v131 offset:18576
	v_cvt_pk_bf16_f32 v130, v50, v51
	v_cvt_pk_bf16_f32 v131, v52, v53
	ds_write_b16 v0, v130 offset:17024
	ds_write_b16_d16_hi v0, v130 offset:17552
	ds_write_b16 v0, v131 offset:18080
	ds_write_b16_d16_hi v0, v131 offset:18608
	v_cvt_pk_bf16_f32 v130, v34, v35
	v_cvt_pk_bf16_f32 v131, v36, v37
	ds_write_b16 v0, v130 offset:17056
	ds_write_b16_d16_hi v0, v130 offset:17584
	ds_write_b16 v0, v131 offset:18112
	ds_write_b16_d16_hi v0, v131 offset:18640
	v_cvt_pk_bf16_f32 v130, v18, v19
	v_cvt_pk_bf16_f32 v131, v20, v21
	ds_write_b16 v0, v130 offset:17088
	ds_write_b16_d16_hi v0, v130 offset:17616
	ds_write_b16 v0, v131 offset:18144
	ds_write_b16_d16_hi v0, v131 offset:18672
	v_cvt_pk_bf16_f32 v130, v2, v3
	v_cvt_pk_bf16_f32 v131, v4, v5
	ds_write_b16 v0, v130 offset:17120
	ds_write_b16_d16_hi v0, v130 offset:17648
	ds_write_b16 v0, v131 offset:18176
	ds_write_b16_d16_hi v0, v131 offset:18704
	v_cvt_pk_bf16_f32 v130, v118, v119
	v_cvt_pk_bf16_f32 v131, v120, v121
	ds_write_b16 v0, v130 offset:19008
	ds_write_b16_d16_hi v0, v130 offset:19536
	ds_write_b16 v0, v131 offset:20064
	ds_write_b16_d16_hi v0, v131 offset:20592
	v_cvt_pk_bf16_f32 v130, v102, v103
	v_cvt_pk_bf16_f32 v131, v104, v105
	ds_write_b16 v0, v130 offset:19040
	ds_write_b16_d16_hi v0, v130 offset:19568
	ds_write_b16 v0, v131 offset:20096
	ds_write_b16_d16_hi v0, v131 offset:20624
	v_cvt_pk_bf16_f32 v130, v86, v87
	v_cvt_pk_bf16_f32 v131, v88, v89
	ds_write_b16 v0, v130 offset:19072
	ds_write_b16_d16_hi v0, v130 offset:19600
	ds_write_b16 v0, v131 offset:20128
	ds_write_b16_d16_hi v0, v131 offset:20656
	v_cvt_pk_bf16_f32 v130, v70, v71
	v_cvt_pk_bf16_f32 v131, v72, v73
	ds_write_b16 v0, v130 offset:19104
	ds_write_b16_d16_hi v0, v130 offset:19632
	ds_write_b16 v0, v131 offset:20160
	ds_write_b16_d16_hi v0, v131 offset:20688
	v_cvt_pk_bf16_f32 v130, v54, v55
	v_cvt_pk_bf16_f32 v131, v56, v57
	ds_write_b16 v0, v130 offset:19136
	ds_write_b16_d16_hi v0, v130 offset:19664
	ds_write_b16 v0, v131 offset:20192
	ds_write_b16_d16_hi v0, v131 offset:20720
	v_cvt_pk_bf16_f32 v130, v38, v39
	v_cvt_pk_bf16_f32 v131, v40, v41
	ds_write_b16 v0, v130 offset:19168
	ds_write_b16_d16_hi v0, v130 offset:19696
	ds_write_b16 v0, v131 offset:20224
	ds_write_b16_d16_hi v0, v131 offset:20752
	v_cvt_pk_bf16_f32 v130, v22, v23
	v_cvt_pk_bf16_f32 v131, v24, v25
	ds_write_b16 v0, v130 offset:19200
	ds_write_b16_d16_hi v0, v130 offset:19728
	ds_write_b16 v0, v131 offset:20256
	ds_write_b16_d16_hi v0, v131 offset:20784
	v_cvt_pk_bf16_f32 v130, v6, v7
	s_lshl_b32 s4, s81, 10
	v_cvt_pk_bf16_f32 v131, v8, v9
	ds_write_b16 v0, v130 offset:19232
	ds_write_b16_d16_hi v0, v130 offset:19760
	ds_write_b16 v0, v131 offset:20288
	ds_write_b16_d16_hi v0, v131 offset:20816
	v_and_b32_e32 v130, 31, v136
	s_add_i32 s4, s46, s4
	v_lshlrev_b32_e32 v0, 4, v130
	v_ashrrev_i32_e32 v137, 5, v136
	s_add_i32 s6, s4, 0xfffffc00
	v_lshl_or_b32 v138, v130, 3, s49
	v_mad_u64_u32 v[130:131], s[4:5], v137, s7, v[0:1]
	s_waitcnt lgkmcnt(0)
	s_barrier
	ds_read_b128 v[130:133], v130
	v_add_u32_e32 v137, s6, v137
	v_mad_u64_u32 v[140:141], s[4:5], v137, s96, v[138:139]
	v_mov_b32_e32 v141, v1
	v_lshl_add_u64 v[140:141], v[140:141], 1, s[40:41]
	s_waitcnt lgkmcnt(0)
	global_store_dwordx4 v[140:141], v[130:133], off
	s_nop 1
	v_add_u32_e32 v130, 0x100, v136
	v_ashrrev_i32_e32 v137, 5, v130
	v_mad_u64_u32 v[130:131], s[4:5], v137, s7, v[0:1]
	ds_read_b128 v[130:133], v130
	v_add_u32_e32 v137, s6, v137
	v_mad_u64_u32 v[140:141], s[4:5], v137, s96, v[138:139]
	v_mov_b32_e32 v141, v1
	v_lshl_add_u64 v[140:141], v[140:141], 1, s[40:41]
	s_waitcnt lgkmcnt(0)
	global_store_dwordx4 v[140:141], v[130:133], off
	s_nop 1
	v_add_u32_e32 v130, 0x200, v136
	v_ashrrev_i32_e32 v137, 5, v130
	v_mad_u64_u32 v[130:131], s[4:5], v137, s7, v[0:1]
	ds_read_b128 v[130:133], v130
	v_add_u32_e32 v137, s6, v137
	v_mad_u64_u32 v[140:141], s[4:5], v137, s96, v[138:139]
	v_mov_b32_e32 v141, v1
	v_lshl_add_u64 v[140:141], v[140:141], 1, s[40:41]
	s_waitcnt lgkmcnt(0)
	global_store_dwordx4 v[140:141], v[130:133], off
	s_nop 1
	v_add_u32_e32 v130, 0x300, v136
	v_ashrrev_i32_e32 v137, 5, v130
	v_mad_u64_u32 v[130:131], s[4:5], v137, s7, v[0:1]
	ds_read_b128 v[130:133], v130
	v_add_u32_e32 v137, s6, v137
	v_mad_u64_u32 v[140:141], s[4:5], v137, s96, v[138:139]
	v_mov_b32_e32 v141, v1
	v_lshl_add_u64 v[140:141], v[140:141], 1, s[40:41]
	s_waitcnt lgkmcnt(0)
	global_store_dwordx4 v[140:141], v[130:133], off
	s_nop 1
	v_add_u32_e32 v130, 0x400, v136
	v_ashrrev_i32_e32 v137, 5, v130
	v_mad_u64_u32 v[130:131], s[4:5], v137, s7, v[0:1]
	ds_read_b128 v[130:133], v130
	v_add_u32_e32 v137, s6, v137
	v_mad_u64_u32 v[140:141], s[4:5], v137, s96, v[138:139]
	v_mov_b32_e32 v141, v1
	v_lshl_add_u64 v[140:141], v[140:141], 1, s[40:41]
	s_waitcnt lgkmcnt(0)
	global_store_dwordx4 v[140:141], v[130:133], off
	s_nop 1
	v_add_u32_e32 v130, 0x500, v136
	v_ashrrev_i32_e32 v137, 5, v130
	v_mad_u64_u32 v[130:131], s[4:5], v137, s7, v[0:1]
	ds_read_b128 v[130:133], v130
	v_add_u32_e32 v137, s6, v137
	v_mad_u64_u32 v[140:141], s[4:5], v137, s96, v[138:139]
	v_mov_b32_e32 v141, v1
	v_lshl_add_u64 v[140:141], v[140:141], 1, s[40:41]
	s_waitcnt lgkmcnt(0)
	global_store_dwordx4 v[140:141], v[130:133], off
	s_nop 1
	v_add_u32_e32 v130, 0x600, v136
	v_ashrrev_i32_e32 v137, 5, v130
	v_mad_u64_u32 v[130:131], s[4:5], v137, s7, v[0:1]
	ds_read_b128 v[130:133], v130
	v_add_u32_e32 v137, s6, v137
	v_mad_u64_u32 v[140:141], s[4:5], v137, s96, v[138:139]
	v_mov_b32_e32 v141, v1
	v_lshl_add_u64 v[140:141], v[140:141], 1, s[40:41]
	s_waitcnt lgkmcnt(0)
	global_store_dwordx4 v[140:141], v[130:133], off
	s_nop 1
	v_add_u32_e32 v130, 0x700, v136
	v_ashrrev_i32_e32 v137, 5, v130
	v_mad_u64_u32 v[130:131], s[4:5], v137, s7, v[0:1]
	ds_read_b128 v[130:133], v130
	v_add_u32_e32 v137, s6, v137
	v_mad_u64_u32 v[140:141], s[4:5], v137, s96, v[138:139]
	v_mov_b32_e32 v141, v1
	v_lshl_add_u64 v[140:141], v[140:141], 1, s[40:41]
	s_waitcnt lgkmcnt(0)
	global_store_dwordx4 v[140:141], v[130:133], off
	s_nop 1
	v_add_u32_e32 v130, 0x800, v136
	v_ashrrev_i32_e32 v137, 5, v130
	v_mad_u64_u32 v[130:131], s[4:5], v137, s7, v[0:1]
	ds_read_b128 v[130:133], v130
	v_add_u32_e32 v137, s6, v137
	v_mad_u64_u32 v[140:141], s[4:5], v137, s96, v[138:139]
	v_mov_b32_e32 v141, v1
	v_lshl_add_u64 v[140:141], v[140:141], 1, s[40:41]
	s_waitcnt lgkmcnt(0)
	global_store_dwordx4 v[140:141], v[130:133], off
	s_nop 1
	v_add_u32_e32 v130, 0x900, v136
	v_ashrrev_i32_e32 v137, 5, v130
	v_mad_u64_u32 v[130:131], s[4:5], v137, s7, v[0:1]
	ds_read_b128 v[130:133], v130
	v_add_u32_e32 v137, s6, v137
	v_mad_u64_u32 v[140:141], s[4:5], v137, s96, v[138:139]
	v_mov_b32_e32 v141, v1
	v_lshl_add_u64 v[140:141], v[140:141], 1, s[40:41]
	s_waitcnt lgkmcnt(0)
	global_store_dwordx4 v[140:141], v[130:133], off
	s_nop 1
	v_add_u32_e32 v130, 0xa00, v136
	v_ashrrev_i32_e32 v137, 5, v130
	v_mad_u64_u32 v[130:131], s[4:5], v137, s7, v[0:1]
	ds_read_b128 v[130:133], v130
	v_add_u32_e32 v137, s6, v137
	v_mad_u64_u32 v[140:141], s[4:5], v137, s96, v[138:139]
	v_mov_b32_e32 v141, v1
	v_lshl_add_u64 v[140:141], v[140:141], 1, s[40:41]
	s_waitcnt lgkmcnt(0)
	global_store_dwordx4 v[140:141], v[130:133], off
	s_nop 1
	v_add_u32_e32 v130, 0xb00, v136
	v_ashrrev_i32_e32 v137, 5, v130
	v_mad_u64_u32 v[130:131], s[4:5], v137, s7, v[0:1]
	ds_read_b128 v[130:133], v130
	v_add_u32_e32 v137, s6, v137
	v_mad_u64_u32 v[140:141], s[4:5], v137, s96, v[138:139]
	v_mov_b32_e32 v141, v1
	v_lshl_add_u64 v[140:141], v[140:141], 1, s[40:41]
	s_waitcnt lgkmcnt(0)
	global_store_dwordx4 v[140:141], v[130:133], off
	s_nop 1
	v_add_u32_e32 v130, 0xc00, v136
	v_ashrrev_i32_e32 v137, 5, v130
	v_mad_u64_u32 v[130:131], s[4:5], v137, s7, v[0:1]
	ds_read_b128 v[130:133], v130
	v_add_u32_e32 v137, s6, v137
	v_mad_u64_u32 v[140:141], s[4:5], v137, s96, v[138:139]
	v_mov_b32_e32 v141, v1
	v_lshl_add_u64 v[140:141], v[140:141], 1, s[40:41]
	s_waitcnt lgkmcnt(0)
	global_store_dwordx4 v[140:141], v[130:133], off
	s_nop 1
	v_add_u32_e32 v130, 0xd00, v136
	v_ashrrev_i32_e32 v137, 5, v130
	v_mad_u64_u32 v[130:131], s[4:5], v137, s7, v[0:1]
	ds_read_b128 v[130:133], v130
	v_add_u32_e32 v137, s6, v137
	v_mad_u64_u32 v[140:141], s[4:5], v137, s96, v[138:139]
	v_mov_b32_e32 v141, v1
	v_lshl_add_u64 v[140:141], v[140:141], 1, s[40:41]
	s_waitcnt lgkmcnt(0)
	global_store_dwordx4 v[140:141], v[130:133], off
	s_nop 1
	v_add_u32_e32 v130, 0xe00, v136
	v_ashrrev_i32_e32 v137, 5, v130
	v_mad_u64_u32 v[130:131], s[4:5], v137, s7, v[0:1]
	ds_read_b128 v[130:133], v130
	v_add_u32_e32 v137, s6, v137
	v_mad_u64_u32 v[140:141], s[4:5], v137, s96, v[138:139]
	v_mov_b32_e32 v141, v1
	v_lshl_add_u64 v[140:141], v[140:141], 1, s[40:41]
	s_waitcnt lgkmcnt(0)
	global_store_dwordx4 v[140:141], v[130:133], off
	s_nop 1
	v_add_u32_e32 v130, 0xf00, v136
	v_ashrrev_i32_e32 v137, 5, v130
	v_mad_u64_u32 v[130:131], s[4:5], v137, s7, v[0:1]
	ds_read_b128 v[130:133], v130
	v_add_u32_e32 v0, s6, v137
	v_mad_u64_u32 v[138:139], s[4:5], v0, s96, v[138:139]
	v_mov_b32_e32 v139, v1
	v_lshl_add_u64 v[138:139], v[138:139], 1, s[40:41]
	s_waitcnt lgkmcnt(0)
	global_store_dwordx4 v[138:139], v[130:133], off
	s_waitcnt lgkmcnt(0)
	s_barrier

.LBB0_277:
	s_andn2_b64 vcc, exec, s[50:51]
	s_cbranch_vccnz .LBB0_236
	s_cmp_lt_i32 s80, 4
	s_cselect_b64 vcc, -1, 0
	v_mov_b32_e32 v0, 0x3db504f3
	v_lshrrev_b32_e32 v130, 6, v136
	v_cndmask_b32_e32 v0, 1.0, v0, vcc
	v_mul_lo_u32 v130, v130, s14
	v_and_b32_e32 v131, 15, v136
	v_and_or_b32 v132, v136, 48, v130
	s_movk_i32 s4, 0x90
	v_pk_mul_f32 v[4:5], v[0:1], v[4:5] op_sel_hi:[0,1]
	v_pk_mul_f32 v[2:3], v[0:1], v[2:3] op_sel_hi:[0,1]
	v_pk_mul_f32 v[8:9], v[0:1], v[8:9] op_sel_hi:[0,1]
	v_pk_mul_f32 v[6:7], v[0:1], v[6:7] op_sel_hi:[0,1]
	v_mad_u32_u24 v131, v131, s4, v132
	v_pk_mul_f32 v[124:125], v[0:1], v[124:125] op_sel_hi:[0,1]
	v_pk_mul_f32 v[122:123], v[0:1], v[122:123] op_sel_hi:[0,1]
	v_pk_mul_f32 v[128:129], v[0:1], v[128:129] op_sel_hi:[0,1]
	v_pk_mul_f32 v[126:127], v[0:1], v[126:127] op_sel_hi:[0,1]
	v_pk_mul_f32 v[116:117], v[0:1], v[116:117] op_sel_hi:[0,1]
	v_pk_mul_f32 v[114:115], v[0:1], v[114:115] op_sel_hi:[0,1]
	v_pk_mul_f32 v[120:121], v[0:1], v[120:121] op_sel_hi:[0,1]
	v_pk_mul_f32 v[118:119], v[0:1], v[118:119] op_sel_hi:[0,1]
	v_pk_mul_f32 v[108:109], v[0:1], v[108:109] op_sel_hi:[0,1]
	v_pk_mul_f32 v[106:107], v[0:1], v[106:107] op_sel_hi:[0,1]
	v_pk_mul_f32 v[112:113], v[0:1], v[112:113] op_sel_hi:[0,1]
	v_pk_mul_f32 v[110:111], v[0:1], v[110:111] op_sel_hi:[0,1]
	v_pk_mul_f32 v[100:101], v[0:1], v[100:101] op_sel_hi:[0,1]
	v_pk_mul_f32 v[98:99], v[0:1], v[98:99] op_sel_hi:[0,1]
	v_pk_mul_f32 v[104:105], v[0:1], v[104:105] op_sel_hi:[0,1]
	v_pk_mul_f32 v[102:103], v[0:1], v[102:103] op_sel_hi:[0,1]
	v_pk_mul_f32 v[92:93], v[0:1], v[92:93] op_sel_hi:[0,1]
	v_pk_mul_f32 v[90:91], v[0:1], v[90:91] op_sel_hi:[0,1]
	v_pk_mul_f32 v[96:97], v[0:1], v[96:97] op_sel_hi:[0,1]
	v_pk_mul_f32 v[94:95], v[0:1], v[94:95] op_sel_hi:[0,1]
	v_pk_mul_f32 v[84:85], v[0:1], v[84:85] op_sel_hi:[0,1]
	v_pk_mul_f32 v[82:83], v[0:1], v[82:83] op_sel_hi:[0,1]
	v_pk_mul_f32 v[88:89], v[0:1], v[88:89] op_sel_hi:[0,1]
	v_pk_mul_f32 v[86:87], v[0:1], v[86:87] op_sel_hi:[0,1]
	v_pk_mul_f32 v[76:77], v[0:1], v[76:77] op_sel_hi:[0,1]
	v_pk_mul_f32 v[74:75], v[0:1], v[74:75] op_sel_hi:[0,1]
	v_pk_mul_f32 v[80:81], v[0:1], v[80:81] op_sel_hi:[0,1]
	v_pk_mul_f32 v[78:79], v[0:1], v[78:79] op_sel_hi:[0,1]
	v_pk_mul_f32 v[68:69], v[0:1], v[68:69] op_sel_hi:[0,1]
	v_pk_mul_f32 v[66:67], v[0:1], v[66:67] op_sel_hi:[0,1]
	v_pk_mul_f32 v[72:73], v[0:1], v[72:73] op_sel_hi:[0,1]
	v_pk_mul_f32 v[70:71], v[0:1], v[70:71] op_sel_hi:[0,1]
	v_pk_mul_f32 v[60:61], v[0:1], v[60:61] op_sel_hi:[0,1]
	v_pk_mul_f32 v[58:59], v[0:1], v[58:59] op_sel_hi:[0,1]
	v_pk_mul_f32 v[64:65], v[0:1], v[64:65] op_sel_hi:[0,1]
	v_pk_mul_f32 v[62:63], v[0:1], v[62:63] op_sel_hi:[0,1]
	v_pk_mul_f32 v[52:53], v[0:1], v[52:53] op_sel_hi:[0,1]
	v_pk_mul_f32 v[50:51], v[0:1], v[50:51] op_sel_hi:[0,1]
	v_pk_mul_f32 v[56:57], v[0:1], v[56:57] op_sel_hi:[0,1]
	v_pk_mul_f32 v[54:55], v[0:1], v[54:55] op_sel_hi:[0,1]
	v_pk_mul_f32 v[44:45], v[0:1], v[44:45] op_sel_hi:[0,1]
	v_pk_mul_f32 v[42:43], v[0:1], v[42:43] op_sel_hi:[0,1]
	v_pk_mul_f32 v[48:49], v[0:1], v[48:49] op_sel_hi:[0,1]
	v_pk_mul_f32 v[46:47], v[0:1], v[46:47] op_sel_hi:[0,1]
	v_pk_mul_f32 v[36:37], v[0:1], v[36:37] op_sel_hi:[0,1]
	v_pk_mul_f32 v[34:35], v[0:1], v[34:35] op_sel_hi:[0,1]
	v_pk_mul_f32 v[40:41], v[0:1], v[40:41] op_sel_hi:[0,1]
	v_pk_mul_f32 v[38:39], v[0:1], v[38:39] op_sel_hi:[0,1]
	v_pk_mul_f32 v[28:29], v[0:1], v[28:29] op_sel_hi:[0,1]
	v_pk_mul_f32 v[26:27], v[0:1], v[26:27] op_sel_hi:[0,1]
	v_pk_mul_f32 v[32:33], v[0:1], v[32:33] op_sel_hi:[0,1]
	v_pk_mul_f32 v[30:31], v[0:1], v[30:31] op_sel_hi:[0,1]
	v_pk_mul_f32 v[20:21], v[0:1], v[20:21] op_sel_hi:[0,1]
	v_pk_mul_f32 v[18:19], v[0:1], v[18:19] op_sel_hi:[0,1]
	v_pk_mul_f32 v[24:25], v[0:1], v[24:25] op_sel_hi:[0,1]
	v_pk_mul_f32 v[22:23], v[0:1], v[22:23] op_sel_hi:[0,1]
	v_pk_mul_f32 v[12:13], v[0:1], v[12:13] op_sel_hi:[0,1]
	v_pk_mul_f32 v[10:11], v[0:1], v[10:11] op_sel_hi:[0,1]
	v_pk_mul_f32 v[16:17], v[0:1], v[16:17] op_sel_hi:[0,1]
	v_pk_mul_f32 v[14:15], v[0:1], v[14:15] op_sel_hi:[0,1]
	v_cvt_pk_bf16_f32 v2, v2, v3
	v_cvt_pk_bf16_f32 v3, v4, v5
	v_cvt_pk_bf16_f32 v4, v6, v7
	v_cvt_pk_bf16_f32 v5, v8, v9
	v_and_b32_e32 v0, 0xffffff80, v136
	s_waitcnt vmcnt(0)
	ds_write_b128 v131, v[2:5] offset:16192
	v_add_u32_e32 v2, s48, v0
	v_ashrrev_i32_e32 v3, 31, v2
	v_lshlrev_b64 v[2:3], 11, v[2:3]
	v_lshl_add_u64 v[2:3], s[42:43], 0, v[2:3]
	v_and_b32_e32 v0, 64, v136
	v_lshl_add_u64 v[2:3], s[46:47], 1, v[2:3]
	v_lshlrev_b32_e32 v0, 1, v0
	v_lshl_add_u64 v[6:7], v[2:3], 0, v[0:1]
	v_lshlrev_b32_e32 v0, 4, v136
	v_and_b32_e32 v0, 0x70, v0
	v_cvt_pk_bf16_f32 v122, v122, v123
	v_cvt_pk_bf16_f32 v123, v124, v125
	v_cvt_pk_bf16_f32 v124, v126, v127
	v_cvt_pk_bf16_f32 v125, v128, v129
	v_cvt_pk_bf16_f32 v114, v114, v115
	v_cvt_pk_bf16_f32 v115, v116, v117
	v_cvt_pk_bf16_f32 v116, v118, v119
	v_cvt_pk_bf16_f32 v117, v120, v121
	v_cvt_pk_bf16_f32 v106, v106, v107
	v_cvt_pk_bf16_f32 v107, v108, v109
	v_cvt_pk_bf16_f32 v108, v110, v111
	v_cvt_pk_bf16_f32 v109, v112, v113
	v_cvt_pk_bf16_f32 v98, v98, v99
	v_cvt_pk_bf16_f32 v99, v100, v101
	v_cvt_pk_bf16_f32 v100, v102, v103
	v_cvt_pk_bf16_f32 v101, v104, v105
	v_cvt_pk_bf16_f32 v90, v90, v91
	v_cvt_pk_bf16_f32 v91, v92, v93
	v_cvt_pk_bf16_f32 v92, v94, v95
	v_cvt_pk_bf16_f32 v93, v96, v97
	v_cvt_pk_bf16_f32 v82, v82, v83
	v_cvt_pk_bf16_f32 v83, v84, v85
	v_cvt_pk_bf16_f32 v84, v86, v87
	v_cvt_pk_bf16_f32 v85, v88, v89
	v_cvt_pk_bf16_f32 v74, v74, v75
	v_cvt_pk_bf16_f32 v75, v76, v77
	v_cvt_pk_bf16_f32 v76, v78, v79
	v_cvt_pk_bf16_f32 v77, v80, v81
	v_cvt_pk_bf16_f32 v66, v66, v67
	v_cvt_pk_bf16_f32 v67, v68, v69
	v_cvt_pk_bf16_f32 v68, v70, v71
	v_cvt_pk_bf16_f32 v69, v72, v73
	v_cvt_pk_bf16_f32 v58, v58, v59
	v_cvt_pk_bf16_f32 v59, v60, v61
	v_cvt_pk_bf16_f32 v60, v62, v63
	v_cvt_pk_bf16_f32 v61, v64, v65
	v_cvt_pk_bf16_f32 v50, v50, v51
	v_cvt_pk_bf16_f32 v51, v52, v53
	v_cvt_pk_bf16_f32 v52, v54, v55
	v_cvt_pk_bf16_f32 v53, v56, v57
	v_cvt_pk_bf16_f32 v42, v42, v43
	v_cvt_pk_bf16_f32 v43, v44, v45
	v_cvt_pk_bf16_f32 v44, v46, v47
	v_cvt_pk_bf16_f32 v45, v48, v49
	v_cvt_pk_bf16_f32 v34, v34, v35
	v_cvt_pk_bf16_f32 v35, v36, v37
	v_cvt_pk_bf16_f32 v36, v38, v39
	v_cvt_pk_bf16_f32 v37, v40, v41
	v_cvt_pk_bf16_f32 v26, v26, v27
	v_cvt_pk_bf16_f32 v27, v28, v29
	v_cvt_pk_bf16_f32 v28, v30, v31
	v_cvt_pk_bf16_f32 v29, v32, v33
	v_cvt_pk_bf16_f32 v18, v18, v19
	v_cvt_pk_bf16_f32 v19, v20, v21
	v_cvt_pk_bf16_f32 v20, v22, v23
	v_cvt_pk_bf16_f32 v21, v24, v25
	v_cvt_pk_bf16_f32 v10, v10, v11
	v_cvt_pk_bf16_f32 v11, v12, v13
	v_cvt_pk_bf16_f32 v12, v14, v15
	v_cvt_pk_bf16_f32 v13, v16, v17
	v_bfe_u32 v8, v136, 3, 3
	v_or_b32_e32 v2, v130, v0
	ds_write_b128 v131, v[122:125]
	ds_write_b128 v131, v[114:117] offset:64
	ds_write_b128 v131, v[106:109] offset:2304
	ds_write_b128 v131, v[98:101] offset:2368
	ds_write_b128 v131, v[90:93] offset:4608
	ds_write_b128 v131, v[82:85] offset:4672
	ds_write_b128 v131, v[74:77] offset:6912
	ds_write_b128 v131, v[66:69] offset:6976
	ds_write_b128 v131, v[58:61] offset:9216
	ds_write_b128 v131, v[50:53] offset:9280
	ds_write_b128 v131, v[42:45] offset:11520
	ds_write_b128 v131, v[34:37] offset:11584
	ds_write_b128 v131, v[26:29] offset:13824
	ds_write_b128 v131, v[18:21] offset:13888
	ds_write_b128 v131, v[10:13] offset:16128
	s_waitcnt lgkmcnt(0)
	v_mad_u32_u24 v10, v8, s4, v2
	ds_read_b128 v[2:5], v10
	v_lshl_add_u64 v[6:7], v[6:7], 0, v[0:1]
	v_lshlrev_b32_e32 v0, 11, v8
	v_lshl_add_u64 v[8:9], v[6:7], 0, v[0:1]
	s_waitcnt lgkmcnt(0)
	global_store_dwordx4 v[8:9], v[2:5], off
	ds_read_b128 v[2:5], v10 offset:1152
	v_or_b32_e32 v8, 0x4000, v0
	v_mov_b32_e32 v9, v1
	v_lshl_add_u64 v[8:9], v[6:7], 0, v[8:9]
	s_waitcnt lgkmcnt(0)
	global_store_dwordx4 v[8:9], v[2:5], off
	ds_read_b128 v[2:5], v10 offset:2304
	v_or_b32_e32 v8, 0x8000, v0
	v_mov_b32_e32 v9, v1
	v_lshl_add_u64 v[8:9], v[6:7], 0, v[8:9]
	s_waitcnt lgkmcnt(0)
	global_store_dwordx4 v[8:9], v[2:5], off
	ds_read_b128 v[2:5], v10 offset:3456
	v_or_b32_e32 v8, 0xc000, v0
	v_mov_b32_e32 v9, v1
	v_lshl_add_u64 v[8:9], v[6:7], 0, v[8:9]
	s_waitcnt lgkmcnt(0)
	global_store_dwordx4 v[8:9], v[2:5], off
	ds_read_b128 v[2:5], v10 offset:4608
	v_or_b32_e32 v8, 0x10000, v0
	v_mov_b32_e32 v9, v1
	v_lshl_add_u64 v[8:9], v[6:7], 0, v[8:9]
	s_waitcnt lgkmcnt(0)
	global_store_dwordx4 v[8:9], v[2:5], off
	ds_read_b128 v[2:5], v10 offset:5760
	v_or_b32_e32 v8, 0x14000, v0
	v_mov_b32_e32 v9, v1
	v_lshl_add_u64 v[8:9], v[6:7], 0, v[8:9]
	s_waitcnt lgkmcnt(0)
	global_store_dwordx4 v[8:9], v[2:5], off
	ds_read_b128 v[2:5], v10 offset:6912
	v_or_b32_e32 v8, 0x18000, v0
	v_mov_b32_e32 v9, v1
	v_lshl_add_u64 v[8:9], v[6:7], 0, v[8:9]
	s_waitcnt lgkmcnt(0)
	global_store_dwordx4 v[8:9], v[2:5], off
	ds_read_b128 v[2:5], v10 offset:8064
	v_or_b32_e32 v8, 0x1c000, v0
	v_mov_b32_e32 v9, v1
	v_lshl_add_u64 v[8:9], v[6:7], 0, v[8:9]
	s_waitcnt lgkmcnt(0)
	global_store_dwordx4 v[8:9], v[2:5], off
	ds_read_b128 v[2:5], v10 offset:9216
	v_or_b32_e32 v8, 0x20000, v0
	v_mov_b32_e32 v9, v1
	v_lshl_add_u64 v[8:9], v[6:7], 0, v[8:9]
	s_waitcnt lgkmcnt(0)
	global_store_dwordx4 v[8:9], v[2:5], off
	ds_read_b128 v[2:5], v10 offset:10368
	v_or_b32_e32 v8, 0x24000, v0
	v_mov_b32_e32 v9, v1
	v_lshl_add_u64 v[8:9], v[6:7], 0, v[8:9]
	s_waitcnt lgkmcnt(0)
	global_store_dwordx4 v[8:9], v[2:5], off
	ds_read_b128 v[2:5], v10 offset:11520
	v_or_b32_e32 v8, 0x28000, v0
	v_mov_b32_e32 v9, v1
	v_lshl_add_u64 v[8:9], v[6:7], 0, v[8:9]
	s_waitcnt lgkmcnt(0)
	global_store_dwordx4 v[8:9], v[2:5], off
	ds_read_b128 v[2:5], v10 offset:12672
	v_or_b32_e32 v8, 0x2c000, v0
	v_mov_b32_e32 v9, v1
	v_lshl_add_u64 v[8:9], v[6:7], 0, v[8:9]
	s_waitcnt lgkmcnt(0)
	global_store_dwordx4 v[8:9], v[2:5], off
	ds_read_b128 v[2:5], v10 offset:13824
	v_or_b32_e32 v8, 0x30000, v0
	v_mov_b32_e32 v9, v1
	v_lshl_add_u64 v[8:9], v[6:7], 0, v[8:9]
	s_waitcnt lgkmcnt(0)
	global_store_dwordx4 v[8:9], v[2:5], off
	ds_read_b128 v[2:5], v10 offset:14976
	v_or_b32_e32 v8, 0x34000, v0
	v_mov_b32_e32 v9, v1
	v_lshl_add_u64 v[8:9], v[6:7], 0, v[8:9]
	s_waitcnt lgkmcnt(0)
	global_store_dwordx4 v[8:9], v[2:5], off
	ds_read_b128 v[2:5], v10 offset:16128
	v_or_b32_e32 v8, 0x38000, v0
	v_mov_b32_e32 v9, v1
	v_lshl_add_u64 v[8:9], v[6:7], 0, v[8:9]
	v_or_b32_e32 v0, 0x3c000, v0
	s_waitcnt lgkmcnt(0)
	global_store_dwordx4 v[8:9], v[2:5], off
	ds_read_b128 v[2:5], v10 offset:17280
	v_lshl_add_u64 v[6:7], v[6:7], 0, v[0:1]
	s_waitcnt lgkmcnt(0)
	global_store_dwordx4 v[6:7], v[2:5], off
	s_waitcnt lgkmcnt(0)
	s_barrier
	s_branch .LBB0_236

.LBB0_290:
	v_ashrrev_i32_e32 v4, 5, v0
	v_cvt_f32_i32_e32 v4, v4
	s_movk_i32 s4, 0x6ff
	v_mul_f32_e32 v4, v156, v4
	v_mul_f32_e32 v6, 0.15915494, v4
	v_cos_f32_e32 v7, v6
	v_add_co_u32_e32 v4, vcc, 0xffffe000, v2
	s_nop 1
	v_addc_co_u32_e32 v5, vcc, -1, v3, vcc
	global_store_dword v[4:5], v7, off
	v_sin_f32_e32 v4, v6
	v_cmp_lt_i32_e32 vcc, s4, v0
	s_or_b64 s[26:27], vcc, s[26:27]
	global_store_dword v[2:3], v4, off
	v_add_u32_e32 v4, 0x100, v0
	v_lshl_add_u64 v[2:3], v[2:3], 0, s[86:87]
	v_mov_b32_e32 v0, v4
	s_andn2_b64 exec, exec, s[26:27]
	s_cbranch_execnz .LBB0_290

.LBB0_301:
	s_or_b64 exec, exec, s[54:55]
	v_ashrrev_i32_e32 v3, 31, v2
	v_lshlrev_b64 v[2:3], 11, v[2:3]
	v_lshl_add_u64 v[2:3], s[0:1], 0, v[2:3]
	v_lshlrev_b32_e32 v0, 1, v5
	v_lshl_add_u64 v[2:3], v[2:3], 0, v[0:1]
	v_add_co_u32_e32 v2, vcc, 0x600000, v2
	v_add_u32_e32 v20, 0x100, v20
	s_nop 0
	v_addc_co_u32_e32 v3, vcc, 0, v3, vcc
	v_add_co_u32_e32 v4, vcc, 1, v4
	s_or_b64 s[52:53], vcc, s[52:53]
	v_subrev_u32_e32 v240, s94, v2
	v_bfe_u32 v241, v240, 6, 5
	v_and_b32_e32 v242, 63, v240
	v_lshl_or_b32 v242, v241, 10, v242
	v_bfe_u32 v241, v240, 11, 4
	v_lshl_or_b32 v242, v241, 6, v242
	v_and_b32_e32 v241, 0x7fff, v240
	v_sub_u32_e32 v242, v242, v241
	v_ashrrev_i32_e32 v243, 31, v242
	v_lshl_add_u64 v[240:241], v[2:3], 0, v[242:243]
	global_store_short v[240:241], v6, off
	s_andn2_b64 exec, exec, s[52:53]
	s_cbranch_execz .LBB0_304

.LBB0_307:
	s_or_b64 exec, exec, s[52:53]
	v_ashrrev_i32_e32 v19, 31, v18
	v_lshlrev_b64 v[18:19], 11, v[18:19]
	v_lshl_add_u64 v[18:19], v[16:17], 0, v[18:19]
	v_add_co_u32_e32 v18, vcc, 0x600000, v18
	s_nop 1
	v_addc_co_u32_e32 v19, vcc, 0, v19, vcc
	v_cmp_lt_i32_e32 vcc, s82, v20
	s_or_b64 s[50:51], vcc, s[50:51]
	v_add_u32_e32 v20, 0x400, v20
	v_subrev_u32_e32 v240, s94, v18
	v_bfe_u32 v241, v240, 6, 5
	v_and_b32_e32 v242, 63, v240
	v_lshl_or_b32 v242, v241, 10, v242
	v_bfe_u32 v241, v240, 11, 4
	v_lshl_or_b32 v242, v241, 6, v242
	v_and_b32_e32 v241, 0x7fff, v240
	v_sub_u32_e32 v242, v242, v241
	v_ashrrev_i32_e32 v243, 31, v242
	v_lshl_add_u64 v[240:241], v[18:19], 0, v[242:243]
	global_store_short v[240:241], v21, off
	s_andn2_b64 exec, exec, s[50:51]
	s_cbranch_execz .LBB0_316

.LBB0_310:
	s_or_b64 exec, exec, s[52:53]
	v_ashrrev_i32_e32 v19, 31, v18
	v_lshlrev_b64 v[18:19], 11, v[18:19]
	v_lshl_add_u64 v[18:19], v[4:5], 0, v[18:19]
	v_add_co_u32_e32 v18, vcc, 0x600000, v18
	v_add_u32_e32 v22, 0x100, v20
	s_nop 0
	v_addc_co_u32_e32 v19, vcc, 0, v19, vcc
	v_subrev_u32_e32 v240, s94, v18
	v_bfe_u32 v241, v240, 6, 5
	v_and_b32_e32 v242, 63, v240
	v_lshl_or_b32 v242, v241, 10, v242
	v_bfe_u32 v241, v240, 11, 4
	v_lshl_or_b32 v242, v241, 6, v242
	v_and_b32_e32 v241, 0x7fff, v240
	v_sub_u32_e32 v242, v242, v241
	v_ashrrev_i32_e32 v243, 31, v242
	v_lshl_add_u64 v[240:241], v[18:19], 0, v[242:243]
	global_store_short v[240:241], v0, off
	v_ashrrev_i32_e32 v0, 10, v22
	v_add_u32_e32 v18, s6, v0
	v_cmp_gt_i32_e32 vcc, 32, v18
	s_and_saveexec_b64 s[52:53], vcc
	s_cbranch_execz .LBB0_312
	v_ashrrev_i32_e32 v24, 4, v18
	v_ashrrev_i32_e32 v25, 31, v24
	v_and_b32_e32 v0, 15, v18
	v_lshlrev_b64 v[24:25], 16, v[24:25]
	v_lshl_add_u64 v[24:25], v[6:7], 0, v[24:25]
	v_lshlrev_b32_e32 v0, 2, v0
	v_lshl_add_u64 v[24:25], v[24:25], 0, v[0:1]
	global_load_dword v0, v[24:25], off
	s_waitcnt vmcnt(0)
	v_cvt_pk_bf16_f32 v21, v0, s0
.LBB0_312:
	s_or_b64 exec, exec, s[52:53]
	v_ashrrev_i32_e32 v19, 31, v18
	v_lshlrev_b64 v[18:19], 11, v[18:19]
	v_lshl_add_u64 v[18:19], v[8:9], 0, v[18:19]
	v_add_co_u32_e32 v18, vcc, 0x600000, v18
	v_add_u32_e32 v22, 0x100, v22
	s_nop 0
	v_addc_co_u32_e32 v19, vcc, 0, v19, vcc
	v_ashrrev_i32_e32 v0, 10, v22
	v_subrev_u32_e32 v240, s94, v18
	v_bfe_u32 v241, v240, 6, 5
	v_and_b32_e32 v242, 63, v240
	v_lshl_or_b32 v242, v241, 10, v242
	v_bfe_u32 v241, v240, 11, 4
	v_lshl_or_b32 v242, v241, 6, v242
	v_and_b32_e32 v241, 0x7fff, v240
	v_sub_u32_e32 v242, v242, v241
	v_ashrrev_i32_e32 v243, 31, v242
	v_lshl_add_u64 v[240:241], v[18:19], 0, v[242:243]
	global_store_short v[240:241], v21, off
	v_add_u32_e32 v18, s6, v0
	v_cmp_gt_i32_e32 vcc, 32, v18
	v_mov_b32_e32 v21, 0
	v_mov_b32_e32 v0, 0
	s_and_saveexec_b64 s[52:53], vcc
	s_cbranch_execz .LBB0_314
	v_ashrrev_i32_e32 v24, 4, v18
	v_ashrrev_i32_e32 v25, 31, v24
	v_and_b32_e32 v0, 15, v18
	v_lshlrev_b64 v[24:25], 16, v[24:25]
	v_lshl_add_u64 v[24:25], v[10:11], 0, v[24:25]
	v_lshlrev_b32_e32 v0, 2, v0
	v_lshl_add_u64 v[24:25], v[24:25], 0, v[0:1]
	global_load_dword v0, v[24:25], off
	s_waitcnt vmcnt(0)
	v_cvt_pk_bf16_f32 v0, v0, s0
.LBB0_314:
	s_or_b64 exec, exec, s[52:53]
	v_ashrrev_i32_e32 v19, 31, v18
	v_lshlrev_b64 v[18:19], 11, v[18:19]
	v_lshl_add_u64 v[18:19], v[12:13], 0, v[18:19]
	v_add_co_u32_e32 v18, vcc, 0x600000, v18
	s_nop 1
	v_addc_co_u32_e32 v19, vcc, 0, v19, vcc
	v_subrev_u32_e32 v240, s94, v18
	v_bfe_u32 v241, v240, 6, 5
	v_and_b32_e32 v242, 63, v240
	v_lshl_or_b32 v242, v241, 10, v242
	v_bfe_u32 v241, v240, 11, 4
	v_lshl_or_b32 v242, v241, 6, v242
	v_and_b32_e32 v241, 0x7fff, v240
	v_sub_u32_e32 v242, v242, v241
	v_ashrrev_i32_e32 v243, 31, v242
	v_lshl_add_u64 v[240:241], v[18:19], 0, v[242:243]
	global_store_short v[240:241], v0, off
	v_add_u32_e32 v0, 0x100, v22
	v_ashrrev_i32_e32 v0, 10, v0
	v_add_u32_e32 v18, s6, v0
	v_cmp_gt_i32_e32 vcc, 32, v18
	s_and_saveexec_b64 s[52:53], vcc
	s_cbranch_execz .LBB0_307
	v_ashrrev_i32_e32 v22, 4, v18
	v_ashrrev_i32_e32 v23, 31, v22
	v_and_b32_e32 v0, 15, v18
	v_lshlrev_b64 v[22:23], 16, v[22:23]
	v_lshl_add_u64 v[22:23], v[14:15], 0, v[22:23]
	v_lshlrev_b32_e32 v0, 2, v0
	v_lshl_add_u64 v[22:23], v[22:23], 0, v[0:1]
	global_load_dword v0, v[22:23], off
	s_waitcnt vmcnt(0)
	v_cvt_pk_bf16_f32 v21, v0, s0
	s_branch .LBB0_307

.LBB0_319:
	s_andn2_b64 vcc, exec, s[26:27]
	s_cbranch_vccnz .LBB0_321
	ds_read2_b32 v[2:3], v39 offset1:65
	ds_read2_b32 v[4:5], v39 offset0:130 offset1:195
	v_add_u32_e32 v0, 0x400, v39
	ds_read2_b32 v[8:9], v0 offset0:134 offset1:199
	v_mov_b32_e32 v109, v1
	s_waitcnt lgkmcnt(0)
	v_cvt_pk_bf16_f32 v2, v2, v3
	v_cvt_pk_bf16_f32 v3, v4, v5
	ds_read2_b32 v[4:5], v0 offset0:4 offset1:69
	v_lshl_add_u64 v[6:7], s[24:25], 0, v[108:109]
	v_add_u32_e32 v0, 0x400, v162
	s_waitcnt lgkmcnt(0)
	v_cvt_pk_bf16_f32 v4, v4, v5
	v_cvt_pk_bf16_f32 v5, v8, v9
	v_add_u32_e32 v8, s4, v153
	v_ashrrev_i32_e32 v9, 31, v8
	v_lshlrev_b64 v[8:9], 11, v[8:9]
	v_lshl_add_u64 v[8:9], v[6:7], 0, v[8:9]
	v_subrev_u32_e32 v240, s94, v8
	v_bfe_u32 v241, v240, 6, 5
	v_and_b32_e32 v242, 63, v240
	v_lshl_or_b32 v242, v241, 10, v242
	v_bfe_u32 v241, v240, 11, 4
	v_lshl_or_b32 v242, v241, 6, v242
	v_and_b32_e32 v241, 0x7fff, v240
	v_sub_u32_e32 v242, v242, v241
	v_ashrrev_i32_e32 v243, 31, v242
	v_lshl_add_u64 v[240:241], v[8:9], 0, v[242:243]
	global_store_dwordx4 v[240:241], v[2:5], off
	ds_read2_b32 v[2:3], v162 offset1:65
	ds_read2_b32 v[4:5], v162 offset0:130 offset1:195
	ds_read2_b32 v[8:9], v0 offset0:134 offset1:199
	s_waitcnt lgkmcnt(0)
	v_cvt_pk_bf16_f32 v2, v2, v3
	v_cvt_pk_bf16_f32 v3, v4, v5
	ds_read2_b32 v[4:5], v0 offset0:4 offset1:69
	s_waitcnt lgkmcnt(0)
	v_cvt_pk_bf16_f32 v4, v4, v5
	v_cvt_pk_bf16_f32 v5, v8, v9
	v_add_u32_e32 v8, s4, v161
	v_ashrrev_i32_e32 v9, 31, v8
	v_lshlrev_b64 v[8:9], 11, v[8:9]
	v_lshl_add_u64 v[6:7], v[6:7], 0, v[8:9]
	v_subrev_u32_e32 v240, s94, v6
	v_bfe_u32 v241, v240, 6, 5
	v_and_b32_e32 v242, 63, v240
	v_lshl_or_b32 v242, v241, 10, v242
	v_bfe_u32 v241, v240, 11, 4
	v_lshl_or_b32 v242, v241, 6, v242
	v_and_b32_e32 v241, 0x7fff, v240
	v_sub_u32_e32 v242, v242, v241
	v_ashrrev_i32_e32 v243, 31, v242
	v_lshl_add_u64 v[240:241], v[6:7], 0, v[242:243]
	global_store_dwordx4 v[240:241], v[2:5], off

.LBB0_331:
	v_and_b32_e32 v9, 0x3fffffe0, v6
	v_lshl_or_b32 v9, v9, 2, v34
	ds_read_b32 v7, v0
	ds_read_b32 v10, v9 offset:38016
	v_ashrrev_i32_e32 v8, 5, v6
	v_cmp_lt_i32_e32 vcc, 31, v6
	v_add_u32_e32 v0, 0x400, v0
	s_or_b64 s[22:23], vcc, s[22:23]
	s_waitcnt lgkmcnt(0)
	v_add_f32_e32 v7, v7, v10
	ds_read_b32 v10, v9 offset:39168
	ds_read_b32 v9, v9 offset:40320
	s_waitcnt lgkmcnt(0)
	v_add_f32_e32 v7, v7, v10
	s_waitcnt lgkmcnt(0)
	v_add_f32_e32 v7, v7, v9
	global_load_dword v9, v[2:3], off
	s_waitcnt vmcnt(0)
	v_add_f32_e32 v7, v7, v9
	v_ashrrev_i32_e32 v9, 31, v8
	v_lshl_add_u64 v[8:9], s[26:27], 0, v[8:9]
	v_mad_u64_u32 v[10:11], s[4:5], v8, s33, v[4:5]
	v_mov_b32_e32 v8, v11
	v_mad_u64_u32 v[8:9], s[4:5], v9, s33, v[8:9]
	v_mov_b32_e32 v11, v8
	global_store_dword v[10:11], v7, off
	v_add_u32_e32 v7, 0x100, v6
	v_mov_b32_e32 v6, v7
	s_andn2_b64 exec, exec, s[22:23]
	s_cbranch_execnz .LBB0_331
	s_branch .LBB0_283
